# first K step of a tile: the two waits that only guard loads drained by the previous epilogue are skipped on all but the first tile of a GEMM call, so a tile no longer waits for the previous tile's res
# speedup vs baseline: 1.0003x; 1.0003x over previous
; #define PG8_STAGE(bufoff, gbase, voff) do { _Pragma("unroll") for (int _i = 0; _i < 2; ++_i) \
;         __builtin_amdgcn_global_load_lds((const unsigned*)((const char*)(gbase) + (voff)[_i]), (PG8_LAS unsigned*)(lds + (bufoff) + ldsw + _i * 8192), 16, 0, 0); } while (0)
; #define PG8_WAIT_V(n) asm volatile("s_waitcnt vmcnt(" #n ")" ::: "memory")
; #define PG8_BAR __builtin_amdgcn_s_barrier()
; template <class Epi, class Sched, bool ALIGN_EPI = false, bool SP2 = false, bool F8 = false>
; __device__ __forceinline__ void gemm_phase(PG8_LAS unsigned char* lds, const Gemm g, const Sched& S, const Epi& E) {
;     ...
;     for (int i = 0; i < 2; ++i) { int R, C; stage_rc(tid * 16 + i * 8192, R, C); const int Rb = Epi::PERM ? ((R & ~31) + perm32(R & 31)) : R;
;         voffA[i] = (unsigned)(R * K + C) * 2u; voffB[i] = (unsigned)(Rb * K + C) * 2u; }
;     const size_t kstep = (size_t)(BK * 2);
;     const size_t hstep = (size_t)HALF * K * 2;
;     const size_t tstep = 2 * hstep;
;     const unsigned ldsw = (unsigned)wid * 1024u;
;     const int aoff = lds_byte(wr * 64 + fr, fq * 8), boff = lds_byte(wc * 32 + fr, fq * 8);
;     ...
;     if constexpr (SP2) {
;         PG8_STAGE(PG8_SB(0, 0), cB, voffB); PG8_STAGE(PG8_SB(0, 1), cB + hstep, voffB); PG8_STAGE(PG8_SA(0, 0), cA, voffA); PG8_STAGE(PG8_SA(0, 1), cA + hstep, voffA);
;         if (wr == 1) PG8_BAR;
;         PG8_WAIT_V(2); PG8_BAR;
;         PG8_STAGE(PG8_SB(1, 0), cB + kstep, voffB); PG8_STAGE(PG8_SA(1, 0), cA + kstep, voffA); PG8_STAGE(PG8_SB(1, 1), cB + hstep + kstep, voffB);
;         PG8_WAIT_V(6); PG8_BAR;
.LBB0_21:
	s_waitcnt vmcnt(0)
	v_lshrrev_b32_e32 v16, 1, v6
	v_and_b32_e32 v16, 24, v16
	v_and_b32_e32 v7, 15, v6
	v_lshlrev_b32_e32 v17, 1, v16
	v_lshlrev_b32_e32 v6, 2, v6
	s_lshl_b32 s1, s1, 5
	v_lshl_or_b32 v148, s4, 6, v7
	v_lshl_or_b32 v7, v7, 6, v17
	s_lshl_b32 s4, s4, 13
	v_and_b32_e32 v6, 32, v6
	s_and_b32 s1, s1, 0x60
	v_lshl_add_u64 v[8:9], s[10:11], 0, v[160:161]
	v_mov_b32_e32 v129, v161
	v_readlane_b32 s16, v253, 5
	v_bitop3_b32 v17, v7, s4, v6 bitop3:0xde
	s_lshl_b32 s4, s1, 7
	v_lshl_add_u64 v[10:11], s[10:11], 0, v[128:129]
	v_mov_b32_e32 v133, v161
	v_readlane_b32 s17, v253, 6
	v_bitop3_b32 v149, v7, s4, v6 bitop3:0xde
	s_add_i32 m0, s35, 0x18000
	v_lshl_add_u64 v[6:7], v[8:9], 0, s[14:15]
	v_lshl_add_u64 v[12:13], s[16:17], 0, v[132:133]
	v_mov_b32_e32 v131, v161
	s_waitcnt vmcnt(2)
	s_barrier
	global_load_lds_dwordx4 v[6:7], off
	v_lshl_add_u64 v[6:7], v[10:11], 0, s[14:15]
	s_add_i32 m0, s35, 0x1a000
	s_add_i32 s55, s35, 0x8000
	s_add_i32 s58, s35, 0xa000
	v_lshl_add_u64 v[14:15], s[16:17], 0, v[130:131]
	global_load_lds_dwordx4 v[6:7], off
	v_lshl_add_u64 v[6:7], v[12:13], 0, s[14:15]
	s_mov_b32 m0, s55
	s_add_u32 s4, s10, 0x80080
	global_load_lds_dwordx4 v[6:7], off
	v_lshl_add_u64 v[6:7], v[14:15], 0, s[14:15]
	s_mov_b32 m0, s58
	s_addc_u32 s5, s11, 0
	global_load_lds_dwordx4 v[6:7], off
	s_add_i32 m0, s35, 0x1c000
	v_lshl_add_u64 v[6:7], s[4:5], 0, v[160:161]
	global_load_lds_dwordx4 v[6:7], off
	v_lshl_add_u64 v[6:7], s[4:5], 0, v[128:129]
	s_add_i32 m0, s35, 0x1e000
	s_cmpk_lt_u32 s0, 0x100
	global_load_lds_dwordx4 v[6:7], off
	v_lshlrev_b32_e32 v6, 15, v4
	v_and_b32_e32 v6, 0xffff0000, v6
	v_lshl_add_u32 v3, v3, 12, v6
	v_and_b32_e32 v4, 1, v4
	v_lshl_or_b32 v3, v4, 6, v3
	v_lshl_add_u32 v134, v5, 1, v3
	v_lshlrev_b32_e32 v3, 15, v0
	v_and_b32_e32 v3, 0xffff0000, v3
	s_waitcnt vmcnt(6)
	v_or_b32_e32 v150, s1, v16
	v_lshl_add_u32 v1, v1, 12, v3
	v_and_b32_e32 v0, 1, v0
	v_readlane_b32 s0, v253, 3
	v_lshl_or_b32 v0, v0, 6, v1
	v_readlane_b32 s1, v253, 4
	s_cselect_b64 s[4:5], -1, 0
	v_mov_b32_e32 v135, v161
	v_lshl_add_u32 v136, v2, 1, v0
	v_mov_b32_e32 v137, v161
	s_mov_b32 s59, 0
	v_add_u32_e32 v151, 0, v17
	v_readlane_b32 s8, v253, 0
	s_mov_b32 s9, s0
	s_mov_b64 s[0:1], s[16:17]
	s_barrier
	s_mov_b32 s101, 0
	s_branch .LBB0_25

; #define PG8_STAGE(bufoff, gbase, voff) do { _Pragma("unroll") for (int _i = 0; _i < 2; ++_i) \
;         __builtin_amdgcn_global_load_lds((const unsigned*)((const char*)(gbase) + (voff)[_i]), (PG8_LAS unsigned*)(lds + (bufoff) + ldsw + _i * 8192), 16, 0, 0); } while (0)
; #define PG8_WAIT_V(n) asm volatile("s_waitcnt vmcnt(" #n ")" ::: "memory")
; #define PG8_WAIT_L(n) asm volatile("s_waitcnt lgkmcnt(" #n ")" ::: "memory")
; #define PG8_BAR __builtin_amdgcn_s_barrier()
; #define PG8_SCHED __builtin_amdgcn_sched_barrier(0)
; template <class Epi, class Sched, bool ALIGN_EPI = false, bool SP2 = false, bool F8 = false>
; __device__ __forceinline__ void gemm_phase(PG8_LAS unsigned char* lds, const Gemm g, const Sched& S, const Epi& E) {
;     ...
;         const bool has_next = S.next(ui + 1, nxt);
;         const char* nA = has_next ? (const char*)g.A + (size_t)nxt.pm * tstep : cA; const char* nB = has_next ? (const char*)g.Bt + (size_t)nxt.pn * tstep : cB;
;         for (int t = 0; t < nt; t += 2) {
;             const bool last = (t == nt - 2);
;             const char* a1 = cA + (size_t)(t + 1) * kstep;
;             const char* a2 = last ? nA : cA + (size_t)(t + 2) * kstep; const char* b2 = last ? nB : cB + (size_t)(t + 2) * kstep;
;             const char* a3 = a2 + kstep; const char* b3 = b2 + kstep;
;             if (last && has_next) S.a_ready(nxt);
;             if constexpr (SP2) {
;             PG8_LDB(B0, 0, 0); PG8_LDB(B1, 0, 1); PG8_SCHED; PG8_LDA(At, 0, 0); PG8_STAGE(PG8_SA(1, 1), a1 + hstep, voffA);
;             PG8_WAIT_V(8); PG8_WAIT_L(0); PG8_BAR; PG8_MMA(0, 0, At, B0); PG8_MMA(0, 1, At, B1); PG8_BAR; PG8_SCHED;
;             PG8_LDA(At, 0, 1); PG8_STAGE(PG8_SB(0, 0), b2, voffB); PG8_STAGE(PG8_SB(0, 1), b2 + hstep, voffB); PG8_STAGE(PG8_SA(0, 0), a2, voffA);
;             PG8_WAIT_V(8); PG8_WAIT_L(0); PG8_BAR; PG8_MMA(1, 0, At, B0); PG8_MMA(1, 1, At, B1); PG8_BAR; PG8_SCHED;
.LBB0_31:
	s_ashr_i32 s47, s46, 31
	s_lshl_b64 s[16:17], s[46:47], 20
	v_readlane_b32 s28, v251, 7
	v_readlane_b32 s29, v251, 8
	s_add_u32 s48, s28, s16
	s_addc_u32 s49, s29, s17
	s_and_b64 s[16:17], s[38:39], exec
	s_cselect_b32 s19, s49, s1
	s_cselect_b32 s23, s48, s0
	s_ashr_i32 s45, s44, 31
	s_lshl_b64 s[16:17], s[44:45], 20
	s_add_u32 s50, s13, s16
	s_addc_u32 s51, s22, s17
	s_and_b64 s[16:17], s[38:39], exec
	s_cselect_b32 s28, s51, s11
	s_cselect_b32 s29, s50, s10
	s_add_u32 s0, s0, 0x80080
	s_addc_u32 s1, s1, 0
	s_add_u32 s45, s10, 0x100
	s_addc_u32 s47, s11, 0
	s_mov_b32 s52, -2
	s_add_u32 s10, s0, 0xfff80080
	s_addc_u32 s11, s1, -1
	s_add_i32 s53, 0, 0x10000
	s_cmp_eq_u32 s52, 28
	s_cselect_b32 s17, s19, s11
	s_cselect_b32 s16, s23, s10
	v_add_u32_e32 v146, s53, v149
	s_cselect_b32 s11, s28, s47
	s_cselect_b32 s10, s29, s45
	s_add_i32 s56, 0, 0x14000
	ds_read_b128 v[138:141], v146
	ds_read_b128 v[142:145], v146 offset:1024
	ds_read_b128 v[152:155], v146 offset:2048
	ds_read_b128 v[156:159], v146 offset:3072
	v_add_u32_e32 v146, s56, v149
	ds_read_b128 v[184:187], v146
	ds_read_b128 v[188:191], v146 offset:1024
	ds_read_b128 v[192:195], v146 offset:2048
	ds_read_b128 v[196:199], v146 offset:3072
	v_lshl_add_u64 v[146:147], s[0:1], 0, v[134:135]
	s_add_i32 m0, s35, 0xc000
	ds_read_b128 v[200:203], v151
	ds_read_b128 v[214:217], v151 offset:1024
	ds_read_b128 v[218:221], v151 offset:2048
	ds_read_b128 v[222:225], v151 offset:3072
	ds_read_b128 v[226:229], v151 offset:4096
	ds_read_b128 v[230:233], v151 offset:5120
	ds_read_b128 v[234:237], v151 offset:6144
	ds_read_b128 v[238:241], v151 offset:7168
	global_load_lds_dwordx4 v[146:147], off
	v_lshl_add_u64 v[146:147], s[0:1], 0, v[136:137]
	s_add_i32 m0, s35, 0xe000
	s_nop 0
	global_load_lds_dwordx4 v[146:147], off
	s_cmp_lg_u32 s101, 0
	s_cbranch_scc1 .Lgk_nw1_32
	s_waitcnt vmcnt(8)
.Lgk_nw1_32:
	s_waitcnt lgkmcnt(0)
	s_barrier
	s_setprio 1
	s_waitcnt lgkmcnt(0)
	v_mfma_f32_16x16x32_bf16 v[124:127], v[138:141], v[200:203], 0
	v_mfma_f32_16x16x32_bf16 v[120:123], v[152:155], v[200:203], 0
	v_mfma_f32_16x16x32_bf16 v[108:111], v[138:141], v[218:221], 0
	v_mfma_f32_16x16x32_bf16 v[104:107], v[152:155], v[218:221], 0
	v_mfma_f32_16x16x32_bf16 v[92:95], v[138:141], v[226:229], 0
	v_mfma_f32_16x16x32_bf16 v[88:91], v[152:155], v[226:229], 0
	v_mfma_f32_16x16x32_bf16 v[76:79], v[138:141], v[234:237], 0
	v_mfma_f32_16x16x32_bf16 v[72:75], v[152:155], v[234:237], 0
	v_mfma_f32_16x16x32_bf16 v[124:127], v[142:145], v[214:217], v[124:127]
	v_mfma_f32_16x16x32_bf16 v[120:123], v[156:159], v[214:217], v[120:123]
	v_mfma_f32_16x16x32_bf16 v[108:111], v[142:145], v[222:225], v[108:111]
	v_mfma_f32_16x16x32_bf16 v[104:107], v[156:159], v[222:225], v[104:107]
	v_mfma_f32_16x16x32_bf16 v[92:95], v[142:145], v[230:233], v[92:95]
	v_mfma_f32_16x16x32_bf16 v[88:91], v[156:159], v[230:233], v[88:91]
	v_mfma_f32_16x16x32_bf16 v[76:79], v[142:145], v[238:241], v[76:79]
	v_mfma_f32_16x16x32_bf16 v[72:75], v[156:159], v[238:241], v[72:75]
	s_setprio 0
	s_setprio 1
	v_mfma_f32_16x16x32_bf16 v[116:119], v[184:187], v[200:203], 0
	v_mfma_f32_16x16x32_bf16 v[112:115], v[192:195], v[200:203], 0
	v_mfma_f32_16x16x32_bf16 v[100:103], v[184:187], v[218:221], 0
	v_mfma_f32_16x16x32_bf16 v[96:99], v[192:195], v[218:221], 0
	v_mfma_f32_16x16x32_bf16 v[84:87], v[184:187], v[226:229], 0
	v_mfma_f32_16x16x32_bf16 v[80:83], v[192:195], v[226:229], 0
	v_mfma_f32_16x16x32_bf16 v[68:71], v[184:187], v[234:237], 0
	v_mfma_f32_16x16x32_bf16 v[64:67], v[192:195], v[234:237], 0
	v_mfma_f32_16x16x32_bf16 v[116:119], v[188:191], v[214:217], v[116:119]
	v_mfma_f32_16x16x32_bf16 v[112:115], v[196:199], v[214:217], v[112:115]
	v_mfma_f32_16x16x32_bf16 v[100:103], v[188:191], v[222:225], v[100:103]
	v_mfma_f32_16x16x32_bf16 v[96:99], v[196:199], v[222:225], v[96:99]
	v_mfma_f32_16x16x32_bf16 v[84:87], v[188:191], v[230:233], v[84:87]
	v_mfma_f32_16x16x32_bf16 v[80:83], v[196:199], v[230:233], v[80:83]
	v_mfma_f32_16x16x32_bf16 v[68:71], v[188:191], v[238:241], v[68:71]
	v_mfma_f32_16x16x32_bf16 v[64:67], v[196:199], v[238:241], v[64:67]
	s_setprio 0
	s_barrier
	s_add_i32 s53, s53, s34
	v_lshl_add_u64 v[146:147], s[10:11], 0, v[160:161]
	s_mov_b32 m0, s53
	ds_read_b128 v[200:203], v151 offset:16384
	ds_read_b128 v[214:217], v151 offset:17408
	ds_read_b128 v[218:221], v151 offset:18432
	ds_read_b128 v[222:225], v151 offset:19456
	ds_read_b128 v[226:229], v151 offset:20480
	ds_read_b128 v[230:233], v151 offset:21504
	ds_read_b128 v[234:237], v151 offset:22528
	ds_read_b128 v[238:241], v151 offset:23552
	global_load_lds_dwordx4 v[146:147], off
	s_add_i32 m0, s53, 0x2000
	s_add_u32 s60, s10, 0x80000
	v_lshl_add_u64 v[162:163], s[10:11], 0, v[128:129]
	s_addc_u32 s61, s11, 0
	s_add_i32 s53, s56, s34
	global_load_lds_dwordx4 v[162:163], off
	v_lshl_add_u64 v[242:243], s[60:61], 0, v[160:161]
	s_mov_b32 m0, s53
	v_lshl_add_u64 v[244:245], s[16:17], 0, v[130:131]
	global_load_lds_dwordx4 v[242:243], off
	v_lshl_add_u64 v[242:243], s[60:61], 0, v[128:129]
	s_add_i32 m0, s53, 0x2000
	s_nop 0
	global_load_lds_dwordx4 v[242:243], off
	v_lshl_add_u64 v[242:243], s[16:17], 0, v[132:133]
	s_mov_b32 m0, s35
	s_nop 0
	global_load_lds_dwordx4 v[242:243], off
	s_mov_b32 m0, s36
	s_nop 0
	global_load_lds_dwordx4 v[244:245], off
	s_cmp_lg_u32 s101, 0
	s_cbranch_scc1 .Lgk_nw2_32
	s_waitcnt vmcnt(8)
; #define PG8_STAGE(bufoff, gbase, voff) do { _Pragma("unroll") for (int _i = 0; _i < 2; ++_i) \
;         __builtin_amdgcn_global_load_lds((const unsigned*)((const char*)(gbase) + (voff)[_i]), (PG8_LAS unsigned*)(lds + (bufoff) + ldsw + _i * 8192), 16, 0, 0); } while (0)
; #define PG8_WAIT_V(n) asm volatile("s_waitcnt vmcnt(" #n ")" ::: "memory")
; #define PG8_WAIT_L(n) asm volatile("s_waitcnt lgkmcnt(" #n ")" ::: "memory")
; #define PG8_BAR __builtin_amdgcn_s_barrier()
; #define PG8_SCHED __builtin_amdgcn_sched_barrier(0)
; template <class Epi, class Sched, bool ALIGN_EPI = false, bool SP2 = false, bool F8 = false>
; __device__ __forceinline__ void gemm_phase(PG8_LAS unsigned char* lds, const Gemm g, const Sched& S, const Epi& E) {
;     ...
;             PG8_WAIT_V(8); PG8_WAIT_L(0); PG8_BAR; PG8_MMA(1, 0, At, B0); PG8_MMA(1, 1, At, B1); PG8_BAR; PG8_SCHED;
;             PG8_LDB(B0, 1, 0); PG8_LDB(B1, 1, 1); PG8_SCHED; PG8_LDA(At, 1, 0); PG8_STAGE(PG8_SA(0, 1), a2 + hstep, voffA);
;             PG8_WAIT_V(8); PG8_WAIT_L(0); PG8_BAR; PG8_MMA(0, 0, At, B0); PG8_MMA(0, 1, At, B1); PG8_BAR; PG8_SCHED;
.Lgk_nw2_32:
	s_waitcnt lgkmcnt(0)
	s_barrier
	s_setprio 1
	s_waitcnt lgkmcnt(0)
	v_mfma_f32_16x16x32_bf16 v[60:63], v[138:141], v[200:203], 0
	v_mfma_f32_16x16x32_bf16 v[56:59], v[152:155], v[200:203], 0
	v_mfma_f32_16x16x32_bf16 v[44:47], v[138:141], v[218:221], 0
	v_mfma_f32_16x16x32_bf16 v[40:43], v[152:155], v[218:221], 0
	v_mfma_f32_16x16x32_bf16 v[28:31], v[138:141], v[226:229], 0
	v_mfma_f32_16x16x32_bf16 v[24:27], v[152:155], v[226:229], 0
	v_mfma_f32_16x16x32_bf16 v[12:15], v[138:141], v[234:237], 0
	v_mfma_f32_16x16x32_bf16 v[8:11], v[152:155], v[234:237], 0
	v_mfma_f32_16x16x32_bf16 v[60:63], v[142:145], v[214:217], v[60:63]
	v_mfma_f32_16x16x32_bf16 v[56:59], v[156:159], v[214:217], v[56:59]
	v_mfma_f32_16x16x32_bf16 v[44:47], v[142:145], v[222:225], v[44:47]
	v_mfma_f32_16x16x32_bf16 v[40:43], v[156:159], v[222:225], v[40:43]
	v_mfma_f32_16x16x32_bf16 v[28:31], v[142:145], v[230:233], v[28:31]
	v_mfma_f32_16x16x32_bf16 v[24:27], v[156:159], v[230:233], v[24:27]
	v_mfma_f32_16x16x32_bf16 v[12:15], v[142:145], v[238:241], v[12:15]
	v_mfma_f32_16x16x32_bf16 v[8:11], v[156:159], v[238:241], v[8:11]
	s_setprio 0
	s_setprio 1
	v_mfma_f32_16x16x32_bf16 v[52:55], v[184:187], v[200:203], 0
	v_mfma_f32_16x16x32_bf16 v[48:51], v[192:195], v[200:203], 0
	v_mfma_f32_16x16x32_bf16 v[36:39], v[184:187], v[218:221], 0
	v_mfma_f32_16x16x32_bf16 v[32:35], v[192:195], v[218:221], 0
	v_mfma_f32_16x16x32_bf16 v[20:23], v[184:187], v[226:229], 0
	v_mfma_f32_16x16x32_bf16 v[16:19], v[192:195], v[226:229], 0
	v_mfma_f32_16x16x32_bf16 v[4:7], v[184:187], v[234:237], 0
	v_mfma_f32_16x16x32_bf16 v[0:3], v[192:195], v[234:237], 0
	v_mfma_f32_16x16x32_bf16 v[52:55], v[188:191], v[214:217], v[52:55]
	v_mfma_f32_16x16x32_bf16 v[48:51], v[196:199], v[214:217], v[48:51]
	v_mfma_f32_16x16x32_bf16 v[36:39], v[188:191], v[222:225], v[36:39]
	v_mfma_f32_16x16x32_bf16 v[32:35], v[196:199], v[222:225], v[32:35]
	v_mfma_f32_16x16x32_bf16 v[20:23], v[188:191], v[230:233], v[20:23]
	v_mfma_f32_16x16x32_bf16 v[16:19], v[196:199], v[230:233], v[16:19]
	v_mfma_f32_16x16x32_bf16 v[4:7], v[188:191], v[238:241], v[4:7]
	v_mfma_f32_16x16x32_bf16 v[0:3], v[196:199], v[238:241], v[0:3]
	s_setprio 0
	s_barrier
	s_add_i32 s53, 0, 0x18000
	s_add_i32 s56, 0, 0x1c000
	v_add_u32_e32 v156, s53, v149
	v_add_u32_e32 v196, s56, v149
	ds_read_b128 v[138:141], v156
	ds_read_b128 v[142:145], v156 offset:1024
	ds_read_b128 v[152:155], v156 offset:2048
	ds_read_b128 v[156:159], v156 offset:3072
	ds_read_b128 v[184:187], v196
	ds_read_b128 v[188:191], v196 offset:1024
	ds_read_b128 v[192:195], v196 offset:2048
	ds_read_b128 v[196:199], v196 offset:3072
	s_add_u32 s16, s16, 0x80000
	s_addc_u32 s17, s17, 0
	s_mov_b32 m0, s37
	v_lshl_add_u64 v[246:247], s[16:17], 0, v[132:133]
	ds_read_b128 v[200:203], v151 offset:32768
	ds_read_b128 v[214:217], v151 offset:33792
	ds_read_b128 v[218:221], v151 offset:34816
	ds_read_b128 v[222:225], v151 offset:35840
	ds_read_b128 v[226:229], v151 offset:36864
	ds_read_b128 v[230:233], v151 offset:37888
	ds_read_b128 v[234:237], v151 offset:38912
	ds_read_b128 v[238:241], v151 offset:39936
	global_load_lds_dwordx4 v[246:247], off
	v_lshl_add_u64 v[246:247], s[16:17], 0, v[130:131]
	s_mov_b32 m0, s54
	s_nop 0
	global_load_lds_dwordx4 v[246:247], off
	s_waitcnt vmcnt(8)
	s_waitcnt lgkmcnt(0)
	s_barrier
	s_setprio 1
	s_waitcnt lgkmcnt(0)
	v_mfma_f32_16x16x32_bf16 v[124:127], v[138:141], v[200:203], v[124:127]
	v_mfma_f32_16x16x32_bf16 v[120:123], v[152:155], v[200:203], v[120:123]
	v_mfma_f32_16x16x32_bf16 v[108:111], v[138:141], v[218:221], v[108:111]
	v_mfma_f32_16x16x32_bf16 v[104:107], v[152:155], v[218:221], v[104:107]
	v_mfma_f32_16x16x32_bf16 v[92:95], v[138:141], v[226:229], v[92:95]
	v_mfma_f32_16x16x32_bf16 v[88:91], v[152:155], v[226:229], v[88:91]
	v_mfma_f32_16x16x32_bf16 v[76:79], v[138:141], v[234:237], v[76:79]
	v_mfma_f32_16x16x32_bf16 v[72:75], v[152:155], v[234:237], v[72:75]
	v_mfma_f32_16x16x32_bf16 v[124:127], v[142:145], v[214:217], v[124:127]
	v_mfma_f32_16x16x32_bf16 v[120:123], v[156:159], v[214:217], v[120:123]
	v_mfma_f32_16x16x32_bf16 v[108:111], v[142:145], v[222:225], v[108:111]
	v_mfma_f32_16x16x32_bf16 v[104:107], v[156:159], v[222:225], v[104:107]
	v_mfma_f32_16x16x32_bf16 v[92:95], v[142:145], v[230:233], v[92:95]
	v_mfma_f32_16x16x32_bf16 v[88:91], v[156:159], v[230:233], v[88:91]
	v_mfma_f32_16x16x32_bf16 v[76:79], v[142:145], v[238:241], v[76:79]
	v_mfma_f32_16x16x32_bf16 v[72:75], v[156:159], v[238:241], v[72:75]
	s_setprio 0
	s_setprio 1
	v_mfma_f32_16x16x32_bf16 v[116:119], v[184:187], v[200:203], v[116:119]
	v_mfma_f32_16x16x32_bf16 v[112:115], v[192:195], v[200:203], v[112:115]
	v_mfma_f32_16x16x32_bf16 v[100:103], v[184:187], v[218:221], v[100:103]
	v_mfma_f32_16x16x32_bf16 v[96:99], v[192:195], v[218:221], v[96:99]
	v_mfma_f32_16x16x32_bf16 v[84:87], v[184:187], v[226:229], v[84:87]
	v_mfma_f32_16x16x32_bf16 v[80:83], v[192:195], v[226:229], v[80:83]
	v_mfma_f32_16x16x32_bf16 v[68:71], v[184:187], v[234:237], v[68:71]
	v_mfma_f32_16x16x32_bf16 v[64:67], v[192:195], v[234:237], v[64:67]
	v_mfma_f32_16x16x32_bf16 v[116:119], v[188:191], v[214:217], v[116:119]
	v_mfma_f32_16x16x32_bf16 v[112:115], v[196:199], v[214:217], v[112:115]
	v_mfma_f32_16x16x32_bf16 v[100:103], v[188:191], v[222:225], v[100:103]
	v_mfma_f32_16x16x32_bf16 v[96:99], v[196:199], v[222:225], v[96:99]
	v_mfma_f32_16x16x32_bf16 v[84:87], v[188:191], v[230:233], v[84:87]
	v_mfma_f32_16x16x32_bf16 v[80:83], v[196:199], v[230:233], v[80:83]
	v_mfma_f32_16x16x32_bf16 v[68:71], v[188:191], v[238:241], v[68:71]
	v_mfma_f32_16x16x32_bf16 v[64:67], v[196:199], v[238:241], v[64:67]
	s_setprio 0
	s_barrier
; #define PG8_STAGE(bufoff, gbase, voff) do { _Pragma("unroll") for (int _i = 0; _i < 2; ++_i) \
;         __builtin_amdgcn_global_load_lds((const unsigned*)((const char*)(gbase) + (voff)[_i]), (PG8_LAS unsigned*)(lds + (bufoff) + ldsw + _i * 8192), 16, 0, 0); } while (0)
; #define PG8_WAIT_V(n) asm volatile("s_waitcnt vmcnt(" #n ")" ::: "memory")
; #define PG8_WAIT_L(n) asm volatile("s_waitcnt lgkmcnt(" #n ")" ::: "memory")
; #define PG8_BAR __builtin_amdgcn_s_barrier()
; #define PG8_SCHED __builtin_amdgcn_sched_barrier(0)
; template <class Epi, class Sched, bool ALIGN_EPI = false, bool SP2 = false, bool F8 = false>
; __device__ __forceinline__ void gemm_phase(PG8_LAS unsigned char* lds, const Gemm g, const Sched& S, const Epi& E) {
;     ...
;             PG8_LDA(At, 1, 1); PG8_STAGE(PG8_SB(1, 0), b3, voffB); PG8_STAGE(PG8_SB(1, 1), b3 + hstep, voffB); PG8_STAGE(PG8_SA(1, 0), a3, voffA);
;             PG8_WAIT_V(8); PG8_WAIT_L(0); PG8_BAR; PG8_MMA(1, 0, At, B0); PG8_MMA(1, 1, At, B1); PG8_BAR; PG8_SCHED;
	s_add_i32 s16, s53, s34
	v_lshl_add_u64 v[146:147], v[146:147], 0, s[14:15]
	s_mov_b32 m0, s16
	ds_read_b128 v[200:203], v151 offset:49152
	ds_read_b128 v[214:217], v151 offset:50176
	ds_read_b128 v[218:221], v151 offset:51200
	ds_read_b128 v[222:225], v151 offset:52224
	ds_read_b128 v[226:229], v151 offset:53248
	ds_read_b128 v[230:233], v151 offset:54272
	ds_read_b128 v[234:237], v151 offset:55296
	ds_read_b128 v[238:241], v151 offset:56320
	global_load_lds_dwordx4 v[146:147], off
	s_add_i32 m0, s16, 0x2000
	s_add_u32 s10, s10, 0x80080
	v_lshl_add_u64 v[146:147], v[162:163], 0, s[14:15]
	s_addc_u32 s11, s11, 0
	s_add_i32 s16, s56, s34
	global_load_lds_dwordx4 v[146:147], off
	v_lshl_add_u64 v[146:147], s[10:11], 0, v[160:161]
	s_mov_b32 m0, s16
	s_nop 0
	global_load_lds_dwordx4 v[146:147], off
	v_lshl_add_u64 v[146:147], s[10:11], 0, v[128:129]
	s_add_i32 m0, s16, 0x2000
	s_nop 0
	global_load_lds_dwordx4 v[146:147], off
	v_lshl_add_u64 v[146:147], v[242:243], 0, s[14:15]
	s_mov_b32 m0, s55
	s_nop 0
	global_load_lds_dwordx4 v[146:147], off
	v_lshl_add_u64 v[146:147], v[244:245], 0, s[14:15]
	s_mov_b32 m0, s58
	s_nop 0
	global_load_lds_dwordx4 v[146:147], off
	s_waitcnt vmcnt(8)
	s_waitcnt lgkmcnt(0)
	s_barrier
	s_setprio 1
	s_waitcnt lgkmcnt(0)
	v_mfma_f32_16x16x32_bf16 v[60:63], v[138:141], v[200:203], v[60:63]
	v_mfma_f32_16x16x32_bf16 v[56:59], v[152:155], v[200:203], v[56:59]
	v_mfma_f32_16x16x32_bf16 v[44:47], v[138:141], v[218:221], v[44:47]
	v_mfma_f32_16x16x32_bf16 v[40:43], v[152:155], v[218:221], v[40:43]
	v_mfma_f32_16x16x32_bf16 v[28:31], v[138:141], v[226:229], v[28:31]
	v_mfma_f32_16x16x32_bf16 v[24:27], v[152:155], v[226:229], v[24:27]
	v_mfma_f32_16x16x32_bf16 v[12:15], v[138:141], v[234:237], v[12:15]
	v_mfma_f32_16x16x32_bf16 v[8:11], v[152:155], v[234:237], v[8:11]
	v_mfma_f32_16x16x32_bf16 v[60:63], v[142:145], v[214:217], v[60:63]
	v_mfma_f32_16x16x32_bf16 v[56:59], v[156:159], v[214:217], v[56:59]
	v_mfma_f32_16x16x32_bf16 v[44:47], v[142:145], v[222:225], v[44:47]
	v_mfma_f32_16x16x32_bf16 v[40:43], v[156:159], v[222:225], v[40:43]
	v_mfma_f32_16x16x32_bf16 v[28:31], v[142:145], v[230:233], v[28:31]
	v_mfma_f32_16x16x32_bf16 v[24:27], v[156:159], v[230:233], v[24:27]
	v_mfma_f32_16x16x32_bf16 v[12:15], v[142:145], v[238:241], v[12:15]
	v_mfma_f32_16x16x32_bf16 v[8:11], v[156:159], v[238:241], v[8:11]
	s_setprio 0
	s_setprio 1
	v_mfma_f32_16x16x32_bf16 v[52:55], v[184:187], v[200:203], v[52:55]
	v_mfma_f32_16x16x32_bf16 v[48:51], v[192:195], v[200:203], v[48:51]
	v_mfma_f32_16x16x32_bf16 v[36:39], v[184:187], v[218:221], v[36:39]
	v_mfma_f32_16x16x32_bf16 v[32:35], v[192:195], v[218:221], v[32:35]
	v_mfma_f32_16x16x32_bf16 v[20:23], v[184:187], v[226:229], v[20:23]
	v_mfma_f32_16x16x32_bf16 v[16:19], v[192:195], v[226:229], v[16:19]
	v_mfma_f32_16x16x32_bf16 v[4:7], v[184:187], v[234:237], v[4:7]
	v_mfma_f32_16x16x32_bf16 v[0:3], v[192:195], v[234:237], v[0:3]
	v_mfma_f32_16x16x32_bf16 v[52:55], v[188:191], v[214:217], v[52:55]
	v_mfma_f32_16x16x32_bf16 v[48:51], v[196:199], v[214:217], v[48:51]
	v_mfma_f32_16x16x32_bf16 v[36:39], v[188:191], v[222:225], v[36:39]
	v_mfma_f32_16x16x32_bf16 v[32:35], v[196:199], v[222:225], v[32:35]
	v_mfma_f32_16x16x32_bf16 v[20:23], v[188:191], v[230:233], v[20:23]
	v_mfma_f32_16x16x32_bf16 v[16:19], v[196:199], v[230:233], v[16:19]
	v_mfma_f32_16x16x32_bf16 v[4:7], v[188:191], v[238:241], v[4:7]
	v_mfma_f32_16x16x32_bf16 v[0:3], v[196:199], v[238:241], v[0:3]
	s_setprio 0
	s_barrier
	s_add_i32 s52, s52, 2
	s_add_u32 s0, s0, 0x100
	s_addc_u32 s1, s1, 0
	s_add_u32 s45, s45, 0x100
	s_addc_u32 s47, s47, 0
	s_cmp_gt_u32 s52, 29
	s_cbranch_scc0 .LBB0_32
	s_branch .Lgk_after_32

; __device__ __forceinline__ unsigned pk2(float lo, float hi) { return f2bf(lo) | (f2bf(hi) << 16); }
;     __device__ __forceinline__ void operator()(const f32x4 (&acc)[2][2][4][2], const pg8::Unit& u, int wr, int wc, int fr, int fq) const {
;     ...
;                 const size_t row = (size_t)(row0 + ai * 128 + m * 16);
;                 float ssq = 0.f, rstd = 1.f;
;                 if constexpr (MODE == 8) rstd = 1.f / sqrtf(rs[row] * (1.f / DM) + EPS);
; #pragma unroll
;                 for (int bj = 0; bj < 2; ++bj) {
;                     const int col = col0 + bj * 128;
;                     f32x4 v0 = acc[ai][bj][m][0], v1 = acc[ai][bj][m][1];
;     ...
;                     } else if constexpr (MODE == 8) {
;                         const f32x4 b0 = *(const f32x4*)(vec + col), b1 = *(const f32x4*)(vec + col + 4);
;                         float r[8] = {v0[0] * rstd + b0[0], v0[1] * rstd + b0[1], v0[2] * rstd + b0[2], v0[3] * rstd + b0[3], v1[0] * rstd + b1[0], v1[1] * rstd + b1[1], v1[2] * rstd + b1[2], v1[3] * rstd + b1[3]};
; #pragma unroll
;                         for (int i = 0; i < 8; ++i) { const float q = fmaxf(r[i], 0.f); r[i] = q * q; }
;                         u32x4 w; w.x = pk2(r[0], r[1]); w.y = pk2(r[2], r[3]); w.z = pk2(r[4], r[5]); w.w = pk2(r[6], r[7]);
;                         *(u32x4*)(ob + row * HIDN + col) = w;
.LBB0_35:
	v_lshl_add_u32 v144, s9, 8, v148
	v_lshl_or_b32 v146, s8, 8, v150
	v_readlane_b32 s8, v251, 21
	v_ashrrev_i32_e32 v145, 31, v144
	v_readlane_b32 s9, v251, 22
	s_mov_b32 s10, 0xf800000
	s_nop 0
	v_lshl_add_u64 v[138:139], v[144:145], 2, s[8:9]
	global_load_dword v214, v[138:139], off
	v_or_b32_e32 v224, 16, v144
	v_ashrrev_i32_e32 v225, 31, v224
	v_lshl_add_u64 v[224:225], v[224:225], 2, s[8:9]
	global_load_dword v215, v[224:225], off
	v_or_b32_e32 v224, 32, v144
	v_ashrrev_i32_e32 v225, 31, v224
	v_lshl_add_u64 v[224:225], v[224:225], 2, s[8:9]
	global_load_dword v216, v[224:225], off
	v_or_b32_e32 v224, 48, v144
	v_ashrrev_i32_e32 v225, 31, v224
	v_lshl_add_u64 v[224:225], v[224:225], 2, s[8:9]
	global_load_dword v217, v[224:225], off
	global_load_dword v218, v[138:139], off offset:512
	global_load_dword v219, v[138:139], off offset:576
	global_load_dword v220, v[138:139], off offset:640
	global_load_dword v221, v[138:139], off offset:704
	v_readlane_b32 s0, v251, 23
	v_readlane_b32 s1, v251, 24
	v_ashrrev_i32_e32 v147, 31, v146
	s_nop 1
	v_lshl_add_u64 v[222:223], v[146:147], 2, s[0:1]
	global_load_dwordx4 v[188:191], v[222:223], off offset:16
	global_load_dwordx4 v[192:195], v[222:223], off
	v_or_b32_e32 v224, 0x80, v146
	v_ashrrev_i32_e32 v225, 31, v224
	v_lshl_add_u64 v[224:225], v[224:225], 2, s[0:1]
	global_load_dwordx4 v[196:199], v[224:225], off offset:16
	global_load_dwordx4 v[200:203], v[224:225], off
	s_waitcnt vmcnt(0)
	v_fmamk_f32 v140, v214, 0x3a000000, v205
	v_readlane_b32 s0, v251, 23
	v_readlane_b32 s1, v251, 24
	v_ashrrev_i32_e32 v147, 31, v146
	v_rsq_f32_e32 v152, v140
	v_lshl_add_u64 v[140:141], v[146:147], 2, s[0:1]
	v_lshlrev_b64 v[142:143], 14, v[144:145]
	s_waitcnt vmcnt(0)
	v_fma_f32 v145, v121, v152, v189
	v_fma_f32 v124, v124, v152, v192
	v_fma_f32 v125, v125, v152, v193
	v_fma_f32 v126, v126, v152, v194
	v_fma_f32 v187, v127, v152, v195
	v_fma_f32 v127, v120, v152, v188
	v_fma_f32 v157, v123, v152, v191
	v_fma_f32 v153, v122, v152, v190
	v_max_f32_e32 v120, 0, v124
	v_max_f32_e32 v122, 0, v125
	v_max_f32_e32 v121, 0, v126
	v_max_f32_e32 v123, 0, v187
	v_max_f32_e32 v124, 0, v127
	v_max_f32_e32 v126, 0, v145
	v_max_f32_e32 v127, 0, v157
	v_max_f32_e32 v125, 0, v153
	v_pk_mul_f32 v[122:123], v[122:123], v[122:123]
	v_pk_mul_f32 v[126:127], v[126:127], v[126:127]
	v_pk_mul_f32 v[124:125], v[124:125], v[124:125]
	v_pk_mul_f32 v[120:121], v[120:121], v[120:121]
	v_cvt_pk_bf16_f32 v120, v120, v122
	v_cvt_pk_bf16_f32 v121, v121, v123
	v_cvt_pk_bf16_f32 v122, v124, v126
	v_cvt_pk_bf16_f32 v123, v125, v127
	v_lshl_add_u64 v[124:125], s[20:21], 0, v[142:143]
	v_lshlrev_b64 v[142:143], 1, v[146:147]
	v_lshl_add_u64 v[124:125], v[124:125], 0, v[142:143]
	global_store_dwordx4 v[124:125], v[120:123], off
	s_nop 1
	v_or_b32_e32 v120, 0x80, v146
	v_ashrrev_i32_e32 v121, 31, v120
	v_lshl_add_u64 v[126:127], v[120:121], 2, s[0:1]
	v_fma_f32 v123, v115, v152, v199
	v_fma_f32 v116, v116, v152, v200
	v_fma_f32 v117, v117, v152, v201
	v_fma_f32 v118, v118, v152, v202
	v_fma_f32 v157, v119, v152, v203
	v_fma_f32 v119, v112, v152, v196
	v_fma_f32 v120, v113, v152, v197
	v_fma_f32 v121, v114, v152, v198
	v_max_f32_e32 v112, 0, v116
	v_max_f32_e32 v114, 0, v117
	v_max_f32_e32 v113, 0, v118
	v_max_f32_e32 v115, 0, v157
	v_max_f32_e32 v116, 0, v119
	v_max_f32_e32 v118, 0, v120
	v_max_f32_e32 v119, 0, v123
	v_max_f32_e32 v117, 0, v121
	v_pk_mul_f32 v[114:115], v[114:115], v[114:115]
	v_pk_mul_f32 v[118:119], v[118:119], v[118:119]
	v_pk_mul_f32 v[112:113], v[112:113], v[112:113]
	v_pk_mul_f32 v[116:117], v[116:117], v[116:117]
	v_cvt_pk_bf16_f32 v112, v112, v114
	v_cvt_pk_bf16_f32 v113, v113, v115
	v_cvt_pk_bf16_f32 v114, v116, v118
	v_cvt_pk_bf16_f32 v115, v117, v119
	global_store_dwordx4 v[124:125], v[112:115], off offset:256
	s_nop 1
	v_or_b32_e32 v112, 16, v144
	v_ashrrev_i32_e32 v113, 31, v112
	v_lshl_add_u64 v[114:115], v[112:113], 2, s[8:9]
	v_lshlrev_b64 v[112:113], 14, v[112:113]
	v_fmamk_f32 v114, v215, 0x3a000000, v205
	v_rsq_f32_e32 v114, v114
	s_nop 0
	v_fma_f32 v115, v105, v114, v189
	v_fma_f32 v108, v108, v114, v192
	v_fma_f32 v109, v109, v114, v193
	v_fma_f32 v110, v110, v114, v194
	v_fma_f32 v123, v111, v114, v195
	v_fma_f32 v111, v104, v114, v188
	v_fma_f32 v119, v107, v114, v191
	v_fma_f32 v116, v106, v114, v190
	v_max_f32_e32 v104, 0, v108
	v_max_f32_e32 v106, 0, v109
	v_max_f32_e32 v105, 0, v110
	v_max_f32_e32 v107, 0, v123
	v_max_f32_e32 v108, 0, v111
	v_max_f32_e32 v110, 0, v115
	v_max_f32_e32 v111, 0, v119
	v_max_f32_e32 v109, 0, v116
	v_pk_mul_f32 v[106:107], v[106:107], v[106:107]
	v_pk_mul_f32 v[110:111], v[110:111], v[110:111]
	v_pk_mul_f32 v[108:109], v[108:109], v[108:109]
	v_pk_mul_f32 v[104:105], v[104:105], v[104:105]
	v_cvt_pk_bf16_f32 v104, v104, v106
	v_cvt_pk_bf16_f32 v105, v105, v107
	v_cvt_pk_bf16_f32 v106, v108, v110
	v_cvt_pk_bf16_f32 v107, v109, v111
	v_lshl_add_u64 v[108:109], s[20:21], 0, v[112:113]
	v_lshl_add_u64 v[108:109], v[108:109], 0, v[142:143]
	global_store_dwordx4 v[108:109], v[104:107], off
	s_nop 1
	s_nop 0
	v_fma_f32 v107, v99, v114, v199
	v_fma_f32 v100, v100, v114, v200
	v_fma_f32 v101, v101, v114, v201
	v_fma_f32 v102, v102, v114, v202
	v_fma_f32 v113, v103, v114, v203
	v_fma_f32 v103, v96, v114, v196
	v_fma_f32 v104, v97, v114, v197
	v_fma_f32 v105, v98, v114, v198
	v_max_f32_e32 v96, 0, v100
	v_max_f32_e32 v98, 0, v101
	v_max_f32_e32 v97, 0, v102
	v_max_f32_e32 v99, 0, v113
	v_max_f32_e32 v100, 0, v103
	v_max_f32_e32 v102, 0, v104
	v_max_f32_e32 v103, 0, v107
	v_max_f32_e32 v101, 0, v105
	v_pk_mul_f32 v[98:99], v[98:99], v[98:99]
	v_pk_mul_f32 v[102:103], v[102:103], v[102:103]
; __device__ __forceinline__ unsigned pk2(float lo, float hi) { return f2bf(lo) | (f2bf(hi) << 16); }
;     __device__ __forceinline__ void operator()(const f32x4 (&acc)[2][2][4][2], const pg8::Unit& u, int wr, int wc, int fr, int fq) const {
;     ...
;                     } else if constexpr (MODE == 8) {
;                         const f32x4 b0 = *(const f32x4*)(vec + col), b1 = *(const f32x4*)(vec + col + 4);
;                         float r[8] = {v0[0] * rstd + b0[0], v0[1] * rstd + b0[1], v0[2] * rstd + b0[2], v0[3] * rstd + b0[3], v1[0] * rstd + b1[0], v1[1] * rstd + b1[1], v1[2] * rstd + b1[2], v1[3] * rstd + b1[3]};
; #pragma unroll
;                         for (int i = 0; i < 8; ++i) { const float q = fmaxf(r[i], 0.f); r[i] = q * q; }
;                         u32x4 w; w.x = pk2(r[0], r[1]); w.y = pk2(r[2], r[3]); w.z = pk2(r[4], r[5]); w.w = pk2(r[6], r[7]);
;                         *(u32x4*)(ob + row * HIDN + col) = w;
	v_pk_mul_f32 v[96:97], v[96:97], v[96:97]
	v_pk_mul_f32 v[100:101], v[100:101], v[100:101]
	v_cvt_pk_bf16_f32 v96, v96, v98
	v_cvt_pk_bf16_f32 v97, v97, v99
	v_cvt_pk_bf16_f32 v98, v100, v102
	v_cvt_pk_bf16_f32 v99, v101, v103
	global_store_dwordx4 v[108:109], v[96:99], off offset:256
	s_nop 1
	v_or_b32_e32 v96, 32, v144
	v_ashrrev_i32_e32 v97, 31, v96
	v_lshl_add_u64 v[98:99], v[96:97], 2, s[8:9]
	v_lshlrev_b64 v[96:97], 14, v[96:97]
	v_fmamk_f32 v98, v216, 0x3a000000, v205
	v_rsq_f32_e32 v98, v98
	s_nop 0
	v_fma_f32 v99, v89, v98, v189
	v_fma_f32 v92, v92, v98, v192
	v_fma_f32 v93, v93, v98, v193
	v_fma_f32 v94, v94, v98, v194
	v_fma_f32 v107, v95, v98, v195
	v_fma_f32 v95, v88, v98, v188
	v_fma_f32 v103, v91, v98, v191
	v_fma_f32 v100, v90, v98, v190
	v_max_f32_e32 v88, 0, v92
	v_max_f32_e32 v90, 0, v93
	v_max_f32_e32 v89, 0, v94
	v_max_f32_e32 v91, 0, v107
	v_max_f32_e32 v92, 0, v95
	v_max_f32_e32 v94, 0, v99
	v_max_f32_e32 v95, 0, v103
	v_max_f32_e32 v93, 0, v100
	v_pk_mul_f32 v[90:91], v[90:91], v[90:91]
	v_pk_mul_f32 v[94:95], v[94:95], v[94:95]
	v_pk_mul_f32 v[92:93], v[92:93], v[92:93]
	v_pk_mul_f32 v[88:89], v[88:89], v[88:89]
	v_cvt_pk_bf16_f32 v88, v88, v90
	v_cvt_pk_bf16_f32 v89, v89, v91
	v_cvt_pk_bf16_f32 v90, v92, v94
	v_cvt_pk_bf16_f32 v91, v93, v95
	v_lshl_add_u64 v[92:93], s[20:21], 0, v[96:97]
	v_lshl_add_u64 v[92:93], v[92:93], 0, v[142:143]
	global_store_dwordx4 v[92:93], v[88:91], off
	s_nop 1
	s_nop 0
	v_fma_f32 v91, v83, v98, v199
	v_fma_f32 v84, v84, v98, v200
	v_fma_f32 v85, v85, v98, v201
	v_fma_f32 v86, v86, v98, v202
	v_fma_f32 v97, v87, v98, v203
	v_fma_f32 v87, v80, v98, v196
	v_fma_f32 v88, v81, v98, v197
	v_fma_f32 v89, v82, v98, v198
	v_max_f32_e32 v80, 0, v84
	v_max_f32_e32 v82, 0, v85
	v_max_f32_e32 v81, 0, v86
	v_max_f32_e32 v83, 0, v97
	v_max_f32_e32 v84, 0, v87
	v_max_f32_e32 v86, 0, v88
	v_max_f32_e32 v87, 0, v91
	v_max_f32_e32 v85, 0, v89
	v_pk_mul_f32 v[82:83], v[82:83], v[82:83]
	v_pk_mul_f32 v[86:87], v[86:87], v[86:87]
	v_pk_mul_f32 v[80:81], v[80:81], v[80:81]
	v_pk_mul_f32 v[84:85], v[84:85], v[84:85]
	v_cvt_pk_bf16_f32 v80, v80, v82
	v_cvt_pk_bf16_f32 v81, v81, v83
	v_cvt_pk_bf16_f32 v82, v84, v86
	v_cvt_pk_bf16_f32 v83, v85, v87
	global_store_dwordx4 v[92:93], v[80:83], off offset:256
	s_nop 1
	v_or_b32_e32 v80, 48, v144
	v_ashrrev_i32_e32 v81, 31, v80
	v_lshl_add_u64 v[82:83], v[80:81], 2, s[8:9]
	v_lshlrev_b64 v[80:81], 14, v[80:81]
	v_fmamk_f32 v82, v217, 0x3a000000, v205
	v_rsq_f32_e32 v82, v82
	s_nop 0
	v_fma_f32 v83, v73, v82, v189
	v_fma_f32 v76, v76, v82, v192
	v_fma_f32 v77, v77, v82, v193
	v_fma_f32 v78, v78, v82, v194
	v_fma_f32 v91, v79, v82, v195
	v_fma_f32 v79, v72, v82, v188
	v_fma_f32 v87, v75, v82, v191
	v_fma_f32 v84, v74, v82, v190
	v_max_f32_e32 v72, 0, v76
	v_max_f32_e32 v74, 0, v77
	v_max_f32_e32 v73, 0, v78
	v_max_f32_e32 v75, 0, v91
	v_max_f32_e32 v76, 0, v79
	v_max_f32_e32 v78, 0, v83
	v_max_f32_e32 v79, 0, v87
	v_max_f32_e32 v77, 0, v84
	v_pk_mul_f32 v[74:75], v[74:75], v[74:75]
	v_pk_mul_f32 v[78:79], v[78:79], v[78:79]
	v_pk_mul_f32 v[76:77], v[76:77], v[76:77]
	v_pk_mul_f32 v[72:73], v[72:73], v[72:73]
	v_cvt_pk_bf16_f32 v72, v72, v74
	v_cvt_pk_bf16_f32 v73, v73, v75
	v_cvt_pk_bf16_f32 v74, v76, v78
	v_cvt_pk_bf16_f32 v75, v77, v79
	v_lshl_add_u64 v[76:77], s[20:21], 0, v[80:81]
	v_lshl_add_u64 v[76:77], v[76:77], 0, v[142:143]
	global_store_dwordx4 v[76:77], v[72:75], off
	s_nop 1
	s_nop 0
	v_fma_f32 v75, v67, v82, v199
	v_fma_f32 v68, v68, v82, v200
	v_fma_f32 v69, v69, v82, v201
	v_fma_f32 v70, v70, v82, v202
	v_fma_f32 v81, v71, v82, v203
	v_fma_f32 v71, v64, v82, v196
	v_fma_f32 v72, v65, v82, v197
	v_fma_f32 v73, v66, v82, v198
	v_max_f32_e32 v64, 0, v68
	v_max_f32_e32 v66, 0, v69
	v_max_f32_e32 v65, 0, v70
	v_max_f32_e32 v67, 0, v81
	v_max_f32_e32 v68, 0, v71
	v_max_f32_e32 v70, 0, v72
	v_max_f32_e32 v71, 0, v75
	v_max_f32_e32 v69, 0, v73
	v_pk_mul_f32 v[66:67], v[66:67], v[66:67]
	v_pk_mul_f32 v[70:71], v[70:71], v[70:71]
	v_pk_mul_f32 v[64:65], v[64:65], v[64:65]
	v_pk_mul_f32 v[68:69], v[68:69], v[68:69]
	v_cvt_pk_bf16_f32 v64, v64, v66
	v_cvt_pk_bf16_f32 v65, v65, v67
	v_cvt_pk_bf16_f32 v66, v68, v70
	v_cvt_pk_bf16_f32 v67, v69, v71
	global_store_dwordx4 v[76:77], v[64:67], off offset:256
	s_nop 1
	v_fmamk_f32 v64, v218, 0x3a000000, v205
	s_mov_b64 s[0:1], 0x200000
	v_rsq_f32_e32 v64, v64
	s_nop 0
	v_fma_f32 v65, v57, v64, v189
	v_fma_f32 v60, v60, v64, v192
	v_fma_f32 v61, v61, v64, v193
	v_fma_f32 v62, v62, v64, v194
	v_fma_f32 v73, v63, v64, v195
	v_fma_f32 v63, v56, v64, v188
	v_fma_f32 v69, v59, v64, v191
	v_fma_f32 v66, v58, v64, v190
	v_max_f32_e32 v56, 0, v60
	v_max_f32_e32 v58, 0, v61
	v_max_f32_e32 v57, 0, v62
	v_max_f32_e32 v59, 0, v73
	v_max_f32_e32 v60, 0, v63
	v_max_f32_e32 v62, 0, v65
	v_max_f32_e32 v63, 0, v69
	v_max_f32_e32 v61, 0, v66
	v_pk_mul_f32 v[58:59], v[58:59], v[58:59]
	v_pk_mul_f32 v[62:63], v[62:63], v[62:63]
	v_pk_mul_f32 v[60:61], v[60:61], v[60:61]
	v_bfe_u32 v67, v59, 16, 1
	v_bfe_u32 v68, v58, 16, 1
	v_add3_u32 v68, v58, v68, s33
	v_add3_u32 v67, v59, v67, s33
	v_pk_mul_f32 v[56:57], v[56:57], v[56:57]
	v_cvt_pk_bf16_f32 v59, v61, v63
	v_cvt_pk_bf16_f32 v58, v60, v62
	v_bfe_u32 v62, v56, 16, 1
	v_bfe_u32 v63, v57, 16, 1
	v_add3_u32 v57, v57, v63, s33
	v_add3_u32 v56, v56, v62, s33
	v_lshl_add_u64 v[60:61], v[124:125], 0, s[0:1]
	s_mov_b32 s0, 0x200000
	v_lshrrev_b32_e32 v56, 16, v56
	v_lshrrev_b32_e32 v57, 16, v57
	v_add_co_u32_e32 v62, vcc, s0, v124
	v_and_or_b32 v57, v67, s67, v57
	v_and_or_b32 v56, v68, s67, v56
	v_addc_co_u32_e32 v63, vcc, 0, v125, vcc
	global_store_dwordx4 v[62:63], v[56:59], off
	s_nop 1
; __device__ __forceinline__ unsigned pk2(float lo, float hi) { return f2bf(lo) | (f2bf(hi) << 16); }
;     __device__ __forceinline__ void operator()(const f32x4 (&acc)[2][2][4][2], const pg8::Unit& u, int wr, int wc, int fr, int fq) const {
;     ...
;                     } else if constexpr (MODE == 8) {
;                         const f32x4 b0 = *(const f32x4*)(vec + col), b1 = *(const f32x4*)(vec + col + 4);
;                         float r[8] = {v0[0] * rstd + b0[0], v0[1] * rstd + b0[1], v0[2] * rstd + b0[2], v0[3] * rstd + b0[3], v1[0] * rstd + b1[0], v1[1] * rstd + b1[1], v1[2] * rstd + b1[2], v1[3] * rstd + b1[3]};
; #pragma unroll
;                         for (int i = 0; i < 8; ++i) { const float q = fmaxf(r[i], 0.f); r[i] = q * q; }
;                         u32x4 w; w.x = pk2(r[0], r[1]); w.y = pk2(r[2], r[3]); w.z = pk2(r[4], r[5]); w.w = pk2(r[6], r[7]);
;                         *(u32x4*)(ob + row * HIDN + col) = w;
	s_nop 0
	v_fma_f32 v59, v51, v64, v199
	v_fma_f32 v52, v52, v64, v200
	v_fma_f32 v53, v53, v64, v201
	v_fma_f32 v54, v54, v64, v202
	v_fma_f32 v69, v55, v64, v203
	v_fma_f32 v55, v48, v64, v196
	v_fma_f32 v56, v49, v64, v197
	v_fma_f32 v57, v50, v64, v198
	v_max_f32_e32 v48, 0, v52
	v_max_f32_e32 v50, 0, v53
	v_max_f32_e32 v49, 0, v54
	v_max_f32_e32 v51, 0, v69
	v_max_f32_e32 v52, 0, v55
	v_max_f32_e32 v54, 0, v56
	v_max_f32_e32 v55, 0, v59
	v_max_f32_e32 v53, 0, v57
	v_pk_mul_f32 v[50:51], v[50:51], v[50:51]
	v_pk_mul_f32 v[54:55], v[54:55], v[54:55]
	v_pk_mul_f32 v[48:49], v[48:49], v[48:49]
	v_pk_mul_f32 v[52:53], v[52:53], v[52:53]
	v_cvt_pk_bf16_f32 v48, v48, v50
	v_cvt_pk_bf16_f32 v49, v49, v51
	v_cvt_pk_bf16_f32 v50, v52, v54
	v_cvt_pk_bf16_f32 v51, v53, v55
	global_store_dwordx4 v[60:61], v[48:51], off offset:256
	s_nop 1
	v_fmamk_f32 v48, v219, 0x3a000000, v205
	s_mov_b64 s[0:1], 0x240000
	v_rsq_f32_e32 v48, v48
	s_nop 0
	v_fma_f32 v49, v41, v48, v189
	v_fma_f32 v44, v44, v48, v192
	v_fma_f32 v45, v45, v48, v193
	v_fma_f32 v46, v46, v48, v194
	v_fma_f32 v57, v47, v48, v195
	v_fma_f32 v47, v40, v48, v188
	v_fma_f32 v53, v43, v48, v191
	v_fma_f32 v50, v42, v48, v190
	v_max_f32_e32 v40, 0, v44
	v_max_f32_e32 v42, 0, v45
	v_max_f32_e32 v41, 0, v46
	v_max_f32_e32 v43, 0, v57
	v_max_f32_e32 v44, 0, v47
	v_max_f32_e32 v46, 0, v49
	v_max_f32_e32 v47, 0, v53
	v_max_f32_e32 v45, 0, v50
	v_pk_mul_f32 v[42:43], v[42:43], v[42:43]
	v_pk_mul_f32 v[46:47], v[46:47], v[46:47]
	v_pk_mul_f32 v[44:45], v[44:45], v[44:45]
	v_bfe_u32 v51, v43, 16, 1
	v_bfe_u32 v52, v42, 16, 1
	v_add3_u32 v52, v42, v52, s33
	v_add3_u32 v51, v43, v51, s33
	v_pk_mul_f32 v[40:41], v[40:41], v[40:41]
	v_cvt_pk_bf16_f32 v43, v45, v47
	v_cvt_pk_bf16_f32 v42, v44, v46
	v_bfe_u32 v46, v40, 16, 1
	v_bfe_u32 v47, v41, 16, 1
	v_add3_u32 v41, v41, v47, s33
	v_add3_u32 v40, v40, v46, s33
	v_lshl_add_u64 v[44:45], v[124:125], 0, s[0:1]
	s_mov_b32 s0, 0x240000
	v_lshrrev_b32_e32 v40, 16, v40
	v_lshrrev_b32_e32 v41, 16, v41
	v_add_co_u32_e32 v46, vcc, s0, v124
	v_and_or_b32 v41, v51, s67, v41
	v_and_or_b32 v40, v52, s67, v40
	v_addc_co_u32_e32 v47, vcc, 0, v125, vcc
	global_store_dwordx4 v[46:47], v[40:43], off
	s_nop 1
	s_nop 0
	v_fma_f32 v43, v35, v48, v199
	v_fma_f32 v36, v36, v48, v200
	v_fma_f32 v37, v37, v48, v201
	v_fma_f32 v38, v38, v48, v202
	v_fma_f32 v53, v39, v48, v203
	v_fma_f32 v39, v32, v48, v196
	v_fma_f32 v40, v33, v48, v197
	v_fma_f32 v41, v34, v48, v198
	v_max_f32_e32 v32, 0, v36
	v_max_f32_e32 v34, 0, v37
	v_max_f32_e32 v33, 0, v38
	v_max_f32_e32 v35, 0, v53
	v_max_f32_e32 v36, 0, v39
	v_max_f32_e32 v38, 0, v40
	v_max_f32_e32 v39, 0, v43
	v_max_f32_e32 v37, 0, v41
	v_pk_mul_f32 v[34:35], v[34:35], v[34:35]
	v_pk_mul_f32 v[38:39], v[38:39], v[38:39]
	v_pk_mul_f32 v[32:33], v[32:33], v[32:33]
	v_pk_mul_f32 v[36:37], v[36:37], v[36:37]
	v_cvt_pk_bf16_f32 v32, v32, v34
	v_cvt_pk_bf16_f32 v33, v33, v35
	v_cvt_pk_bf16_f32 v34, v36, v38
	v_cvt_pk_bf16_f32 v35, v37, v39
	global_store_dwordx4 v[44:45], v[32:35], off offset:256
	s_nop 1
	v_fmamk_f32 v32, v220, 0x3a000000, v205
	s_mov_b64 s[0:1], 0x280000
	v_rsq_f32_e32 v32, v32
	s_nop 0
	v_fma_f32 v33, v25, v32, v189
	v_fma_f32 v28, v28, v32, v192
	v_fma_f32 v29, v29, v32, v193
	v_fma_f32 v30, v30, v32, v194
	v_fma_f32 v41, v31, v32, v195
	v_fma_f32 v31, v24, v32, v188
	v_fma_f32 v37, v27, v32, v191
	v_fma_f32 v34, v26, v32, v190
	v_max_f32_e32 v24, 0, v28
	v_max_f32_e32 v26, 0, v29
	v_max_f32_e32 v25, 0, v30
	v_max_f32_e32 v27, 0, v41
	v_max_f32_e32 v28, 0, v31
	v_max_f32_e32 v30, 0, v33
	v_max_f32_e32 v31, 0, v37
	v_max_f32_e32 v29, 0, v34
	v_pk_mul_f32 v[26:27], v[26:27], v[26:27]
	v_pk_mul_f32 v[30:31], v[30:31], v[30:31]
	v_pk_mul_f32 v[28:29], v[28:29], v[28:29]
	v_bfe_u32 v35, v27, 16, 1
; #define PG8_BAR __builtin_amdgcn_s_barrier()
; __device__ __forceinline__ unsigned pk2(float lo, float hi) { return f2bf(lo) | (f2bf(hi) << 16); }
; template <class Epi, class Sched, bool ALIGN_EPI = false, bool SP2 = false, bool F8 = false>
; __device__ __forceinline__ void gemm_phase(PG8_LAS unsigned char* lds, const Gemm g, const Sched& S, const Epi& E) {
;     ...
;         if constexpr (!Epi::AFTER_DRAIN) { E(acc, cur, wr, wc, fr, fq); S.done(cur); }
;         if (!has_next) break;
; #pragma unroll
;         for (int a = 0; a < 2; ++a)
; #pragma unroll
;             for (int b = 0; b < 2; ++b)
; #pragma unroll
;                 for (int m = 0; m < 4; ++m)
; #pragma unroll
;                     for (int n = 0; n < 2; ++n) acc[a][b][m][n] = (f32x4){0.f, 0.f, 0.f, 0.f};
;         cur = nxt; cA = nA; cB = nB; ++ui;
;         if constexpr (ALIGN_EPI) { if (wr == 1) PG8_BAR; }
;     __device__ __forceinline__ void operator()(const f32x4 (&acc)[2][2][4][2], const pg8::Unit& u, int wr, int wc, int fr, int fq) const {
;     ...
;                     } else if constexpr (MODE == 8) {
;                         const f32x4 b0 = *(const f32x4*)(vec + col), b1 = *(const f32x4*)(vec + col + 4);
;                         float r[8] = {v0[0] * rstd + b0[0], v0[1] * rstd + b0[1], v0[2] * rstd + b0[2], v0[3] * rstd + b0[3], v1[0] * rstd + b1[0], v1[1] * rstd + b1[1], v1[2] * rstd + b1[2], v1[3] * rstd + b1[3]};
; #pragma unroll
;                         for (int i = 0; i < 8; ++i) { const float q = fmaxf(r[i], 0.f); r[i] = q * q; }
;                         u32x4 w; w.x = pk2(r[0], r[1]); w.y = pk2(r[2], r[3]); w.z = pk2(r[4], r[5]); w.w = pk2(r[6], r[7]);
;                         *(u32x4*)(ob + row * HIDN + col) = w;
	v_bfe_u32 v36, v26, 16, 1
	v_add3_u32 v36, v26, v36, s33
	v_add3_u32 v35, v27, v35, s33
	v_pk_mul_f32 v[24:25], v[24:25], v[24:25]
	v_cvt_pk_bf16_f32 v27, v29, v31
	v_cvt_pk_bf16_f32 v26, v28, v30
	v_bfe_u32 v30, v24, 16, 1
	v_bfe_u32 v31, v25, 16, 1
	v_add3_u32 v25, v25, v31, s33
	v_add3_u32 v24, v24, v30, s33
	v_lshl_add_u64 v[28:29], v[124:125], 0, s[0:1]
	s_mov_b32 s0, 0x280000
	v_lshrrev_b32_e32 v24, 16, v24
	v_lshrrev_b32_e32 v25, 16, v25
	v_add_co_u32_e32 v30, vcc, s0, v124
	v_and_or_b32 v25, v35, s67, v25
	v_and_or_b32 v24, v36, s67, v24
	v_addc_co_u32_e32 v31, vcc, 0, v125, vcc
	global_store_dwordx4 v[30:31], v[24:27], off
	s_nop 1
	s_nop 0
	v_fma_f32 v27, v19, v32, v199
	v_fma_f32 v20, v20, v32, v200
	v_fma_f32 v21, v21, v32, v201
	v_fma_f32 v22, v22, v32, v202
	v_fma_f32 v37, v23, v32, v203
	v_fma_f32 v23, v16, v32, v196
	v_fma_f32 v24, v17, v32, v197
	v_fma_f32 v25, v18, v32, v198
	v_max_f32_e32 v16, 0, v20
	v_max_f32_e32 v18, 0, v21
	v_max_f32_e32 v17, 0, v22
	v_max_f32_e32 v19, 0, v37
	v_max_f32_e32 v20, 0, v23
	v_max_f32_e32 v22, 0, v24
	v_max_f32_e32 v23, 0, v27
	v_max_f32_e32 v21, 0, v25
	v_pk_mul_f32 v[18:19], v[18:19], v[18:19]
	v_pk_mul_f32 v[22:23], v[22:23], v[22:23]
	v_pk_mul_f32 v[16:17], v[16:17], v[16:17]
	v_pk_mul_f32 v[20:21], v[20:21], v[20:21]
	v_cvt_pk_bf16_f32 v16, v16, v18
	v_cvt_pk_bf16_f32 v17, v17, v19
	v_cvt_pk_bf16_f32 v18, v20, v22
	v_cvt_pk_bf16_f32 v19, v21, v23
	global_store_dwordx4 v[28:29], v[16:19], off offset:256
	s_nop 1
	v_fmamk_f32 v16, v221, 0x3a000000, v205
	s_mov_b64 s[0:1], 0x2c0000
	v_rsq_f32_e32 v16, v16
	s_nop 0
	v_fma_f32 v17, v9, v16, v189
	v_fma_f32 v12, v12, v16, v192
	v_fma_f32 v13, v13, v16, v193
	v_fma_f32 v14, v14, v16, v194
	v_fma_f32 v25, v15, v16, v195
	v_fma_f32 v15, v8, v16, v188
	v_fma_f32 v21, v11, v16, v191
	v_fma_f32 v18, v10, v16, v190
	v_max_f32_e32 v8, 0, v12
	v_max_f32_e32 v10, 0, v13
	v_max_f32_e32 v9, 0, v14
	v_max_f32_e32 v11, 0, v25
	v_max_f32_e32 v12, 0, v15
	v_max_f32_e32 v14, 0, v17
	v_max_f32_e32 v15, 0, v21
	v_max_f32_e32 v13, 0, v18
	v_pk_mul_f32 v[10:11], v[10:11], v[10:11]
	v_pk_mul_f32 v[14:15], v[14:15], v[14:15]
	v_pk_mul_f32 v[12:13], v[12:13], v[12:13]
	v_bfe_u32 v19, v11, 16, 1
	v_bfe_u32 v20, v10, 16, 1
	v_add3_u32 v20, v10, v20, s33
	v_add3_u32 v19, v11, v19, s33
	v_pk_mul_f32 v[8:9], v[8:9], v[8:9]
	v_cvt_pk_bf16_f32 v11, v13, v15
	v_cvt_pk_bf16_f32 v10, v12, v14
	v_bfe_u32 v14, v8, 16, 1
	v_bfe_u32 v15, v9, 16, 1
	v_add3_u32 v9, v9, v15, s33
	v_add3_u32 v8, v8, v14, s33
	v_lshl_add_u64 v[12:13], v[124:125], 0, s[0:1]
	s_mov_b32 s0, 0x2c0000
	v_lshrrev_b32_e32 v8, 16, v8
	v_lshrrev_b32_e32 v9, 16, v9
	v_add_co_u32_e32 v14, vcc, s0, v124
	v_and_or_b32 v9, v19, s67, v9
	v_and_or_b32 v8, v20, s67, v8
	v_addc_co_u32_e32 v15, vcc, 0, v125, vcc
	global_store_dwordx4 v[14:15], v[8:11], off
	s_nop 0
	s_mov_b64 s[0:1], -1
	s_andn2_b64 vcc, exec, s[38:39]
	v_fma_f32 v11, v3, v16, v199
	v_fma_f32 v4, v4, v16, v200
	v_fma_f32 v5, v5, v16, v201
	v_fma_f32 v6, v6, v16, v202
	v_fma_f32 v21, v7, v16, v203
	v_fma_f32 v7, v0, v16, v196
	v_fma_f32 v8, v1, v16, v197
	v_fma_f32 v9, v2, v16, v198
	v_max_f32_e32 v0, 0, v4
	v_max_f32_e32 v2, 0, v5
	v_max_f32_e32 v1, 0, v6
	v_max_f32_e32 v3, 0, v21
	v_max_f32_e32 v4, 0, v7
	v_max_f32_e32 v6, 0, v8
	v_max_f32_e32 v7, 0, v11
	v_max_f32_e32 v5, 0, v9
	v_pk_mul_f32 v[2:3], v[2:3], v[2:3]
	v_pk_mul_f32 v[6:7], v[6:7], v[6:7]
	v_pk_mul_f32 v[0:1], v[0:1], v[0:1]
	v_pk_mul_f32 v[4:5], v[4:5], v[4:5]
	v_cvt_pk_bf16_f32 v0, v0, v2
	v_cvt_pk_bf16_f32 v1, v1, v3
	v_cvt_pk_bf16_f32 v2, v4, v6
	v_cvt_pk_bf16_f32 v3, v5, v7
	global_store_dwordx4 v[12:13], v[0:3], off offset:256
	s_mov_b32 s101, 1
	s_cbranch_vccnz .LBB0_24
	s_andn2_b64 vcc, exec, s[42:43]
	s_cbranch_vccnz .LBB0_23
	s_barrier
	s_branch .LBB0_23

; #define PG8_STAGE(bufoff, gbase, voff) do { _Pragma("unroll") for (int _i = 0; _i < 2; ++_i) \
;         __builtin_amdgcn_global_load_lds((const unsigned*)((const char*)(gbase) + (voff)[_i]), (PG8_LAS unsigned*)(lds + (bufoff) + ldsw + _i * 8192), 16, 0, 0); } while (0)
; #define PG8_WAIT_V(n) asm volatile("s_waitcnt vmcnt(" #n ")" ::: "memory")
; #define PG8_BAR __builtin_amdgcn_s_barrier()
; template <class Epi, class Sched, bool ALIGN_EPI = false, bool SP2 = false, bool F8 = false>
; __device__ __forceinline__ void gemm_phase(PG8_LAS unsigned char* lds, const Gemm g, const Sched& S, const Epi& E) {
;     ...
;     for (int i = 0; i < 2; ++i) { int R, C; stage_rc(tid * 16 + i * 8192, R, C); const int Rb = Epi::PERM ? ((R & ~31) + perm32(R & 31)) : R;
;         voffA[i] = (unsigned)(R * K + C) * 2u; voffB[i] = (unsigned)(Rb * K + C) * 2u; }
;     const size_t kstep = (size_t)(BK * 2);
;     const size_t hstep = (size_t)HALF * K * 2;
;     const size_t tstep = 2 * hstep;
;     const unsigned ldsw = (unsigned)wid * 1024u;
;     const int aoff = lds_byte(wr * 64 + fr, fq * 8), boff = lds_byte(wc * 32 + fr, fq * 8);
;     ...
;     if constexpr (SP2) {
;         PG8_STAGE(PG8_SB(0, 0), cB, voffB); PG8_STAGE(PG8_SB(0, 1), cB + hstep, voffB); PG8_STAGE(PG8_SA(0, 0), cA, voffA); PG8_STAGE(PG8_SA(0, 1), cA + hstep, voffA);
;         if (wr == 1) PG8_BAR;
;         PG8_WAIT_V(2); PG8_BAR;
;         PG8_STAGE(PG8_SB(1, 0), cB + kstep, voffB); PG8_STAGE(PG8_SA(1, 0), cA + kstep, voffA); PG8_STAGE(PG8_SB(1, 1), cB + hstep + kstep, voffB);
;         PG8_WAIT_V(6); PG8_BAR;
.LBB0_49:
	v_readlane_b32 s28, v250, 24
	v_readlane_b32 s29, v250, 25
	s_add_u32 s4, s28, 0x4000
	s_addc_u32 s5, s29, 0
	s_waitcnt vmcnt(0)
	v_bfe_u32 v16, v11, 4, 2
	s_add_u32 s42, s28, 0x8000
	v_and_b32_e32 v15, 15, v11
	v_lshlrev_b32_e32 v17, 4, v16
	v_lshlrev_b32_e32 v11, 2, v11
	s_addc_u32 s43, s29, 0
	v_lshl_or_b32 v150, s0, 6, v15
	v_lshl_or_b32 v15, v15, 6, v17
	s_lshl_b32 s0, s0, 13
	v_and_b32_e32 v11, 32, v11
	v_bitop3_b32 v17, v15, s0, v11 bitop3:0xde
	s_lshl_b32 s0, s1, 5
	s_and_b32 s9, s0, 0x60
	s_add_i32 m0, s17, 0x18000
	v_lshl_add_u64 v[6:7], v[6:7], 0, s[14:15]
	s_lshl_b32 s0, s9, 7
	s_waitcnt vmcnt(2)
	s_barrier
	global_load_lds_dwordx4 v[6:7], off
	v_lshl_add_u64 v[4:5], v[4:5], 0, s[14:15]
	s_add_i32 m0, s17, 0x1a000
	s_add_i32 s52, s17, 0x8000
	s_add_i32 s53, s17, 0xa000
	v_bitop3_b32 v151, v15, s0, v11 bitop3:0xde
	global_load_lds_dwordx4 v[4:5], off
	v_lshl_add_u64 v[0:1], v[0:1], 0, s[14:15]
	s_mov_b32 m0, s52
	s_add_u32 s0, s58, 0x80080
	global_load_lds_dwordx4 v[0:1], off
	v_lshl_add_u64 v[0:1], v[2:3], 0, s[14:15]
	s_mov_b32 m0, s53
	s_addc_u32 s1, s59, 0
	global_load_lds_dwordx4 v[0:1], off
	s_add_i32 m0, s17, 0x1c000
	v_lshl_add_u64 v[0:1], s[0:1], 0, v[160:161]
	global_load_lds_dwordx4 v[0:1], off
	v_lshl_add_u64 v[0:1], s[0:1], 0, v[132:133]
	s_add_i32 m0, s17, 0x1e000
	s_cmpk_lt_u32 s8, 0x100
	global_load_lds_dwordx4 v[0:1], off
	v_lshlrev_b32_e32 v0, 15, v8
	v_and_b32_e32 v0, 0xffff0000, v0
	v_lshl_add_u32 v0, v9, 12, v0
	v_and_b32_e32 v1, 1, v8
	v_lshl_or_b32 v0, v1, 6, v0
	v_lshl_add_u32 v134, v10, 1, v0
	v_lshlrev_b32_e32 v0, 15, v12
	v_and_b32_e32 v0, 0xffff0000, v0
	s_waitcnt vmcnt(6)
	v_lshl_add_u32 v0, v13, 12, v0
	v_and_b32_e32 v1, 1, v12
	v_lshl_or_b32 v0, v1, 6, v0
	v_readlane_b32 s62, v251, 21
	v_readlane_b32 s30, v250, 29
	s_cselect_b64 s[44:45], -1, 0
	s_mov_b32 s0, 0
	v_cmp_eq_u32_e64 s[38:39], 0, v16
	v_lshl_or_b32 v152, v16, 3, s9
	v_mov_b32_e32 v135, v161
	v_lshl_add_u32 v136, v14, 1, v0
	v_mov_b32_e32 v137, v161
	v_add_u32_e32 v153, 0, v17
	v_readlane_b32 s63, v251, 22
	v_readlane_b32 s31, v250, 30
	s_barrier
	s_mov_b32 s101, 0
	s_branch .LBB0_52

; #define PG8_STAGE(bufoff, gbase, voff) do { _Pragma("unroll") for (int _i = 0; _i < 2; ++_i) \
;         __builtin_amdgcn_global_load_lds((const unsigned*)((const char*)(gbase) + (voff)[_i]), (PG8_LAS unsigned*)(lds + (bufoff) + ldsw + _i * 8192), 16, 0, 0); } while (0)
; #define PG8_WAIT_V(n) asm volatile("s_waitcnt vmcnt(" #n ")" ::: "memory")
; #define PG8_WAIT_L(n) asm volatile("s_waitcnt lgkmcnt(" #n ")" ::: "memory")
; #define PG8_BAR __builtin_amdgcn_s_barrier()
; #define PG8_SCHED __builtin_amdgcn_sched_barrier(0)
; template <class Epi, class Sched, bool ALIGN_EPI = false, bool SP2 = false, bool F8 = false>
; __device__ __forceinline__ void gemm_phase(PG8_LAS unsigned char* lds, const Gemm g, const Sched& S, const Epi& E) {
;     ...
;         const bool has_next = S.next(ui + 1, nxt);
;         const char* nA = has_next ? (const char*)g.A + (size_t)nxt.pm * tstep : cA; const char* nB = has_next ? (const char*)g.Bt + (size_t)nxt.pn * tstep : cB;
;         for (int t = 0; t < nt; t += 2) {
;             const bool last = (t == nt - 2);
;             const char* a1 = cA + (size_t)(t + 1) * kstep;
;             const char* a2 = last ? nA : cA + (size_t)(t + 2) * kstep; const char* b2 = last ? nB : cB + (size_t)(t + 2) * kstep;
;             const char* a3 = a2 + kstep; const char* b3 = b2 + kstep;
;             if (last && has_next) S.a_ready(nxt);
;             if constexpr (SP2) {
;             PG8_LDB(B0, 0, 0); PG8_LDB(B1, 0, 1); PG8_SCHED; PG8_LDA(At, 0, 0); PG8_STAGE(PG8_SA(1, 1), a1 + hstep, voffA);
;             PG8_WAIT_V(8); PG8_WAIT_L(0); PG8_BAR; PG8_MMA(0, 0, At, B0); PG8_MMA(0, 1, At, B1); PG8_BAR; PG8_SCHED;
;             PG8_LDA(At, 0, 1); PG8_STAGE(PG8_SB(0, 0), b2, voffB); PG8_STAGE(PG8_SB(0, 1), b2 + hstep, voffB); PG8_STAGE(PG8_SA(0, 0), a2, voffA);
;             PG8_WAIT_V(8); PG8_WAIT_L(0); PG8_BAR; PG8_MMA(1, 0, At, B0); PG8_MMA(1, 1, At, B1); PG8_BAR; PG8_SCHED;
.LBB0_58:
	s_ashr_i32 s49, s48, 31
	s_lshl_b64 s[8:9], s[48:49], 20
	s_add_u32 s50, s26, s8
	s_addc_u32 s51, s27, s9
	s_and_b64 s[8:9], s[40:41], exec
	s_cselect_b32 s1, s51, s37
	s_cselect_b32 s8, s50, s36
	s_ashr_i32 s47, s46, 31
	s_lshl_b64 s[28:29], s[46:47], 20
	s_add_u32 s54, s13, s28
	s_addc_u32 s55, s22, s29
	s_and_b64 s[28:29], s[40:41], exec
	s_cselect_b32 s9, s55, s59
	s_cselect_b32 s11, s54, s58
	s_add_u32 s36, s36, 0x80080
	s_addc_u32 s37, s37, 0
	s_add_u32 s19, s58, 0x100
	s_addc_u32 s23, s59, 0
	s_mov_b32 s28, -2
	s_add_u32 s29, s36, 0xfff80080
	s_addc_u32 s34, s37, -1
	s_add_i32 s35, 0, 0x10000
	s_cmp_eq_u32 s28, 28
	s_cselect_b32 s61, s1, s34
	s_cselect_b32 s60, s8, s29
	s_cselect_b32 s59, s9, s23
	s_cselect_b32 s58, s11, s19
	s_add_i32 s29, 0, 0x14000
	v_add_u32_e32 v154, s35, v151
	v_add_u32_e32 v158, s29, v151
	ds_read_b128 v[138:141], v154
	ds_read_b128 v[142:145], v154 offset:1024
	ds_read_b128 v[146:149], v154 offset:2048
	ds_read_b128 v[154:157], v154 offset:3072
	ds_read_b128 v[184:187], v158
	ds_read_b128 v[188:191], v158 offset:1024
	ds_read_b128 v[192:195], v158 offset:2048
	ds_read_b128 v[196:199], v158 offset:3072
	v_lshl_add_u64 v[158:159], s[36:37], 0, v[134:135]
	s_add_i32 m0, s17, 0xc000
	ds_read_b128 v[200:203], v153
	ds_read_b128 v[214:217], v153 offset:1024
	ds_read_b128 v[218:221], v153 offset:2048
	ds_read_b128 v[222:225], v153 offset:3072
	ds_read_b128 v[226:229], v153 offset:4096
	ds_read_b128 v[230:233], v153 offset:5120
	ds_read_b128 v[234:237], v153 offset:6144
	ds_read_b128 v[238:241], v153 offset:7168
	global_load_lds_dwordx4 v[158:159], off
	v_lshl_add_u64 v[158:159], s[36:37], 0, v[136:137]
	s_add_i32 m0, s17, 0xe000
	s_nop 0
	global_load_lds_dwordx4 v[158:159], off
	s_cmp_lg_u32 s101, 0
	s_cbranch_scc1 .Lgk_nw1_59
	s_waitcnt vmcnt(8)
.Lgk_nw1_59:
	s_waitcnt lgkmcnt(0)
	s_barrier
	s_setprio 1
	s_waitcnt lgkmcnt(0)
	v_mfma_f32_16x16x32_bf16 v[124:127], v[138:141], v[200:203], 0
	v_mfma_f32_16x16x32_bf16 v[120:123], v[146:149], v[200:203], 0
	v_mfma_f32_16x16x32_bf16 v[108:111], v[138:141], v[218:221], 0
	v_mfma_f32_16x16x32_bf16 v[104:107], v[146:149], v[218:221], 0
	v_mfma_f32_16x16x32_bf16 v[92:95], v[138:141], v[226:229], 0
	v_mfma_f32_16x16x32_bf16 v[88:91], v[146:149], v[226:229], 0
	v_mfma_f32_16x16x32_bf16 v[76:79], v[138:141], v[234:237], 0
	v_mfma_f32_16x16x32_bf16 v[72:75], v[146:149], v[234:237], 0
	v_mfma_f32_16x16x32_bf16 v[124:127], v[142:145], v[214:217], v[124:127]
	v_mfma_f32_16x16x32_bf16 v[120:123], v[154:157], v[214:217], v[120:123]
	v_mfma_f32_16x16x32_bf16 v[108:111], v[142:145], v[222:225], v[108:111]
	v_mfma_f32_16x16x32_bf16 v[104:107], v[154:157], v[222:225], v[104:107]
	v_mfma_f32_16x16x32_bf16 v[92:95], v[142:145], v[230:233], v[92:95]
	v_mfma_f32_16x16x32_bf16 v[88:91], v[154:157], v[230:233], v[88:91]
	v_mfma_f32_16x16x32_bf16 v[76:79], v[142:145], v[238:241], v[76:79]
	v_mfma_f32_16x16x32_bf16 v[72:75], v[154:157], v[238:241], v[72:75]
	s_setprio 0
	s_setprio 1
	v_mfma_f32_16x16x32_bf16 v[116:119], v[184:187], v[200:203], 0
	v_mfma_f32_16x16x32_bf16 v[112:115], v[192:195], v[200:203], 0
	v_mfma_f32_16x16x32_bf16 v[100:103], v[184:187], v[218:221], 0
	v_mfma_f32_16x16x32_bf16 v[96:99], v[192:195], v[218:221], 0
	v_mfma_f32_16x16x32_bf16 v[84:87], v[184:187], v[226:229], 0
	v_mfma_f32_16x16x32_bf16 v[80:83], v[192:195], v[226:229], 0
	v_mfma_f32_16x16x32_bf16 v[68:71], v[184:187], v[234:237], 0
	v_mfma_f32_16x16x32_bf16 v[64:67], v[192:195], v[234:237], 0
	v_mfma_f32_16x16x32_bf16 v[116:119], v[188:191], v[214:217], v[116:119]
	v_mfma_f32_16x16x32_bf16 v[112:115], v[196:199], v[214:217], v[112:115]
	v_mfma_f32_16x16x32_bf16 v[100:103], v[188:191], v[222:225], v[100:103]
	v_mfma_f32_16x16x32_bf16 v[96:99], v[196:199], v[222:225], v[96:99]
	v_mfma_f32_16x16x32_bf16 v[84:87], v[188:191], v[230:233], v[84:87]
	v_mfma_f32_16x16x32_bf16 v[80:83], v[196:199], v[230:233], v[80:83]
	v_mfma_f32_16x16x32_bf16 v[68:71], v[188:191], v[238:241], v[68:71]
	v_mfma_f32_16x16x32_bf16 v[64:67], v[196:199], v[238:241], v[64:67]
	s_setprio 0
	s_barrier
	s_add_i32 s34, s35, s64
	v_lshl_add_u64 v[158:159], s[58:59], 0, v[160:161]
	s_mov_b32 m0, s34
	ds_read_b128 v[200:203], v153 offset:16384
	ds_read_b128 v[214:217], v153 offset:17408
	ds_read_b128 v[218:221], v153 offset:18432
	ds_read_b128 v[222:225], v153 offset:19456
	ds_read_b128 v[226:229], v153 offset:20480
	ds_read_b128 v[230:233], v153 offset:21504
	ds_read_b128 v[234:237], v153 offset:22528
	ds_read_b128 v[238:241], v153 offset:23552
	global_load_lds_dwordx4 v[158:159], off
	s_add_i32 m0, s34, 0x2000
	s_add_u32 s34, s58, 0x80000
	v_lshl_add_u64 v[162:163], s[58:59], 0, v[132:133]
	s_addc_u32 s35, s59, 0
	s_add_i32 s29, s29, s64
	global_load_lds_dwordx4 v[162:163], off
	v_lshl_add_u64 v[242:243], s[34:35], 0, v[160:161]
	s_mov_b32 m0, s29
	v_lshl_add_u64 v[244:245], s[60:61], 0, v[130:131]
	global_load_lds_dwordx4 v[242:243], off
	v_lshl_add_u64 v[242:243], s[34:35], 0, v[132:133]
	s_add_i32 m0, s29, 0x2000
	s_nop 0
	global_load_lds_dwordx4 v[242:243], off
	v_lshl_add_u64 v[242:243], s[60:61], 0, v[128:129]
	s_mov_b32 m0, s17
	s_nop 0
	global_load_lds_dwordx4 v[242:243], off
	s_mov_b32 m0, s65
	s_nop 0
	global_load_lds_dwordx4 v[244:245], off
	s_cmp_lg_u32 s101, 0
	s_cbranch_scc1 .Lgk_nw2_59
	s_waitcnt vmcnt(8)
; #define PG8_STAGE(bufoff, gbase, voff) do { _Pragma("unroll") for (int _i = 0; _i < 2; ++_i) \
;         __builtin_amdgcn_global_load_lds((const unsigned*)((const char*)(gbase) + (voff)[_i]), (PG8_LAS unsigned*)(lds + (bufoff) + ldsw + _i * 8192), 16, 0, 0); } while (0)
; #define PG8_WAIT_V(n) asm volatile("s_waitcnt vmcnt(" #n ")" ::: "memory")
; #define PG8_WAIT_L(n) asm volatile("s_waitcnt lgkmcnt(" #n ")" ::: "memory")
; #define PG8_BAR __builtin_amdgcn_s_barrier()
; #define PG8_SCHED __builtin_amdgcn_sched_barrier(0)
; template <class Epi, class Sched, bool ALIGN_EPI = false, bool SP2 = false, bool F8 = false>
; __device__ __forceinline__ void gemm_phase(PG8_LAS unsigned char* lds, const Gemm g, const Sched& S, const Epi& E) {
;     ...
;             PG8_WAIT_V(8); PG8_WAIT_L(0); PG8_BAR; PG8_MMA(1, 0, At, B0); PG8_MMA(1, 1, At, B1); PG8_BAR; PG8_SCHED;
;             PG8_LDB(B0, 1, 0); PG8_LDB(B1, 1, 1); PG8_SCHED; PG8_LDA(At, 1, 0); PG8_STAGE(PG8_SA(0, 1), a2 + hstep, voffA);
;             PG8_WAIT_V(8); PG8_WAIT_L(0); PG8_BAR; PG8_MMA(0, 0, At, B0); PG8_MMA(0, 1, At, B1); PG8_BAR; PG8_SCHED;
.Lgk_nw2_59:
	s_waitcnt lgkmcnt(0)
	s_barrier
	s_setprio 1
	s_waitcnt lgkmcnt(0)
	v_mfma_f32_16x16x32_bf16 v[60:63], v[138:141], v[200:203], 0
	v_mfma_f32_16x16x32_bf16 v[56:59], v[146:149], v[200:203], 0
	v_mfma_f32_16x16x32_bf16 v[44:47], v[138:141], v[218:221], 0
	v_mfma_f32_16x16x32_bf16 v[40:43], v[146:149], v[218:221], 0
	v_mfma_f32_16x16x32_bf16 v[28:31], v[138:141], v[226:229], 0
	v_mfma_f32_16x16x32_bf16 v[24:27], v[146:149], v[226:229], 0
	v_mfma_f32_16x16x32_bf16 v[12:15], v[138:141], v[234:237], 0
	v_mfma_f32_16x16x32_bf16 v[8:11], v[146:149], v[234:237], 0
	v_mfma_f32_16x16x32_bf16 v[60:63], v[142:145], v[214:217], v[60:63]
	v_mfma_f32_16x16x32_bf16 v[56:59], v[154:157], v[214:217], v[56:59]
	v_mfma_f32_16x16x32_bf16 v[44:47], v[142:145], v[222:225], v[44:47]
	v_mfma_f32_16x16x32_bf16 v[40:43], v[154:157], v[222:225], v[40:43]
	v_mfma_f32_16x16x32_bf16 v[28:31], v[142:145], v[230:233], v[28:31]
	v_mfma_f32_16x16x32_bf16 v[24:27], v[154:157], v[230:233], v[24:27]
	v_mfma_f32_16x16x32_bf16 v[12:15], v[142:145], v[238:241], v[12:15]
	v_mfma_f32_16x16x32_bf16 v[8:11], v[154:157], v[238:241], v[8:11]
	s_setprio 0
	s_setprio 1
	v_mfma_f32_16x16x32_bf16 v[52:55], v[184:187], v[200:203], 0
	v_mfma_f32_16x16x32_bf16 v[48:51], v[192:195], v[200:203], 0
	v_mfma_f32_16x16x32_bf16 v[36:39], v[184:187], v[218:221], 0
	v_mfma_f32_16x16x32_bf16 v[32:35], v[192:195], v[218:221], 0
	v_mfma_f32_16x16x32_bf16 v[20:23], v[184:187], v[226:229], 0
	v_mfma_f32_16x16x32_bf16 v[16:19], v[192:195], v[226:229], 0
	v_mfma_f32_16x16x32_bf16 v[4:7], v[184:187], v[234:237], 0
	v_mfma_f32_16x16x32_bf16 v[0:3], v[192:195], v[234:237], 0
	v_mfma_f32_16x16x32_bf16 v[52:55], v[188:191], v[214:217], v[52:55]
	v_mfma_f32_16x16x32_bf16 v[48:51], v[196:199], v[214:217], v[48:51]
	v_mfma_f32_16x16x32_bf16 v[36:39], v[188:191], v[222:225], v[36:39]
	v_mfma_f32_16x16x32_bf16 v[32:35], v[196:199], v[222:225], v[32:35]
	v_mfma_f32_16x16x32_bf16 v[20:23], v[188:191], v[230:233], v[20:23]
	v_mfma_f32_16x16x32_bf16 v[16:19], v[196:199], v[230:233], v[16:19]
	v_mfma_f32_16x16x32_bf16 v[4:7], v[188:191], v[238:241], v[4:7]
	v_mfma_f32_16x16x32_bf16 v[0:3], v[196:199], v[238:241], v[0:3]
	s_setprio 0
	s_barrier
	s_add_i32 s29, 0, 0x18000
	s_add_i32 s47, 0, 0x1c000
	v_add_u32_e32 v154, s29, v151
	v_add_u32_e32 v196, s47, v151
	ds_read_b128 v[138:141], v154
	ds_read_b128 v[142:145], v154 offset:1024
	ds_read_b128 v[146:149], v154 offset:2048
	ds_read_b128 v[154:157], v154 offset:3072
	ds_read_b128 v[184:187], v196
	ds_read_b128 v[188:191], v196 offset:1024
	ds_read_b128 v[192:195], v196 offset:2048
	ds_read_b128 v[196:199], v196 offset:3072
	s_add_u32 s34, s60, 0x80000
	s_addc_u32 s35, s61, 0
	s_mov_b32 m0, s74
	v_lshl_add_u64 v[246:247], s[34:35], 0, v[128:129]
	ds_read_b128 v[200:203], v153 offset:32768
	ds_read_b128 v[214:217], v153 offset:33792
	ds_read_b128 v[218:221], v153 offset:34816
	ds_read_b128 v[222:225], v153 offset:35840
	ds_read_b128 v[226:229], v153 offset:36864
	ds_read_b128 v[230:233], v153 offset:37888
	ds_read_b128 v[234:237], v153 offset:38912
	ds_read_b128 v[238:241], v153 offset:39936
	global_load_lds_dwordx4 v[246:247], off
	v_lshl_add_u64 v[246:247], s[34:35], 0, v[130:131]
	s_mov_b32 m0, s75
	s_nop 0
	global_load_lds_dwordx4 v[246:247], off
	s_waitcnt vmcnt(8)
	s_waitcnt lgkmcnt(0)
	s_barrier
	s_setprio 1
	s_waitcnt lgkmcnt(0)
	v_mfma_f32_16x16x32_bf16 v[124:127], v[138:141], v[200:203], v[124:127]
	v_mfma_f32_16x16x32_bf16 v[120:123], v[146:149], v[200:203], v[120:123]
	v_mfma_f32_16x16x32_bf16 v[108:111], v[138:141], v[218:221], v[108:111]
	v_mfma_f32_16x16x32_bf16 v[104:107], v[146:149], v[218:221], v[104:107]
	v_mfma_f32_16x16x32_bf16 v[92:95], v[138:141], v[226:229], v[92:95]
	v_mfma_f32_16x16x32_bf16 v[88:91], v[146:149], v[226:229], v[88:91]
	v_mfma_f32_16x16x32_bf16 v[76:79], v[138:141], v[234:237], v[76:79]
	v_mfma_f32_16x16x32_bf16 v[72:75], v[146:149], v[234:237], v[72:75]
	v_mfma_f32_16x16x32_bf16 v[124:127], v[142:145], v[214:217], v[124:127]
	v_mfma_f32_16x16x32_bf16 v[120:123], v[154:157], v[214:217], v[120:123]
	v_mfma_f32_16x16x32_bf16 v[108:111], v[142:145], v[222:225], v[108:111]
	v_mfma_f32_16x16x32_bf16 v[104:107], v[154:157], v[222:225], v[104:107]
	v_mfma_f32_16x16x32_bf16 v[92:95], v[142:145], v[230:233], v[92:95]
	v_mfma_f32_16x16x32_bf16 v[88:91], v[154:157], v[230:233], v[88:91]
	v_mfma_f32_16x16x32_bf16 v[76:79], v[142:145], v[238:241], v[76:79]
	v_mfma_f32_16x16x32_bf16 v[72:75], v[154:157], v[238:241], v[72:75]
	s_setprio 0
	s_setprio 1
	v_mfma_f32_16x16x32_bf16 v[116:119], v[184:187], v[200:203], v[116:119]
	v_mfma_f32_16x16x32_bf16 v[112:115], v[192:195], v[200:203], v[112:115]
	v_mfma_f32_16x16x32_bf16 v[100:103], v[184:187], v[218:221], v[100:103]
	v_mfma_f32_16x16x32_bf16 v[96:99], v[192:195], v[218:221], v[96:99]
	v_mfma_f32_16x16x32_bf16 v[84:87], v[184:187], v[226:229], v[84:87]
	v_mfma_f32_16x16x32_bf16 v[80:83], v[192:195], v[226:229], v[80:83]
	v_mfma_f32_16x16x32_bf16 v[68:71], v[184:187], v[234:237], v[68:71]
	v_mfma_f32_16x16x32_bf16 v[64:67], v[192:195], v[234:237], v[64:67]
	v_mfma_f32_16x16x32_bf16 v[116:119], v[188:191], v[214:217], v[116:119]
	v_mfma_f32_16x16x32_bf16 v[112:115], v[196:199], v[214:217], v[112:115]
	v_mfma_f32_16x16x32_bf16 v[100:103], v[188:191], v[222:225], v[100:103]
	v_mfma_f32_16x16x32_bf16 v[96:99], v[196:199], v[222:225], v[96:99]
	v_mfma_f32_16x16x32_bf16 v[84:87], v[188:191], v[230:233], v[84:87]
	v_mfma_f32_16x16x32_bf16 v[80:83], v[196:199], v[230:233], v[80:83]
	v_mfma_f32_16x16x32_bf16 v[68:71], v[188:191], v[238:241], v[68:71]
	v_mfma_f32_16x16x32_bf16 v[64:67], v[196:199], v[238:241], v[64:67]
	s_setprio 0
	s_barrier
; #define PG8_STAGE(bufoff, gbase, voff) do { _Pragma("unroll") for (int _i = 0; _i < 2; ++_i) \
;         __builtin_amdgcn_global_load_lds((const unsigned*)((const char*)(gbase) + (voff)[_i]), (PG8_LAS unsigned*)(lds + (bufoff) + ldsw + _i * 8192), 16, 0, 0); } while (0)
; #define PG8_WAIT_V(n) asm volatile("s_waitcnt vmcnt(" #n ")" ::: "memory")
; #define PG8_WAIT_L(n) asm volatile("s_waitcnt lgkmcnt(" #n ")" ::: "memory")
; #define PG8_BAR __builtin_amdgcn_s_barrier()
; #define PG8_SCHED __builtin_amdgcn_sched_barrier(0)
; template <class Epi, class Sched, bool ALIGN_EPI = false, bool SP2 = false, bool F8 = false>
; __device__ __forceinline__ void gemm_phase(PG8_LAS unsigned char* lds, const Gemm g, const Sched& S, const Epi& E) {
;     ...
;             PG8_LDA(At, 1, 1); PG8_STAGE(PG8_SB(1, 0), b3, voffB); PG8_STAGE(PG8_SB(1, 1), b3 + hstep, voffB); PG8_STAGE(PG8_SA(1, 0), a3, voffA);
;             PG8_WAIT_V(8); PG8_WAIT_L(0); PG8_BAR; PG8_MMA(1, 0, At, B0); PG8_MMA(1, 1, At, B1); PG8_BAR; PG8_SCHED;
	s_add_i32 s29, s29, s64
	v_lshl_add_u64 v[158:159], v[158:159], 0, s[14:15]
	s_mov_b32 m0, s29
	ds_read_b128 v[200:203], v153 offset:49152
	ds_read_b128 v[214:217], v153 offset:50176
	ds_read_b128 v[218:221], v153 offset:51200
	ds_read_b128 v[222:225], v153 offset:52224
	ds_read_b128 v[226:229], v153 offset:53248
	ds_read_b128 v[230:233], v153 offset:54272
	ds_read_b128 v[234:237], v153 offset:55296
	ds_read_b128 v[238:241], v153 offset:56320
	global_load_lds_dwordx4 v[158:159], off
	s_add_i32 m0, s29, 0x2000
	s_add_u32 s34, s58, 0x80080
	v_lshl_add_u64 v[158:159], v[162:163], 0, s[14:15]
	s_addc_u32 s35, s59, 0
	s_add_i32 s29, s47, s64
	global_load_lds_dwordx4 v[158:159], off
	v_lshl_add_u64 v[158:159], s[34:35], 0, v[160:161]
	s_mov_b32 m0, s29
	s_nop 0
	global_load_lds_dwordx4 v[158:159], off
	v_lshl_add_u64 v[158:159], s[34:35], 0, v[132:133]
	s_add_i32 m0, s29, 0x2000
	s_nop 0
	global_load_lds_dwordx4 v[158:159], off
	v_lshl_add_u64 v[158:159], v[242:243], 0, s[14:15]
	s_mov_b32 m0, s52
	s_nop 0
	global_load_lds_dwordx4 v[158:159], off
	v_lshl_add_u64 v[158:159], v[244:245], 0, s[14:15]
	s_mov_b32 m0, s53
	s_nop 0
	global_load_lds_dwordx4 v[158:159], off
	s_waitcnt vmcnt(8)
	s_waitcnt lgkmcnt(0)
	s_barrier
	s_setprio 1
	s_waitcnt lgkmcnt(0)
	v_mfma_f32_16x16x32_bf16 v[60:63], v[138:141], v[200:203], v[60:63]
	v_mfma_f32_16x16x32_bf16 v[56:59], v[146:149], v[200:203], v[56:59]
	v_mfma_f32_16x16x32_bf16 v[44:47], v[138:141], v[218:221], v[44:47]
	v_mfma_f32_16x16x32_bf16 v[40:43], v[146:149], v[218:221], v[40:43]
	v_mfma_f32_16x16x32_bf16 v[28:31], v[138:141], v[226:229], v[28:31]
	v_mfma_f32_16x16x32_bf16 v[24:27], v[146:149], v[226:229], v[24:27]
	v_mfma_f32_16x16x32_bf16 v[12:15], v[138:141], v[234:237], v[12:15]
	v_mfma_f32_16x16x32_bf16 v[8:11], v[146:149], v[234:237], v[8:11]
	v_mfma_f32_16x16x32_bf16 v[60:63], v[142:145], v[214:217], v[60:63]
	v_mfma_f32_16x16x32_bf16 v[56:59], v[154:157], v[214:217], v[56:59]
	v_mfma_f32_16x16x32_bf16 v[44:47], v[142:145], v[222:225], v[44:47]
	v_mfma_f32_16x16x32_bf16 v[40:43], v[154:157], v[222:225], v[40:43]
	v_mfma_f32_16x16x32_bf16 v[28:31], v[142:145], v[230:233], v[28:31]
	v_mfma_f32_16x16x32_bf16 v[24:27], v[154:157], v[230:233], v[24:27]
	v_mfma_f32_16x16x32_bf16 v[12:15], v[142:145], v[238:241], v[12:15]
	v_mfma_f32_16x16x32_bf16 v[8:11], v[154:157], v[238:241], v[8:11]
	s_setprio 0
	s_setprio 1
	v_mfma_f32_16x16x32_bf16 v[52:55], v[184:187], v[200:203], v[52:55]
	v_mfma_f32_16x16x32_bf16 v[48:51], v[192:195], v[200:203], v[48:51]
	v_mfma_f32_16x16x32_bf16 v[36:39], v[184:187], v[218:221], v[36:39]
	v_mfma_f32_16x16x32_bf16 v[32:35], v[192:195], v[218:221], v[32:35]
	v_mfma_f32_16x16x32_bf16 v[20:23], v[184:187], v[226:229], v[20:23]
	v_mfma_f32_16x16x32_bf16 v[16:19], v[192:195], v[226:229], v[16:19]
	v_mfma_f32_16x16x32_bf16 v[4:7], v[184:187], v[234:237], v[4:7]
	v_mfma_f32_16x16x32_bf16 v[0:3], v[192:195], v[234:237], v[0:3]
	v_mfma_f32_16x16x32_bf16 v[52:55], v[188:191], v[214:217], v[52:55]
	v_mfma_f32_16x16x32_bf16 v[48:51], v[196:199], v[214:217], v[48:51]
	v_mfma_f32_16x16x32_bf16 v[36:39], v[188:191], v[222:225], v[36:39]
	v_mfma_f32_16x16x32_bf16 v[32:35], v[196:199], v[222:225], v[32:35]
	v_mfma_f32_16x16x32_bf16 v[20:23], v[188:191], v[230:233], v[20:23]
	v_mfma_f32_16x16x32_bf16 v[16:19], v[196:199], v[230:233], v[16:19]
	v_mfma_f32_16x16x32_bf16 v[4:7], v[188:191], v[238:241], v[4:7]
	v_mfma_f32_16x16x32_bf16 v[0:3], v[196:199], v[238:241], v[0:3]
	s_setprio 0
	s_barrier
	s_add_i32 s28, s28, 2
	s_add_u32 s36, s36, 0x100
	s_addc_u32 s37, s37, 0
	s_add_u32 s19, s19, 0x100
	s_addc_u32 s23, s23, 0
	s_cmp_gt_u32 s28, 29
	s_cbranch_scc0 .LBB0_59
	s_branch .Lgk_after_59

; #define PG8_BAR __builtin_amdgcn_s_barrier()
; __device__ __forceinline__ float swap32_sum(float a, float b) { unsigned x, y; pl32(__builtin_bit_cast(unsigned, a), __builtin_bit_cast(unsigned, b), x, y); return __builtin_bit_cast(float, x) + __builtin_bit_cast(float, y); }
; __device__ __forceinline__ float swap16_sum(float a, float b) { unsigned x, y; pl16(__builtin_bit_cast(unsigned, a), __builtin_bit_cast(unsigned, b), x, y); return __builtin_bit_cast(float, x) + __builtin_bit_cast(float, y); }
; template <class Epi, class Sched, bool ALIGN_EPI = false, bool SP2 = false, bool F8 = false>
; __device__ __forceinline__ void gemm_phase(PG8_LAS unsigned char* lds, const Gemm g, const Sched& S, const Epi& E) {
;     ...
;         if constexpr (!Epi::AFTER_DRAIN) { E(acc, cur, wr, wc, fr, fq); S.done(cur); }
;         if (!has_next) break;
; #pragma unroll
;         for (int a = 0; a < 2; ++a)
; #pragma unroll
;             for (int b = 0; b < 2; ++b)
; #pragma unroll
;                 for (int m = 0; m < 4; ++m)
; #pragma unroll
;                     for (int n = 0; n < 2; ++n) acc[a][b][m][n] = (f32x4){0.f, 0.f, 0.f, 0.f};
;         cur = nxt; cA = nA; cB = nB; ++ui;
;         if constexpr (ALIGN_EPI) { if (wr == 1) PG8_BAR; }
;     __device__ __forceinline__ void operator()(const f32x4 (&acc)[2][2][4][2], const pg8::Unit& u, int wr, int wc, int fr, int fq) const {
;     ...
;                 if constexpr (MODE == 7) {
;                     ssq = swap16_sum(ssq, ssq); ssq = swap32_sum(ssq, ssq);
;                     if (fq == 0) (void)__hip_atomic_fetch_add(rs + row, ssq, __ATOMIC_RELAXED, __HIP_MEMORY_SCOPE_AGENT);
;                 }
.LBB0_78:
	s_or_b64 exec, exec, s[10:11]
	s_andn2_b64 vcc, exec, s[40:41]
	s_mov_b64 s[10:11], -1
	s_mov_b32 s101, 1
	s_cbranch_vccnz .LBB0_51
	s_andn2_b64 vcc, exec, s[68:69]
	s_cbranch_vccnz .LBB0_50
	s_barrier
	s_branch .LBB0_50

; #define PG8_STAGE(bufoff, gbase, voff) do { _Pragma("unroll") for (int _i = 0; _i < 2; ++_i) \
;         __builtin_amdgcn_global_load_lds((const unsigned*)((const char*)(gbase) + (voff)[_i]), (PG8_LAS unsigned*)(lds + (bufoff) + ldsw + _i * 8192), 16, 0, 0); } while (0)
; #define PG8_WAIT_V(n) asm volatile("s_waitcnt vmcnt(" #n ")" ::: "memory")
; #define PG8_BAR __builtin_amdgcn_s_barrier()
; template <class Epi, class Sched, bool ALIGN_EPI = false, bool SP2 = false, bool F8 = false>
; __device__ __forceinline__ void gemm_phase(PG8_LAS unsigned char* lds, const Gemm g, const Sched& S, const Epi& E) {
;     ...
;     for (int i = 0; i < 2; ++i) { int R, C; stage_rc(tid * 16 + i * 8192, R, C); const int Rb = Epi::PERM ? ((R & ~31) + perm32(R & 31)) : R;
;         voffA[i] = (unsigned)(R * K + C) * 2u; voffB[i] = (unsigned)(Rb * K + C) * 2u; }
;     const size_t kstep = (size_t)(BK * 2);
;     const size_t hstep = (size_t)HALF * K * 2;
;     const size_t tstep = 2 * hstep;
;     const unsigned ldsw = (unsigned)wid * 1024u;
;     const int aoff = lds_byte(wr * 64 + fr, fq * 8), boff = lds_byte(wc * 32 + fr, fq * 8);
;     ...
;     if constexpr (SP2) {
;         PG8_STAGE(PG8_SB(0, 0), cB, voffB); PG8_STAGE(PG8_SB(0, 1), cB + hstep, voffB); PG8_STAGE(PG8_SA(0, 0), cA, voffA); PG8_STAGE(PG8_SA(0, 1), cA + hstep, voffA);
;         if (wr == 1) PG8_BAR;
;         PG8_WAIT_V(2); PG8_BAR;
;         PG8_STAGE(PG8_SB(1, 0), cB + kstep, voffB); PG8_STAGE(PG8_SA(1, 0), cA + kstep, voffA); PG8_STAGE(PG8_SB(1, 1), cB + hstep + kstep, voffB);
;         PG8_WAIT_V(6); PG8_BAR;
.LBB0_87:
	s_waitcnt vmcnt(0)
	v_lshrrev_b32_e32 v16, 1, v6
	v_and_b32_e32 v16, 24, v16
	s_lshl_b32 s5, s5, 5
	v_and_b32_e32 v7, 15, v6
	v_lshlrev_b32_e32 v17, 1, v16
	v_lshlrev_b32_e32 v6, 2, v6
	s_and_b32 s10, s5, 0x60
	v_lshl_add_u64 v[8:9], s[44:45], 0, v[160:161]
	v_mov_b32_e32 v129, v161
	v_readlane_b32 s42, v253, 14
	v_lshl_or_b32 v142, s8, 6, v7
	v_lshl_or_b32 v7, v7, 6, v17
	s_lshl_b32 s8, s8, 13
	v_and_b32_e32 v6, 32, v6
	s_lshl_b32 s5, s10, 7
	v_lshl_add_u64 v[10:11], s[44:45], 0, v[128:129]
	v_mov_b32_e32 v133, v161
	v_readlane_b32 s43, v253, 15
	v_bitop3_b32 v17, v7, s8, v6 bitop3:0xde
	v_bitop3_b32 v143, v7, s5, v6 bitop3:0xde
	s_add_i32 m0, s35, 0x18000
	v_lshl_add_u64 v[6:7], v[8:9], 0, s[14:15]
	v_lshl_add_u64 v[12:13], s[42:43], 0, v[132:133]
	v_mov_b32_e32 v131, v161
	s_waitcnt vmcnt(2)
	s_barrier
	global_load_lds_dwordx4 v[6:7], off
	v_lshl_add_u64 v[6:7], v[10:11], 0, s[14:15]
	s_add_i32 m0, s35, 0x1a000
	s_add_i32 s51, s35, 0x8000
	s_add_i32 s52, s35, 0xa000
	v_lshl_add_u64 v[14:15], s[42:43], 0, v[130:131]
	global_load_lds_dwordx4 v[6:7], off
	v_lshl_add_u64 v[6:7], v[12:13], 0, s[14:15]
	s_mov_b32 m0, s51
	s_add_u32 s8, s44, 0x20080
	global_load_lds_dwordx4 v[6:7], off
	v_lshl_add_u64 v[6:7], v[14:15], 0, s[14:15]
	s_mov_b32 m0, s52
	s_addc_u32 s9, s45, 0
	global_load_lds_dwordx4 v[6:7], off
	s_add_i32 m0, s35, 0x1c000
	v_lshl_add_u64 v[6:7], s[8:9], 0, v[160:161]
	global_load_lds_dwordx4 v[6:7], off
	v_lshl_add_u64 v[6:7], s[8:9], 0, v[128:129]
	s_add_i32 m0, s35, 0x1e000
	s_cmpk_lt_u32 s4, 0x100
	global_load_lds_dwordx4 v[6:7], off
	v_lshlrev_b32_e32 v6, 13, v4
	v_and_b32_e32 v6, 0xffffc000, v6
	v_lshl_add_u32 v3, v3, 10, v6
	v_and_b32_e32 v4, 1, v4
	v_lshl_or_b32 v3, v4, 6, v3
	v_lshl_add_u32 v134, v5, 1, v3
	v_lshlrev_b32_e32 v3, 13, v0
	v_and_b32_e32 v3, 0xffffc000, v3
	s_waitcnt vmcnt(6)
	v_lshl_add_u32 v1, v1, 10, v3
	v_and_b32_e32 v0, 1, v0
	v_or_b32_e32 v144, s10, v16
	v_lshl_or_b32 v0, v0, 6, v1
	v_readlane_b32 s10, v253, 20
	s_cselect_b64 s[4:5], -1, 0
	v_mov_b32_e32 v135, v161
	v_lshl_add_u32 v136, v2, 1, v0
	v_mov_b32_e32 v137, v161
	s_mov_b32 s53, 0
	v_add_u32_e32 v145, 0, v17
	v_readlane_b32 s8, v253, 11
	s_mov_b32 s9, s10
	s_barrier
	v_readlane_b32 s11, v253, 21
	s_mov_b32 s101, 0
	s_branch .LBB0_90

; #define PG8_STAGE(bufoff, gbase, voff) do { _Pragma("unroll") for (int _i = 0; _i < 2; ++_i) \
;         __builtin_amdgcn_global_load_lds((const unsigned*)((const char*)(gbase) + (voff)[_i]), (PG8_LAS unsigned*)(lds + (bufoff) + ldsw + _i * 8192), 16, 0, 0); } while (0)
; #define PG8_WAIT_V(n) asm volatile("s_waitcnt vmcnt(" #n ")" ::: "memory")
; #define PG8_WAIT_L(n) asm volatile("s_waitcnt lgkmcnt(" #n ")" ::: "memory")
; #define PG8_BAR __builtin_amdgcn_s_barrier()
; #define PG8_SCHED __builtin_amdgcn_sched_barrier(0)
; template <class Epi, class Sched, bool ALIGN_EPI = false, bool SP2 = false, bool F8 = false>
; __device__ __forceinline__ void gemm_phase(PG8_LAS unsigned char* lds, const Gemm g, const Sched& S, const Epi& E) {
;     ...
;         const bool has_next = S.next(ui + 1, nxt);
;         const char* nA = has_next ? (const char*)g.A + (size_t)nxt.pm * tstep : cA; const char* nB = has_next ? (const char*)g.Bt + (size_t)nxt.pn * tstep : cB;
;         for (int t = 0; t < nt; t += 2) {
;             const bool last = (t == nt - 2);
;             const char* a1 = cA + (size_t)(t + 1) * kstep;
;             const char* a2 = last ? nA : cA + (size_t)(t + 2) * kstep; const char* b2 = last ? nB : cB + (size_t)(t + 2) * kstep;
;             const char* a3 = a2 + kstep; const char* b3 = b2 + kstep;
;             if (last && has_next) S.a_ready(nxt);
;             if constexpr (SP2) {
;             PG8_LDB(B0, 0, 0); PG8_LDB(B1, 0, 1); PG8_SCHED; PG8_LDA(At, 0, 0); PG8_STAGE(PG8_SA(1, 1), a1 + hstep, voffA);
;             PG8_WAIT_V(8); PG8_WAIT_L(0); PG8_BAR; PG8_MMA(0, 0, At, B0); PG8_MMA(0, 1, At, B1); PG8_BAR; PG8_SCHED;
;             PG8_LDA(At, 0, 1); PG8_STAGE(PG8_SB(0, 0), b2, voffB); PG8_STAGE(PG8_SB(0, 1), b2 + hstep, voffB); PG8_STAGE(PG8_SA(0, 0), a2, voffA);
;             PG8_WAIT_V(8); PG8_WAIT_L(0); PG8_BAR; PG8_MMA(1, 0, At, B0); PG8_MMA(1, 1, At, B1); PG8_BAR; PG8_SCHED;
.LBB0_96:
	s_ashr_i32 s17, s16, 31
	s_lshl_b64 s[28:29], s[16:17], 18
	s_add_u32 s36, s62, s28
	s_addc_u32 s37, s63, s29
	s_and_b64 s[28:29], s[38:39], exec
	s_cselect_b32 s17, s37, s43
	s_cselect_b32 s19, s36, s42
	s_ashr_i32 s11, s10, 31
	s_lshl_b64 s[28:29], s[10:11], 18
	s_add_u32 s40, s13, s28
	s_addc_u32 s41, s22, s29
	s_and_b64 s[28:29], s[38:39], exec
	s_cselect_b32 s11, s41, s45
	s_cselect_b32 s23, s40, s44
	s_add_u32 s42, s42, 0x20080
	s_addc_u32 s43, s43, 0
	s_add_u32 s28, s44, 0x100
	s_addc_u32 s29, s45, 0
	s_mov_b32 s54, -2
	s_add_u32 s44, s42, 0xfffe0080
	s_addc_u32 s45, s43, -1
	s_add_i32 s55, 0, 0x10000
	s_cmp_eq_u32 s54, 4
	s_cselect_b32 s47, s17, s45
	s_cselect_b32 s46, s19, s44
	s_cselect_b32 s45, s11, s29
	s_cselect_b32 s44, s23, s28
	s_add_i32 s56, 0, 0x14000
	v_add_u32_e32 v154, s55, v143
	v_add_u32_e32 v158, s56, v143
	ds_read_b128 v[138:141], v154
	ds_read_b128 v[146:149], v154 offset:1024
	ds_read_b128 v[150:153], v154 offset:2048
	ds_read_b128 v[154:157], v154 offset:3072
	ds_read_b128 v[184:187], v158
	ds_read_b128 v[188:191], v158 offset:1024
	ds_read_b128 v[192:195], v158 offset:2048
	ds_read_b128 v[196:199], v158 offset:3072
	v_lshl_add_u64 v[158:159], s[42:43], 0, v[134:135]
	s_add_i32 m0, s35, 0xc000
	ds_read_b128 v[200:203], v145
	ds_read_b128 v[214:217], v145 offset:1024
	ds_read_b128 v[218:221], v145 offset:2048
	ds_read_b128 v[222:225], v145 offset:3072
	ds_read_b128 v[226:229], v145 offset:4096
	ds_read_b128 v[230:233], v145 offset:5120
	ds_read_b128 v[234:237], v145 offset:6144
	ds_read_b128 v[238:241], v145 offset:7168
	global_load_lds_dwordx4 v[158:159], off
	v_lshl_add_u64 v[158:159], s[42:43], 0, v[136:137]
	s_add_i32 m0, s35, 0xe000
	s_nop 0
	global_load_lds_dwordx4 v[158:159], off
	s_cmp_lg_u32 s101, 0
	s_cbranch_scc1 .Lgk_nw1_97
	s_waitcnt vmcnt(8)
.Lgk_nw1_97:
	s_waitcnt lgkmcnt(0)
	s_barrier
	s_setprio 1
	s_waitcnt lgkmcnt(0)
	v_mfma_f32_16x16x32_bf16 v[124:127], v[138:141], v[200:203], 0
	v_mfma_f32_16x16x32_bf16 v[120:123], v[150:153], v[200:203], 0
	v_mfma_f32_16x16x32_bf16 v[108:111], v[138:141], v[218:221], 0
	v_mfma_f32_16x16x32_bf16 v[104:107], v[150:153], v[218:221], 0
	v_mfma_f32_16x16x32_bf16 v[92:95], v[138:141], v[226:229], 0
	v_mfma_f32_16x16x32_bf16 v[88:91], v[150:153], v[226:229], 0
	v_mfma_f32_16x16x32_bf16 v[76:79], v[138:141], v[234:237], 0
	v_mfma_f32_16x16x32_bf16 v[72:75], v[150:153], v[234:237], 0
	v_mfma_f32_16x16x32_bf16 v[124:127], v[146:149], v[214:217], v[124:127]
	v_mfma_f32_16x16x32_bf16 v[120:123], v[154:157], v[214:217], v[120:123]
	v_mfma_f32_16x16x32_bf16 v[108:111], v[146:149], v[222:225], v[108:111]
	v_mfma_f32_16x16x32_bf16 v[104:107], v[154:157], v[222:225], v[104:107]
	v_mfma_f32_16x16x32_bf16 v[92:95], v[146:149], v[230:233], v[92:95]
	v_mfma_f32_16x16x32_bf16 v[88:91], v[154:157], v[230:233], v[88:91]
	v_mfma_f32_16x16x32_bf16 v[76:79], v[146:149], v[238:241], v[76:79]
	v_mfma_f32_16x16x32_bf16 v[72:75], v[154:157], v[238:241], v[72:75]
	s_setprio 0
	s_setprio 1
	v_mfma_f32_16x16x32_bf16 v[116:119], v[184:187], v[200:203], 0
	v_mfma_f32_16x16x32_bf16 v[112:115], v[192:195], v[200:203], 0
	v_mfma_f32_16x16x32_bf16 v[100:103], v[184:187], v[218:221], 0
	v_mfma_f32_16x16x32_bf16 v[96:99], v[192:195], v[218:221], 0
	v_mfma_f32_16x16x32_bf16 v[84:87], v[184:187], v[226:229], 0
	v_mfma_f32_16x16x32_bf16 v[80:83], v[192:195], v[226:229], 0
	v_mfma_f32_16x16x32_bf16 v[68:71], v[184:187], v[234:237], 0
	v_mfma_f32_16x16x32_bf16 v[64:67], v[192:195], v[234:237], 0
	v_mfma_f32_16x16x32_bf16 v[116:119], v[188:191], v[214:217], v[116:119]
	v_mfma_f32_16x16x32_bf16 v[112:115], v[196:199], v[214:217], v[112:115]
	v_mfma_f32_16x16x32_bf16 v[100:103], v[188:191], v[222:225], v[100:103]
	v_mfma_f32_16x16x32_bf16 v[96:99], v[196:199], v[222:225], v[96:99]
	v_mfma_f32_16x16x32_bf16 v[84:87], v[188:191], v[230:233], v[84:87]
	v_mfma_f32_16x16x32_bf16 v[80:83], v[196:199], v[230:233], v[80:83]
	v_mfma_f32_16x16x32_bf16 v[68:71], v[188:191], v[238:241], v[68:71]
	v_mfma_f32_16x16x32_bf16 v[64:67], v[196:199], v[238:241], v[64:67]
	s_setprio 0
	s_barrier
	s_add_i32 s55, s55, s34
	v_lshl_add_u64 v[158:159], s[44:45], 0, v[160:161]
	s_mov_b32 m0, s55
	ds_read_b128 v[200:203], v145 offset:16384
	ds_read_b128 v[214:217], v145 offset:17408
	ds_read_b128 v[218:221], v145 offset:18432
	ds_read_b128 v[222:225], v145 offset:19456
	ds_read_b128 v[226:229], v145 offset:20480
	ds_read_b128 v[230:233], v145 offset:21504
	ds_read_b128 v[234:237], v145 offset:22528
	ds_read_b128 v[238:241], v145 offset:23552
	global_load_lds_dwordx4 v[158:159], off
	s_add_i32 m0, s55, 0x2000
	s_add_u32 s58, s44, 0x20000
	v_lshl_add_u64 v[162:163], s[44:45], 0, v[128:129]
	s_addc_u32 s59, s45, 0
	s_add_i32 s55, s56, s34
	global_load_lds_dwordx4 v[162:163], off
	v_lshl_add_u64 v[242:243], s[58:59], 0, v[160:161]
	s_mov_b32 m0, s55
	v_lshl_add_u64 v[244:245], s[46:47], 0, v[130:131]
	global_load_lds_dwordx4 v[242:243], off
	v_lshl_add_u64 v[242:243], s[58:59], 0, v[128:129]
	s_add_i32 m0, s55, 0x2000
	s_nop 0
	global_load_lds_dwordx4 v[242:243], off
	v_lshl_add_u64 v[242:243], s[46:47], 0, v[132:133]
	s_mov_b32 m0, s35
	s_nop 0
	global_load_lds_dwordx4 v[242:243], off
	s_mov_b32 m0, s48
	s_nop 0
	global_load_lds_dwordx4 v[244:245], off
	s_cmp_lg_u32 s101, 0
	s_cbranch_scc1 .Lgk_nw2_97
	s_waitcnt vmcnt(8)
; #define PG8_STAGE(bufoff, gbase, voff) do { _Pragma("unroll") for (int _i = 0; _i < 2; ++_i) \
;         __builtin_amdgcn_global_load_lds((const unsigned*)((const char*)(gbase) + (voff)[_i]), (PG8_LAS unsigned*)(lds + (bufoff) + ldsw + _i * 8192), 16, 0, 0); } while (0)
; #define PG8_WAIT_V(n) asm volatile("s_waitcnt vmcnt(" #n ")" ::: "memory")
; #define PG8_WAIT_L(n) asm volatile("s_waitcnt lgkmcnt(" #n ")" ::: "memory")
; #define PG8_BAR __builtin_amdgcn_s_barrier()
; #define PG8_SCHED __builtin_amdgcn_sched_barrier(0)
; template <class Epi, class Sched, bool ALIGN_EPI = false, bool SP2 = false, bool F8 = false>
; __device__ __forceinline__ void gemm_phase(PG8_LAS unsigned char* lds, const Gemm g, const Sched& S, const Epi& E) {
;     ...
;             PG8_WAIT_V(8); PG8_WAIT_L(0); PG8_BAR; PG8_MMA(1, 0, At, B0); PG8_MMA(1, 1, At, B1); PG8_BAR; PG8_SCHED;
;             PG8_LDB(B0, 1, 0); PG8_LDB(B1, 1, 1); PG8_SCHED; PG8_LDA(At, 1, 0); PG8_STAGE(PG8_SA(0, 1), a2 + hstep, voffA);
;             PG8_WAIT_V(8); PG8_WAIT_L(0); PG8_BAR; PG8_MMA(0, 0, At, B0); PG8_MMA(0, 1, At, B1); PG8_BAR; PG8_SCHED;
.Lgk_nw2_97:
	s_waitcnt lgkmcnt(0)
	s_barrier
	s_setprio 1
	s_waitcnt lgkmcnt(0)
	v_mfma_f32_16x16x32_bf16 v[60:63], v[138:141], v[200:203], 0
	v_mfma_f32_16x16x32_bf16 v[56:59], v[150:153], v[200:203], 0
	v_mfma_f32_16x16x32_bf16 v[44:47], v[138:141], v[218:221], 0
	v_mfma_f32_16x16x32_bf16 v[40:43], v[150:153], v[218:221], 0
	v_mfma_f32_16x16x32_bf16 v[28:31], v[138:141], v[226:229], 0
	v_mfma_f32_16x16x32_bf16 v[24:27], v[150:153], v[226:229], 0
	v_mfma_f32_16x16x32_bf16 v[12:15], v[138:141], v[234:237], 0
	v_mfma_f32_16x16x32_bf16 v[8:11], v[150:153], v[234:237], 0
	v_mfma_f32_16x16x32_bf16 v[60:63], v[146:149], v[214:217], v[60:63]
	v_mfma_f32_16x16x32_bf16 v[56:59], v[154:157], v[214:217], v[56:59]
	v_mfma_f32_16x16x32_bf16 v[44:47], v[146:149], v[222:225], v[44:47]
	v_mfma_f32_16x16x32_bf16 v[40:43], v[154:157], v[222:225], v[40:43]
	v_mfma_f32_16x16x32_bf16 v[28:31], v[146:149], v[230:233], v[28:31]
	v_mfma_f32_16x16x32_bf16 v[24:27], v[154:157], v[230:233], v[24:27]
	v_mfma_f32_16x16x32_bf16 v[12:15], v[146:149], v[238:241], v[12:15]
	v_mfma_f32_16x16x32_bf16 v[8:11], v[154:157], v[238:241], v[8:11]
	s_setprio 0
	s_setprio 1
	v_mfma_f32_16x16x32_bf16 v[52:55], v[184:187], v[200:203], 0
	v_mfma_f32_16x16x32_bf16 v[48:51], v[192:195], v[200:203], 0
	v_mfma_f32_16x16x32_bf16 v[36:39], v[184:187], v[218:221], 0
	v_mfma_f32_16x16x32_bf16 v[32:35], v[192:195], v[218:221], 0
	v_mfma_f32_16x16x32_bf16 v[20:23], v[184:187], v[226:229], 0
	v_mfma_f32_16x16x32_bf16 v[16:19], v[192:195], v[226:229], 0
	v_mfma_f32_16x16x32_bf16 v[4:7], v[184:187], v[234:237], 0
	v_mfma_f32_16x16x32_bf16 v[0:3], v[192:195], v[234:237], 0
	v_mfma_f32_16x16x32_bf16 v[52:55], v[188:191], v[214:217], v[52:55]
	v_mfma_f32_16x16x32_bf16 v[48:51], v[196:199], v[214:217], v[48:51]
	v_mfma_f32_16x16x32_bf16 v[36:39], v[188:191], v[222:225], v[36:39]
	v_mfma_f32_16x16x32_bf16 v[32:35], v[196:199], v[222:225], v[32:35]
	v_mfma_f32_16x16x32_bf16 v[20:23], v[188:191], v[230:233], v[20:23]
	v_mfma_f32_16x16x32_bf16 v[16:19], v[196:199], v[230:233], v[16:19]
	v_mfma_f32_16x16x32_bf16 v[4:7], v[188:191], v[238:241], v[4:7]
	v_mfma_f32_16x16x32_bf16 v[0:3], v[196:199], v[238:241], v[0:3]
	s_setprio 0
	s_barrier
	s_add_i32 s55, 0, 0x18000
	s_add_i32 s56, 0, 0x1c000
	v_add_u32_e32 v154, s55, v143
	v_add_u32_e32 v196, s56, v143
	ds_read_b128 v[138:141], v154
	ds_read_b128 v[146:149], v154 offset:1024
	ds_read_b128 v[150:153], v154 offset:2048
	ds_read_b128 v[154:157], v154 offset:3072
	ds_read_b128 v[184:187], v196
	ds_read_b128 v[188:191], v196 offset:1024
	ds_read_b128 v[192:195], v196 offset:2048
	ds_read_b128 v[196:199], v196 offset:3072
	s_add_u32 s46, s46, 0x20000
	s_addc_u32 s47, s47, 0
	s_mov_b32 m0, s49
	v_lshl_add_u64 v[246:247], s[46:47], 0, v[132:133]
	ds_read_b128 v[200:203], v145 offset:32768
	ds_read_b128 v[214:217], v145 offset:33792
	ds_read_b128 v[218:221], v145 offset:34816
	ds_read_b128 v[222:225], v145 offset:35840
	ds_read_b128 v[226:229], v145 offset:36864
	ds_read_b128 v[230:233], v145 offset:37888
	ds_read_b128 v[234:237], v145 offset:38912
	ds_read_b128 v[238:241], v145 offset:39936
	global_load_lds_dwordx4 v[246:247], off
	v_lshl_add_u64 v[246:247], s[46:47], 0, v[130:131]
	s_mov_b32 m0, s50
	s_nop 0
	global_load_lds_dwordx4 v[246:247], off
	s_waitcnt vmcnt(8)
	s_waitcnt lgkmcnt(0)
	s_barrier
	s_setprio 1
	s_waitcnt lgkmcnt(0)
	v_mfma_f32_16x16x32_bf16 v[124:127], v[138:141], v[200:203], v[124:127]
	v_mfma_f32_16x16x32_bf16 v[120:123], v[150:153], v[200:203], v[120:123]
	v_mfma_f32_16x16x32_bf16 v[108:111], v[138:141], v[218:221], v[108:111]
	v_mfma_f32_16x16x32_bf16 v[104:107], v[150:153], v[218:221], v[104:107]
	v_mfma_f32_16x16x32_bf16 v[92:95], v[138:141], v[226:229], v[92:95]
	v_mfma_f32_16x16x32_bf16 v[88:91], v[150:153], v[226:229], v[88:91]
	v_mfma_f32_16x16x32_bf16 v[76:79], v[138:141], v[234:237], v[76:79]
	v_mfma_f32_16x16x32_bf16 v[72:75], v[150:153], v[234:237], v[72:75]
	v_mfma_f32_16x16x32_bf16 v[124:127], v[146:149], v[214:217], v[124:127]
	v_mfma_f32_16x16x32_bf16 v[120:123], v[154:157], v[214:217], v[120:123]
	v_mfma_f32_16x16x32_bf16 v[108:111], v[146:149], v[222:225], v[108:111]
	v_mfma_f32_16x16x32_bf16 v[104:107], v[154:157], v[222:225], v[104:107]
	v_mfma_f32_16x16x32_bf16 v[92:95], v[146:149], v[230:233], v[92:95]
	v_mfma_f32_16x16x32_bf16 v[88:91], v[154:157], v[230:233], v[88:91]
	v_mfma_f32_16x16x32_bf16 v[76:79], v[146:149], v[238:241], v[76:79]
	v_mfma_f32_16x16x32_bf16 v[72:75], v[154:157], v[238:241], v[72:75]
	s_setprio 0
	s_setprio 1
	v_mfma_f32_16x16x32_bf16 v[116:119], v[184:187], v[200:203], v[116:119]
	v_mfma_f32_16x16x32_bf16 v[112:115], v[192:195], v[200:203], v[112:115]
	v_mfma_f32_16x16x32_bf16 v[100:103], v[184:187], v[218:221], v[100:103]
	v_mfma_f32_16x16x32_bf16 v[96:99], v[192:195], v[218:221], v[96:99]
	v_mfma_f32_16x16x32_bf16 v[84:87], v[184:187], v[226:229], v[84:87]
	v_mfma_f32_16x16x32_bf16 v[80:83], v[192:195], v[226:229], v[80:83]
	v_mfma_f32_16x16x32_bf16 v[68:71], v[184:187], v[234:237], v[68:71]
	v_mfma_f32_16x16x32_bf16 v[64:67], v[192:195], v[234:237], v[64:67]
	v_mfma_f32_16x16x32_bf16 v[116:119], v[188:191], v[214:217], v[116:119]
	v_mfma_f32_16x16x32_bf16 v[112:115], v[196:199], v[214:217], v[112:115]
	v_mfma_f32_16x16x32_bf16 v[100:103], v[188:191], v[222:225], v[100:103]
	v_mfma_f32_16x16x32_bf16 v[96:99], v[196:199], v[222:225], v[96:99]
	v_mfma_f32_16x16x32_bf16 v[84:87], v[188:191], v[230:233], v[84:87]
	v_mfma_f32_16x16x32_bf16 v[80:83], v[196:199], v[230:233], v[80:83]
	v_mfma_f32_16x16x32_bf16 v[68:71], v[188:191], v[238:241], v[68:71]
	v_mfma_f32_16x16x32_bf16 v[64:67], v[196:199], v[238:241], v[64:67]
	s_setprio 0
	s_barrier
; #define PG8_STAGE(bufoff, gbase, voff) do { _Pragma("unroll") for (int _i = 0; _i < 2; ++_i) \
;         __builtin_amdgcn_global_load_lds((const unsigned*)((const char*)(gbase) + (voff)[_i]), (PG8_LAS unsigned*)(lds + (bufoff) + ldsw + _i * 8192), 16, 0, 0); } while (0)
; #define PG8_WAIT_V(n) asm volatile("s_waitcnt vmcnt(" #n ")" ::: "memory")
; #define PG8_WAIT_L(n) asm volatile("s_waitcnt lgkmcnt(" #n ")" ::: "memory")
; #define PG8_BAR __builtin_amdgcn_s_barrier()
; #define PG8_SCHED __builtin_amdgcn_sched_barrier(0)
; template <class Epi, class Sched, bool ALIGN_EPI = false, bool SP2 = false, bool F8 = false>
; __device__ __forceinline__ void gemm_phase(PG8_LAS unsigned char* lds, const Gemm g, const Sched& S, const Epi& E) {
;     ...
;             PG8_LDA(At, 1, 1); PG8_STAGE(PG8_SB(1, 0), b3, voffB); PG8_STAGE(PG8_SB(1, 1), b3 + hstep, voffB); PG8_STAGE(PG8_SA(1, 0), a3, voffA);
;             PG8_WAIT_V(8); PG8_WAIT_L(0); PG8_BAR; PG8_MMA(1, 0, At, B0); PG8_MMA(1, 1, At, B1); PG8_BAR; PG8_SCHED;
	s_add_i32 s46, s55, s34
	v_lshl_add_u64 v[158:159], v[158:159], 0, s[14:15]
	s_mov_b32 m0, s46
	ds_read_b128 v[200:203], v145 offset:49152
	ds_read_b128 v[214:217], v145 offset:50176
	ds_read_b128 v[218:221], v145 offset:51200
	ds_read_b128 v[222:225], v145 offset:52224
	ds_read_b128 v[226:229], v145 offset:53248
	ds_read_b128 v[230:233], v145 offset:54272
	ds_read_b128 v[234:237], v145 offset:55296
	ds_read_b128 v[238:241], v145 offset:56320
	global_load_lds_dwordx4 v[158:159], off
	s_add_i32 m0, s46, 0x2000
	s_add_u32 s44, s44, 0x20080
	v_lshl_add_u64 v[158:159], v[162:163], 0, s[14:15]
	s_addc_u32 s45, s45, 0
	s_add_i32 s46, s56, s34
	global_load_lds_dwordx4 v[158:159], off
	v_lshl_add_u64 v[158:159], s[44:45], 0, v[160:161]
	s_mov_b32 m0, s46
	s_nop 0
	global_load_lds_dwordx4 v[158:159], off
	v_lshl_add_u64 v[158:159], s[44:45], 0, v[128:129]
	s_add_i32 m0, s46, 0x2000
	s_nop 0
	global_load_lds_dwordx4 v[158:159], off
	v_lshl_add_u64 v[158:159], v[242:243], 0, s[14:15]
	s_mov_b32 m0, s51
	s_nop 0
	global_load_lds_dwordx4 v[158:159], off
	v_lshl_add_u64 v[158:159], v[244:245], 0, s[14:15]
	s_mov_b32 m0, s52
	s_nop 0
	global_load_lds_dwordx4 v[158:159], off
	s_waitcnt vmcnt(8)
	s_waitcnt lgkmcnt(0)
	s_barrier
	s_setprio 1
	s_waitcnt lgkmcnt(0)
	v_mfma_f32_16x16x32_bf16 v[60:63], v[138:141], v[200:203], v[60:63]
	v_mfma_f32_16x16x32_bf16 v[56:59], v[150:153], v[200:203], v[56:59]
	v_mfma_f32_16x16x32_bf16 v[44:47], v[138:141], v[218:221], v[44:47]
	v_mfma_f32_16x16x32_bf16 v[40:43], v[150:153], v[218:221], v[40:43]
	v_mfma_f32_16x16x32_bf16 v[28:31], v[138:141], v[226:229], v[28:31]
	v_mfma_f32_16x16x32_bf16 v[24:27], v[150:153], v[226:229], v[24:27]
	v_mfma_f32_16x16x32_bf16 v[12:15], v[138:141], v[234:237], v[12:15]
	v_mfma_f32_16x16x32_bf16 v[8:11], v[150:153], v[234:237], v[8:11]
	v_mfma_f32_16x16x32_bf16 v[60:63], v[146:149], v[214:217], v[60:63]
	v_mfma_f32_16x16x32_bf16 v[56:59], v[154:157], v[214:217], v[56:59]
	v_mfma_f32_16x16x32_bf16 v[44:47], v[146:149], v[222:225], v[44:47]
	v_mfma_f32_16x16x32_bf16 v[40:43], v[154:157], v[222:225], v[40:43]
	v_mfma_f32_16x16x32_bf16 v[28:31], v[146:149], v[230:233], v[28:31]
	v_mfma_f32_16x16x32_bf16 v[24:27], v[154:157], v[230:233], v[24:27]
	v_mfma_f32_16x16x32_bf16 v[12:15], v[146:149], v[238:241], v[12:15]
	v_mfma_f32_16x16x32_bf16 v[8:11], v[154:157], v[238:241], v[8:11]
	s_setprio 0
	s_setprio 1
	v_mfma_f32_16x16x32_bf16 v[52:55], v[184:187], v[200:203], v[52:55]
	v_mfma_f32_16x16x32_bf16 v[48:51], v[192:195], v[200:203], v[48:51]
	v_mfma_f32_16x16x32_bf16 v[36:39], v[184:187], v[218:221], v[36:39]
	v_mfma_f32_16x16x32_bf16 v[32:35], v[192:195], v[218:221], v[32:35]
	v_mfma_f32_16x16x32_bf16 v[20:23], v[184:187], v[226:229], v[20:23]
	v_mfma_f32_16x16x32_bf16 v[16:19], v[192:195], v[226:229], v[16:19]
	v_mfma_f32_16x16x32_bf16 v[4:7], v[184:187], v[234:237], v[4:7]
	v_mfma_f32_16x16x32_bf16 v[0:3], v[192:195], v[234:237], v[0:3]
	v_mfma_f32_16x16x32_bf16 v[52:55], v[188:191], v[214:217], v[52:55]
	v_mfma_f32_16x16x32_bf16 v[48:51], v[196:199], v[214:217], v[48:51]
	v_mfma_f32_16x16x32_bf16 v[36:39], v[188:191], v[222:225], v[36:39]
	v_mfma_f32_16x16x32_bf16 v[32:35], v[196:199], v[222:225], v[32:35]
	v_mfma_f32_16x16x32_bf16 v[20:23], v[188:191], v[230:233], v[20:23]
	v_mfma_f32_16x16x32_bf16 v[16:19], v[196:199], v[230:233], v[16:19]
	v_mfma_f32_16x16x32_bf16 v[4:7], v[188:191], v[238:241], v[4:7]
	v_mfma_f32_16x16x32_bf16 v[0:3], v[196:199], v[238:241], v[0:3]
	s_setprio 0
	s_barrier
	s_add_i32 s54, s54, 2
	s_add_u32 s42, s42, 0x100
	s_addc_u32 s43, s43, 0
	s_add_u32 s28, s28, 0x100
	s_addc_u32 s29, s29, 0
	s_cmp_gt_u32 s54, 5
	s_cbranch_scc0 .LBB0_97
	s_branch .Lgk_after_97

; __device__ __forceinline__ unsigned pk2(float lo, float hi) { return f2bf(lo) | (f2bf(hi) << 16); }
;     __device__ __forceinline__ void operator()(const f32x4 (&acc)[2][2][4][2], const pg8::Unit& u, int wr, int wc, int fr, int fq) const {
;         const int row0 = u.pm * 256 + wr * 64 + fr, col0 = u.pn * 256 + wc * 32 + 8 * fq;
; #pragma unroll
;         for (int ai = 0; ai < 2; ++ai)
; #pragma unroll
;             for (int m = 0; m < 4; ++m) {
;                 const size_t row = (size_t)(row0 + ai * 128 + m * 16);
;                 float ssq = 0.f, rstd = 1.f;
;                 if constexpr (MODE == 8) rstd = 1.f / sqrtf(rs[row] * (1.f / DM) + EPS);
; #pragma unroll
;                 for (int bj = 0; bj < 2; ++bj) {
;                     const int col = col0 + bj * 128;
;                     f32x4 v0 = acc[ai][bj][m][0], v1 = acc[ai][bj][m][1];
;     ...
;                     } else if constexpr (MODE == 2 || MODE == 3) {
;                         const u32x4 g = *(const u32x4*)(aux + row * 4096 + (MODE == 3 ? 2048 : 0) + col);
;                         float r[8] = {v0[0], v0[1], v0[2], v0[3], v1[0], v1[1], v1[2], v1[3]};
;                         const unsigned gw[4] = {g.x, g.y, g.z, g.w};
; #pragma unroll
;                         for (int i = 0; i < 4; ++i) { r[2 * i] *= bf2f(gw[i] & 0xffffu); r[2 * i + 1] *= __builtin_bit_cast(float, gw[i] & 0xffff0000u); }
;                         if constexpr (MODE == 3) { const u32x4 pv = *(const u32x4*)(ob + row * 2048 + col); const unsigned pw[4] = {pv.x, pv.y, pv.z, pv.w};
; #pragma unroll
;                             for (int i = 0; i < 4; ++i) { r[2 * i] += bf2f(pw[i] & 0xffffu); r[2 * i + 1] += __builtin_bit_cast(float, pw[i] & 0xffff0000u); } }
;                         u32x4 w; w.x = pk2(r[0], r[1]); w.y = pk2(r[2], r[3]); w.z = pk2(r[4], r[5]); w.w = pk2(r[6], r[7]);
;                         *(u32x4*)(ob + row * 2048 + col) = w;
.LBB0_100:
	v_lshl_add_u32 v140, s9, 8, v142
	v_lshl_or_b32 v138, s8, 8, v144
	v_ashrrev_i32_e32 v141, 31, v140
	v_lshlrev_b64 v[146:147], 13, v[140:141]
	v_ashrrev_i32_e32 v139, 31, v138
	v_lshl_add_u64 v[146:147], s[24:25], 0, v[146:147]
	v_lshlrev_b64 v[138:139], 1, v[138:139]
	v_lshl_add_u64 v[152:153], v[146:147], 0, v[138:139]
	global_load_dwordx4 v[184:187], v[152:153], off
	global_load_dwordx4 v[188:191], v[152:153], off offset:256
	v_or_b32_e32 v242, 16, v140
	v_ashrrev_i32_e32 v243, 31, v242
	v_lshlrev_b64 v[244:245], 13, v[242:243]
	v_lshl_add_u64 v[242:243], s[24:25], 0, v[244:245]
	v_lshl_add_u64 v[242:243], v[242:243], 0, v[138:139]
	global_load_dwordx4 v[192:195], v[242:243], off
	global_load_dwordx4 v[196:199], v[242:243], off offset:256
	v_or_b32_e32 v242, 32, v140
	v_ashrrev_i32_e32 v243, 31, v242
	v_lshlrev_b64 v[244:245], 13, v[242:243]
	v_lshl_add_u64 v[242:243], s[24:25], 0, v[244:245]
	v_lshl_add_u64 v[242:243], v[242:243], 0, v[138:139]
	global_load_dwordx4 v[200:203], v[242:243], off
	global_load_dwordx4 v[214:217], v[242:243], off offset:256
	v_or_b32_e32 v242, 48, v140
	v_ashrrev_i32_e32 v243, 31, v242
	v_lshlrev_b64 v[244:245], 13, v[242:243]
	v_lshl_add_u64 v[242:243], s[24:25], 0, v[244:245]
	v_lshl_add_u64 v[242:243], v[242:243], 0, v[138:139]
	global_load_dwordx4 v[218:221], v[242:243], off
	global_load_dwordx4 v[222:225], v[242:243], off offset:256
	v_add_u32_e32 v242, 0x80, v140
	v_ashrrev_i32_e32 v243, 31, v242
	v_lshlrev_b64 v[244:245], 13, v[242:243]
	v_lshl_add_u64 v[242:243], s[24:25], 0, v[244:245]
	v_lshl_add_u64 v[242:243], v[242:243], 0, v[138:139]
	global_load_dwordx4 v[226:229], v[242:243], off
	global_load_dwordx4 v[230:233], v[242:243], off offset:256
	v_add_u32_e32 v242, 0x90, v140
	v_ashrrev_i32_e32 v243, 31, v242
	v_lshlrev_b64 v[244:245], 13, v[242:243]
	v_lshl_add_u64 v[242:243], s[24:25], 0, v[244:245]
	v_lshl_add_u64 v[242:243], v[242:243], 0, v[138:139]
	global_load_dwordx4 v[234:237], v[242:243], off
	global_load_dwordx4 v[238:241], v[242:243], off offset:256
	v_mov_b32_e32 v157, v126
	v_mov_b32_e32 v126, v125
	v_mov_b32_e32 v156, v124
	v_lshlrev_b64 v[150:151], 12, v[140:141]
	s_mov_b64 s[42:43], -1
	s_andn2_b64 vcc, exec, s[38:39]
	s_waitcnt vmcnt(10)
	v_lshlrev_b32_e32 v155, 16, v185
	v_lshlrev_b32_e32 v154, 16, v184
	v_and_b32_e32 v147, 0xffff0000, v185
	v_and_b32_e32 v146, 0xffff0000, v184
	v_pk_mul_f32 v[124:125], v[126:127], v[146:147]
	v_lshlrev_b32_e32 v127, 16, v187
	v_lshlrev_b32_e32 v126, 16, v186
	v_mov_b32_e32 v146, v120
	v_mov_b32_e32 v147, v122
	v_pk_mul_f32 v[126:127], v[146:147], v[126:127]
	v_and_b32_e32 v147, 0xffff0000, v187
	v_and_b32_e32 v146, 0xffff0000, v186
	v_mov_b32_e32 v122, v121
	v_pk_mul_f32 v[120:121], v[122:123], v[146:147]
	v_pk_mul_f32 v[154:155], v[156:157], v[154:155]
	v_cvt_pk_bf16_f32 v123, v155, v125
	v_cvt_pk_bf16_f32 v122, v154, v124
	v_cvt_pk_bf16_f32 v125, v127, v121
	v_cvt_pk_bf16_f32 v124, v126, v120
	v_lshl_add_u64 v[120:121], s[26:27], 0, v[150:151]
	v_lshl_add_u64 v[120:121], v[120:121], 0, v[138:139]
	global_store_dwordx4 v[120:121], v[122:125], off
	v_mov_b32_e32 v147, v118
	v_mov_b32_e32 v118, v117
	v_mov_b32_e32 v146, v116
	v_lshlrev_b32_e32 v123, 16, v189
	v_lshlrev_b32_e32 v122, 16, v188
	v_and_b32_e32 v125, 0xffff0000, v189
	v_and_b32_e32 v124, 0xffff0000, v188
	v_pk_mul_f32 v[116:117], v[118:119], v[124:125]
	v_lshlrev_b32_e32 v119, 16, v191
	v_lshlrev_b32_e32 v118, 16, v190
	v_mov_b32_e32 v124, v112
	v_mov_b32_e32 v125, v114
	v_pk_mul_f32 v[118:119], v[124:125], v[118:119]
	v_and_b32_e32 v125, 0xffff0000, v191
	v_and_b32_e32 v124, 0xffff0000, v190
	v_mov_b32_e32 v114, v113
	v_pk_mul_f32 v[112:113], v[114:115], v[124:125]
	v_pk_mul_f32 v[122:123], v[146:147], v[122:123]
	v_cvt_pk_bf16_f32 v115, v119, v113
	v_cvt_pk_bf16_f32 v114, v118, v112
	v_cvt_pk_bf16_f32 v113, v123, v117
	v_cvt_pk_bf16_f32 v112, v122, v116
	global_store_dwordx4 v[120:121], v[112:115], off offset:256
	v_mov_b32_e32 v123, v110
	v_mov_b32_e32 v110, v109
	v_or_b32_e32 v112, 16, v140
	v_ashrrev_i32_e32 v113, 31, v112
	v_lshlrev_b64 v[114:115], 13, v[112:113]
	v_lshlrev_b64 v[118:119], 12, v[112:113]
	v_lshl_add_u64 v[112:113], s[24:25], 0, v[114:115]
	v_lshl_add_u64 v[112:113], v[112:113], 0, v[138:139]
	v_add_u32_e32 v242, 0xa0, v140
	v_ashrrev_i32_e32 v243, 31, v242
	v_lshlrev_b64 v[244:245], 13, v[242:243]
	v_lshl_add_u64 v[242:243], s[24:25], 0, v[244:245]
	v_lshl_add_u64 v[242:243], v[242:243], 0, v[138:139]
	global_load_dwordx4 v[184:187], v[242:243], off
	global_load_dwordx4 v[188:191], v[242:243], off offset:256
	v_mov_b32_e32 v122, v108
	s_waitcnt vmcnt(12)
; __device__ __forceinline__ unsigned pk2(float lo, float hi) { return f2bf(lo) | (f2bf(hi) << 16); }
;     __device__ __forceinline__ void operator()(const f32x4 (&acc)[2][2][4][2], const pg8::Unit& u, int wr, int wc, int fr, int fq) const {
;         const int row0 = u.pm * 256 + wr * 64 + fr, col0 = u.pn * 256 + wc * 32 + 8 * fq;
; #pragma unroll
;         for (int ai = 0; ai < 2; ++ai)
; #pragma unroll
;             for (int m = 0; m < 4; ++m) {
;                 const size_t row = (size_t)(row0 + ai * 128 + m * 16);
;                 float ssq = 0.f, rstd = 1.f;
;                 if constexpr (MODE == 8) rstd = 1.f / sqrtf(rs[row] * (1.f / DM) + EPS);
; #pragma unroll
;                 for (int bj = 0; bj < 2; ++bj) {
;                     const int col = col0 + bj * 128;
;                     f32x4 v0 = acc[ai][bj][m][0], v1 = acc[ai][bj][m][1];
;     ...
;                     } else if constexpr (MODE == 2 || MODE == 3) {
;                         const u32x4 g = *(const u32x4*)(aux + row * 4096 + (MODE == 3 ? 2048 : 0) + col);
;                         float r[8] = {v0[0], v0[1], v0[2], v0[3], v1[0], v1[1], v1[2], v1[3]};
;                         const unsigned gw[4] = {g.x, g.y, g.z, g.w};
; #pragma unroll
;                         for (int i = 0; i < 4; ++i) { r[2 * i] *= bf2f(gw[i] & 0xffffu); r[2 * i + 1] *= __builtin_bit_cast(float, gw[i] & 0xffff0000u); }
;                         if constexpr (MODE == 3) { const u32x4 pv = *(const u32x4*)(ob + row * 2048 + col); const unsigned pw[4] = {pv.x, pv.y, pv.z, pv.w};
; #pragma unroll
;                             for (int i = 0; i < 4; ++i) { r[2 * i] += bf2f(pw[i] & 0xffffu); r[2 * i + 1] += __builtin_bit_cast(float, pw[i] & 0xffff0000u); } }
;                         u32x4 w; w.x = pk2(r[0], r[1]); w.y = pk2(r[2], r[3]); w.z = pk2(r[4], r[5]); w.w = pk2(r[6], r[7]);
;                         *(u32x4*)(ob + row * 2048 + col) = w;
	v_lshlrev_b32_e32 v121, 16, v193
	v_lshlrev_b32_e32 v120, 16, v192
	v_and_b32_e32 v115, 0xffff0000, v193
	v_and_b32_e32 v114, 0xffff0000, v192
	v_pk_mul_f32 v[108:109], v[110:111], v[114:115]
	v_lshlrev_b32_e32 v111, 16, v195
	v_lshlrev_b32_e32 v110, 16, v194
	v_mov_b32_e32 v114, v104
	v_mov_b32_e32 v115, v106
	v_pk_mul_f32 v[110:111], v[114:115], v[110:111]
	v_and_b32_e32 v115, 0xffff0000, v195
	v_and_b32_e32 v114, 0xffff0000, v194
	v_mov_b32_e32 v106, v105
	v_pk_mul_f32 v[104:105], v[106:107], v[114:115]
	v_pk_mul_f32 v[120:121], v[122:123], v[120:121]
	v_cvt_pk_bf16_f32 v107, v121, v109
	v_cvt_pk_bf16_f32 v106, v120, v108
	v_cvt_pk_bf16_f32 v109, v111, v105
	v_cvt_pk_bf16_f32 v108, v110, v104
	v_lshl_add_u64 v[104:105], s[26:27], 0, v[118:119]
	v_lshl_add_u64 v[104:105], v[104:105], 0, v[138:139]
	global_store_dwordx4 v[104:105], v[106:109], off
	v_mov_b32_e32 v113, v102
	v_mov_b32_e32 v102, v101
	v_mov_b32_e32 v112, v100
	v_lshlrev_b32_e32 v107, 16, v197
	v_lshlrev_b32_e32 v106, 16, v196
	v_and_b32_e32 v109, 0xffff0000, v197
	v_and_b32_e32 v108, 0xffff0000, v196
	v_pk_mul_f32 v[102:103], v[102:103], v[108:109]
	v_lshlrev_b32_e32 v101, 16, v199
	v_lshlrev_b32_e32 v100, 16, v198
	v_mov_b32_e32 v108, v96
	v_mov_b32_e32 v109, v98
	v_pk_mul_f32 v[100:101], v[108:109], v[100:101]
	v_and_b32_e32 v109, 0xffff0000, v199
	v_and_b32_e32 v108, 0xffff0000, v198
	v_mov_b32_e32 v98, v97
	v_pk_mul_f32 v[96:97], v[98:99], v[108:109]
	v_pk_mul_f32 v[106:107], v[112:113], v[106:107]
	v_cvt_pk_bf16_f32 v99, v101, v97
	v_cvt_pk_bf16_f32 v98, v100, v96
	v_cvt_pk_bf16_f32 v97, v107, v103
	v_cvt_pk_bf16_f32 v96, v106, v102
	global_store_dwordx4 v[104:105], v[96:99], off offset:256
	v_mov_b32_e32 v107, v94
	v_mov_b32_e32 v94, v93
	v_or_b32_e32 v96, 32, v140
	v_ashrrev_i32_e32 v97, 31, v96
	v_lshlrev_b64 v[98:99], 13, v[96:97]
	v_lshlrev_b64 v[102:103], 12, v[96:97]
	v_lshl_add_u64 v[96:97], s[24:25], 0, v[98:99]
	v_lshl_add_u64 v[96:97], v[96:97], 0, v[138:139]
	v_add_u32_e32 v242, 0xb0, v140
	v_ashrrev_i32_e32 v243, 31, v242
	v_lshlrev_b64 v[244:245], 13, v[242:243]
	v_lshl_add_u64 v[242:243], s[24:25], 0, v[244:245]
	v_lshl_add_u64 v[242:243], v[242:243], 0, v[138:139]
	global_load_dwordx4 v[192:195], v[242:243], off
	global_load_dwordx4 v[196:199], v[242:243], off offset:256
	v_mov_b32_e32 v106, v92
	s_waitcnt vmcnt(14)
	v_lshlrev_b32_e32 v105, 16, v201
	v_lshlrev_b32_e32 v104, 16, v200
	v_and_b32_e32 v99, 0xffff0000, v201
	v_and_b32_e32 v98, 0xffff0000, v200
	v_pk_mul_f32 v[92:93], v[94:95], v[98:99]
	v_lshlrev_b32_e32 v95, 16, v203
	v_lshlrev_b32_e32 v94, 16, v202
	v_mov_b32_e32 v98, v88
	v_mov_b32_e32 v99, v90
	v_pk_mul_f32 v[94:95], v[98:99], v[94:95]
	v_and_b32_e32 v99, 0xffff0000, v203
	v_and_b32_e32 v98, 0xffff0000, v202
	v_mov_b32_e32 v90, v89
	v_pk_mul_f32 v[88:89], v[90:91], v[98:99]
	v_pk_mul_f32 v[104:105], v[106:107], v[104:105]
	v_cvt_pk_bf16_f32 v91, v105, v93
	v_cvt_pk_bf16_f32 v90, v104, v92
	v_cvt_pk_bf16_f32 v93, v95, v89
	v_cvt_pk_bf16_f32 v92, v94, v88
	v_lshl_add_u64 v[88:89], s[26:27], 0, v[102:103]
	v_lshl_add_u64 v[88:89], v[88:89], 0, v[138:139]
	global_store_dwordx4 v[88:89], v[90:93], off
	v_mov_b32_e32 v97, v86
	v_mov_b32_e32 v86, v85
	v_mov_b32_e32 v96, v84
	v_lshlrev_b32_e32 v91, 16, v215
	v_lshlrev_b32_e32 v90, 16, v214
	v_and_b32_e32 v93, 0xffff0000, v215
	v_and_b32_e32 v92, 0xffff0000, v214
	v_pk_mul_f32 v[84:85], v[86:87], v[92:93]
	v_lshlrev_b32_e32 v87, 16, v217
	v_lshlrev_b32_e32 v86, 16, v216
	v_mov_b32_e32 v92, v80
	v_mov_b32_e32 v93, v82
	v_pk_mul_f32 v[86:87], v[92:93], v[86:87]
	v_and_b32_e32 v93, 0xffff0000, v217
	v_and_b32_e32 v92, 0xffff0000, v216
	v_mov_b32_e32 v82, v81
	v_pk_mul_f32 v[80:81], v[82:83], v[92:93]
	v_pk_mul_f32 v[90:91], v[96:97], v[90:91]
	v_cvt_pk_bf16_f32 v83, v87, v81
	v_cvt_pk_bf16_f32 v82, v86, v80
	v_cvt_pk_bf16_f32 v81, v91, v85
	v_cvt_pk_bf16_f32 v80, v90, v84
	global_store_dwordx4 v[88:89], v[80:83], off offset:256
	v_mov_b32_e32 v91, v78
	v_mov_b32_e32 v78, v77
	v_or_b32_e32 v80, 48, v140
	v_ashrrev_i32_e32 v81, 31, v80
	v_lshlrev_b64 v[82:83], 13, v[80:81]
	v_lshlrev_b64 v[86:87], 12, v[80:81]
	v_lshl_add_u64 v[80:81], s[24:25], 0, v[82:83]
	v_lshl_add_u64 v[80:81], v[80:81], 0, v[138:139]
	v_mov_b32_e32 v90, v76
	s_waitcnt vmcnt(14)
	v_lshlrev_b32_e32 v89, 16, v219
	v_lshlrev_b32_e32 v88, 16, v218
	v_and_b32_e32 v83, 0xffff0000, v219
	v_and_b32_e32 v82, 0xffff0000, v218
	v_pk_mul_f32 v[76:77], v[78:79], v[82:83]
	v_lshlrev_b32_e32 v79, 16, v221
	v_lshlrev_b32_e32 v78, 16, v220
	v_mov_b32_e32 v82, v72
	v_mov_b32_e32 v83, v74
	v_pk_mul_f32 v[78:79], v[82:83], v[78:79]
	v_and_b32_e32 v83, 0xffff0000, v221
	v_and_b32_e32 v82, 0xffff0000, v220
	v_mov_b32_e32 v74, v73
	v_pk_mul_f32 v[72:73], v[74:75], v[82:83]
	v_pk_mul_f32 v[88:89], v[90:91], v[88:89]
	v_cvt_pk_bf16_f32 v75, v89, v77
	v_cvt_pk_bf16_f32 v74, v88, v76
	v_cvt_pk_bf16_f32 v77, v79, v73
	v_cvt_pk_bf16_f32 v76, v78, v72
	v_lshl_add_u64 v[72:73], s[26:27], 0, v[86:87]
	v_lshl_add_u64 v[72:73], v[72:73], 0, v[138:139]
	global_store_dwordx4 v[72:73], v[74:77], off
	v_mov_b32_e32 v81, v70
	v_mov_b32_e32 v70, v69
	v_mov_b32_e32 v80, v68
	v_lshlrev_b32_e32 v79, 16, v223
	v_lshlrev_b32_e32 v78, 16, v222
	v_and_b32_e32 v75, 0xffff0000, v223
	v_and_b32_e32 v74, 0xffff0000, v222
	v_pk_mul_f32 v[68:69], v[70:71], v[74:75]
	v_lshlrev_b32_e32 v71, 16, v225
	v_lshlrev_b32_e32 v70, 16, v224
	v_mov_b32_e32 v74, v64
	v_mov_b32_e32 v75, v66
	v_pk_mul_f32 v[70:71], v[74:75], v[70:71]
	v_and_b32_e32 v75, 0xffff0000, v225
	v_and_b32_e32 v74, 0xffff0000, v224
	v_mov_b32_e32 v66, v65
	v_pk_mul_f32 v[64:65], v[66:67], v[74:75]
	v_pk_mul_f32 v[78:79], v[80:81], v[78:79]
	v_cvt_pk_bf16_f32 v67, v71, v65
	v_cvt_pk_bf16_f32 v66, v70, v64
	v_cvt_pk_bf16_f32 v65, v79, v69
	v_cvt_pk_bf16_f32 v64, v78, v68
	global_store_dwordx4 v[72:73], v[64:67], off offset:256
	v_mov_b32_e32 v75, v62
	v_mov_b32_e32 v62, v61
	v_add_u32_e32 v64, 0x80, v140
	v_ashrrev_i32_e32 v65, 31, v64
	v_lshlrev_b64 v[66:67], 13, v[64:65]
	v_lshlrev_b64 v[70:71], 12, v[64:65]
	v_lshl_add_u64 v[64:65], s[24:25], 0, v[66:67]
	v_lshl_add_u64 v[64:65], v[64:65], 0, v[138:139]
	v_mov_b32_e32 v74, v60
	s_waitcnt vmcnt(14)
; __device__ __forceinline__ unsigned pk2(float lo, float hi) { return f2bf(lo) | (f2bf(hi) << 16); }
;     __device__ __forceinline__ void operator()(const f32x4 (&acc)[2][2][4][2], const pg8::Unit& u, int wr, int wc, int fr, int fq) const {
;         const int row0 = u.pm * 256 + wr * 64 + fr, col0 = u.pn * 256 + wc * 32 + 8 * fq;
; #pragma unroll
;         for (int ai = 0; ai < 2; ++ai)
; #pragma unroll
;             for (int m = 0; m < 4; ++m) {
;                 const size_t row = (size_t)(row0 + ai * 128 + m * 16);
;                 float ssq = 0.f, rstd = 1.f;
;                 if constexpr (MODE == 8) rstd = 1.f / sqrtf(rs[row] * (1.f / DM) + EPS);
; #pragma unroll
;                 for (int bj = 0; bj < 2; ++bj) {
;                     const int col = col0 + bj * 128;
;                     f32x4 v0 = acc[ai][bj][m][0], v1 = acc[ai][bj][m][1];
;     ...
;                     } else if constexpr (MODE == 2 || MODE == 3) {
;                         const u32x4 g = *(const u32x4*)(aux + row * 4096 + (MODE == 3 ? 2048 : 0) + col);
;                         float r[8] = {v0[0], v0[1], v0[2], v0[3], v1[0], v1[1], v1[2], v1[3]};
;                         const unsigned gw[4] = {g.x, g.y, g.z, g.w};
; #pragma unroll
;                         for (int i = 0; i < 4; ++i) { r[2 * i] *= bf2f(gw[i] & 0xffffu); r[2 * i + 1] *= __builtin_bit_cast(float, gw[i] & 0xffff0000u); }
;                         if constexpr (MODE == 3) { const u32x4 pv = *(const u32x4*)(ob + row * 2048 + col); const unsigned pw[4] = {pv.x, pv.y, pv.z, pv.w};
; #pragma unroll
;                             for (int i = 0; i < 4; ++i) { r[2 * i] += bf2f(pw[i] & 0xffffu); r[2 * i + 1] += __builtin_bit_cast(float, pw[i] & 0xffff0000u); } }
;                         u32x4 w; w.x = pk2(r[0], r[1]); w.y = pk2(r[2], r[3]); w.z = pk2(r[4], r[5]); w.w = pk2(r[6], r[7]);
;                         *(u32x4*)(ob + row * 2048 + col) = w;
	v_lshlrev_b32_e32 v73, 16, v227
	v_lshlrev_b32_e32 v72, 16, v226
	v_and_b32_e32 v67, 0xffff0000, v227
	v_and_b32_e32 v66, 0xffff0000, v226
	v_pk_mul_f32 v[60:61], v[62:63], v[66:67]
	v_lshlrev_b32_e32 v63, 16, v229
	v_lshlrev_b32_e32 v62, 16, v228
	v_mov_b32_e32 v66, v56
	v_mov_b32_e32 v67, v58
	v_pk_mul_f32 v[62:63], v[66:67], v[62:63]
	v_and_b32_e32 v67, 0xffff0000, v229
	v_and_b32_e32 v66, 0xffff0000, v228
	v_mov_b32_e32 v58, v57
	v_pk_mul_f32 v[56:57], v[58:59], v[66:67]
	v_pk_mul_f32 v[72:73], v[74:75], v[72:73]
	v_cvt_pk_bf16_f32 v59, v73, v61
	v_cvt_pk_bf16_f32 v58, v72, v60
	v_cvt_pk_bf16_f32 v61, v63, v57
	v_cvt_pk_bf16_f32 v60, v62, v56
	v_lshl_add_u64 v[56:57], s[26:27], 0, v[70:71]
	v_lshl_add_u64 v[56:57], v[56:57], 0, v[138:139]
	global_store_dwordx4 v[56:57], v[58:61], off
	v_mov_b32_e32 v65, v54
	v_mov_b32_e32 v54, v53
	v_mov_b32_e32 v64, v52
	v_lshlrev_b32_e32 v63, 16, v231
	v_lshlrev_b32_e32 v62, 16, v230
	v_and_b32_e32 v59, 0xffff0000, v231
	v_and_b32_e32 v58, 0xffff0000, v230
	v_pk_mul_f32 v[52:53], v[54:55], v[58:59]
	v_lshlrev_b32_e32 v55, 16, v233
	v_lshlrev_b32_e32 v54, 16, v232
	v_mov_b32_e32 v58, v48
	v_mov_b32_e32 v59, v50
	v_pk_mul_f32 v[54:55], v[58:59], v[54:55]
	v_and_b32_e32 v59, 0xffff0000, v233
	v_and_b32_e32 v58, 0xffff0000, v232
	v_mov_b32_e32 v50, v49
	v_pk_mul_f32 v[48:49], v[50:51], v[58:59]
	v_pk_mul_f32 v[62:63], v[64:65], v[62:63]
	v_cvt_pk_bf16_f32 v51, v55, v49
	v_cvt_pk_bf16_f32 v50, v54, v48
	v_cvt_pk_bf16_f32 v49, v63, v53
	v_cvt_pk_bf16_f32 v48, v62, v52
	global_store_dwordx4 v[56:57], v[48:51], off offset:256
	v_mov_b32_e32 v59, v46
	v_mov_b32_e32 v46, v45
	v_add_u32_e32 v48, 0x90, v140
	v_ashrrev_i32_e32 v49, 31, v48
	v_lshlrev_b64 v[50:51], 13, v[48:49]
	v_lshlrev_b64 v[54:55], 12, v[48:49]
	v_lshl_add_u64 v[48:49], s[24:25], 0, v[50:51]
	v_lshl_add_u64 v[48:49], v[48:49], 0, v[138:139]
	v_mov_b32_e32 v58, v44
	s_waitcnt vmcnt(14)
	v_lshlrev_b32_e32 v57, 16, v235
	v_lshlrev_b32_e32 v56, 16, v234
	v_and_b32_e32 v51, 0xffff0000, v235
	v_and_b32_e32 v50, 0xffff0000, v234
	v_pk_mul_f32 v[44:45], v[46:47], v[50:51]
	v_lshlrev_b32_e32 v47, 16, v237
	v_lshlrev_b32_e32 v46, 16, v236
	v_mov_b32_e32 v50, v40
	v_mov_b32_e32 v51, v42
	v_pk_mul_f32 v[46:47], v[50:51], v[46:47]
	v_and_b32_e32 v51, 0xffff0000, v237
	v_and_b32_e32 v50, 0xffff0000, v236
	v_mov_b32_e32 v42, v41
	v_pk_mul_f32 v[40:41], v[42:43], v[50:51]
	v_pk_mul_f32 v[56:57], v[58:59], v[56:57]
	v_cvt_pk_bf16_f32 v43, v57, v45
	v_cvt_pk_bf16_f32 v42, v56, v44
	v_cvt_pk_bf16_f32 v45, v47, v41
	v_cvt_pk_bf16_f32 v44, v46, v40
	v_lshl_add_u64 v[40:41], s[26:27], 0, v[54:55]
	v_lshl_add_u64 v[40:41], v[40:41], 0, v[138:139]
	global_store_dwordx4 v[40:41], v[42:45], off
	v_mov_b32_e32 v49, v38
	v_mov_b32_e32 v38, v37
	v_mov_b32_e32 v48, v36
	v_lshlrev_b32_e32 v47, 16, v239
	v_lshlrev_b32_e32 v46, 16, v238
	v_and_b32_e32 v43, 0xffff0000, v239
	v_and_b32_e32 v42, 0xffff0000, v238
	v_pk_mul_f32 v[36:37], v[38:39], v[42:43]
	v_lshlrev_b32_e32 v39, 16, v241
	v_lshlrev_b32_e32 v38, 16, v240
	v_mov_b32_e32 v42, v32
	v_mov_b32_e32 v43, v34
	v_pk_mul_f32 v[38:39], v[42:43], v[38:39]
	v_and_b32_e32 v43, 0xffff0000, v241
	v_and_b32_e32 v42, 0xffff0000, v240
	v_mov_b32_e32 v34, v33
	v_pk_mul_f32 v[32:33], v[34:35], v[42:43]
	v_pk_mul_f32 v[46:47], v[48:49], v[46:47]
	v_cvt_pk_bf16_f32 v35, v39, v33
	v_cvt_pk_bf16_f32 v34, v38, v32
	v_cvt_pk_bf16_f32 v33, v47, v37
	v_cvt_pk_bf16_f32 v32, v46, v36
	global_store_dwordx4 v[40:41], v[32:35], off offset:256
	v_mov_b32_e32 v43, v30
	v_mov_b32_e32 v30, v29
	v_add_u32_e32 v32, 0xa0, v140
	v_ashrrev_i32_e32 v33, 31, v32
	v_lshlrev_b64 v[34:35], 13, v[32:33]
	v_lshlrev_b64 v[38:39], 12, v[32:33]
	v_lshl_add_u64 v[32:33], s[24:25], 0, v[34:35]
	v_lshl_add_u64 v[32:33], v[32:33], 0, v[138:139]
	v_mov_b32_e32 v42, v28
	s_waitcnt vmcnt(12)
; #define PG8_BAR __builtin_amdgcn_s_barrier()
; __device__ __forceinline__ unsigned pk2(float lo, float hi) { return f2bf(lo) | (f2bf(hi) << 16); }
; template <class Epi, class Sched, bool ALIGN_EPI = false, bool SP2 = false, bool F8 = false>
; __device__ __forceinline__ void gemm_phase(PG8_LAS unsigned char* lds, const Gemm g, const Sched& S, const Epi& E) {
;     ...
;         if constexpr (!Epi::AFTER_DRAIN) { E(acc, cur, wr, wc, fr, fq); S.done(cur); }
;         if (!has_next) break;
; #pragma unroll
;         for (int a = 0; a < 2; ++a)
; #pragma unroll
;             for (int b = 0; b < 2; ++b)
; #pragma unroll
;                 for (int m = 0; m < 4; ++m)
; #pragma unroll
;                     for (int n = 0; n < 2; ++n) acc[a][b][m][n] = (f32x4){0.f, 0.f, 0.f, 0.f};
;         cur = nxt; cA = nA; cB = nB; ++ui;
;         if constexpr (ALIGN_EPI) { if (wr == 1) PG8_BAR; }
;     __device__ __forceinline__ void operator()(const f32x4 (&acc)[2][2][4][2], const pg8::Unit& u, int wr, int wc, int fr, int fq) const {
;     ...
;                     } else if constexpr (MODE == 2 || MODE == 3) {
;                         const u32x4 g = *(const u32x4*)(aux + row * 4096 + (MODE == 3 ? 2048 : 0) + col);
;                         float r[8] = {v0[0], v0[1], v0[2], v0[3], v1[0], v1[1], v1[2], v1[3]};
;                         const unsigned gw[4] = {g.x, g.y, g.z, g.w};
; #pragma unroll
;                         for (int i = 0; i < 4; ++i) { r[2 * i] *= bf2f(gw[i] & 0xffffu); r[2 * i + 1] *= __builtin_bit_cast(float, gw[i] & 0xffff0000u); }
;                         if constexpr (MODE == 3) { const u32x4 pv = *(const u32x4*)(ob + row * 2048 + col); const unsigned pw[4] = {pv.x, pv.y, pv.z, pv.w};
; #pragma unroll
;                             for (int i = 0; i < 4; ++i) { r[2 * i] += bf2f(pw[i] & 0xffffu); r[2 * i + 1] += __builtin_bit_cast(float, pw[i] & 0xffff0000u); } }
;                         u32x4 w; w.x = pk2(r[0], r[1]); w.y = pk2(r[2], r[3]); w.z = pk2(r[4], r[5]); w.w = pk2(r[6], r[7]);
;                         *(u32x4*)(ob + row * 2048 + col) = w;
	v_lshlrev_b32_e32 v41, 16, v185
	v_lshlrev_b32_e32 v40, 16, v184
	v_and_b32_e32 v35, 0xffff0000, v185
	v_and_b32_e32 v34, 0xffff0000, v184
	v_pk_mul_f32 v[28:29], v[30:31], v[34:35]
	v_lshlrev_b32_e32 v31, 16, v187
	v_lshlrev_b32_e32 v30, 16, v186
	v_mov_b32_e32 v34, v24
	v_mov_b32_e32 v35, v26
	v_pk_mul_f32 v[30:31], v[34:35], v[30:31]
	v_and_b32_e32 v35, 0xffff0000, v187
	v_and_b32_e32 v34, 0xffff0000, v186
	v_mov_b32_e32 v26, v25
	v_pk_mul_f32 v[24:25], v[26:27], v[34:35]
	v_pk_mul_f32 v[40:41], v[42:43], v[40:41]
	v_cvt_pk_bf16_f32 v27, v41, v29
	v_cvt_pk_bf16_f32 v26, v40, v28
	v_cvt_pk_bf16_f32 v29, v31, v25
	v_cvt_pk_bf16_f32 v28, v30, v24
	v_lshl_add_u64 v[24:25], s[26:27], 0, v[38:39]
	v_lshl_add_u64 v[24:25], v[24:25], 0, v[138:139]
	global_store_dwordx4 v[24:25], v[26:29], off
	v_mov_b32_e32 v33, v22
	v_mov_b32_e32 v22, v21
	v_mov_b32_e32 v32, v20
	v_lshlrev_b32_e32 v31, 16, v189
	v_lshlrev_b32_e32 v30, 16, v188
	v_and_b32_e32 v27, 0xffff0000, v189
	v_and_b32_e32 v26, 0xffff0000, v188
	v_pk_mul_f32 v[20:21], v[22:23], v[26:27]
	v_lshlrev_b32_e32 v23, 16, v191
	v_lshlrev_b32_e32 v22, 16, v190
	v_mov_b32_e32 v26, v16
	v_mov_b32_e32 v27, v18
	v_pk_mul_f32 v[22:23], v[26:27], v[22:23]
	v_and_b32_e32 v27, 0xffff0000, v191
	v_and_b32_e32 v26, 0xffff0000, v190
	v_mov_b32_e32 v18, v17
	v_pk_mul_f32 v[16:17], v[18:19], v[26:27]
	v_pk_mul_f32 v[30:31], v[32:33], v[30:31]
	v_cvt_pk_bf16_f32 v19, v23, v17
	v_cvt_pk_bf16_f32 v18, v22, v16
	v_cvt_pk_bf16_f32 v17, v31, v21
	v_cvt_pk_bf16_f32 v16, v30, v20
	global_store_dwordx4 v[24:25], v[16:19], off offset:256
	v_mov_b32_e32 v27, v14
	v_mov_b32_e32 v14, v13
	v_add_u32_e32 v16, 0xb0, v140
	v_ashrrev_i32_e32 v17, 31, v16
	v_lshlrev_b64 v[18:19], 13, v[16:17]
	v_lshlrev_b64 v[22:23], 12, v[16:17]
	v_lshl_add_u64 v[16:17], s[24:25], 0, v[18:19]
	v_lshl_add_u64 v[16:17], v[16:17], 0, v[138:139]
	v_mov_b32_e32 v26, v12
	s_waitcnt vmcnt(10)
	v_lshlrev_b32_e32 v25, 16, v193
	v_lshlrev_b32_e32 v24, 16, v192
	v_and_b32_e32 v19, 0xffff0000, v193
	v_and_b32_e32 v18, 0xffff0000, v192
	v_pk_mul_f32 v[12:13], v[14:15], v[18:19]
	v_lshlrev_b32_e32 v15, 16, v195
	v_lshlrev_b32_e32 v14, 16, v194
	v_mov_b32_e32 v18, v8
	v_mov_b32_e32 v19, v10
	v_pk_mul_f32 v[14:15], v[18:19], v[14:15]
	v_and_b32_e32 v19, 0xffff0000, v195
	v_and_b32_e32 v18, 0xffff0000, v194
	v_mov_b32_e32 v10, v9
	v_pk_mul_f32 v[8:9], v[10:11], v[18:19]
	v_pk_mul_f32 v[24:25], v[26:27], v[24:25]
	v_cvt_pk_bf16_f32 v11, v25, v13
	v_cvt_pk_bf16_f32 v10, v24, v12
	v_cvt_pk_bf16_f32 v13, v15, v9
	v_cvt_pk_bf16_f32 v12, v14, v8
	v_lshl_add_u64 v[8:9], s[26:27], 0, v[22:23]
	v_lshl_add_u64 v[8:9], v[8:9], 0, v[138:139]
	global_store_dwordx4 v[8:9], v[10:13], off
	v_mov_b32_e32 v17, v6
	v_mov_b32_e32 v6, v5
	v_mov_b32_e32 v16, v4
	v_lshlrev_b32_e32 v15, 16, v197
	v_lshlrev_b32_e32 v14, 16, v196
	v_and_b32_e32 v11, 0xffff0000, v197
	v_and_b32_e32 v10, 0xffff0000, v196
	v_pk_mul_f32 v[4:5], v[6:7], v[10:11]
	v_lshlrev_b32_e32 v7, 16, v199
	v_lshlrev_b32_e32 v6, 16, v198
	v_mov_b32_e32 v10, v0
	v_mov_b32_e32 v11, v2
	v_pk_mul_f32 v[6:7], v[10:11], v[6:7]
	v_and_b32_e32 v11, 0xffff0000, v199
	v_and_b32_e32 v10, 0xffff0000, v198
	v_mov_b32_e32 v2, v1
	v_pk_mul_f32 v[0:1], v[2:3], v[10:11]
	v_pk_mul_f32 v[14:15], v[16:17], v[14:15]
	v_cvt_pk_bf16_f32 v3, v7, v1
	v_cvt_pk_bf16_f32 v2, v6, v0
	v_cvt_pk_bf16_f32 v1, v15, v5
	v_cvt_pk_bf16_f32 v0, v14, v4
	global_store_dwordx4 v[8:9], v[0:3], off offset:256
	s_mov_b32 s101, 1
	s_cbranch_vccnz .LBB0_89
	s_andn2_b64 vcc, exec, s[0:1]
	s_cbranch_vccnz .LBB0_88
	s_barrier
	s_branch .LBB0_88

; #define PG8_STAGE(bufoff, gbase, voff) do { _Pragma("unroll") for (int _i = 0; _i < 2; ++_i) \
;         __builtin_amdgcn_global_load_lds((const unsigned*)((const char*)(gbase) + (voff)[_i]), (PG8_LAS unsigned*)(lds + (bufoff) + ldsw + _i * 8192), 16, 0, 0); } while (0)
; #define PG8_WAIT_V(n) asm volatile("s_waitcnt vmcnt(" #n ")" ::: "memory")
; #define PG8_BAR __builtin_amdgcn_s_barrier()
; template <class Epi, class Sched, bool ALIGN_EPI = false, bool SP2 = false, bool F8 = false>
; __device__ __forceinline__ void gemm_phase(PG8_LAS unsigned char* lds, const Gemm g, const Sched& S, const Epi& E) {
;     int tid_ = threadIdx.x; asm volatile("" : "+v"(tid_)); const int tid = tid_, wid = __builtin_amdgcn_readfirstlane(tid >> 6), lane = tid & 63, wr = wid >> 2, wc = wid & 3, fr = lane & 15, fq = lane >> 4;
;     const int K = g.K, nt = K / BK;
;     unsigned voffA[2], voffB[2];
; #pragma unroll
;     for (int i = 0; i < 2; ++i) { int R, C; stage_rc(tid * 16 + i * 8192, R, C); const int Rb = Epi::PERM ? ((R & ~31) + perm32(R & 31)) : R;
;         voffA[i] = (unsigned)(R * K + C) * 2u; voffB[i] = (unsigned)(Rb * K + C) * 2u; }
;     const size_t kstep = (size_t)(BK * 2);
;     const size_t hstep = (size_t)HALF * K * 2;
;     const size_t tstep = 2 * hstep;
;     const unsigned ldsw = (unsigned)wid * 1024u;
;     const int aoff = lds_byte(wr * 64 + fr, fq * 8), boff = lds_byte(wc * 32 + fr, fq * 8);
;     ...
;         PG8_STAGE(PG8_SB(0, 0), cB, voffB); PG8_STAGE(PG8_SB(0, 1), cB + hstep, voffB); PG8_STAGE(PG8_SA(0, 0), cA, voffA); PG8_STAGE(PG8_SA(0, 1), cA + hstep, voffA);
;         if (wr == 1) PG8_BAR;
;         PG8_WAIT_V(2); PG8_BAR;
;         PG8_STAGE(PG8_SB(1, 0), cB + kstep, voffB); PG8_STAGE(PG8_SA(1, 0), cA + kstep, voffA); PG8_STAGE(PG8_SB(1, 1), cB + hstep + kstep, voffB);
;         PG8_WAIT_V(6); PG8_BAR;
.LBB0_107:
	s_waitcnt vmcnt(0)
	v_lshrrev_b32_e32 v16, 1, v6
	v_and_b32_e32 v16, 24, v16
	s_lshl_b32 s5, s5, 5
	v_and_b32_e32 v7, 15, v6
	v_lshlrev_b32_e32 v17, 1, v16
	v_lshlrev_b32_e32 v6, 2, v6
	s_and_b32 s10, s5, 0x60
	v_lshl_add_u64 v[8:9], s[36:37], 0, v[160:161]
	v_mov_b32_e32 v129, v161
	v_readlane_b32 s28, v253, 23
	v_lshl_or_b32 v144, s8, 6, v7
	v_lshl_or_b32 v7, v7, 6, v17
	s_lshl_b32 s8, s8, 13
	v_and_b32_e32 v6, 32, v6
	s_lshl_b32 s5, s10, 7
	v_lshl_add_u64 v[10:11], s[36:37], 0, v[128:129]
	v_mov_b32_e32 v133, v161
	v_readlane_b32 s29, v253, 24
	v_bitop3_b32 v17, v7, s8, v6 bitop3:0xde
	v_bitop3_b32 v145, v7, s5, v6 bitop3:0xde
	s_add_i32 m0, s35, 0x18000
	v_lshl_add_u64 v[6:7], v[8:9], 0, s[14:15]
	v_lshl_add_u64 v[12:13], s[28:29], 0, v[132:133]
	v_mov_b32_e32 v131, v161
	s_waitcnt vmcnt(2)
	s_barrier
	global_load_lds_dwordx4 v[6:7], off
	v_lshl_add_u64 v[6:7], v[10:11], 0, s[14:15]
	s_add_i32 m0, s35, 0x1a000
	s_add_i32 s51, s35, 0x8000
	s_add_i32 s52, s35, 0xa000
	v_lshl_add_u64 v[14:15], s[28:29], 0, v[130:131]
	global_load_lds_dwordx4 v[6:7], off
	v_lshl_add_u64 v[6:7], v[12:13], 0, s[14:15]
	s_mov_b32 m0, s51
	s_add_u32 s8, s36, 0x40080
	global_load_lds_dwordx4 v[6:7], off
	v_lshl_add_u64 v[6:7], v[14:15], 0, s[14:15]
	s_mov_b32 m0, s52
	s_addc_u32 s9, s37, 0
	global_load_lds_dwordx4 v[6:7], off
	s_add_i32 m0, s35, 0x1c000
	v_lshl_add_u64 v[6:7], s[8:9], 0, v[160:161]
	global_load_lds_dwordx4 v[6:7], off
	v_lshl_add_u64 v[6:7], s[8:9], 0, v[128:129]
	s_add_i32 m0, s35, 0x1e000
	v_or_b32_e32 v146, s10, v16
	global_load_lds_dwordx4 v[6:7], off
	v_lshlrev_b32_e32 v6, 14, v4
	v_and_b32_e32 v6, 0xffff8000, v6
	v_lshl_add_u32 v3, v3, 11, v6
	v_and_b32_e32 v4, 1, v4
	v_lshl_or_b32 v3, v4, 6, v3
	v_lshl_add_u32 v134, v5, 1, v3
	v_lshlrev_b32_e32 v3, 14, v0
	v_and_b32_e32 v3, 0xffff8000, v3
	s_waitcnt vmcnt(6)
	v_lshl_add_u32 v1, v1, 11, v3
	v_and_b32_e32 v0, 1, v0
	v_readlane_b32 s10, v253, 20
	s_cmpk_lt_u32 s4, 0x100
	v_lshl_or_b32 v0, v0, 6, v1
	v_readlane_b32 s11, v253, 21
	s_cselect_b64 s[4:5], -1, 0
	v_mov_b32_e32 v135, v161
	v_lshl_add_u32 v136, v2, 1, v0
	v_mov_b32_e32 v137, v161
	s_mov_b32 s53, 0
	v_add_u32_e32 v147, 0, v17
	v_readlane_b32 s8, v253, 11
	s_mov_b32 s9, s10
	s_mov_b64 s[10:11], s[28:29]
	s_barrier
	s_mov_b32 s101, 0
	s_branch .LBB0_110

; #define PG8_STAGE(bufoff, gbase, voff) do { _Pragma("unroll") for (int _i = 0; _i < 2; ++_i) \
;         __builtin_amdgcn_global_load_lds((const unsigned*)((const char*)(gbase) + (voff)[_i]), (PG8_LAS unsigned*)(lds + (bufoff) + ldsw + _i * 8192), 16, 0, 0); } while (0)
; #define PG8_WAIT_V(n) asm volatile("s_waitcnt vmcnt(" #n ")" ::: "memory")
; #define PG8_WAIT_L(n) asm volatile("s_waitcnt lgkmcnt(" #n ")" ::: "memory")
; #define PG8_BAR __builtin_amdgcn_s_barrier()
; #define PG8_SCHED __builtin_amdgcn_sched_barrier(0)
; template <class Epi, class Sched, bool ALIGN_EPI = false, bool SP2 = false, bool F8 = false>
; __device__ __forceinline__ void gemm_phase(PG8_LAS unsigned char* lds, const Gemm g, const Sched& S, const Epi& E) {
;     ...
;             PG8_LDB(B0, 0, 0); PG8_LDB(B1, 0, 1); PG8_SCHED; PG8_LDA(At, 0, 0); PG8_STAGE(PG8_SA(1, 1), a1 + hstep, voffA);
;             PG8_WAIT_V(8); PG8_WAIT_L(0); PG8_BAR; PG8_MMA(0, 0, At, B0); PG8_MMA(0, 1, At, B1); PG8_BAR; PG8_SCHED;
;             PG8_LDA(At, 0, 1); PG8_STAGE(PG8_SB(0, 0), b2, voffB); PG8_STAGE(PG8_SB(0, 1), b2 + hstep, voffB); PG8_STAGE(PG8_SA(0, 0), a2, voffA);
.LBB0_116:
	s_ashr_i32 s41, s40, 31
	s_lshl_b64 s[28:29], s[40:41], 19
	s_add_u32 s42, s96, s28
	v_readlane_b32 s17, v253, 22
	s_addc_u32 s43, s17, s29
	s_and_b64 s[28:29], s[38:39], exec
	s_cselect_b32 s19, s43, s11
	s_cselect_b32 s23, s42, s10
	s_ashr_i32 s17, s16, 31
	s_lshl_b64 s[28:29], s[16:17], 19
	s_add_u32 s44, s22, s28
	s_addc_u32 s45, s34, s29
	s_and_b64 s[28:29], s[38:39], exec
	s_cselect_b32 s17, s45, s37
	s_cselect_b32 s28, s44, s36
	s_add_u32 s10, s10, 0x40080
	s_addc_u32 s11, s11, 0
	s_add_u32 s29, s36, 0x100
	s_addc_u32 s41, s37, 0
	s_mov_b32 s54, -2
	s_add_u32 s36, s10, 0xfffc0080
	s_addc_u32 s37, s11, -1
	s_add_i32 s55, 0, 0x10000
	s_cmp_eq_u32 s54, 12
	s_cselect_b32 s47, s19, s37
	s_cselect_b32 s46, s23, s36
	v_add_u32_e32 v142, s55, v145
	s_cselect_b32 s37, s17, s41
	s_cselect_b32 s36, s28, s29
	s_add_i32 s56, 0, 0x14000
	ds_read_b128 v[138:141], v142
	ds_read_b128 v[148:151], v142 offset:1024
	ds_read_b128 v[152:155], v142 offset:2048
	ds_read_b128 v[156:159], v142 offset:3072
	v_add_u32_e32 v142, s56, v145
	ds_read_b128 v[184:187], v142
	ds_read_b128 v[188:191], v142 offset:1024
	ds_read_b128 v[192:195], v142 offset:2048
	ds_read_b128 v[196:199], v142 offset:3072
	v_lshl_add_u64 v[142:143], s[10:11], 0, v[134:135]
	s_add_i32 m0, s35, 0xc000
	ds_read_b128 v[200:203], v147
	ds_read_b128 v[214:217], v147 offset:1024
	ds_read_b128 v[218:221], v147 offset:2048
	ds_read_b128 v[222:225], v147 offset:3072
	ds_read_b128 v[226:229], v147 offset:4096
	ds_read_b128 v[230:233], v147 offset:5120
	ds_read_b128 v[234:237], v147 offset:6144
	ds_read_b128 v[238:241], v147 offset:7168
	global_load_lds_dwordx4 v[142:143], off
	v_lshl_add_u64 v[142:143], s[10:11], 0, v[136:137]
	s_add_i32 m0, s35, 0xe000
	s_nop 0
	global_load_lds_dwordx4 v[142:143], off
	s_cmp_lg_u32 s101, 0
	s_cbranch_scc1 .Lgk_nw1_117
	s_waitcnt vmcnt(8)
.Lgk_nw1_117:
	s_waitcnt lgkmcnt(0)
	s_barrier
	s_setprio 1
	s_waitcnt lgkmcnt(0)
	v_mfma_f32_16x16x32_bf16 v[124:127], v[138:141], v[200:203], 0
	v_mfma_f32_16x16x32_bf16 v[120:123], v[152:155], v[200:203], 0
	v_mfma_f32_16x16x32_bf16 v[108:111], v[138:141], v[218:221], 0
	v_mfma_f32_16x16x32_bf16 v[104:107], v[152:155], v[218:221], 0
	v_mfma_f32_16x16x32_bf16 v[92:95], v[138:141], v[226:229], 0
	v_mfma_f32_16x16x32_bf16 v[88:91], v[152:155], v[226:229], 0
	v_mfma_f32_16x16x32_bf16 v[76:79], v[138:141], v[234:237], 0
	v_mfma_f32_16x16x32_bf16 v[72:75], v[152:155], v[234:237], 0
	v_mfma_f32_16x16x32_bf16 v[124:127], v[148:151], v[214:217], v[124:127]
	v_mfma_f32_16x16x32_bf16 v[120:123], v[156:159], v[214:217], v[120:123]
	v_mfma_f32_16x16x32_bf16 v[108:111], v[148:151], v[222:225], v[108:111]
	v_mfma_f32_16x16x32_bf16 v[104:107], v[156:159], v[222:225], v[104:107]
	v_mfma_f32_16x16x32_bf16 v[92:95], v[148:151], v[230:233], v[92:95]
	v_mfma_f32_16x16x32_bf16 v[88:91], v[156:159], v[230:233], v[88:91]
	v_mfma_f32_16x16x32_bf16 v[76:79], v[148:151], v[238:241], v[76:79]
	v_mfma_f32_16x16x32_bf16 v[72:75], v[156:159], v[238:241], v[72:75]
	s_setprio 0
	s_setprio 1
	v_mfma_f32_16x16x32_bf16 v[116:119], v[184:187], v[200:203], 0
	v_mfma_f32_16x16x32_bf16 v[112:115], v[192:195], v[200:203], 0
	v_mfma_f32_16x16x32_bf16 v[100:103], v[184:187], v[218:221], 0
	v_mfma_f32_16x16x32_bf16 v[96:99], v[192:195], v[218:221], 0
	v_mfma_f32_16x16x32_bf16 v[84:87], v[184:187], v[226:229], 0
	v_mfma_f32_16x16x32_bf16 v[80:83], v[192:195], v[226:229], 0
	v_mfma_f32_16x16x32_bf16 v[68:71], v[184:187], v[234:237], 0
	v_mfma_f32_16x16x32_bf16 v[64:67], v[192:195], v[234:237], 0
	v_mfma_f32_16x16x32_bf16 v[116:119], v[188:191], v[214:217], v[116:119]
	v_mfma_f32_16x16x32_bf16 v[112:115], v[196:199], v[214:217], v[112:115]
	v_mfma_f32_16x16x32_bf16 v[100:103], v[188:191], v[222:225], v[100:103]
	v_mfma_f32_16x16x32_bf16 v[96:99], v[196:199], v[222:225], v[96:99]
	v_mfma_f32_16x16x32_bf16 v[84:87], v[188:191], v[230:233], v[84:87]
	v_mfma_f32_16x16x32_bf16 v[80:83], v[196:199], v[230:233], v[80:83]
	v_mfma_f32_16x16x32_bf16 v[68:71], v[188:191], v[238:241], v[68:71]
	v_mfma_f32_16x16x32_bf16 v[64:67], v[196:199], v[238:241], v[64:67]
	s_setprio 0
	s_barrier
	s_add_i32 s55, s55, s13
	v_lshl_add_u64 v[142:143], s[36:37], 0, v[160:161]
	s_mov_b32 m0, s55
	ds_read_b128 v[200:203], v147 offset:16384
	ds_read_b128 v[214:217], v147 offset:17408
	ds_read_b128 v[218:221], v147 offset:18432
	ds_read_b128 v[222:225], v147 offset:19456
	ds_read_b128 v[226:229], v147 offset:20480
	ds_read_b128 v[230:233], v147 offset:21504
	ds_read_b128 v[234:237], v147 offset:22528
	ds_read_b128 v[238:241], v147 offset:23552
	global_load_lds_dwordx4 v[142:143], off
	s_add_i32 m0, s55, 0x2000
	s_add_u32 s58, s36, 0x40000
	v_lshl_add_u64 v[162:163], s[36:37], 0, v[128:129]
	s_addc_u32 s59, s37, 0
	s_add_i32 s55, s56, s13
	global_load_lds_dwordx4 v[162:163], off
	v_lshl_add_u64 v[242:243], s[58:59], 0, v[160:161]
	s_mov_b32 m0, s55
	v_lshl_add_u64 v[244:245], s[46:47], 0, v[130:131]
	global_load_lds_dwordx4 v[242:243], off
	v_lshl_add_u64 v[242:243], s[58:59], 0, v[128:129]
	s_add_i32 m0, s55, 0x2000
	s_nop 0
	global_load_lds_dwordx4 v[242:243], off
	v_lshl_add_u64 v[242:243], s[46:47], 0, v[132:133]
	s_mov_b32 m0, s35
	s_nop 0
	global_load_lds_dwordx4 v[242:243], off
	s_mov_b32 m0, s48
	s_nop 0
	global_load_lds_dwordx4 v[244:245], off
	s_cmp_lg_u32 s101, 0
	s_cbranch_scc1 .Lgk_nw2_117
	s_waitcnt vmcnt(8)
; #define PG8_STAGE(bufoff, gbase, voff) do { _Pragma("unroll") for (int _i = 0; _i < 2; ++_i) \
;         __builtin_amdgcn_global_load_lds((const unsigned*)((const char*)(gbase) + (voff)[_i]), (PG8_LAS unsigned*)(lds + (bufoff) + ldsw + _i * 8192), 16, 0, 0); } while (0)
; #define PG8_WAIT_V(n) asm volatile("s_waitcnt vmcnt(" #n ")" ::: "memory")
; #define PG8_WAIT_L(n) asm volatile("s_waitcnt lgkmcnt(" #n ")" ::: "memory")
; #define PG8_BAR __builtin_amdgcn_s_barrier()
; #define PG8_SCHED __builtin_amdgcn_sched_barrier(0)
; template <class Epi, class Sched, bool ALIGN_EPI = false, bool SP2 = false, bool F8 = false>
; __device__ __forceinline__ void gemm_phase(PG8_LAS unsigned char* lds, const Gemm g, const Sched& S, const Epi& E) {
;     ...
;             PG8_WAIT_V(8); PG8_WAIT_L(0); PG8_BAR; PG8_MMA(1, 0, At, B0); PG8_MMA(1, 1, At, B1); PG8_BAR; PG8_SCHED;
;             PG8_LDB(B0, 1, 0); PG8_LDB(B1, 1, 1); PG8_SCHED; PG8_LDA(At, 1, 0); PG8_STAGE(PG8_SA(0, 1), a2 + hstep, voffA);
;             PG8_WAIT_V(8); PG8_WAIT_L(0); PG8_BAR; PG8_MMA(0, 0, At, B0); PG8_MMA(0, 1, At, B1); PG8_BAR; PG8_SCHED;
.Lgk_nw2_117:
	s_waitcnt lgkmcnt(0)
	s_barrier
	s_setprio 1
	s_waitcnt lgkmcnt(0)
	v_mfma_f32_16x16x32_bf16 v[60:63], v[138:141], v[200:203], 0
	v_mfma_f32_16x16x32_bf16 v[56:59], v[152:155], v[200:203], 0
	v_mfma_f32_16x16x32_bf16 v[44:47], v[138:141], v[218:221], 0
	v_mfma_f32_16x16x32_bf16 v[40:43], v[152:155], v[218:221], 0
	v_mfma_f32_16x16x32_bf16 v[28:31], v[138:141], v[226:229], 0
	v_mfma_f32_16x16x32_bf16 v[24:27], v[152:155], v[226:229], 0
	v_mfma_f32_16x16x32_bf16 v[12:15], v[138:141], v[234:237], 0
	v_mfma_f32_16x16x32_bf16 v[8:11], v[152:155], v[234:237], 0
	v_mfma_f32_16x16x32_bf16 v[60:63], v[148:151], v[214:217], v[60:63]
	v_mfma_f32_16x16x32_bf16 v[56:59], v[156:159], v[214:217], v[56:59]
	v_mfma_f32_16x16x32_bf16 v[44:47], v[148:151], v[222:225], v[44:47]
	v_mfma_f32_16x16x32_bf16 v[40:43], v[156:159], v[222:225], v[40:43]
	v_mfma_f32_16x16x32_bf16 v[28:31], v[148:151], v[230:233], v[28:31]
	v_mfma_f32_16x16x32_bf16 v[24:27], v[156:159], v[230:233], v[24:27]
	v_mfma_f32_16x16x32_bf16 v[12:15], v[148:151], v[238:241], v[12:15]
	v_mfma_f32_16x16x32_bf16 v[8:11], v[156:159], v[238:241], v[8:11]
	s_setprio 0
	s_setprio 1
	v_mfma_f32_16x16x32_bf16 v[52:55], v[184:187], v[200:203], 0
	v_mfma_f32_16x16x32_bf16 v[48:51], v[192:195], v[200:203], 0
	v_mfma_f32_16x16x32_bf16 v[36:39], v[184:187], v[218:221], 0
	v_mfma_f32_16x16x32_bf16 v[32:35], v[192:195], v[218:221], 0
	v_mfma_f32_16x16x32_bf16 v[20:23], v[184:187], v[226:229], 0
	v_mfma_f32_16x16x32_bf16 v[16:19], v[192:195], v[226:229], 0
	v_mfma_f32_16x16x32_bf16 v[4:7], v[184:187], v[234:237], 0
	v_mfma_f32_16x16x32_bf16 v[0:3], v[192:195], v[234:237], 0
	v_mfma_f32_16x16x32_bf16 v[52:55], v[188:191], v[214:217], v[52:55]
	v_mfma_f32_16x16x32_bf16 v[48:51], v[196:199], v[214:217], v[48:51]
	v_mfma_f32_16x16x32_bf16 v[36:39], v[188:191], v[222:225], v[36:39]
	v_mfma_f32_16x16x32_bf16 v[32:35], v[196:199], v[222:225], v[32:35]
	v_mfma_f32_16x16x32_bf16 v[20:23], v[188:191], v[230:233], v[20:23]
	v_mfma_f32_16x16x32_bf16 v[16:19], v[196:199], v[230:233], v[16:19]
	v_mfma_f32_16x16x32_bf16 v[4:7], v[188:191], v[238:241], v[4:7]
	v_mfma_f32_16x16x32_bf16 v[0:3], v[196:199], v[238:241], v[0:3]
	s_setprio 0
	s_barrier
	s_add_i32 s55, 0, 0x18000
	s_add_i32 s56, 0, 0x1c000
	v_add_u32_e32 v156, s55, v145
	v_add_u32_e32 v196, s56, v145
	ds_read_b128 v[138:141], v156
	ds_read_b128 v[148:151], v156 offset:1024
	ds_read_b128 v[152:155], v156 offset:2048
	ds_read_b128 v[156:159], v156 offset:3072
	ds_read_b128 v[184:187], v196
	ds_read_b128 v[188:191], v196 offset:1024
	ds_read_b128 v[192:195], v196 offset:2048
	ds_read_b128 v[196:199], v196 offset:3072
	s_add_u32 s46, s46, 0x40000
	s_addc_u32 s47, s47, 0
	s_mov_b32 m0, s49
	v_lshl_add_u64 v[246:247], s[46:47], 0, v[132:133]
	ds_read_b128 v[200:203], v147 offset:32768
	ds_read_b128 v[214:217], v147 offset:33792
	ds_read_b128 v[218:221], v147 offset:34816
	ds_read_b128 v[222:225], v147 offset:35840
	ds_read_b128 v[226:229], v147 offset:36864
	ds_read_b128 v[230:233], v147 offset:37888
	ds_read_b128 v[234:237], v147 offset:38912
	ds_read_b128 v[238:241], v147 offset:39936
	global_load_lds_dwordx4 v[246:247], off
	v_lshl_add_u64 v[246:247], s[46:47], 0, v[130:131]
	s_mov_b32 m0, s50
	s_nop 0
	global_load_lds_dwordx4 v[246:247], off
	s_waitcnt vmcnt(8)
	s_waitcnt lgkmcnt(0)
	s_barrier
	s_setprio 1
	s_waitcnt lgkmcnt(0)
	v_mfma_f32_16x16x32_bf16 v[124:127], v[138:141], v[200:203], v[124:127]
	v_mfma_f32_16x16x32_bf16 v[120:123], v[152:155], v[200:203], v[120:123]
	v_mfma_f32_16x16x32_bf16 v[108:111], v[138:141], v[218:221], v[108:111]
	v_mfma_f32_16x16x32_bf16 v[104:107], v[152:155], v[218:221], v[104:107]
	v_mfma_f32_16x16x32_bf16 v[92:95], v[138:141], v[226:229], v[92:95]
	v_mfma_f32_16x16x32_bf16 v[88:91], v[152:155], v[226:229], v[88:91]
	v_mfma_f32_16x16x32_bf16 v[76:79], v[138:141], v[234:237], v[76:79]
	v_mfma_f32_16x16x32_bf16 v[72:75], v[152:155], v[234:237], v[72:75]
	v_mfma_f32_16x16x32_bf16 v[124:127], v[148:151], v[214:217], v[124:127]
	v_mfma_f32_16x16x32_bf16 v[120:123], v[156:159], v[214:217], v[120:123]
	v_mfma_f32_16x16x32_bf16 v[108:111], v[148:151], v[222:225], v[108:111]
	v_mfma_f32_16x16x32_bf16 v[104:107], v[156:159], v[222:225], v[104:107]
	v_mfma_f32_16x16x32_bf16 v[92:95], v[148:151], v[230:233], v[92:95]
	v_mfma_f32_16x16x32_bf16 v[88:91], v[156:159], v[230:233], v[88:91]
	v_mfma_f32_16x16x32_bf16 v[76:79], v[148:151], v[238:241], v[76:79]
	v_mfma_f32_16x16x32_bf16 v[72:75], v[156:159], v[238:241], v[72:75]
	s_setprio 0
	s_setprio 1
	v_mfma_f32_16x16x32_bf16 v[116:119], v[184:187], v[200:203], v[116:119]
	v_mfma_f32_16x16x32_bf16 v[112:115], v[192:195], v[200:203], v[112:115]
	v_mfma_f32_16x16x32_bf16 v[100:103], v[184:187], v[218:221], v[100:103]
	v_mfma_f32_16x16x32_bf16 v[96:99], v[192:195], v[218:221], v[96:99]
	v_mfma_f32_16x16x32_bf16 v[84:87], v[184:187], v[226:229], v[84:87]
	v_mfma_f32_16x16x32_bf16 v[80:83], v[192:195], v[226:229], v[80:83]
	v_mfma_f32_16x16x32_bf16 v[68:71], v[184:187], v[234:237], v[68:71]
	v_mfma_f32_16x16x32_bf16 v[64:67], v[192:195], v[234:237], v[64:67]
	v_mfma_f32_16x16x32_bf16 v[116:119], v[188:191], v[214:217], v[116:119]
	v_mfma_f32_16x16x32_bf16 v[112:115], v[196:199], v[214:217], v[112:115]
	v_mfma_f32_16x16x32_bf16 v[100:103], v[188:191], v[222:225], v[100:103]
	v_mfma_f32_16x16x32_bf16 v[96:99], v[196:199], v[222:225], v[96:99]
	v_mfma_f32_16x16x32_bf16 v[84:87], v[188:191], v[230:233], v[84:87]
	v_mfma_f32_16x16x32_bf16 v[80:83], v[196:199], v[230:233], v[80:83]
	v_mfma_f32_16x16x32_bf16 v[68:71], v[188:191], v[238:241], v[68:71]
	v_mfma_f32_16x16x32_bf16 v[64:67], v[196:199], v[238:241], v[64:67]
	s_setprio 0
	s_barrier
; #define PG8_STAGE(bufoff, gbase, voff) do { _Pragma("unroll") for (int _i = 0; _i < 2; ++_i) \
;         __builtin_amdgcn_global_load_lds((const unsigned*)((const char*)(gbase) + (voff)[_i]), (PG8_LAS unsigned*)(lds + (bufoff) + ldsw + _i * 8192), 16, 0, 0); } while (0)
; #define PG8_WAIT_V(n) asm volatile("s_waitcnt vmcnt(" #n ")" ::: "memory")
; #define PG8_WAIT_L(n) asm volatile("s_waitcnt lgkmcnt(" #n ")" ::: "memory")
; #define PG8_BAR __builtin_amdgcn_s_barrier()
; #define PG8_SCHED __builtin_amdgcn_sched_barrier(0)
; template <class Epi, class Sched, bool ALIGN_EPI = false, bool SP2 = false, bool F8 = false>
; __device__ __forceinline__ void gemm_phase(PG8_LAS unsigned char* lds, const Gemm g, const Sched& S, const Epi& E) {
;     ...
;             PG8_LDA(At, 1, 1); PG8_STAGE(PG8_SB(1, 0), b3, voffB); PG8_STAGE(PG8_SB(1, 1), b3 + hstep, voffB); PG8_STAGE(PG8_SA(1, 0), a3, voffA);
;             PG8_WAIT_V(8); PG8_WAIT_L(0); PG8_BAR; PG8_MMA(1, 0, At, B0); PG8_MMA(1, 1, At, B1); PG8_BAR; PG8_SCHED;
	s_add_i32 s46, s55, s13
	v_lshl_add_u64 v[142:143], v[142:143], 0, s[14:15]
	s_mov_b32 m0, s46
	ds_read_b128 v[200:203], v147 offset:49152
	ds_read_b128 v[214:217], v147 offset:50176
	ds_read_b128 v[218:221], v147 offset:51200
	ds_read_b128 v[222:225], v147 offset:52224
	ds_read_b128 v[226:229], v147 offset:53248
	ds_read_b128 v[230:233], v147 offset:54272
	ds_read_b128 v[234:237], v147 offset:55296
	ds_read_b128 v[238:241], v147 offset:56320
	global_load_lds_dwordx4 v[142:143], off
	s_add_i32 m0, s46, 0x2000
	s_add_u32 s36, s36, 0x40080
	v_lshl_add_u64 v[142:143], v[162:163], 0, s[14:15]
	s_addc_u32 s37, s37, 0
	s_add_i32 s46, s56, s13
	global_load_lds_dwordx4 v[142:143], off
	v_lshl_add_u64 v[142:143], s[36:37], 0, v[160:161]
	s_mov_b32 m0, s46
	s_nop 0
	global_load_lds_dwordx4 v[142:143], off
	v_lshl_add_u64 v[142:143], s[36:37], 0, v[128:129]
	s_add_i32 m0, s46, 0x2000
	s_nop 0
	global_load_lds_dwordx4 v[142:143], off
	v_lshl_add_u64 v[142:143], v[242:243], 0, s[14:15]
	s_mov_b32 m0, s51
	s_nop 0
	global_load_lds_dwordx4 v[142:143], off
	v_lshl_add_u64 v[142:143], v[244:245], 0, s[14:15]
	s_mov_b32 m0, s52
	s_nop 0
	global_load_lds_dwordx4 v[142:143], off
	s_waitcnt vmcnt(8)
	s_waitcnt lgkmcnt(0)
	s_barrier
	s_setprio 1
	s_waitcnt lgkmcnt(0)
	v_mfma_f32_16x16x32_bf16 v[60:63], v[138:141], v[200:203], v[60:63]
	v_mfma_f32_16x16x32_bf16 v[56:59], v[152:155], v[200:203], v[56:59]
	v_mfma_f32_16x16x32_bf16 v[44:47], v[138:141], v[218:221], v[44:47]
	v_mfma_f32_16x16x32_bf16 v[40:43], v[152:155], v[218:221], v[40:43]
	v_mfma_f32_16x16x32_bf16 v[28:31], v[138:141], v[226:229], v[28:31]
	v_mfma_f32_16x16x32_bf16 v[24:27], v[152:155], v[226:229], v[24:27]
	v_mfma_f32_16x16x32_bf16 v[12:15], v[138:141], v[234:237], v[12:15]
	v_mfma_f32_16x16x32_bf16 v[8:11], v[152:155], v[234:237], v[8:11]
	v_mfma_f32_16x16x32_bf16 v[60:63], v[148:151], v[214:217], v[60:63]
	v_mfma_f32_16x16x32_bf16 v[56:59], v[156:159], v[214:217], v[56:59]
	v_mfma_f32_16x16x32_bf16 v[44:47], v[148:151], v[222:225], v[44:47]
	v_mfma_f32_16x16x32_bf16 v[40:43], v[156:159], v[222:225], v[40:43]
	v_mfma_f32_16x16x32_bf16 v[28:31], v[148:151], v[230:233], v[28:31]
	v_mfma_f32_16x16x32_bf16 v[24:27], v[156:159], v[230:233], v[24:27]
	v_mfma_f32_16x16x32_bf16 v[12:15], v[148:151], v[238:241], v[12:15]
	v_mfma_f32_16x16x32_bf16 v[8:11], v[156:159], v[238:241], v[8:11]
	s_setprio 0
	s_setprio 1
	v_mfma_f32_16x16x32_bf16 v[52:55], v[184:187], v[200:203], v[52:55]
	v_mfma_f32_16x16x32_bf16 v[48:51], v[192:195], v[200:203], v[48:51]
	v_mfma_f32_16x16x32_bf16 v[36:39], v[184:187], v[218:221], v[36:39]
	v_mfma_f32_16x16x32_bf16 v[32:35], v[192:195], v[218:221], v[32:35]
	v_mfma_f32_16x16x32_bf16 v[20:23], v[184:187], v[226:229], v[20:23]
	v_mfma_f32_16x16x32_bf16 v[16:19], v[192:195], v[226:229], v[16:19]
	v_mfma_f32_16x16x32_bf16 v[4:7], v[184:187], v[234:237], v[4:7]
	v_mfma_f32_16x16x32_bf16 v[0:3], v[192:195], v[234:237], v[0:3]
	v_mfma_f32_16x16x32_bf16 v[52:55], v[188:191], v[214:217], v[52:55]
	v_mfma_f32_16x16x32_bf16 v[48:51], v[196:199], v[214:217], v[48:51]
	v_mfma_f32_16x16x32_bf16 v[36:39], v[188:191], v[222:225], v[36:39]
	v_mfma_f32_16x16x32_bf16 v[32:35], v[196:199], v[222:225], v[32:35]
	v_mfma_f32_16x16x32_bf16 v[20:23], v[188:191], v[230:233], v[20:23]
	v_mfma_f32_16x16x32_bf16 v[16:19], v[196:199], v[230:233], v[16:19]
	v_mfma_f32_16x16x32_bf16 v[4:7], v[188:191], v[238:241], v[4:7]
	v_mfma_f32_16x16x32_bf16 v[0:3], v[196:199], v[238:241], v[0:3]
	s_setprio 0
	s_barrier
	s_add_i32 s54, s54, 2
	s_add_u32 s10, s10, 0x100
	s_addc_u32 s11, s11, 0
	s_add_u32 s29, s29, 0x100
	s_addc_u32 s41, s41, 0
	s_cmp_gt_u32 s54, 13
	s_cbranch_scc0 .LBB0_117
	s_branch .Lgk_after_117

;     __device__ __forceinline__ void operator()(const f32x4 (&acc)[2][2][4][2], const pg8::Unit& u, int wr, int wc, int fr, int fq) const {
;         const int row0 = u.pm * 256 + wr * 64 + fr, col0 = u.pn * 256 + wc * 32 + 8 * fq;
; #pragma unroll
;         for (int ai = 0; ai < 2; ++ai)
; #pragma unroll
;             for (int m = 0; m < 4; ++m) {
;                 const size_t row = (size_t)(row0 + ai * 128 + m * 16);
;                 float ssq = 0.f, rstd = 1.f;
;                 if constexpr (MODE == 8) rstd = 1.f / sqrtf(rs[row] * (1.f / DM) + EPS);
; #pragma unroll
;                 for (int bj = 0; bj < 2; ++bj) {
;                     const int col = col0 + bj * 128;
;                     f32x4 v0 = acc[ai][bj][m][0], v1 = acc[ai][bj][m][1];
;                     if constexpr (MODE == 0 || MODE == 1) { v0 = v0 * scale; v1 = v1 * scale; }
;                     if constexpr (MODE == 6) { float* p = of + row * IDXW + col; *(f32x4*)p = v0; *(f32x4*)(p + 4) = v1; }
;                     else if constexpr (MODE == 0) {
;                         if (u.pn >= COL_BV / 256) {
;                             const float x8[8] = {v0[0], v0[1], v0[2], v0[3], v1[0], v1[1], v1[2], v1[3]};
;                             *(u32x2*)((unsigned char*)aux + row * 1024 + (col - COL_BV)) = to_fp8x8(x8);
;                         } else { u32x4 w; w.x = pk2(v0[0], v0[1]); w.y = pk2(v0[2], v0[3]); w.z = pk2(v1[0], v1[1]); w.w = pk2(v1[2], v1[3]);
;                             *(u32x4*)(ob + row * QKVW + col) = w; }
;                     } else if constexpr (MODE == 1) {
;                         const f32x4 b0 = *(const f32x4*)(vec + col), b1 = *(const f32x4*)(vec + col + 4);
;                         float r[8];
; #pragma unroll
;                         for (int i = 0; i < 4; ++i) { r[i] = 1.f / (1.f + __expf(-(v0[i] + b0[i]))); r[4 + i] = 1.f / (1.f + __expf(-(v1[i] + b1[i]))); }
;                         u32x4 w; w.x = pk2(r[0], r[1]); w.y = pk2(r[2], r[3]); w.z = pk2(r[4], r[5]); w.w = pk2(r[6], r[7]);
;                         *(u32x4*)(ob + row * 4096 + col) = w;
;                     } else if constexpr (MODE == 2 || MODE == 3) {
;                         const u32x4 g = *(const u32x4*)(aux + row * 4096 + (MODE == 3 ? 2048 : 0) + col);
;                         float r[8] = {v0[0], v0[1], v0[2], v0[3], v1[0], v1[1], v1[2], v1[3]};
.LBB0_120:
	v_lshl_add_u32 v140, s9, 8, v144
	v_ashrrev_i32_e32 v141, 31, v140
	v_lshl_or_b32 v156, s8, 8, v146
	v_lshlrev_b64 v[138:139], 13, v[140:141]
	v_lshlrev_b64 v[142:143], 12, v[140:141]
	v_lshl_add_u64 v[138:139], s[24:25], 0, v[138:139]
	s_mov_b64 s[8:9], 0x1000
	v_ashrrev_i32_e32 v157, 31, v156
	v_lshl_add_u64 v[158:159], v[138:139], 0, s[8:9]
	v_lshlrev_b64 v[138:139], 1, v[156:157]
	v_lshl_add_u64 v[142:143], s[26:27], 0, v[142:143]
	v_lshl_add_u64 v[148:149], v[158:159], 0, v[138:139]
	v_lshl_add_u64 v[142:143], v[142:143], 0, v[138:139]
	global_load_dwordx4 v[200:203], v[148:149], off
	global_load_dwordx4 v[214:217], v[142:143], off
	v_or_b32_e32 v186, 0x80, v156
	v_ashrrev_i32_e32 v187, 31, v186
	v_lshlrev_b64 v[188:189], 1, v[186:187]
	v_lshl_add_u64 v[186:187], v[158:159], 0, v[188:189]
	global_load_dwordx4 v[218:221], v[186:187], off
	global_load_dwordx4 v[222:225], v[142:143], off offset:256
	v_or_b32_e32 v186, 16, v140
	v_ashrrev_i32_e32 v187, 31, v186
	v_lshlrev_b64 v[188:189], 13, v[186:187]
	v_lshl_add_u64 v[188:189], s[24:25], 0, v[188:189]
	v_lshl_add_u64 v[188:189], v[188:189], 0, s[8:9]
	v_lshl_add_u64 v[190:191], v[188:189], 0, v[138:139]
	global_load_dwordx4 v[226:229], v[190:191], off
	v_or_b32_e32 v186, 16, v140
	v_ashrrev_i32_e32 v187, 31, v186
	v_lshlrev_b64 v[186:187], 12, v[186:187]
	v_lshl_add_u64 v[186:187], s[26:27], 0, v[186:187]
	v_lshl_add_u64 v[186:187], v[186:187], 0, v[138:139]
	global_load_dwordx4 v[230:233], v[186:187], off
	v_or_b32_e32 v186, 0x80, v156
	v_ashrrev_i32_e32 v187, 31, v186
	v_lshlrev_b64 v[188:189], 1, v[186:187]
	v_or_b32_e32 v190, 16, v140
	v_ashrrev_i32_e32 v191, 31, v190
	v_lshlrev_b64 v[192:193], 13, v[190:191]
	v_lshl_add_u64 v[192:193], s[24:25], 0, v[192:193]
	v_lshl_add_u64 v[192:193], v[192:193], 0, s[8:9]
	v_lshl_add_u64 v[194:195], v[192:193], 0, v[188:189]
	global_load_dwordx4 v[234:237], v[194:195], off
	v_or_b32_e32 v186, 16, v140
	v_ashrrev_i32_e32 v187, 31, v186
	v_lshlrev_b64 v[186:187], 12, v[186:187]
	v_lshl_add_u64 v[186:187], s[26:27], 0, v[186:187]
	v_lshl_add_u64 v[186:187], v[186:187], 0, v[138:139]
	global_load_dwordx4 v[238:241], v[186:187], off offset:256
	v_mov_b32_e32 v184, v124
	v_mov_b32_e32 v185, v126
	v_mov_b32_e32 v126, v125
	s_mov_b64 s[10:11], -1
	s_andn2_b64 vcc, exec, s[38:39]
	s_waitcnt vmcnt(4)
	v_lshlrev_b32_e32 v163, 16, v201
	v_lshlrev_b32_e32 v162, 16, v200
	v_and_b32_e32 v149, 0xffff0000, v201
	v_and_b32_e32 v148, 0xffff0000, v200
	v_lshlrev_b32_e32 v125, 16, v215
	v_lshlrev_b32_e32 v124, 16, v214
	v_and_b32_e32 v153, 0xffff0000, v215
	v_and_b32_e32 v152, 0xffff0000, v214
	v_pk_fma_f32 v[126:127], v[126:127], v[148:149], v[152:153]
	v_lshlrev_b32_e32 v149, 16, v203
	v_lshlrev_b32_e32 v148, 16, v202
	v_mov_b32_e32 v152, v120
	v_mov_b32_e32 v153, v122
	v_mov_b32_e32 v122, v121
	v_lshlrev_b32_e32 v121, 16, v217
	v_lshlrev_b32_e32 v120, 16, v216
	v_and_b32_e32 v151, 0xffff0000, v203
	v_and_b32_e32 v150, 0xffff0000, v202
	v_pk_fma_f32 v[120:121], v[152:153], v[148:149], v[120:121]
	v_and_b32_e32 v149, 0xffff0000, v217
	v_and_b32_e32 v148, 0xffff0000, v216
	v_pk_fma_f32 v[122:123], v[122:123], v[150:151], v[148:149]
	v_pk_fma_f32 v[124:125], v[184:185], v[162:163], v[124:125]
	v_cvt_pk_bf16_f32 v123, v121, v123
	v_cvt_pk_bf16_f32 v122, v120, v122
	v_cvt_pk_bf16_f32 v121, v125, v127
	v_cvt_pk_bf16_f32 v120, v124, v126
	global_store_dwordx4 v[142:143], v[120:123], off
	v_mov_b32_e32 v152, v116
	v_mov_b32_e32 v153, v118
	v_or_b32_e32 v120, 0x80, v156
	v_ashrrev_i32_e32 v121, 31, v120
	v_lshlrev_b64 v[124:125], 1, v[120:121]
	v_lshl_add_u64 v[120:121], v[158:159], 0, v[124:125]
	s_nop 0
	v_mov_b32_e32 v118, v117
	v_lshlrev_b32_e32 v127, 16, v219
	v_lshlrev_b32_e32 v126, 16, v218
	v_lshlrev_b32_e32 v117, 16, v223
	v_lshlrev_b32_e32 v116, 16, v222
	v_and_b32_e32 v121, 0xffff0000, v219
	v_and_b32_e32 v120, 0xffff0000, v218
	v_pk_fma_f32 v[116:117], v[152:153], v[126:127], v[116:117]
	v_and_b32_e32 v127, 0xffff0000, v223
	v_and_b32_e32 v126, 0xffff0000, v222
	v_pk_fma_f32 v[118:119], v[118:119], v[120:121], v[126:127]
	v_lshlrev_b32_e32 v121, 16, v221
	v_lshlrev_b32_e32 v120, 16, v220
	v_mov_b32_e32 v126, v112
	v_mov_b32_e32 v127, v114
	v_mov_b32_e32 v114, v113
	v_lshlrev_b32_e32 v113, 16, v225
	v_lshlrev_b32_e32 v112, 16, v224
	v_and_b32_e32 v123, 0xffff0000, v221
	v_and_b32_e32 v122, 0xffff0000, v220
	v_pk_fma_f32 v[112:113], v[126:127], v[120:121], v[112:113]
	v_and_b32_e32 v121, 0xffff0000, v225
	v_and_b32_e32 v120, 0xffff0000, v224
	v_pk_fma_f32 v[114:115], v[114:115], v[122:123], v[120:121]
	v_cvt_pk_bf16_f32 v115, v113, v115
	v_cvt_pk_bf16_f32 v114, v112, v114
	v_cvt_pk_bf16_f32 v113, v117, v119
	v_cvt_pk_bf16_f32 v112, v116, v118
	global_store_dwordx4 v[142:143], v[112:115], off offset:256
	v_mov_b32_e32 v142, v108
	v_mov_b32_e32 v143, v110
	v_or_b32_e32 v112, 16, v140
	v_ashrrev_i32_e32 v113, 31, v112
	v_lshlrev_b64 v[114:115], 13, v[112:113]
	v_lshlrev_b64 v[112:113], 12, v[112:113]
	v_lshl_add_u64 v[114:115], s[24:25], 0, v[114:115]
	v_lshl_add_u64 v[114:115], v[114:115], 0, s[8:9]
	v_lshl_add_u64 v[112:113], s[26:27], 0, v[112:113]
	v_lshl_add_u64 v[116:117], v[114:115], 0, v[138:139]
	v_lshl_add_u64 v[112:113], v[112:113], 0, v[138:139]
	v_or_b32_e32 v186, 32, v140
	v_ashrrev_i32_e32 v187, 31, v186
	v_lshlrev_b64 v[188:189], 13, v[186:187]
	v_lshl_add_u64 v[188:189], s[24:25], 0, v[188:189]
	v_lshl_add_u64 v[188:189], v[188:189], 0, s[8:9]
	v_lshl_add_u64 v[190:191], v[188:189], 0, v[138:139]
	global_load_dwordx4 v[200:203], v[190:191], off
	v_or_b32_e32 v186, 32, v140
	v_ashrrev_i32_e32 v187, 31, v186
	v_lshlrev_b64 v[186:187], 12, v[186:187]
	v_lshl_add_u64 v[186:187], s[26:27], 0, v[186:187]
	v_lshl_add_u64 v[186:187], v[186:187], 0, v[138:139]
	global_load_dwordx4 v[214:217], v[186:187], off
	v_or_b32_e32 v186, 0x80, v156
	v_ashrrev_i32_e32 v187, 31, v186
	v_lshlrev_b64 v[188:189], 1, v[186:187]
	v_or_b32_e32 v190, 32, v140
	v_ashrrev_i32_e32 v191, 31, v190
	v_lshlrev_b64 v[192:193], 13, v[190:191]
	v_lshl_add_u64 v[192:193], s[24:25], 0, v[192:193]
	v_lshl_add_u64 v[192:193], v[192:193], 0, s[8:9]
	v_lshl_add_u64 v[194:195], v[192:193], 0, v[188:189]
	global_load_dwordx4 v[218:221], v[194:195], off
	v_or_b32_e32 v186, 32, v140
	v_ashrrev_i32_e32 v187, 31, v186
	v_lshlrev_b64 v[186:187], 12, v[186:187]
	v_lshl_add_u64 v[186:187], s[26:27], 0, v[186:187]
	v_lshl_add_u64 v[186:187], v[186:187], 0, v[138:139]
	global_load_dwordx4 v[222:225], v[186:187], off offset:256
	v_mov_b32_e32 v110, v109
	s_waitcnt vmcnt(6)
; __device__ __forceinline__ unsigned pk2(float lo, float hi) { return f2bf(lo) | (f2bf(hi) << 16); }
;     __device__ __forceinline__ void operator()(const f32x4 (&acc)[2][2][4][2], const pg8::Unit& u, int wr, int wc, int fr, int fq) const {
;     ...
;                     } else if constexpr (MODE == 2 || MODE == 3) {
;                         const u32x4 g = *(const u32x4*)(aux + row * 4096 + (MODE == 3 ? 2048 : 0) + col);
;                         float r[8] = {v0[0], v0[1], v0[2], v0[3], v1[0], v1[1], v1[2], v1[3]};
;                         const unsigned gw[4] = {g.x, g.y, g.z, g.w};
; #pragma unroll
;                         for (int i = 0; i < 4; ++i) { r[2 * i] *= bf2f(gw[i] & 0xffffu); r[2 * i + 1] *= __builtin_bit_cast(float, gw[i] & 0xffff0000u); }
;                         if constexpr (MODE == 3) { const u32x4 pv = *(const u32x4*)(ob + row * 2048 + col); const unsigned pw[4] = {pv.x, pv.y, pv.z, pv.w};
; #pragma unroll
;                             for (int i = 0; i < 4; ++i) { r[2 * i] += bf2f(pw[i] & 0xffffu); r[2 * i + 1] += __builtin_bit_cast(float, pw[i] & 0xffff0000u); } }
;                         u32x4 w; w.x = pk2(r[0], r[1]); w.y = pk2(r[2], r[3]); w.z = pk2(r[4], r[5]); w.w = pk2(r[6], r[7]);
;                         *(u32x4*)(ob + row * 2048 + col) = w;
	v_lshlrev_b32_e32 v127, 16, v227
	v_lshlrev_b32_e32 v126, 16, v226
	v_and_b32_e32 v117, 0xffff0000, v227
	v_and_b32_e32 v116, 0xffff0000, v226
	v_lshlrev_b32_e32 v109, 16, v231
	v_lshlrev_b32_e32 v108, 16, v230
	v_and_b32_e32 v121, 0xffff0000, v231
	v_and_b32_e32 v120, 0xffff0000, v230
	v_pk_fma_f32 v[110:111], v[110:111], v[116:117], v[120:121]
	v_lshlrev_b32_e32 v117, 16, v229
	v_lshlrev_b32_e32 v116, 16, v228
	v_mov_b32_e32 v120, v104
	v_mov_b32_e32 v121, v106
	v_mov_b32_e32 v106, v105
	v_lshlrev_b32_e32 v105, 16, v233
	v_lshlrev_b32_e32 v104, 16, v232
	v_and_b32_e32 v119, 0xffff0000, v229
	v_and_b32_e32 v118, 0xffff0000, v228
	v_pk_fma_f32 v[104:105], v[120:121], v[116:117], v[104:105]
	v_and_b32_e32 v117, 0xffff0000, v233
	v_and_b32_e32 v116, 0xffff0000, v232
	v_pk_fma_f32 v[106:107], v[106:107], v[118:119], v[116:117]
	v_pk_fma_f32 v[108:109], v[142:143], v[126:127], v[108:109]
	v_cvt_pk_bf16_f32 v107, v105, v107
	v_cvt_pk_bf16_f32 v106, v104, v106
	v_cvt_pk_bf16_f32 v105, v109, v111
	v_cvt_pk_bf16_f32 v104, v108, v110
	global_store_dwordx4 v[112:113], v[104:107], off
	v_mov_b32_e32 v116, v100
	v_mov_b32_e32 v117, v102
	v_lshl_add_u64 v[104:105], v[114:115], 0, v[124:125]
	s_nop 0
	v_mov_b32_e32 v102, v101
	v_lshlrev_b32_e32 v115, 16, v235
	v_lshlrev_b32_e32 v114, 16, v234
	v_and_b32_e32 v105, 0xffff0000, v235
	v_and_b32_e32 v104, 0xffff0000, v234
	v_lshlrev_b32_e32 v101, 16, v239
	v_lshlrev_b32_e32 v100, 16, v238
	v_and_b32_e32 v109, 0xffff0000, v239
	v_and_b32_e32 v108, 0xffff0000, v238
	v_pk_fma_f32 v[102:103], v[102:103], v[104:105], v[108:109]
	v_lshlrev_b32_e32 v105, 16, v237
	v_lshlrev_b32_e32 v104, 16, v236
	v_mov_b32_e32 v108, v96
	v_mov_b32_e32 v109, v98
	v_mov_b32_e32 v98, v97
	v_lshlrev_b32_e32 v97, 16, v241
	v_lshlrev_b32_e32 v96, 16, v240
	v_and_b32_e32 v107, 0xffff0000, v237
	v_and_b32_e32 v106, 0xffff0000, v236
	v_pk_fma_f32 v[96:97], v[108:109], v[104:105], v[96:97]
	v_and_b32_e32 v105, 0xffff0000, v241
	v_and_b32_e32 v104, 0xffff0000, v240
	v_pk_fma_f32 v[98:99], v[98:99], v[106:107], v[104:105]
	v_pk_fma_f32 v[100:101], v[116:117], v[114:115], v[100:101]
	v_cvt_pk_bf16_f32 v99, v97, v99
	v_cvt_pk_bf16_f32 v98, v96, v98
	v_cvt_pk_bf16_f32 v97, v101, v103
	v_cvt_pk_bf16_f32 v96, v100, v102
	global_store_dwordx4 v[112:113], v[96:99], off offset:256
	v_mov_b32_e32 v110, v92
	v_mov_b32_e32 v111, v94
	v_or_b32_e32 v96, 32, v140
	v_ashrrev_i32_e32 v97, 31, v96
	v_lshlrev_b64 v[98:99], 13, v[96:97]
	v_lshlrev_b64 v[96:97], 12, v[96:97]
	v_lshl_add_u64 v[98:99], s[24:25], 0, v[98:99]
	v_lshl_add_u64 v[98:99], v[98:99], 0, s[8:9]
	v_lshl_add_u64 v[96:97], s[26:27], 0, v[96:97]
	v_lshl_add_u64 v[100:101], v[98:99], 0, v[138:139]
	v_lshl_add_u64 v[96:97], v[96:97], 0, v[138:139]
	v_or_b32_e32 v186, 48, v140
	v_ashrrev_i32_e32 v187, 31, v186
	v_lshlrev_b64 v[188:189], 13, v[186:187]
	v_lshl_add_u64 v[188:189], s[24:25], 0, v[188:189]
	v_lshl_add_u64 v[188:189], v[188:189], 0, s[8:9]
	v_lshl_add_u64 v[190:191], v[188:189], 0, v[138:139]
	global_load_dwordx4 v[226:229], v[190:191], off
	v_or_b32_e32 v186, 48, v140
	v_ashrrev_i32_e32 v187, 31, v186
	v_lshlrev_b64 v[186:187], 12, v[186:187]
	v_lshl_add_u64 v[186:187], s[26:27], 0, v[186:187]
	v_lshl_add_u64 v[186:187], v[186:187], 0, v[138:139]
	global_load_dwordx4 v[230:233], v[186:187], off
	v_or_b32_e32 v186, 0x80, v156
	v_ashrrev_i32_e32 v187, 31, v186
	v_lshlrev_b64 v[188:189], 1, v[186:187]
	v_or_b32_e32 v190, 48, v140
	v_ashrrev_i32_e32 v191, 31, v190
	v_lshlrev_b64 v[192:193], 13, v[190:191]
	v_lshl_add_u64 v[192:193], s[24:25], 0, v[192:193]
	v_lshl_add_u64 v[192:193], v[192:193], 0, s[8:9]
	v_lshl_add_u64 v[194:195], v[192:193], 0, v[188:189]
	global_load_dwordx4 v[234:237], v[194:195], off
	v_or_b32_e32 v186, 48, v140
	v_ashrrev_i32_e32 v187, 31, v186
	v_lshlrev_b64 v[186:187], 12, v[186:187]
	v_lshl_add_u64 v[186:187], s[26:27], 0, v[186:187]
	v_lshl_add_u64 v[186:187], v[186:187], 0, v[138:139]
	global_load_dwordx4 v[238:241], v[186:187], off offset:256
	v_mov_b32_e32 v94, v93
	s_waitcnt vmcnt(6)
	v_lshlrev_b32_e32 v109, 16, v201
	v_lshlrev_b32_e32 v108, 16, v200
	v_and_b32_e32 v101, 0xffff0000, v201
	v_and_b32_e32 v100, 0xffff0000, v200
	v_lshlrev_b32_e32 v93, 16, v215
	v_lshlrev_b32_e32 v92, 16, v214
	v_and_b32_e32 v105, 0xffff0000, v215
	v_and_b32_e32 v104, 0xffff0000, v214
	v_pk_fma_f32 v[94:95], v[94:95], v[100:101], v[104:105]
	v_lshlrev_b32_e32 v101, 16, v203
	v_lshlrev_b32_e32 v100, 16, v202
	v_mov_b32_e32 v104, v88
	v_mov_b32_e32 v105, v90
	v_mov_b32_e32 v90, v89
	v_lshlrev_b32_e32 v89, 16, v217
	v_lshlrev_b32_e32 v88, 16, v216
	v_and_b32_e32 v103, 0xffff0000, v203
	v_and_b32_e32 v102, 0xffff0000, v202
	v_pk_fma_f32 v[88:89], v[104:105], v[100:101], v[88:89]
	v_and_b32_e32 v101, 0xffff0000, v217
	v_and_b32_e32 v100, 0xffff0000, v216
	v_pk_fma_f32 v[90:91], v[90:91], v[102:103], v[100:101]
	v_pk_fma_f32 v[92:93], v[110:111], v[108:109], v[92:93]
	v_cvt_pk_bf16_f32 v91, v89, v91
	v_cvt_pk_bf16_f32 v90, v88, v90
	v_cvt_pk_bf16_f32 v89, v93, v95
	v_cvt_pk_bf16_f32 v88, v92, v94
	global_store_dwordx4 v[96:97], v[88:91], off
	v_mov_b32_e32 v100, v84
	v_mov_b32_e32 v101, v86
	v_lshl_add_u64 v[88:89], v[98:99], 0, v[124:125]
	s_nop 0
	v_mov_b32_e32 v86, v85
	v_lshlrev_b32_e32 v99, 16, v219
	v_lshlrev_b32_e32 v98, 16, v218
	v_and_b32_e32 v89, 0xffff0000, v219
	v_and_b32_e32 v88, 0xffff0000, v218
	v_lshlrev_b32_e32 v85, 16, v223
	v_lshlrev_b32_e32 v84, 16, v222
	v_and_b32_e32 v93, 0xffff0000, v223
	v_and_b32_e32 v92, 0xffff0000, v222
	v_pk_fma_f32 v[86:87], v[86:87], v[88:89], v[92:93]
	v_lshlrev_b32_e32 v89, 16, v221
	v_lshlrev_b32_e32 v88, 16, v220
	v_mov_b32_e32 v92, v80
; __device__ __forceinline__ unsigned pk2(float lo, float hi) { return f2bf(lo) | (f2bf(hi) << 16); }
;     __device__ __forceinline__ void operator()(const f32x4 (&acc)[2][2][4][2], const pg8::Unit& u, int wr, int wc, int fr, int fq) const {
;     ...
;                     } else if constexpr (MODE == 2 || MODE == 3) {
;                         const u32x4 g = *(const u32x4*)(aux + row * 4096 + (MODE == 3 ? 2048 : 0) + col);
;                         float r[8] = {v0[0], v0[1], v0[2], v0[3], v1[0], v1[1], v1[2], v1[3]};
;                         const unsigned gw[4] = {g.x, g.y, g.z, g.w};
; #pragma unroll
;                         for (int i = 0; i < 4; ++i) { r[2 * i] *= bf2f(gw[i] & 0xffffu); r[2 * i + 1] *= __builtin_bit_cast(float, gw[i] & 0xffff0000u); }
;                         if constexpr (MODE == 3) { const u32x4 pv = *(const u32x4*)(ob + row * 2048 + col); const unsigned pw[4] = {pv.x, pv.y, pv.z, pv.w};
; #pragma unroll
;                             for (int i = 0; i < 4; ++i) { r[2 * i] += bf2f(pw[i] & 0xffffu); r[2 * i + 1] += __builtin_bit_cast(float, pw[i] & 0xffff0000u); } }
;                         u32x4 w; w.x = pk2(r[0], r[1]); w.y = pk2(r[2], r[3]); w.z = pk2(r[4], r[5]); w.w = pk2(r[6], r[7]);
;                         *(u32x4*)(ob + row * 2048 + col) = w;
	v_mov_b32_e32 v93, v82
	v_mov_b32_e32 v82, v81
	v_lshlrev_b32_e32 v81, 16, v225
	v_lshlrev_b32_e32 v80, 16, v224
	v_and_b32_e32 v91, 0xffff0000, v221
	v_and_b32_e32 v90, 0xffff0000, v220
	v_pk_fma_f32 v[80:81], v[92:93], v[88:89], v[80:81]
	v_and_b32_e32 v89, 0xffff0000, v225
	v_and_b32_e32 v88, 0xffff0000, v224
	v_pk_fma_f32 v[82:83], v[82:83], v[90:91], v[88:89]
	v_pk_fma_f32 v[84:85], v[100:101], v[98:99], v[84:85]
	v_cvt_pk_bf16_f32 v83, v81, v83
	v_cvt_pk_bf16_f32 v82, v80, v82
	v_cvt_pk_bf16_f32 v81, v85, v87
	v_cvt_pk_bf16_f32 v80, v84, v86
	global_store_dwordx4 v[96:97], v[80:83], off offset:256
	v_mov_b32_e32 v94, v76
	v_mov_b32_e32 v95, v78
	v_or_b32_e32 v80, 48, v140
	v_ashrrev_i32_e32 v81, 31, v80
	v_lshlrev_b64 v[82:83], 13, v[80:81]
	v_lshlrev_b64 v[80:81], 12, v[80:81]
	v_lshl_add_u64 v[82:83], s[24:25], 0, v[82:83]
	v_lshl_add_u64 v[82:83], v[82:83], 0, s[8:9]
	v_lshl_add_u64 v[80:81], s[26:27], 0, v[80:81]
	v_lshl_add_u64 v[84:85], v[82:83], 0, v[138:139]
	v_lshl_add_u64 v[80:81], v[80:81], 0, v[138:139]
	v_add_u32_e32 v186, 0x80, v140
	v_ashrrev_i32_e32 v187, 31, v186
	v_lshlrev_b64 v[188:189], 13, v[186:187]
	v_lshl_add_u64 v[188:189], s[24:25], 0, v[188:189]
	v_lshl_add_u64 v[188:189], v[188:189], 0, s[8:9]
	v_lshl_add_u64 v[190:191], v[188:189], 0, v[138:139]
	global_load_dwordx4 v[200:203], v[190:191], off
	v_add_u32_e32 v186, 0x80, v140
	v_ashrrev_i32_e32 v187, 31, v186
	v_lshlrev_b64 v[186:187], 12, v[186:187]
	v_lshl_add_u64 v[186:187], s[26:27], 0, v[186:187]
	v_lshl_add_u64 v[186:187], v[186:187], 0, v[138:139]
	global_load_dwordx4 v[214:217], v[186:187], off
	v_or_b32_e32 v186, 0x80, v156
	v_ashrrev_i32_e32 v187, 31, v186
	v_lshlrev_b64 v[188:189], 1, v[186:187]
	v_add_u32_e32 v190, 0x80, v140
	v_ashrrev_i32_e32 v191, 31, v190
	v_lshlrev_b64 v[192:193], 13, v[190:191]
	v_lshl_add_u64 v[192:193], s[24:25], 0, v[192:193]
	v_lshl_add_u64 v[192:193], v[192:193], 0, s[8:9]
	v_lshl_add_u64 v[194:195], v[192:193], 0, v[188:189]
	global_load_dwordx4 v[218:221], v[194:195], off
	v_add_u32_e32 v186, 0x80, v140
	v_ashrrev_i32_e32 v187, 31, v186
	v_lshlrev_b64 v[186:187], 12, v[186:187]
	v_lshl_add_u64 v[186:187], s[26:27], 0, v[186:187]
	v_lshl_add_u64 v[186:187], v[186:187], 0, v[138:139]
	global_load_dwordx4 v[222:225], v[186:187], off offset:256
	v_mov_b32_e32 v78, v77
	s_waitcnt vmcnt(6)
	v_lshlrev_b32_e32 v93, 16, v227
	v_lshlrev_b32_e32 v92, 16, v226
	v_and_b32_e32 v85, 0xffff0000, v227
	v_and_b32_e32 v84, 0xffff0000, v226
	v_lshlrev_b32_e32 v77, 16, v231
	v_lshlrev_b32_e32 v76, 16, v230
	v_and_b32_e32 v89, 0xffff0000, v231
	v_and_b32_e32 v88, 0xffff0000, v230
	v_pk_fma_f32 v[78:79], v[78:79], v[84:85], v[88:89]
	v_lshlrev_b32_e32 v85, 16, v229
	v_lshlrev_b32_e32 v84, 16, v228
	v_mov_b32_e32 v88, v72
	v_mov_b32_e32 v89, v74
	v_mov_b32_e32 v74, v73
	v_lshlrev_b32_e32 v73, 16, v233
	v_lshlrev_b32_e32 v72, 16, v232
	v_and_b32_e32 v87, 0xffff0000, v229
	v_and_b32_e32 v86, 0xffff0000, v228
	v_pk_fma_f32 v[72:73], v[88:89], v[84:85], v[72:73]
	v_and_b32_e32 v85, 0xffff0000, v233
	v_and_b32_e32 v84, 0xffff0000, v232
	v_pk_fma_f32 v[74:75], v[74:75], v[86:87], v[84:85]
	v_pk_fma_f32 v[76:77], v[94:95], v[92:93], v[76:77]
	v_cvt_pk_bf16_f32 v75, v73, v75
	v_cvt_pk_bf16_f32 v74, v72, v74
	v_cvt_pk_bf16_f32 v73, v77, v79
	v_cvt_pk_bf16_f32 v72, v76, v78
	global_store_dwordx4 v[80:81], v[72:75], off
	v_mov_b32_e32 v84, v68
	v_mov_b32_e32 v85, v70
	v_lshl_add_u64 v[72:73], v[82:83], 0, v[124:125]
	s_nop 0
	v_mov_b32_e32 v70, v69
	v_lshlrev_b32_e32 v83, 16, v235
	v_lshlrev_b32_e32 v82, 16, v234
	v_and_b32_e32 v73, 0xffff0000, v235
	v_and_b32_e32 v72, 0xffff0000, v234
	v_lshlrev_b32_e32 v69, 16, v239
	v_lshlrev_b32_e32 v68, 16, v238
	v_and_b32_e32 v77, 0xffff0000, v239
	v_and_b32_e32 v76, 0xffff0000, v238
	v_pk_fma_f32 v[70:71], v[70:71], v[72:73], v[76:77]
	v_lshlrev_b32_e32 v73, 16, v237
	v_lshlrev_b32_e32 v72, 16, v236
	v_mov_b32_e32 v76, v64
	v_mov_b32_e32 v77, v66
	v_mov_b32_e32 v66, v65
	v_lshlrev_b32_e32 v65, 16, v241
	v_lshlrev_b32_e32 v64, 16, v240
	v_and_b32_e32 v75, 0xffff0000, v237
	v_and_b32_e32 v74, 0xffff0000, v236
	v_pk_fma_f32 v[64:65], v[76:77], v[72:73], v[64:65]
	v_and_b32_e32 v73, 0xffff0000, v241
	v_and_b32_e32 v72, 0xffff0000, v240
	v_pk_fma_f32 v[66:67], v[66:67], v[74:75], v[72:73]
	v_pk_fma_f32 v[68:69], v[84:85], v[82:83], v[68:69]
	v_cvt_pk_bf16_f32 v67, v65, v67
	v_cvt_pk_bf16_f32 v66, v64, v66
	v_cvt_pk_bf16_f32 v65, v69, v71
	v_cvt_pk_bf16_f32 v64, v68, v70
	global_store_dwordx4 v[80:81], v[64:67], off offset:256
	v_mov_b32_e32 v78, v60
	v_mov_b32_e32 v79, v62
	v_add_u32_e32 v64, 0x80, v140
	v_ashrrev_i32_e32 v65, 31, v64
	v_lshlrev_b64 v[66:67], 13, v[64:65]
	v_lshlrev_b64 v[64:65], 12, v[64:65]
	v_lshl_add_u64 v[66:67], s[24:25], 0, v[66:67]
	v_lshl_add_u64 v[66:67], v[66:67], 0, s[8:9]
	v_lshl_add_u64 v[64:65], s[26:27], 0, v[64:65]
	v_lshl_add_u64 v[68:69], v[66:67], 0, v[138:139]
	v_lshl_add_u64 v[64:65], v[64:65], 0, v[138:139]
	v_add_u32_e32 v186, 0x90, v140
	v_ashrrev_i32_e32 v187, 31, v186
	v_lshlrev_b64 v[188:189], 13, v[186:187]
	v_lshl_add_u64 v[188:189], s[24:25], 0, v[188:189]
	v_lshl_add_u64 v[188:189], v[188:189], 0, s[8:9]
	v_lshl_add_u64 v[190:191], v[188:189], 0, v[138:139]
	global_load_dwordx4 v[226:229], v[190:191], off
	v_add_u32_e32 v186, 0x90, v140
	v_ashrrev_i32_e32 v187, 31, v186
	v_lshlrev_b64 v[186:187], 12, v[186:187]
	v_lshl_add_u64 v[186:187], s[26:27], 0, v[186:187]
	v_lshl_add_u64 v[186:187], v[186:187], 0, v[138:139]
	global_load_dwordx4 v[230:233], v[186:187], off
	v_or_b32_e32 v186, 0x80, v156
	v_ashrrev_i32_e32 v187, 31, v186
	v_lshlrev_b64 v[188:189], 1, v[186:187]
	v_add_u32_e32 v190, 0x90, v140
	v_ashrrev_i32_e32 v191, 31, v190
	v_lshlrev_b64 v[192:193], 13, v[190:191]
	v_lshl_add_u64 v[192:193], s[24:25], 0, v[192:193]
	v_lshl_add_u64 v[192:193], v[192:193], 0, s[8:9]
	v_lshl_add_u64 v[194:195], v[192:193], 0, v[188:189]
	global_load_dwordx4 v[234:237], v[194:195], off
	v_add_u32_e32 v186, 0x90, v140
	v_ashrrev_i32_e32 v187, 31, v186
	v_lshlrev_b64 v[186:187], 12, v[186:187]
	v_lshl_add_u64 v[186:187], s[26:27], 0, v[186:187]
	v_lshl_add_u64 v[186:187], v[186:187], 0, v[138:139]
	global_load_dwordx4 v[238:241], v[186:187], off offset:256
	v_mov_b32_e32 v62, v61
	s_waitcnt vmcnt(6)
; __device__ __forceinline__ unsigned pk2(float lo, float hi) { return f2bf(lo) | (f2bf(hi) << 16); }
;     __device__ __forceinline__ void operator()(const f32x4 (&acc)[2][2][4][2], const pg8::Unit& u, int wr, int wc, int fr, int fq) const {
;     ...
;                     } else if constexpr (MODE == 2 || MODE == 3) {
;                         const u32x4 g = *(const u32x4*)(aux + row * 4096 + (MODE == 3 ? 2048 : 0) + col);
;                         float r[8] = {v0[0], v0[1], v0[2], v0[3], v1[0], v1[1], v1[2], v1[3]};
;                         const unsigned gw[4] = {g.x, g.y, g.z, g.w};
; #pragma unroll
;                         for (int i = 0; i < 4; ++i) { r[2 * i] *= bf2f(gw[i] & 0xffffu); r[2 * i + 1] *= __builtin_bit_cast(float, gw[i] & 0xffff0000u); }
;                         if constexpr (MODE == 3) { const u32x4 pv = *(const u32x4*)(ob + row * 2048 + col); const unsigned pw[4] = {pv.x, pv.y, pv.z, pv.w};
; #pragma unroll
;                             for (int i = 0; i < 4; ++i) { r[2 * i] += bf2f(pw[i] & 0xffffu); r[2 * i + 1] += __builtin_bit_cast(float, pw[i] & 0xffff0000u); } }
;                         u32x4 w; w.x = pk2(r[0], r[1]); w.y = pk2(r[2], r[3]); w.z = pk2(r[4], r[5]); w.w = pk2(r[6], r[7]);
;                         *(u32x4*)(ob + row * 2048 + col) = w;
	v_lshlrev_b32_e32 v77, 16, v201
	v_lshlrev_b32_e32 v76, 16, v200
	v_and_b32_e32 v69, 0xffff0000, v201
	v_and_b32_e32 v68, 0xffff0000, v200
	v_lshlrev_b32_e32 v61, 16, v215
	v_lshlrev_b32_e32 v60, 16, v214
	v_and_b32_e32 v73, 0xffff0000, v215
	v_and_b32_e32 v72, 0xffff0000, v214
	v_pk_fma_f32 v[62:63], v[62:63], v[68:69], v[72:73]
	v_lshlrev_b32_e32 v69, 16, v203
	v_lshlrev_b32_e32 v68, 16, v202
	v_mov_b32_e32 v72, v56
	v_mov_b32_e32 v73, v58
	v_mov_b32_e32 v58, v57
	v_lshlrev_b32_e32 v57, 16, v217
	v_lshlrev_b32_e32 v56, 16, v216
	v_and_b32_e32 v71, 0xffff0000, v203
	v_and_b32_e32 v70, 0xffff0000, v202
	v_pk_fma_f32 v[56:57], v[72:73], v[68:69], v[56:57]
	v_and_b32_e32 v69, 0xffff0000, v217
	v_and_b32_e32 v68, 0xffff0000, v216
	v_pk_fma_f32 v[58:59], v[58:59], v[70:71], v[68:69]
	v_pk_fma_f32 v[60:61], v[78:79], v[76:77], v[60:61]
	v_cvt_pk_bf16_f32 v59, v57, v59
	v_cvt_pk_bf16_f32 v58, v56, v58
	v_cvt_pk_bf16_f32 v57, v61, v63
	v_cvt_pk_bf16_f32 v56, v60, v62
	global_store_dwordx4 v[64:65], v[56:59], off
	v_mov_b32_e32 v68, v52
	v_mov_b32_e32 v69, v54
	v_lshl_add_u64 v[56:57], v[66:67], 0, v[124:125]
	s_nop 0
	v_mov_b32_e32 v54, v53
	v_lshlrev_b32_e32 v67, 16, v219
	v_lshlrev_b32_e32 v66, 16, v218
	v_and_b32_e32 v57, 0xffff0000, v219
	v_and_b32_e32 v56, 0xffff0000, v218
	v_lshlrev_b32_e32 v53, 16, v223
	v_lshlrev_b32_e32 v52, 16, v222
	v_and_b32_e32 v61, 0xffff0000, v223
	v_and_b32_e32 v60, 0xffff0000, v222
	v_pk_fma_f32 v[54:55], v[54:55], v[56:57], v[60:61]
	v_lshlrev_b32_e32 v57, 16, v221
	v_lshlrev_b32_e32 v56, 16, v220
	v_mov_b32_e32 v60, v48
	v_mov_b32_e32 v61, v50
	v_mov_b32_e32 v50, v49
	v_lshlrev_b32_e32 v49, 16, v225
	v_lshlrev_b32_e32 v48, 16, v224
	v_and_b32_e32 v59, 0xffff0000, v221
	v_and_b32_e32 v58, 0xffff0000, v220
	v_pk_fma_f32 v[48:49], v[60:61], v[56:57], v[48:49]
	v_and_b32_e32 v57, 0xffff0000, v225
	v_and_b32_e32 v56, 0xffff0000, v224
	v_pk_fma_f32 v[50:51], v[50:51], v[58:59], v[56:57]
	v_pk_fma_f32 v[52:53], v[68:69], v[66:67], v[52:53]
	v_cvt_pk_bf16_f32 v51, v49, v51
	v_cvt_pk_bf16_f32 v50, v48, v50
	v_cvt_pk_bf16_f32 v49, v53, v55
	v_cvt_pk_bf16_f32 v48, v52, v54
	global_store_dwordx4 v[64:65], v[48:51], off offset:256
	v_mov_b32_e32 v62, v44
	v_mov_b32_e32 v63, v46
	v_add_u32_e32 v48, 0x90, v140
	v_ashrrev_i32_e32 v49, 31, v48
	v_lshlrev_b64 v[50:51], 13, v[48:49]
	v_lshlrev_b64 v[48:49], 12, v[48:49]
	v_lshl_add_u64 v[50:51], s[24:25], 0, v[50:51]
	v_lshl_add_u64 v[50:51], v[50:51], 0, s[8:9]
	v_lshl_add_u64 v[48:49], s[26:27], 0, v[48:49]
	v_lshl_add_u64 v[52:53], v[50:51], 0, v[138:139]
	v_lshl_add_u64 v[48:49], v[48:49], 0, v[138:139]
	v_add_u32_e32 v186, 0xa0, v140
	v_ashrrev_i32_e32 v187, 31, v186
	v_lshlrev_b64 v[188:189], 13, v[186:187]
	v_lshl_add_u64 v[188:189], s[24:25], 0, v[188:189]
	v_lshl_add_u64 v[188:189], v[188:189], 0, s[8:9]
	v_lshl_add_u64 v[190:191], v[188:189], 0, v[138:139]
	global_load_dwordx4 v[200:203], v[190:191], off
	v_add_u32_e32 v186, 0xa0, v140
	v_ashrrev_i32_e32 v187, 31, v186
	v_lshlrev_b64 v[186:187], 12, v[186:187]
	v_lshl_add_u64 v[186:187], s[26:27], 0, v[186:187]
	v_lshl_add_u64 v[186:187], v[186:187], 0, v[138:139]
	global_load_dwordx4 v[214:217], v[186:187], off
	v_or_b32_e32 v186, 0x80, v156
	v_ashrrev_i32_e32 v187, 31, v186
	v_lshlrev_b64 v[188:189], 1, v[186:187]
	v_add_u32_e32 v190, 0xa0, v140
	v_ashrrev_i32_e32 v191, 31, v190
	v_lshlrev_b64 v[192:193], 13, v[190:191]
	v_lshl_add_u64 v[192:193], s[24:25], 0, v[192:193]
	v_lshl_add_u64 v[192:193], v[192:193], 0, s[8:9]
	v_lshl_add_u64 v[194:195], v[192:193], 0, v[188:189]
	global_load_dwordx4 v[218:221], v[194:195], off
	v_add_u32_e32 v186, 0xa0, v140
	v_ashrrev_i32_e32 v187, 31, v186
	v_lshlrev_b64 v[186:187], 12, v[186:187]
	v_lshl_add_u64 v[186:187], s[26:27], 0, v[186:187]
	v_lshl_add_u64 v[186:187], v[186:187], 0, v[138:139]
	global_load_dwordx4 v[222:225], v[186:187], off offset:256
	v_mov_b32_e32 v46, v45
	s_waitcnt vmcnt(6)
	v_lshlrev_b32_e32 v61, 16, v227
	v_lshlrev_b32_e32 v60, 16, v226
	v_and_b32_e32 v53, 0xffff0000, v227
	v_and_b32_e32 v52, 0xffff0000, v226
	v_lshlrev_b32_e32 v45, 16, v231
	v_lshlrev_b32_e32 v44, 16, v230
	v_and_b32_e32 v57, 0xffff0000, v231
	v_and_b32_e32 v56, 0xffff0000, v230
	v_pk_fma_f32 v[46:47], v[46:47], v[52:53], v[56:57]
	v_lshlrev_b32_e32 v53, 16, v229
	v_lshlrev_b32_e32 v52, 16, v228
	v_mov_b32_e32 v56, v40
	v_mov_b32_e32 v57, v42
	v_mov_b32_e32 v42, v41
	v_lshlrev_b32_e32 v41, 16, v233
	v_lshlrev_b32_e32 v40, 16, v232
	v_and_b32_e32 v55, 0xffff0000, v229
	v_and_b32_e32 v54, 0xffff0000, v228
	v_pk_fma_f32 v[40:41], v[56:57], v[52:53], v[40:41]
	v_and_b32_e32 v53, 0xffff0000, v233
	v_and_b32_e32 v52, 0xffff0000, v232
	v_pk_fma_f32 v[42:43], v[42:43], v[54:55], v[52:53]
	v_pk_fma_f32 v[44:45], v[62:63], v[60:61], v[44:45]
	v_cvt_pk_bf16_f32 v43, v41, v43
	v_cvt_pk_bf16_f32 v42, v40, v42
	v_cvt_pk_bf16_f32 v41, v45, v47
	v_cvt_pk_bf16_f32 v40, v44, v46
	global_store_dwordx4 v[48:49], v[40:43], off
	v_mov_b32_e32 v52, v36
	v_mov_b32_e32 v53, v38
	v_lshl_add_u64 v[40:41], v[50:51], 0, v[124:125]
	s_nop 0
	v_mov_b32_e32 v38, v37
	v_lshlrev_b32_e32 v51, 16, v235
	v_lshlrev_b32_e32 v50, 16, v234
	v_and_b32_e32 v41, 0xffff0000, v235
	v_and_b32_e32 v40, 0xffff0000, v234
	v_lshlrev_b32_e32 v37, 16, v239
	v_lshlrev_b32_e32 v36, 16, v238
	v_and_b32_e32 v45, 0xffff0000, v239
	v_and_b32_e32 v44, 0xffff0000, v238
	v_pk_fma_f32 v[38:39], v[38:39], v[40:41], v[44:45]
	v_lshlrev_b32_e32 v41, 16, v237
	v_lshlrev_b32_e32 v40, 16, v236
	v_mov_b32_e32 v44, v32
	v_mov_b32_e32 v45, v34
	v_mov_b32_e32 v34, v33
	v_lshlrev_b32_e32 v33, 16, v241
	v_lshlrev_b32_e32 v32, 16, v240
	v_and_b32_e32 v43, 0xffff0000, v237
; __device__ __forceinline__ unsigned pk2(float lo, float hi) { return f2bf(lo) | (f2bf(hi) << 16); }
; template <class Epi, class Sched, bool ALIGN_EPI = false, bool SP2 = false, bool F8 = false>
; __device__ __forceinline__ void gemm_phase(PG8_LAS unsigned char* lds, const Gemm g, const Sched& S, const Epi& E) {
;     ...
;         if constexpr (!Epi::AFTER_DRAIN) { E(acc, cur, wr, wc, fr, fq); S.done(cur); }
;         if (!has_next) break;
;     __device__ __forceinline__ void operator()(const f32x4 (&acc)[2][2][4][2], const pg8::Unit& u, int wr, int wc, int fr, int fq) const {
;     ...
;                     } else if constexpr (MODE == 2 || MODE == 3) {
;                         const u32x4 g = *(const u32x4*)(aux + row * 4096 + (MODE == 3 ? 2048 : 0) + col);
;                         float r[8] = {v0[0], v0[1], v0[2], v0[3], v1[0], v1[1], v1[2], v1[3]};
;                         const unsigned gw[4] = {g.x, g.y, g.z, g.w};
; #pragma unroll
;                         for (int i = 0; i < 4; ++i) { r[2 * i] *= bf2f(gw[i] & 0xffffu); r[2 * i + 1] *= __builtin_bit_cast(float, gw[i] & 0xffff0000u); }
;                         if constexpr (MODE == 3) { const u32x4 pv = *(const u32x4*)(ob + row * 2048 + col); const unsigned pw[4] = {pv.x, pv.y, pv.z, pv.w};
; #pragma unroll
;                             for (int i = 0; i < 4; ++i) { r[2 * i] += bf2f(pw[i] & 0xffffu); r[2 * i + 1] += __builtin_bit_cast(float, pw[i] & 0xffff0000u); } }
;                         u32x4 w; w.x = pk2(r[0], r[1]); w.y = pk2(r[2], r[3]); w.z = pk2(r[4], r[5]); w.w = pk2(r[6], r[7]);
;                         *(u32x4*)(ob + row * 2048 + col) = w;
	v_and_b32_e32 v42, 0xffff0000, v236
	v_pk_fma_f32 v[32:33], v[44:45], v[40:41], v[32:33]
	v_and_b32_e32 v41, 0xffff0000, v241
	v_and_b32_e32 v40, 0xffff0000, v240
	v_pk_fma_f32 v[34:35], v[34:35], v[42:43], v[40:41]
	v_pk_fma_f32 v[36:37], v[52:53], v[50:51], v[36:37]
	v_cvt_pk_bf16_f32 v35, v33, v35
	v_cvt_pk_bf16_f32 v34, v32, v34
	v_cvt_pk_bf16_f32 v33, v37, v39
	v_cvt_pk_bf16_f32 v32, v36, v38
	global_store_dwordx4 v[48:49], v[32:35], off offset:256
	v_mov_b32_e32 v46, v28
	v_mov_b32_e32 v47, v30
	v_add_u32_e32 v32, 0xa0, v140
	v_ashrrev_i32_e32 v33, 31, v32
	v_lshlrev_b64 v[34:35], 13, v[32:33]
	v_lshlrev_b64 v[32:33], 12, v[32:33]
	v_lshl_add_u64 v[34:35], s[24:25], 0, v[34:35]
	v_lshl_add_u64 v[34:35], v[34:35], 0, s[8:9]
	v_lshl_add_u64 v[32:33], s[26:27], 0, v[32:33]
	v_lshl_add_u64 v[36:37], v[34:35], 0, v[138:139]
	v_lshl_add_u64 v[32:33], v[32:33], 0, v[138:139]
	v_add_u32_e32 v186, 0xb0, v140
	v_ashrrev_i32_e32 v187, 31, v186
	v_lshlrev_b64 v[188:189], 13, v[186:187]
	v_lshl_add_u64 v[188:189], s[24:25], 0, v[188:189]
	v_lshl_add_u64 v[188:189], v[188:189], 0, s[8:9]
	v_lshl_add_u64 v[190:191], v[188:189], 0, v[138:139]
	global_load_dwordx4 v[226:229], v[190:191], off
	v_add_u32_e32 v186, 0xb0, v140
	v_ashrrev_i32_e32 v187, 31, v186
	v_lshlrev_b64 v[186:187], 12, v[186:187]
	v_lshl_add_u64 v[186:187], s[26:27], 0, v[186:187]
	v_lshl_add_u64 v[186:187], v[186:187], 0, v[138:139]
	global_load_dwordx4 v[230:233], v[186:187], off
	v_or_b32_e32 v186, 0x80, v156
	v_ashrrev_i32_e32 v187, 31, v186
	v_lshlrev_b64 v[188:189], 1, v[186:187]
	v_add_u32_e32 v190, 0xb0, v140
	v_ashrrev_i32_e32 v191, 31, v190
	v_lshlrev_b64 v[192:193], 13, v[190:191]
	v_lshl_add_u64 v[192:193], s[24:25], 0, v[192:193]
	v_lshl_add_u64 v[192:193], v[192:193], 0, s[8:9]
	v_lshl_add_u64 v[194:195], v[192:193], 0, v[188:189]
	global_load_dwordx4 v[234:237], v[194:195], off
	v_add_u32_e32 v186, 0xb0, v140
	v_ashrrev_i32_e32 v187, 31, v186
	v_lshlrev_b64 v[186:187], 12, v[186:187]
	v_lshl_add_u64 v[186:187], s[26:27], 0, v[186:187]
	v_lshl_add_u64 v[186:187], v[186:187], 0, v[138:139]
	global_load_dwordx4 v[238:241], v[186:187], off offset:256
	v_mov_b32_e32 v30, v29
	s_waitcnt vmcnt(6)
	v_lshlrev_b32_e32 v45, 16, v201
	v_lshlrev_b32_e32 v44, 16, v200
	v_and_b32_e32 v37, 0xffff0000, v201
	v_and_b32_e32 v36, 0xffff0000, v200
	v_lshlrev_b32_e32 v29, 16, v215
	v_lshlrev_b32_e32 v28, 16, v214
	v_and_b32_e32 v41, 0xffff0000, v215
	v_and_b32_e32 v40, 0xffff0000, v214
	v_pk_fma_f32 v[30:31], v[30:31], v[36:37], v[40:41]
	v_lshlrev_b32_e32 v37, 16, v203
	v_lshlrev_b32_e32 v36, 16, v202
	v_mov_b32_e32 v40, v24
	v_mov_b32_e32 v41, v26
	v_mov_b32_e32 v26, v25
	v_lshlrev_b32_e32 v25, 16, v217
	v_lshlrev_b32_e32 v24, 16, v216
	v_and_b32_e32 v39, 0xffff0000, v203
	v_and_b32_e32 v38, 0xffff0000, v202
	v_pk_fma_f32 v[24:25], v[40:41], v[36:37], v[24:25]
	v_and_b32_e32 v37, 0xffff0000, v217
	v_and_b32_e32 v36, 0xffff0000, v216
	v_pk_fma_f32 v[26:27], v[26:27], v[38:39], v[36:37]
	v_pk_fma_f32 v[28:29], v[46:47], v[44:45], v[28:29]
	v_cvt_pk_bf16_f32 v27, v25, v27
	v_cvt_pk_bf16_f32 v26, v24, v26
	v_cvt_pk_bf16_f32 v25, v29, v31
	v_cvt_pk_bf16_f32 v24, v28, v30
	global_store_dwordx4 v[32:33], v[24:27], off
	v_mov_b32_e32 v36, v20
	v_mov_b32_e32 v37, v22
	v_lshl_add_u64 v[24:25], v[34:35], 0, v[124:125]
	s_nop 0
	v_mov_b32_e32 v22, v21
	v_lshlrev_b32_e32 v35, 16, v219
	v_lshlrev_b32_e32 v34, 16, v218
	v_and_b32_e32 v25, 0xffff0000, v219
	v_and_b32_e32 v24, 0xffff0000, v218
	v_lshlrev_b32_e32 v21, 16, v223
	v_lshlrev_b32_e32 v20, 16, v222
	v_and_b32_e32 v29, 0xffff0000, v223
	v_and_b32_e32 v28, 0xffff0000, v222
	v_pk_fma_f32 v[22:23], v[22:23], v[24:25], v[28:29]
	v_lshlrev_b32_e32 v25, 16, v221
	v_lshlrev_b32_e32 v24, 16, v220
	v_mov_b32_e32 v28, v16
	v_mov_b32_e32 v29, v18
	v_mov_b32_e32 v18, v17
	v_lshlrev_b32_e32 v17, 16, v225
	v_lshlrev_b32_e32 v16, 16, v224
	v_and_b32_e32 v27, 0xffff0000, v221
	v_and_b32_e32 v26, 0xffff0000, v220
	v_pk_fma_f32 v[16:17], v[28:29], v[24:25], v[16:17]
	v_and_b32_e32 v25, 0xffff0000, v225
	v_and_b32_e32 v24, 0xffff0000, v224
	v_pk_fma_f32 v[18:19], v[18:19], v[26:27], v[24:25]
	v_pk_fma_f32 v[20:21], v[36:37], v[34:35], v[20:21]
	v_cvt_pk_bf16_f32 v19, v17, v19
	v_cvt_pk_bf16_f32 v18, v16, v18
	v_cvt_pk_bf16_f32 v17, v21, v23
	v_cvt_pk_bf16_f32 v16, v20, v22
	global_store_dwordx4 v[32:33], v[16:19], off offset:256
	v_mov_b32_e32 v30, v12
	v_mov_b32_e32 v31, v14
	v_add_u32_e32 v16, 0xb0, v140
	v_ashrrev_i32_e32 v17, 31, v16
	v_lshlrev_b64 v[18:19], 13, v[16:17]
	v_lshlrev_b64 v[16:17], 12, v[16:17]
	v_lshl_add_u64 v[18:19], s[24:25], 0, v[18:19]
	v_lshl_add_u64 v[18:19], v[18:19], 0, s[8:9]
	v_lshl_add_u64 v[16:17], s[26:27], 0, v[16:17]
	v_lshl_add_u64 v[20:21], v[18:19], 0, v[138:139]
	v_lshl_add_u64 v[16:17], v[16:17], 0, v[138:139]
	v_mov_b32_e32 v14, v13
	s_waitcnt vmcnt(2)
	v_lshlrev_b32_e32 v29, 16, v227
	v_lshlrev_b32_e32 v28, 16, v226
	v_and_b32_e32 v21, 0xffff0000, v227
	v_and_b32_e32 v20, 0xffff0000, v226
	v_lshlrev_b32_e32 v13, 16, v231
	v_lshlrev_b32_e32 v12, 16, v230
	v_and_b32_e32 v25, 0xffff0000, v231
	v_and_b32_e32 v24, 0xffff0000, v230
	v_pk_fma_f32 v[14:15], v[14:15], v[20:21], v[24:25]
	v_lshlrev_b32_e32 v21, 16, v229
	v_lshlrev_b32_e32 v20, 16, v228
	v_mov_b32_e32 v24, v8
	v_mov_b32_e32 v25, v10
	v_mov_b32_e32 v10, v9
	v_lshlrev_b32_e32 v9, 16, v233
	v_lshlrev_b32_e32 v8, 16, v232
	v_and_b32_e32 v23, 0xffff0000, v229
	v_and_b32_e32 v22, 0xffff0000, v228
	v_pk_fma_f32 v[8:9], v[24:25], v[20:21], v[8:9]
	v_and_b32_e32 v21, 0xffff0000, v233
	v_and_b32_e32 v20, 0xffff0000, v232
	v_pk_fma_f32 v[10:11], v[10:11], v[22:23], v[20:21]
	v_pk_fma_f32 v[12:13], v[30:31], v[28:29], v[12:13]
	v_cvt_pk_bf16_f32 v11, v9, v11
	v_cvt_pk_bf16_f32 v10, v8, v10
	v_cvt_pk_bf16_f32 v9, v13, v15
	v_cvt_pk_bf16_f32 v8, v12, v14
	global_store_dwordx4 v[16:17], v[8:11], off
	v_mov_b32_e32 v20, v4
	v_mov_b32_e32 v21, v6
	v_lshl_add_u64 v[8:9], v[18:19], 0, v[124:125]
	s_nop 0
	v_mov_b32_e32 v6, v5
	v_lshlrev_b32_e32 v19, 16, v235
	v_lshlrev_b32_e32 v18, 16, v234
	v_and_b32_e32 v13, 0xffff0000, v235
	v_and_b32_e32 v12, 0xffff0000, v234
	v_lshlrev_b32_e32 v5, 16, v239
	v_lshlrev_b32_e32 v4, 16, v238
	v_and_b32_e32 v9, 0xffff0000, v239
	v_and_b32_e32 v8, 0xffff0000, v238
	v_pk_fma_f32 v[6:7], v[6:7], v[12:13], v[8:9]
	v_lshlrev_b32_e32 v9, 16, v237
	v_lshlrev_b32_e32 v8, 16, v236
	v_mov_b32_e32 v12, v0
	v_mov_b32_e32 v13, v2
	v_mov_b32_e32 v2, v1
	v_lshlrev_b32_e32 v1, 16, v241
	v_lshlrev_b32_e32 v0, 16, v240
	v_and_b32_e32 v15, 0xffff0000, v237
	v_and_b32_e32 v14, 0xffff0000, v236
	v_pk_fma_f32 v[0:1], v[12:13], v[8:9], v[0:1]
	v_and_b32_e32 v9, 0xffff0000, v241
	v_and_b32_e32 v8, 0xffff0000, v240
	v_pk_fma_f32 v[2:3], v[2:3], v[14:15], v[8:9]
	v_pk_fma_f32 v[4:5], v[20:21], v[18:19], v[4:5]
	v_cvt_pk_bf16_f32 v3, v1, v3
	v_cvt_pk_bf16_f32 v2, v0, v2
	v_cvt_pk_bf16_f32 v1, v5, v7
	v_cvt_pk_bf16_f32 v0, v4, v6
	global_store_dwordx4 v[16:17], v[0:3], off offset:256
	s_mov_b32 s101, 1
	s_cbranch_vccnz .LBB0_109
; #define PG8_BAR __builtin_amdgcn_s_barrier()
; template <class Epi, class Sched, bool ALIGN_EPI = false, bool SP2 = false, bool F8 = false>
; __device__ __forceinline__ void gemm_phase(PG8_LAS unsigned char* lds, const Gemm g, const Sched& S, const Epi& E) {
;     ...
;         if (!has_next) break;
; #pragma unroll
;         for (int a = 0; a < 2; ++a)
; #pragma unroll
;             for (int b = 0; b < 2; ++b)
; #pragma unroll
;                 for (int m = 0; m < 4; ++m)
; #pragma unroll
;                     for (int n = 0; n < 2; ++n) acc[a][b][m][n] = (f32x4){0.f, 0.f, 0.f, 0.f};
;         cur = nxt; cA = nA; cB = nB; ++ui;
;         if constexpr (ALIGN_EPI) { if (wr == 1) PG8_BAR; }
	s_andn2_b64 vcc, exec, s[0:1]
	s_cbranch_vccnz .LBB0_108
	s_barrier
	s_branch .LBB0_108

; #define PG8_STAGE(bufoff, gbase, voff) do { _Pragma("unroll") for (int _i = 0; _i < 2; ++_i) \
;         __builtin_amdgcn_global_load_lds((const unsigned*)((const char*)(gbase) + (voff)[_i]), (PG8_LAS unsigned*)(lds + (bufoff) + ldsw + _i * 8192), 16, 0, 0); } while (0)
; #define PG8_WAIT_V(n) asm volatile("s_waitcnt vmcnt(" #n ")" ::: "memory")
; #define PG8_BAR __builtin_amdgcn_s_barrier()
; template <class Epi, class Sched, bool ALIGN_EPI = false, bool SP2 = false, bool F8 = false>
; __device__ __forceinline__ void gemm_phase(PG8_LAS unsigned char* lds, const Gemm g, const Sched& S, const Epi& E) {
;     int tid_ = threadIdx.x; asm volatile("" : "+v"(tid_)); const int tid = tid_, wid = __builtin_amdgcn_readfirstlane(tid >> 6), lane = tid & 63, wr = wid >> 2, wc = wid & 3, fr = lane & 15, fq = lane >> 4;
;     const int K = g.K, nt = K / BK;
;     unsigned voffA[2], voffB[2];
; #pragma unroll
;     for (int i = 0; i < 2; ++i) { int R, C; stage_rc(tid * 16 + i * 8192, R, C); const int Rb = Epi::PERM ? ((R & ~31) + perm32(R & 31)) : R;
;         voffA[i] = (unsigned)(R * K + C) * 2u; voffB[i] = (unsigned)(Rb * K + C) * 2u; }
;     const size_t kstep = (size_t)(BK * 2);
;     const size_t hstep = (size_t)HALF * K * 2;
;     const size_t tstep = 2 * hstep;
;     const unsigned ldsw = (unsigned)wid * 1024u;
;     const int aoff = lds_byte(wr * 64 + fr, fq * 8), boff = lds_byte(wc * 32 + fr, fq * 8);
;     ...
;         PG8_STAGE(PG8_SB(0, 0), cB, voffB); PG8_STAGE(PG8_SB(0, 1), cB + hstep, voffB); PG8_STAGE(PG8_SA(0, 0), cA, voffA); PG8_STAGE(PG8_SA(0, 1), cA + hstep, voffA);
;         if (wr == 1) PG8_BAR;
;         PG8_WAIT_V(2); PG8_BAR;
;         PG8_STAGE(PG8_SB(1, 0), cB + kstep, voffB); PG8_STAGE(PG8_SA(1, 0), cA + kstep, voffA); PG8_STAGE(PG8_SB(1, 1), cB + hstep + kstep, voffB);
;         PG8_WAIT_V(6); PG8_BAR;
.LBB0_1112:
	v_lshrrev_b32_e32 v16, 1, v10
	v_and_b32_e32 v16, 24, v16
	s_lshl_b32 s4, s4, 5
	v_and_b32_e32 v11, 15, v10
	v_lshlrev_b32_e32 v17, 1, v16
	v_lshlrev_b32_e32 v10, 2, v10
	s_and_b32 s9, s4, 0x60
	v_lshl_or_b32 v203, s5, 6, v11
	v_lshl_or_b32 v11, v11, 6, v17
	v_and_b32_e32 v10, 32, v10
	s_lshl_b32 s4, s9, 7
	v_bitop3_b32 v213, v11, s4, v10 bitop3:0xde
	v_readlane_b32 s4, v250, 28
	v_readlane_b32 s68, v254, 42
	s_lshl_b32 s5, s5, 13
	s_lshl_b32 s4, s4, 14
	v_readlane_b32 s76, v254, 50
	v_readlane_b32 s28, v253, 62
	v_readlane_b32 s77, v254, 51
	s_add_u32 s4, s76, s4
	v_mov_b32_e32 v189, v161
	v_readlane_b32 s29, v253, 63
	v_bitop3_b32 v17, v11, s5, v10 bitop3:0xde
	s_addc_u32 s5, s77, 0
	s_add_i32 m0, s51, 0x18000
	v_lshl_add_u64 v[0:1], v[0:1], 0, s[14:15]
	v_lshl_add_u64 v[12:13], s[28:29], 0, v[188:189]
	v_mov_b32_e32 v187, v161
	s_waitcnt vmcnt(2)
	s_barrier
	global_load_lds_dwordx4 v[0:1], off
	v_lshl_add_u64 v[0:1], v[2:3], 0, s[14:15]
	s_add_i32 m0, s51, 0x1a000
	s_add_i32 s55, s51, 0x8000
	s_add_i32 s58, s51, 0xa000
	v_lshl_add_u64 v[14:15], s[28:29], 0, v[186:187]
	global_load_lds_dwordx4 v[0:1], off
	v_lshl_add_u64 v[0:1], v[12:13], 0, s[14:15]
	s_mov_b32 m0, s55
	s_add_u32 s10, s36, 0x40080
	global_load_lds_dwordx4 v[0:1], off
	v_lshl_add_u64 v[0:1], v[14:15], 0, s[14:15]
	s_mov_b32 m0, s58
	s_addc_u32 s11, s37, 0
	global_load_lds_dwordx4 v[0:1], off
	s_add_i32 m0, s51, 0x1c000
	v_lshl_add_u64 v[0:1], s[10:11], 0, v[160:161]
	global_load_lds_dwordx4 v[0:1], off
	v_lshl_add_u64 v[0:1], s[10:11], 0, v[184:185]
	s_add_i32 m0, s51, 0x1e000
	v_readlane_b32 s69, v254, 43
	global_load_lds_dwordx4 v[0:1], off
	v_lshlrev_b32_e32 v0, 14, v8
	v_and_b32_e32 v0, 0xffff8000, v0
	v_lshl_add_u32 v0, v7, 11, v0
	v_and_b32_e32 v1, 1, v8
	v_lshl_or_b32 v0, v1, 6, v0
	v_lshl_add_u32 v190, v9, 1, v0
	v_lshlrev_b32_e32 v0, 14, v4
	v_and_b32_e32 v0, 0xffff8000, v0
	v_readlane_b32 s70, v254, 44
	v_readlane_b32 s71, v254, 45
	v_readlane_b32 s72, v254, 46
	v_readlane_b32 s73, v254, 47
	v_readlane_b32 s74, v254, 48
	v_readlane_b32 s75, v254, 49
	v_readlane_b32 s78, v254, 52
	v_readlane_b32 s79, v254, 53
	v_readlane_b32 s80, v254, 54
	v_readlane_b32 s81, v254, 55
	v_readlane_b32 s82, v254, 56
	v_readlane_b32 s83, v254, 57
	s_waitcnt vmcnt(6)
	v_lshl_add_u32 v0, v5, 11, v0
	v_and_b32_e32 v1, 1, v4
	v_readlane_b32 s10, v253, 57
	s_cmpk_lt_u32 s8, 0x100
	v_lshl_or_b32 v0, v1, 6, v0
	v_readlane_b32 s11, v253, 58
	v_readlane_b32 s68, v250, 0
	s_cselect_b64 s[16:17], -1, 0
	v_or_b32_e32 v214, s9, v16
	v_mov_b32_e32 v191, v161
	v_lshl_add_u32 v192, v6, 1, v0
	v_mov_b32_e32 v193, v161
	s_mov_b32 s59, 0
	v_add_u32_e32 v215, 0, v17
	v_readlane_b32 s8, v253, 54
	s_mov_b32 s9, s10
	s_mov_b64 s[10:11], s[28:29]
	v_readlane_b32 s69, v250, 1
	v_readlane_b32 s70, v250, 2
	v_readlane_b32 s71, v250, 3
	v_readlane_b32 s72, v250, 4
	v_readlane_b32 s73, v250, 5
	v_readlane_b32 s76, v250, 8
	v_readlane_b32 s77, v250, 9
	v_readlane_b32 s78, v250, 10
	v_readlane_b32 s79, v250, 11
	v_readlane_b32 s80, v250, 12
	v_readlane_b32 s81, v250, 13
	v_readlane_b32 s82, v250, 14
	v_readlane_b32 s83, v250, 15
	s_barrier
	v_readlane_b32 s74, v250, 6
	v_readlane_b32 s75, v250, 7
	s_mov_b32 s101, 0
	s_branch .LBB0_1115

; #define PG8_STAGE(bufoff, gbase, voff) do { _Pragma("unroll") for (int _i = 0; _i < 2; ++_i) \
;         __builtin_amdgcn_global_load_lds((const unsigned*)((const char*)(gbase) + (voff)[_i]), (PG8_LAS unsigned*)(lds + (bufoff) + ldsw + _i * 8192), 16, 0, 0); } while (0)
; #define PG8_WAIT_V(n) asm volatile("s_waitcnt vmcnt(" #n ")" ::: "memory")
; #define PG8_WAIT_L(n) asm volatile("s_waitcnt lgkmcnt(" #n ")" ::: "memory")
; #define PG8_BAR __builtin_amdgcn_s_barrier()
; #define PG8_SCHED __builtin_amdgcn_sched_barrier(0)
; template <class Epi, class Sched, bool ALIGN_EPI = false, bool SP2 = false, bool F8 = false>
; __device__ __forceinline__ void gemm_phase(PG8_LAS unsigned char* lds, const Gemm g, const Sched& S, const Epi& E) {
;     ...
;             PG8_LDB(B0, 0, 0); PG8_LDB(B1, 0, 1); PG8_SCHED; PG8_LDA(At, 0, 0); PG8_STAGE(PG8_SA(1, 1), a1 + hstep, voffA);
;             PG8_WAIT_V(8); PG8_WAIT_L(0); PG8_BAR; PG8_MMA(0, 0, At, B0); PG8_MMA(0, 1, At, B1); PG8_BAR; PG8_SCHED;
;             PG8_LDA(At, 0, 1); PG8_STAGE(PG8_SB(0, 0), b2, voffB); PG8_STAGE(PG8_SB(0, 1), b2 + hstep, voffB); PG8_STAGE(PG8_SA(0, 0), a2, voffA);
.LBB0_1121:
	s_ashr_i32 s43, s42, 31
	s_lshl_b64 s[28:29], s[42:43], 19
	v_readlane_b32 s19, v253, 59
	s_add_u32 s44, s19, s28
	v_readlane_b32 s19, v253, 60
	s_addc_u32 s45, s19, s29
	s_and_b64 s[28:29], s[38:39], exec
	s_cselect_b32 s19, s45, s11
	s_cselect_b32 s23, s44, s10
	s_ashr_i32 s41, s40, 31
	s_lshl_b64 s[28:29], s[40:41], 19
	s_add_u32 s46, s22, s28
	s_addc_u32 s47, s50, s29
	s_and_b64 s[28:29], s[38:39], exec
	s_cselect_b32 s28, s47, s37
	s_cselect_b32 s29, s46, s36
	s_add_u32 s10, s10, 0x40080
	s_addc_u32 s11, s11, 0
	s_add_u32 s34, s36, 0x100
	s_addc_u32 s35, s37, 0
	s_mov_b32 s41, -2
	s_add_u32 s36, s10, 0xfffc0080
	s_addc_u32 s37, s11, -1
	s_add_i32 s43, 0, 0x10000
	s_cmp_eq_u32 s41, 12
	s_cselect_b32 s49, s19, s37
	s_cselect_b32 s48, s23, s36
	s_cselect_b32 s37, s28, s35
	s_cselect_b32 s36, s29, s34
	s_add_i32 s56, 0, 0x14000
	v_add_u32_e32 v0, s43, v213
	v_add_u32_e32 v12, s56, v213
	ds_read_b128 v[16:19], v0
	ds_read_b128 v[20:23], v0 offset:1024
	ds_read_b128 v[24:27], v0 offset:2048
	ds_read_b128 v[28:31], v0 offset:3072
	ds_read_b128 v[0:3], v12
	ds_read_b128 v[4:7], v12 offset:1024
	ds_read_b128 v[8:11], v12 offset:2048
	ds_read_b128 v[12:15], v12 offset:3072
	v_lshl_add_u64 v[162:163], s[10:11], 0, v[190:191]
	s_add_i32 m0, s51, 0xc000
	ds_read_b128 v[194:197], v215
	ds_read_b128 v[198:201], v215 offset:1024
	ds_read_b128 v[216:219], v215 offset:2048
	ds_read_b128 v[220:223], v215 offset:3072
	ds_read_b128 v[224:227], v215 offset:4096
	ds_read_b128 v[228:231], v215 offset:5120
	ds_read_b128 v[232:235], v215 offset:6144
	ds_read_b128 v[236:239], v215 offset:7168
	global_load_lds_dwordx4 v[162:163], off
	v_lshl_add_u64 v[162:163], s[10:11], 0, v[192:193]
	s_add_i32 m0, s51, 0xe000
	s_nop 0
	global_load_lds_dwordx4 v[162:163], off
	s_cmp_lg_u32 s101, 0
	s_cbranch_scc1 .Lgk_nw1_1122
	s_waitcnt vmcnt(8)
.Lgk_nw1_1122:
	s_waitcnt lgkmcnt(0)
	s_barrier
	s_setprio 1
	s_waitcnt lgkmcnt(0)
	v_mfma_scale_f32_16x16x128_f8f6f4 v[156:159], v[16:23], v[194:201], 0, v202, v202 op_sel_hi:[0,0,0]
	v_mfma_scale_f32_16x16x128_f8f6f4 v[152:155], v[24:31], v[194:201], 0, v202, v202 op_sel_hi:[0,0,0]
	v_mfma_scale_f32_16x16x128_f8f6f4 v[140:143], v[16:23], v[216:223], 0, v202, v202 op_sel_hi:[0,0,0]
	v_mfma_scale_f32_16x16x128_f8f6f4 v[136:139], v[24:31], v[216:223], 0, v202, v202 op_sel_hi:[0,0,0]
	v_mfma_scale_f32_16x16x128_f8f6f4 v[124:127], v[16:23], v[224:231], 0, v202, v202 op_sel_hi:[0,0,0]
	v_mfma_scale_f32_16x16x128_f8f6f4 v[120:123], v[24:31], v[224:231], 0, v202, v202 op_sel_hi:[0,0,0]
	v_mfma_scale_f32_16x16x128_f8f6f4 v[108:111], v[16:23], v[232:239], 0, v202, v202 op_sel_hi:[0,0,0]
	v_mfma_scale_f32_16x16x128_f8f6f4 v[104:107], v[24:31], v[232:239], 0, v202, v202 op_sel_hi:[0,0,0]
	s_setprio 0
	s_setprio 1
	v_mfma_scale_f32_16x16x128_f8f6f4 v[148:151], v[0:7], v[194:201], 0, v202, v202 op_sel_hi:[0,0,0]
	v_mfma_scale_f32_16x16x128_f8f6f4 v[144:147], v[8:15], v[194:201], 0, v202, v202 op_sel_hi:[0,0,0]
	v_mfma_scale_f32_16x16x128_f8f6f4 v[132:135], v[0:7], v[216:223], 0, v202, v202 op_sel_hi:[0,0,0]
	v_mfma_scale_f32_16x16x128_f8f6f4 v[128:131], v[8:15], v[216:223], 0, v202, v202 op_sel_hi:[0,0,0]
	v_mfma_scale_f32_16x16x128_f8f6f4 v[116:119], v[0:7], v[224:231], 0, v202, v202 op_sel_hi:[0,0,0]
	v_mfma_scale_f32_16x16x128_f8f6f4 v[112:115], v[8:15], v[224:231], 0, v202, v202 op_sel_hi:[0,0,0]
	v_mfma_scale_f32_16x16x128_f8f6f4 v[100:103], v[0:7], v[232:239], 0, v202, v202 op_sel_hi:[0,0,0]
	v_mfma_scale_f32_16x16x128_f8f6f4 v[96:99], v[8:15], v[232:239], 0, v202, v202 op_sel_hi:[0,0,0]
	s_setprio 0
	s_barrier
	s_add_i32 s43, s43, s13
	v_lshl_add_u64 v[194:195], s[36:37], 0, v[160:161]
	s_mov_b32 m0, s43
	ds_read_b128 v[216:219], v215 offset:16384
	ds_read_b128 v[220:223], v215 offset:17408
	ds_read_b128 v[224:227], v215 offset:18432
	ds_read_b128 v[228:231], v215 offset:19456
	ds_read_b128 v[232:235], v215 offset:20480
	ds_read_b128 v[236:239], v215 offset:21504
	ds_read_b128 v[240:243], v215 offset:22528
	ds_read_b128 v[244:247], v215 offset:23552
	global_load_lds_dwordx4 v[194:195], off
	s_add_i32 m0, s43, 0x2000
	s_add_u32 s60, s36, 0x40000
	v_lshl_add_u64 v[196:197], s[36:37], 0, v[184:185]
	s_addc_u32 s61, s37, 0
	s_add_i32 s43, s56, s13
	global_load_lds_dwordx4 v[196:197], off
	v_lshl_add_u64 v[162:163], s[60:61], 0, v[160:161]
	s_mov_b32 m0, s43
	v_lshl_add_u64 v[198:199], s[48:49], 0, v[188:189]
	global_load_lds_dwordx4 v[162:163], off
	v_lshl_add_u64 v[162:163], s[60:61], 0, v[184:185]
	s_add_i32 m0, s43, 0x2000
	v_lshl_add_u64 v[200:201], s[48:49], 0, v[186:187]
	global_load_lds_dwordx4 v[162:163], off
	s_mov_b32 m0, s51
	s_nop 0
	global_load_lds_dwordx4 v[198:199], off
	s_mov_b32 m0, s52
	s_nop 0
	global_load_lds_dwordx4 v[200:201], off
	s_cmp_lg_u32 s101, 0
	s_cbranch_scc1 .Lgk_nw2_1122
	s_waitcnt vmcnt(8)
; #define PG8_STAGE(bufoff, gbase, voff) do { _Pragma("unroll") for (int _i = 0; _i < 2; ++_i) \
;         __builtin_amdgcn_global_load_lds((const unsigned*)((const char*)(gbase) + (voff)[_i]), (PG8_LAS unsigned*)(lds + (bufoff) + ldsw + _i * 8192), 16, 0, 0); } while (0)
; #define PG8_WAIT_V(n) asm volatile("s_waitcnt vmcnt(" #n ")" ::: "memory")
; #define PG8_WAIT_L(n) asm volatile("s_waitcnt lgkmcnt(" #n ")" ::: "memory")
; #define PG8_BAR __builtin_amdgcn_s_barrier()
; #define PG8_SCHED __builtin_amdgcn_sched_barrier(0)
; template <class Epi, class Sched, bool ALIGN_EPI = false, bool SP2 = false, bool F8 = false>
; __device__ __forceinline__ void gemm_phase(PG8_LAS unsigned char* lds, const Gemm g, const Sched& S, const Epi& E) {
;     ...
;             PG8_WAIT_V(8); PG8_WAIT_L(0); PG8_BAR; PG8_MMA(1, 0, At, B0); PG8_MMA(1, 1, At, B1); PG8_BAR; PG8_SCHED;
;             PG8_LDB(B0, 1, 0); PG8_LDB(B1, 1, 1); PG8_SCHED; PG8_LDA(At, 1, 0); PG8_STAGE(PG8_SA(0, 1), a2 + hstep, voffA);
;             PG8_WAIT_V(8); PG8_WAIT_L(0); PG8_BAR; PG8_MMA(0, 0, At, B0); PG8_MMA(0, 1, At, B1); PG8_BAR; PG8_SCHED;
.Lgk_nw2_1122:
	s_waitcnt lgkmcnt(0)
	s_barrier
	s_setprio 1
	s_waitcnt lgkmcnt(0)
	v_mfma_scale_f32_16x16x128_f8f6f4 v[92:95], v[16:23], v[216:223], 0, v202, v202 op_sel_hi:[0,0,0]
	v_mfma_scale_f32_16x16x128_f8f6f4 v[88:91], v[24:31], v[216:223], 0, v202, v202 op_sel_hi:[0,0,0]
	v_mfma_scale_f32_16x16x128_f8f6f4 v[76:79], v[16:23], v[224:231], 0, v202, v202 op_sel_hi:[0,0,0]
	v_mfma_scale_f32_16x16x128_f8f6f4 v[72:75], v[24:31], v[224:231], 0, v202, v202 op_sel_hi:[0,0,0]
	v_mfma_scale_f32_16x16x128_f8f6f4 v[60:63], v[16:23], v[232:239], 0, v202, v202 op_sel_hi:[0,0,0]
	v_mfma_scale_f32_16x16x128_f8f6f4 v[56:59], v[24:31], v[232:239], 0, v202, v202 op_sel_hi:[0,0,0]
	v_mfma_scale_f32_16x16x128_f8f6f4 v[44:47], v[16:23], v[240:247], 0, v202, v202 op_sel_hi:[0,0,0]
	v_mfma_scale_f32_16x16x128_f8f6f4 v[40:43], v[24:31], v[240:247], 0, v202, v202 op_sel_hi:[0,0,0]
	s_setprio 0
	s_setprio 1
	v_mfma_scale_f32_16x16x128_f8f6f4 v[84:87], v[0:7], v[216:223], 0, v202, v202 op_sel_hi:[0,0,0]
	v_mfma_scale_f32_16x16x128_f8f6f4 v[80:83], v[8:15], v[216:223], 0, v202, v202 op_sel_hi:[0,0,0]
	v_mfma_scale_f32_16x16x128_f8f6f4 v[68:71], v[0:7], v[224:231], 0, v202, v202 op_sel_hi:[0,0,0]
	v_mfma_scale_f32_16x16x128_f8f6f4 v[64:67], v[8:15], v[224:231], 0, v202, v202 op_sel_hi:[0,0,0]
	v_mfma_scale_f32_16x16x128_f8f6f4 v[52:55], v[0:7], v[232:239], 0, v202, v202 op_sel_hi:[0,0,0]
	v_mfma_scale_f32_16x16x128_f8f6f4 v[48:51], v[8:15], v[232:239], 0, v202, v202 op_sel_hi:[0,0,0]
	v_mfma_scale_f32_16x16x128_f8f6f4 v[36:39], v[0:7], v[240:247], 0, v202, v202 op_sel_hi:[0,0,0]
	v_mfma_scale_f32_16x16x128_f8f6f4 v[32:35], v[8:15], v[240:247], 0, v202, v202 op_sel_hi:[0,0,0]
	s_setprio 0
	s_barrier
	s_add_i32 s43, 0, 0x18000
	s_add_i32 s56, 0, 0x1c000
	v_add_u32_e32 v12, s43, v213
	v_add_u32_e32 v28, s56, v213
	ds_read_b128 v[0:3], v12
	ds_read_b128 v[4:7], v12 offset:1024
	ds_read_b128 v[8:11], v12 offset:2048
	ds_read_b128 v[12:15], v12 offset:3072
	ds_read_b128 v[16:19], v28
	ds_read_b128 v[20:23], v28 offset:1024
	ds_read_b128 v[24:27], v28 offset:2048
	ds_read_b128 v[28:31], v28 offset:3072
	s_add_u32 s48, s48, 0x40000
	s_addc_u32 s49, s49, 0
	s_mov_b32 m0, s53
	v_lshl_add_u64 v[162:163], s[48:49], 0, v[188:189]
	ds_read_b128 v[216:219], v215 offset:32768
	ds_read_b128 v[220:223], v215 offset:33792
	ds_read_b128 v[224:227], v215 offset:34816
	ds_read_b128 v[228:231], v215 offset:35840
	ds_read_b128 v[232:235], v215 offset:36864
	ds_read_b128 v[236:239], v215 offset:37888
	ds_read_b128 v[240:243], v215 offset:38912
	ds_read_b128 v[244:247], v215 offset:39936
	global_load_lds_dwordx4 v[162:163], off
	v_lshl_add_u64 v[162:163], s[48:49], 0, v[186:187]
	s_mov_b32 m0, s54
	s_nop 0
	global_load_lds_dwordx4 v[162:163], off
	s_waitcnt vmcnt(8)
	s_waitcnt lgkmcnt(0)
	s_barrier
	s_setprio 1
	s_waitcnt lgkmcnt(0)
	v_mfma_scale_f32_16x16x128_f8f6f4 v[156:159], v[0:7], v[216:223], v[156:159], v202, v202 op_sel_hi:[0,0,0]
	v_mfma_scale_f32_16x16x128_f8f6f4 v[152:155], v[8:15], v[216:223], v[152:155], v202, v202 op_sel_hi:[0,0,0]
	v_mfma_scale_f32_16x16x128_f8f6f4 v[140:143], v[0:7], v[224:231], v[140:143], v202, v202 op_sel_hi:[0,0,0]
	v_mfma_scale_f32_16x16x128_f8f6f4 v[136:139], v[8:15], v[224:231], v[136:139], v202, v202 op_sel_hi:[0,0,0]
	v_mfma_scale_f32_16x16x128_f8f6f4 v[124:127], v[0:7], v[232:239], v[124:127], v202, v202 op_sel_hi:[0,0,0]
	v_mfma_scale_f32_16x16x128_f8f6f4 v[120:123], v[8:15], v[232:239], v[120:123], v202, v202 op_sel_hi:[0,0,0]
	v_mfma_scale_f32_16x16x128_f8f6f4 v[108:111], v[0:7], v[240:247], v[108:111], v202, v202 op_sel_hi:[0,0,0]
	v_mfma_scale_f32_16x16x128_f8f6f4 v[104:107], v[8:15], v[240:247], v[104:107], v202, v202 op_sel_hi:[0,0,0]
	s_setprio 0
	s_setprio 1
	v_mfma_scale_f32_16x16x128_f8f6f4 v[148:151], v[16:23], v[216:223], v[148:151], v202, v202 op_sel_hi:[0,0,0]
	v_mfma_scale_f32_16x16x128_f8f6f4 v[144:147], v[24:31], v[216:223], v[144:147], v202, v202 op_sel_hi:[0,0,0]
	v_mfma_scale_f32_16x16x128_f8f6f4 v[132:135], v[16:23], v[224:231], v[132:135], v202, v202 op_sel_hi:[0,0,0]
	v_mfma_scale_f32_16x16x128_f8f6f4 v[128:131], v[24:31], v[224:231], v[128:131], v202, v202 op_sel_hi:[0,0,0]
	v_mfma_scale_f32_16x16x128_f8f6f4 v[116:119], v[16:23], v[232:239], v[116:119], v202, v202 op_sel_hi:[0,0,0]
	v_mfma_scale_f32_16x16x128_f8f6f4 v[112:115], v[24:31], v[232:239], v[112:115], v202, v202 op_sel_hi:[0,0,0]
	v_mfma_scale_f32_16x16x128_f8f6f4 v[100:103], v[16:23], v[240:247], v[100:103], v202, v202 op_sel_hi:[0,0,0]
	v_mfma_scale_f32_16x16x128_f8f6f4 v[96:99], v[24:31], v[240:247], v[96:99], v202, v202 op_sel_hi:[0,0,0]
	s_setprio 0
	s_barrier
; #define PG8_STAGE(bufoff, gbase, voff) do { _Pragma("unroll") for (int _i = 0; _i < 2; ++_i) \
;         __builtin_amdgcn_global_load_lds((const unsigned*)((const char*)(gbase) + (voff)[_i]), (PG8_LAS unsigned*)(lds + (bufoff) + ldsw + _i * 8192), 16, 0, 0); } while (0)
; #define PG8_WAIT_V(n) asm volatile("s_waitcnt vmcnt(" #n ")" ::: "memory")
; #define PG8_WAIT_L(n) asm volatile("s_waitcnt lgkmcnt(" #n ")" ::: "memory")
; #define PG8_BAR __builtin_amdgcn_s_barrier()
; #define PG8_SCHED __builtin_amdgcn_sched_barrier(0)
; template <class Epi, class Sched, bool ALIGN_EPI = false, bool SP2 = false, bool F8 = false>
; __device__ __forceinline__ void gemm_phase(PG8_LAS unsigned char* lds, const Gemm g, const Sched& S, const Epi& E) {
;     ...
;             PG8_LDA(At, 1, 1); PG8_STAGE(PG8_SB(1, 0), b3, voffB); PG8_STAGE(PG8_SB(1, 1), b3 + hstep, voffB); PG8_STAGE(PG8_SA(1, 0), a3, voffA);
;             PG8_WAIT_V(8); PG8_WAIT_L(0); PG8_BAR; PG8_MMA(1, 0, At, B0); PG8_MMA(1, 1, At, B1); PG8_BAR; PG8_SCHED;
	s_add_i32 s43, s43, s13
	v_lshl_add_u64 v[162:163], v[194:195], 0, s[14:15]
	s_mov_b32 m0, s43
	ds_read_b128 v[216:219], v215 offset:49152
	ds_read_b128 v[220:223], v215 offset:50176
	ds_read_b128 v[224:227], v215 offset:51200
	ds_read_b128 v[228:231], v215 offset:52224
	ds_read_b128 v[232:235], v215 offset:53248
	ds_read_b128 v[236:239], v215 offset:54272
	ds_read_b128 v[240:243], v215 offset:55296
	ds_read_b128 v[244:247], v215 offset:56320
	global_load_lds_dwordx4 v[162:163], off
	s_add_i32 m0, s43, 0x2000
	s_add_u32 s36, s36, 0x40080
	v_lshl_add_u64 v[162:163], v[196:197], 0, s[14:15]
	s_addc_u32 s37, s37, 0
	s_add_i32 s43, s56, s13
	global_load_lds_dwordx4 v[162:163], off
	v_lshl_add_u64 v[162:163], s[36:37], 0, v[160:161]
	s_mov_b32 m0, s43
	s_nop 0
	global_load_lds_dwordx4 v[162:163], off
	v_lshl_add_u64 v[162:163], s[36:37], 0, v[184:185]
	s_add_i32 m0, s43, 0x2000
	s_nop 0
	global_load_lds_dwordx4 v[162:163], off
	v_lshl_add_u64 v[162:163], v[198:199], 0, s[14:15]
	s_mov_b32 m0, s55
	s_nop 0
	global_load_lds_dwordx4 v[162:163], off
	v_lshl_add_u64 v[162:163], v[200:201], 0, s[14:15]
	s_mov_b32 m0, s58
	s_nop 0
	global_load_lds_dwordx4 v[162:163], off
	s_waitcnt vmcnt(8)
	s_waitcnt lgkmcnt(0)
	s_barrier
	s_setprio 1
	s_waitcnt lgkmcnt(0)
	v_mfma_scale_f32_16x16x128_f8f6f4 v[92:95], v[0:7], v[216:223], v[92:95], v202, v202 op_sel_hi:[0,0,0]
	v_mfma_scale_f32_16x16x128_f8f6f4 v[88:91], v[8:15], v[216:223], v[88:91], v202, v202 op_sel_hi:[0,0,0]
	v_mfma_scale_f32_16x16x128_f8f6f4 v[76:79], v[0:7], v[224:231], v[76:79], v202, v202 op_sel_hi:[0,0,0]
	v_mfma_scale_f32_16x16x128_f8f6f4 v[72:75], v[8:15], v[224:231], v[72:75], v202, v202 op_sel_hi:[0,0,0]
	v_mfma_scale_f32_16x16x128_f8f6f4 v[60:63], v[0:7], v[232:239], v[60:63], v202, v202 op_sel_hi:[0,0,0]
	v_mfma_scale_f32_16x16x128_f8f6f4 v[56:59], v[8:15], v[232:239], v[56:59], v202, v202 op_sel_hi:[0,0,0]
	v_mfma_scale_f32_16x16x128_f8f6f4 v[44:47], v[0:7], v[240:247], v[44:47], v202, v202 op_sel_hi:[0,0,0]
	v_mfma_scale_f32_16x16x128_f8f6f4 v[40:43], v[8:15], v[240:247], v[40:43], v202, v202 op_sel_hi:[0,0,0]
	s_setprio 0
	s_setprio 1
	v_mfma_scale_f32_16x16x128_f8f6f4 v[84:87], v[16:23], v[216:223], v[84:87], v202, v202 op_sel_hi:[0,0,0]
	v_mfma_scale_f32_16x16x128_f8f6f4 v[80:83], v[24:31], v[216:223], v[80:83], v202, v202 op_sel_hi:[0,0,0]
	v_mfma_scale_f32_16x16x128_f8f6f4 v[68:71], v[16:23], v[224:231], v[68:71], v202, v202 op_sel_hi:[0,0,0]
	v_mfma_scale_f32_16x16x128_f8f6f4 v[64:67], v[24:31], v[224:231], v[64:67], v202, v202 op_sel_hi:[0,0,0]
	v_mfma_scale_f32_16x16x128_f8f6f4 v[52:55], v[16:23], v[232:239], v[52:55], v202, v202 op_sel_hi:[0,0,0]
	v_mfma_scale_f32_16x16x128_f8f6f4 v[48:51], v[24:31], v[232:239], v[48:51], v202, v202 op_sel_hi:[0,0,0]
	v_mfma_scale_f32_16x16x128_f8f6f4 v[36:39], v[16:23], v[240:247], v[36:39], v202, v202 op_sel_hi:[0,0,0]
	v_mfma_scale_f32_16x16x128_f8f6f4 v[32:35], v[24:31], v[240:247], v[32:35], v202, v202 op_sel_hi:[0,0,0]
	s_setprio 0
	s_barrier
	s_add_i32 s41, s41, 2
	s_add_u32 s10, s10, 0x100
	s_addc_u32 s11, s11, 0
	s_add_u32 s34, s34, 0x100
	s_addc_u32 s35, s35, 0
	s_cmp_gt_u32 s41, 13
	s_cbranch_scc0 .LBB0_1122
	s_branch .Lgk_after_1122

; __device__ __forceinline__ unsigned pk2(float lo, float hi) { return f2bf(lo) | (f2bf(hi) << 16); }
;     __device__ __forceinline__ void operator()(const f32x4 (&acc)[2][2][4][2], const pg8::Unit& u, int wr, int wc, int fr, int fq) const {
;     ...
;                     } else if constexpr (MODE == 1) {
;                         const f32x4 b0 = *(const f32x4*)(vec + col), b1 = *(const f32x4*)(vec + col + 4);
;                         float r[8];
; #pragma unroll
;                         for (int i = 0; i < 4; ++i) { r[i] = 1.f / (1.f + __expf(-(v0[i] + b0[i]))); r[4 + i] = 1.f / (1.f + __expf(-(v1[i] + b1[i]))); }
;                         u32x4 w; w.x = pk2(r[0], r[1]); w.y = pk2(r[2], r[3]); w.z = pk2(r[4], r[5]); w.w = pk2(r[6], r[7]);
;                         *(u32x4*)(ob + row * 4096 + col) = w;
.LBB0_1125:
	v_lshl_or_b32 v2, s8, 8, v214
	v_ashrrev_i32_e32 v3, 31, v2
	v_lshl_add_u64 v[0:1], v[2:3], 2, s[4:5]
	global_load_dwordx4 v[226:229], v[0:1], off offset:16
	global_load_dwordx4 v[230:233], v[0:1], off
	global_load_dwordx4 v[234:237], v[0:1], off offset:528
	global_load_dwordx4 v[238:241], v[0:1], off offset:512
	s_nop 15
	s_nop 15
	v_lshl_add_u32 v4, s9, 8, v203
	v_ashrrev_i32_e32 v5, 31, v4
	v_lshlrev_b64 v[6:7], 13, v[4:5]
	s_mov_b64 s[10:11], -1
	s_waitcnt vmcnt(0)
	v_fmamk_f32 v13, v155, 0x3c800000, v229
	v_fmamk_f32 v5, v156, 0x3c800000, v230
	v_mul_f32_e32 v5, 0xbfb8aa3b, v5
	v_exp_f32_e32 v14, v5
	v_fmamk_f32 v5, v152, 0x3c800000, v226
	v_mul_f32_e32 v5, 0xbfb8aa3b, v5
	v_exp_f32_e32 v10, v5
	v_fmamk_f32 v5, v157, 0x3c800000, v231
	v_mul_f32_e32 v5, 0xbfb8aa3b, v5
	v_exp_f32_e32 v18, v5
	v_fmamk_f32 v5, v153, 0x3c800000, v227
	v_mul_f32_e32 v5, 0xbfb8aa3b, v5
	v_exp_f32_e32 v8, v5
	v_fmamk_f32 v5, v158, 0x3c800000, v232
	v_mul_f32_e32 v5, 0xbfb8aa3b, v5
	v_exp_f32_e32 v15, v5
	v_fmamk_f32 v5, v154, 0x3c800000, v228
	v_mul_f32_e32 v5, 0xbfb8aa3b, v5
	v_fmamk_f32 v17, v159, 0x3c800000, v233
	v_exp_f32_e32 v11, v5
	v_mul_f32_e32 v5, 0xbfb8aa3b, v17
	v_exp_f32_e32 v19, v5
	v_mul_f32_e32 v5, 0xbfb8aa3b, v13
	v_pk_add_f32 v[12:13], v[14:15], 1.0 op_sel_hi:[1,0]
	v_exp_f32_e32 v9, v5
	v_pk_add_f32 v[10:11], v[10:11], 1.0 op_sel_hi:[1,0]
	v_pk_add_f32 v[8:9], v[8:9], 1.0 op_sel_hi:[1,0]
	v_rcp_f32_e32 v5, v13
	v_pk_add_f32 v[14:15], v[18:19], 1.0 op_sel_hi:[1,0]
	v_rcp_f32_e32 v12, v12
	v_rcp_f32_e32 v13, v14
	v_rcp_f32_e32 v14, v15
	v_rcp_f32_e32 v11, v11
	v_rcp_f32_e32 v10, v10
	v_rcp_f32_e32 v8, v8
	v_rcp_f32_e32 v9, v9
	v_cvt_pk_bf16_f32 v10, v10, v8
	v_cvt_pk_bf16_f32 v8, v12, v13
	v_lshl_add_u64 v[12:13], s[24:25], 0, v[6:7]
	v_lshlrev_b64 v[6:7], 1, v[2:3]
	v_cvt_pk_bf16_f32 v11, v11, v9
	v_cvt_pk_bf16_f32 v9, v5, v14
	v_lshl_add_u64 v[2:3], v[12:13], 0, v[6:7]
	global_store_dwordx4 v[2:3], v[8:11], off
	s_nop 0
	v_fmamk_f32 v13, v147, 0x3c800000, v237
	v_fmamk_f32 v5, v148, 0x3c800000, v238
	v_mul_f32_e32 v5, 0xbfb8aa3b, v5
	v_exp_f32_e32 v14, v5
	v_fmamk_f32 v5, v144, 0x3c800000, v234
	v_mul_f32_e32 v5, 0xbfb8aa3b, v5
	v_exp_f32_e32 v10, v5
	v_fmamk_f32 v5, v149, 0x3c800000, v239
	v_mul_f32_e32 v5, 0xbfb8aa3b, v5
	v_exp_f32_e32 v18, v5
	v_fmamk_f32 v5, v145, 0x3c800000, v235
	v_mul_f32_e32 v5, 0xbfb8aa3b, v5
	v_exp_f32_e32 v8, v5
	v_fmamk_f32 v5, v150, 0x3c800000, v240
	v_mul_f32_e32 v5, 0xbfb8aa3b, v5
	v_exp_f32_e32 v15, v5
	v_fmamk_f32 v5, v146, 0x3c800000, v236
	v_mul_f32_e32 v5, 0xbfb8aa3b, v5
	v_fmamk_f32 v17, v151, 0x3c800000, v241
	v_exp_f32_e32 v11, v5
	v_mul_f32_e32 v5, 0xbfb8aa3b, v17
	v_exp_f32_e32 v19, v5
	v_mul_f32_e32 v5, 0xbfb8aa3b, v13
	v_pk_add_f32 v[12:13], v[14:15], 1.0 op_sel_hi:[1,0]
	v_exp_f32_e32 v9, v5
	v_pk_add_f32 v[10:11], v[10:11], 1.0 op_sel_hi:[1,0]
	v_pk_add_f32 v[8:9], v[8:9], 1.0 op_sel_hi:[1,0]
	v_rcp_f32_e32 v5, v13
	v_rcp_f32_e32 v14, v12
	v_pk_add_f32 v[12:13], v[18:19], 1.0 op_sel_hi:[1,0]
	s_nop 0
	v_rcp_f32_e32 v12, v12
	v_rcp_f32_e32 v13, v13
	v_rcp_f32_e32 v11, v11
	v_rcp_f32_e32 v10, v10
	v_rcp_f32_e32 v8, v8
	v_rcp_f32_e32 v9, v9
	s_nop 0
	v_cvt_pk_bf16_f32 v11, v11, v9
	v_cvt_pk_bf16_f32 v10, v10, v8
	v_cvt_pk_bf16_f32 v9, v5, v13
	v_cvt_pk_bf16_f32 v8, v14, v12
	global_store_dwordx4 v[2:3], v[8:11], off offset:256
	s_nop 1
	s_nop 0
	v_or_b32_e32 v8, 16, v4
	v_ashrrev_i32_e32 v9, 31, v8
	v_lshlrev_b64 v[8:9], 13, v[8:9]
	v_lshl_add_u64 v[8:9], s[24:25], 0, v[8:9]
	v_lshl_add_u64 v[8:9], v[8:9], 0, v[6:7]
	v_fmamk_f32 v13, v139, 0x3c800000, v229
	v_fmamk_f32 v5, v140, 0x3c800000, v230
	v_mul_f32_e32 v5, 0xbfb8aa3b, v5
	v_exp_f32_e32 v14, v5
	v_fmamk_f32 v5, v136, 0x3c800000, v226
	v_mul_f32_e32 v5, 0xbfb8aa3b, v5
	v_exp_f32_e32 v18, v5
	v_fmamk_f32 v5, v141, 0x3c800000, v231
	v_mul_f32_e32 v5, 0xbfb8aa3b, v5
	v_exp_f32_e32 v20, v5
	v_fmamk_f32 v5, v137, 0x3c800000, v227
	v_mul_f32_e32 v5, 0xbfb8aa3b, v5
	v_exp_f32_e32 v10, v5
	v_fmamk_f32 v5, v142, 0x3c800000, v232
	v_mul_f32_e32 v5, 0xbfb8aa3b, v5
	v_exp_f32_e32 v15, v5
	v_fmamk_f32 v5, v138, 0x3c800000, v228
	v_mul_f32_e32 v5, 0xbfb8aa3b, v5
	v_fmamk_f32 v17, v143, 0x3c800000, v233
	v_exp_f32_e32 v19, v5
	v_mul_f32_e32 v5, 0xbfb8aa3b, v17
	v_exp_f32_e32 v21, v5
	v_mul_f32_e32 v5, 0xbfb8aa3b, v13
	v_pk_add_f32 v[12:13], v[14:15], 1.0 op_sel_hi:[1,0]
	v_exp_f32_e32 v11, v5
	s_nop 0
	v_pk_add_f32 v[10:11], v[10:11], 1.0 op_sel_hi:[1,0]
	v_rcp_f32_e32 v5, v13
	v_rcp_f32_e32 v14, v12
	v_pk_add_f32 v[12:13], v[20:21], 1.0 op_sel_hi:[1,0]
	s_nop 0
	v_rcp_f32_e32 v15, v12
	v_rcp_f32_e32 v16, v13
	v_pk_add_f32 v[12:13], v[18:19], 1.0 op_sel_hi:[1,0]
	s_nop 0
	v_rcp_f32_e32 v13, v13
	v_rcp_f32_e32 v12, v12
	v_rcp_f32_e32 v10, v10
	v_rcp_f32_e32 v11, v11
	s_nop 0
	v_cvt_pk_bf16_f32 v13, v13, v11
	v_cvt_pk_bf16_f32 v12, v12, v10
	v_cvt_pk_bf16_f32 v11, v5, v16
	v_cvt_pk_bf16_f32 v10, v14, v15
	global_store_dwordx4 v[8:9], v[10:13], off
	s_nop 1
	s_nop 0
	v_fmamk_f32 v13, v131, 0x3c800000, v237
	v_fmamk_f32 v5, v132, 0x3c800000, v238
	v_mul_f32_e32 v5, 0xbfb8aa3b, v5
	v_exp_f32_e32 v14, v5
	v_fmamk_f32 v5, v128, 0x3c800000, v234
	v_mul_f32_e32 v5, 0xbfb8aa3b, v5
	v_exp_f32_e32 v18, v5
	v_fmamk_f32 v5, v133, 0x3c800000, v239
	v_mul_f32_e32 v5, 0xbfb8aa3b, v5
	v_exp_f32_e32 v20, v5
	v_fmamk_f32 v5, v129, 0x3c800000, v235
	v_mul_f32_e32 v5, 0xbfb8aa3b, v5
	v_exp_f32_e32 v10, v5
	v_fmamk_f32 v5, v134, 0x3c800000, v240
	v_mul_f32_e32 v5, 0xbfb8aa3b, v5
	v_exp_f32_e32 v15, v5
	v_fmamk_f32 v5, v130, 0x3c800000, v236
	v_mul_f32_e32 v5, 0xbfb8aa3b, v5
	v_fmamk_f32 v17, v135, 0x3c800000, v241
	v_exp_f32_e32 v19, v5
	v_mul_f32_e32 v5, 0xbfb8aa3b, v17
; __device__ __forceinline__ unsigned pk2(float lo, float hi) { return f2bf(lo) | (f2bf(hi) << 16); }
;     __device__ __forceinline__ void operator()(const f32x4 (&acc)[2][2][4][2], const pg8::Unit& u, int wr, int wc, int fr, int fq) const {
;     ...
;                     } else if constexpr (MODE == 1) {
;                         const f32x4 b0 = *(const f32x4*)(vec + col), b1 = *(const f32x4*)(vec + col + 4);
;                         float r[8];
; #pragma unroll
;                         for (int i = 0; i < 4; ++i) { r[i] = 1.f / (1.f + __expf(-(v0[i] + b0[i]))); r[4 + i] = 1.f / (1.f + __expf(-(v1[i] + b1[i]))); }
;                         u32x4 w; w.x = pk2(r[0], r[1]); w.y = pk2(r[2], r[3]); w.z = pk2(r[4], r[5]); w.w = pk2(r[6], r[7]);
;                         *(u32x4*)(ob + row * 4096 + col) = w;
	v_exp_f32_e32 v21, v5
	v_mul_f32_e32 v5, 0xbfb8aa3b, v13
	v_pk_add_f32 v[12:13], v[14:15], 1.0 op_sel_hi:[1,0]
	v_exp_f32_e32 v11, v5
	s_nop 0
	v_pk_add_f32 v[10:11], v[10:11], 1.0 op_sel_hi:[1,0]
	v_rcp_f32_e32 v5, v13
	v_rcp_f32_e32 v14, v12
	v_pk_add_f32 v[12:13], v[20:21], 1.0 op_sel_hi:[1,0]
	s_nop 0
	v_rcp_f32_e32 v15, v12
	v_rcp_f32_e32 v16, v13
	v_pk_add_f32 v[12:13], v[18:19], 1.0 op_sel_hi:[1,0]
	s_nop 0
	v_rcp_f32_e32 v13, v13
	v_rcp_f32_e32 v12, v12
	v_rcp_f32_e32 v10, v10
	v_rcp_f32_e32 v11, v11
	s_nop 0
	v_cvt_pk_bf16_f32 v13, v13, v11
	v_cvt_pk_bf16_f32 v12, v12, v10
	v_cvt_pk_bf16_f32 v11, v5, v16
	v_cvt_pk_bf16_f32 v10, v14, v15
	global_store_dwordx4 v[8:9], v[10:13], off offset:256
	s_nop 0
	v_or_b32_e32 v8, 32, v4
	v_ashrrev_i32_e32 v9, 31, v8
	v_lshlrev_b64 v[8:9], 13, v[8:9]
	v_lshl_add_u64 v[8:9], s[24:25], 0, v[8:9]
	v_lshl_add_u64 v[8:9], v[8:9], 0, v[6:7]
	v_or_b32_e32 v4, 48, v4
	v_fmamk_f32 v13, v123, 0x3c800000, v229
	v_fmamk_f32 v5, v124, 0x3c800000, v230
	v_mul_f32_e32 v5, 0xbfb8aa3b, v5
	v_exp_f32_e32 v14, v5
	v_fmamk_f32 v5, v120, 0x3c800000, v226
	v_mul_f32_e32 v5, 0xbfb8aa3b, v5
	v_exp_f32_e32 v18, v5
	v_fmamk_f32 v5, v125, 0x3c800000, v231
	v_mul_f32_e32 v5, 0xbfb8aa3b, v5
	v_exp_f32_e32 v20, v5
	v_fmamk_f32 v5, v121, 0x3c800000, v227
	v_mul_f32_e32 v5, 0xbfb8aa3b, v5
	v_exp_f32_e32 v10, v5
	v_fmamk_f32 v5, v126, 0x3c800000, v232
	v_mul_f32_e32 v5, 0xbfb8aa3b, v5
	v_exp_f32_e32 v15, v5
	v_fmamk_f32 v5, v122, 0x3c800000, v228
	v_mul_f32_e32 v5, 0xbfb8aa3b, v5
	v_fmamk_f32 v17, v127, 0x3c800000, v233
	v_exp_f32_e32 v19, v5
	v_mul_f32_e32 v5, 0xbfb8aa3b, v17
	v_exp_f32_e32 v21, v5
	v_mul_f32_e32 v5, 0xbfb8aa3b, v13
	v_pk_add_f32 v[12:13], v[14:15], 1.0 op_sel_hi:[1,0]
	v_exp_f32_e32 v11, v5
	s_nop 0
	v_pk_add_f32 v[10:11], v[10:11], 1.0 op_sel_hi:[1,0]
	v_rcp_f32_e32 v5, v13
	v_rcp_f32_e32 v14, v12
	v_pk_add_f32 v[12:13], v[20:21], 1.0 op_sel_hi:[1,0]
	s_nop 0
	v_rcp_f32_e32 v15, v12
	v_rcp_f32_e32 v16, v13
	v_pk_add_f32 v[12:13], v[18:19], 1.0 op_sel_hi:[1,0]
	s_nop 0
	v_rcp_f32_e32 v13, v13
	v_rcp_f32_e32 v12, v12
	v_rcp_f32_e32 v10, v10
	v_rcp_f32_e32 v11, v11
	s_nop 0
	v_cvt_pk_bf16_f32 v13, v13, v11
	v_cvt_pk_bf16_f32 v12, v12, v10
	v_cvt_pk_bf16_f32 v11, v5, v16
	v_cvt_pk_bf16_f32 v10, v14, v15
	global_store_dwordx4 v[8:9], v[10:13], off
	s_nop 1
	s_nop 0
	v_fmamk_f32 v13, v115, 0x3c800000, v237
	v_fmamk_f32 v5, v116, 0x3c800000, v238
	v_mul_f32_e32 v5, 0xbfb8aa3b, v5
	v_exp_f32_e32 v14, v5
	v_fmamk_f32 v5, v112, 0x3c800000, v234
	v_mul_f32_e32 v5, 0xbfb8aa3b, v5
	v_exp_f32_e32 v18, v5
	v_fmamk_f32 v5, v117, 0x3c800000, v239
	v_mul_f32_e32 v5, 0xbfb8aa3b, v5
	v_exp_f32_e32 v20, v5
	v_fmamk_f32 v5, v113, 0x3c800000, v235
	v_mul_f32_e32 v5, 0xbfb8aa3b, v5
	v_exp_f32_e32 v10, v5
	v_fmamk_f32 v5, v118, 0x3c800000, v240
	v_mul_f32_e32 v5, 0xbfb8aa3b, v5
	v_exp_f32_e32 v15, v5
	v_fmamk_f32 v5, v114, 0x3c800000, v236
	v_mul_f32_e32 v5, 0xbfb8aa3b, v5
	v_fmamk_f32 v17, v119, 0x3c800000, v241
	v_exp_f32_e32 v19, v5
	v_mul_f32_e32 v5, 0xbfb8aa3b, v17
	v_exp_f32_e32 v21, v5
	v_mul_f32_e32 v5, 0xbfb8aa3b, v13
	v_pk_add_f32 v[12:13], v[14:15], 1.0 op_sel_hi:[1,0]
	v_exp_f32_e32 v11, v5
	s_nop 0
	v_pk_add_f32 v[10:11], v[10:11], 1.0 op_sel_hi:[1,0]
	v_rcp_f32_e32 v5, v13
	v_rcp_f32_e32 v14, v12
	v_pk_add_f32 v[12:13], v[20:21], 1.0 op_sel_hi:[1,0]
	s_nop 0
	v_rcp_f32_e32 v15, v12
	v_rcp_f32_e32 v16, v13
	v_pk_add_f32 v[12:13], v[18:19], 1.0 op_sel_hi:[1,0]
	s_nop 0
	v_rcp_f32_e32 v13, v13
	v_rcp_f32_e32 v12, v12
	v_rcp_f32_e32 v10, v10
	v_div_scale_f32 v17, s[8:9], v11, v11, 1.0
	v_rcp_f32_e32 v18, v17
	s_nop 0
	v_fma_f32 v19, -v17, v18, 1.0
	v_fmac_f32_e32 v18, v19, v18
	v_div_scale_f32 v19, vcc, 1.0, v11, 1.0
	v_mul_f32_e32 v20, v19, v18
	v_fma_f32 v21, -v17, v20, v19
	v_rcp_f32_e32 v11, v11
	s_nop 0
	v_cvt_pk_bf16_f32 v13, v13, v11
	v_cvt_pk_bf16_f32 v12, v12, v10
	v_cvt_pk_bf16_f32 v11, v5, v16
	v_cvt_pk_bf16_f32 v10, v14, v15
	global_store_dwordx4 v[8:9], v[10:13], off offset:256
	s_nop 0
	v_ashrrev_i32_e32 v5, 31, v4
	v_lshlrev_b64 v[4:5], 13, v[4:5]
	v_lshl_add_u64 v[4:5], s[24:25], 0, v[4:5]
	v_lshl_add_u64 v[4:5], v[4:5], 0, v[6:7]
	v_fmamk_f32 v8, v104, 0x3c800000, v226
	v_mul_f32_e32 v8, 0xbfb8aa3b, v8
	v_exp_f32_e32 v16, v8
	v_fmamk_f32 v8, v109, 0x3c800000, v231
	v_mul_f32_e32 v8, 0xbfb8aa3b, v8
	v_fmamk_f32 v12, v108, 0x3c800000, v230
	v_exp_f32_e32 v18, v8
	v_fmamk_f32 v8, v105, 0x3c800000, v227
	v_fmamk_f32 v9, v110, 0x3c800000, v232
	v_mul_f32_e32 v12, 0xbfb8aa3b, v12
	v_mul_f32_e32 v9, 0xbfb8aa3b, v9
	v_exp_f32_e32 v12, v12
	v_exp_f32_e32 v13, v9
	v_fmamk_f32 v9, v106, 0x3c800000, v228
	v_mul_f32_e32 v9, 0xbfb8aa3b, v9
	v_fmamk_f32 v15, v111, 0x3c800000, v233
	v_exp_f32_e32 v17, v9
	v_mul_f32_e32 v9, 0xbfb8aa3b, v15
	v_fmamk_f32 v11, v107, 0x3c800000, v229
	v_exp_f32_e32 v19, v9
	v_mul_f32_e32 v9, 0xbfb8aa3b, v11
	v_pk_add_f32 v[10:11], v[12:13], 1.0 op_sel_hi:[1,0]
	v_mul_f32_e32 v8, 0xbfb8aa3b, v8
	v_exp_f32_e32 v8, v8
	v_exp_f32_e32 v9, v9
	v_rcp_f32_e32 v12, v11
	v_pk_add_f32 v[8:9], v[8:9], 1.0 op_sel_hi:[1,0]
	v_rcp_f32_e32 v13, v10
	v_pk_add_f32 v[10:11], v[18:19], 1.0 op_sel_hi:[1,0]
	s_nop 0
	v_rcp_f32_e32 v14, v10
	v_rcp_f32_e32 v15, v11
	v_pk_add_f32 v[10:11], v[16:17], 1.0 op_sel_hi:[1,0]
	s_nop 0
	v_rcp_f32_e32 v11, v11
	v_rcp_f32_e32 v10, v10
	v_rcp_f32_e32 v8, v8
	v_div_scale_f32 v16, s[8:9], v9, v9, 1.0
	v_rcp_f32_e32 v17, v16
	s_nop 0
	v_fma_f32 v18, -v16, v17, 1.0
	v_fmac_f32_e32 v17, v18, v17
	v_div_scale_f32 v18, vcc, 1.0, v9, 1.0
	v_mul_f32_e32 v19, v18, v17
	v_fma_f32 v20, -v16, v19, v18
	v_fmac_f32_e32 v19, v20, v17
	v_rcp_f32_e32 v9, v9
	s_nop 0
	v_cvt_pk_bf16_f32 v11, v11, v9
; __device__ __forceinline__ unsigned pk2(float lo, float hi) { return f2bf(lo) | (f2bf(hi) << 16); }
;     __device__ __forceinline__ void operator()(const f32x4 (&acc)[2][2][4][2], const pg8::Unit& u, int wr, int wc, int fr, int fq) const {
;     ...
;                     } else if constexpr (MODE == 1) {
;                         const f32x4 b0 = *(const f32x4*)(vec + col), b1 = *(const f32x4*)(vec + col + 4);
;                         float r[8];
; #pragma unroll
;                         for (int i = 0; i < 4; ++i) { r[i] = 1.f / (1.f + __expf(-(v0[i] + b0[i]))); r[4 + i] = 1.f / (1.f + __expf(-(v1[i] + b1[i]))); }
;                         u32x4 w; w.x = pk2(r[0], r[1]); w.y = pk2(r[2], r[3]); w.z = pk2(r[4], r[5]); w.w = pk2(r[6], r[7]);
;                         *(u32x4*)(ob + row * 4096 + col) = w;
	v_cvt_pk_bf16_f32 v10, v10, v8
	v_cvt_pk_bf16_f32 v9, v12, v15
	v_cvt_pk_bf16_f32 v8, v13, v14
	global_store_dwordx4 v[4:5], v[8:11], off
	s_nop 0
	v_fmamk_f32 v6, v96, 0x3c800000, v234
	v_mul_f32_e32 v6, 0xbfb8aa3b, v6
	v_exp_f32_e32 v14, v6
	v_fmamk_f32 v6, v101, 0x3c800000, v239
	v_mul_f32_e32 v6, 0xbfb8aa3b, v6
	v_fmamk_f32 v10, v100, 0x3c800000, v238
	v_exp_f32_e32 v16, v6
	v_fmamk_f32 v6, v97, 0x3c800000, v235
	v_fmamk_f32 v7, v102, 0x3c800000, v240
	v_mul_f32_e32 v10, 0xbfb8aa3b, v10
	v_mul_f32_e32 v7, 0xbfb8aa3b, v7
	v_exp_f32_e32 v10, v10
	v_exp_f32_e32 v11, v7
	v_fmamk_f32 v7, v98, 0x3c800000, v236
	v_mul_f32_e32 v7, 0xbfb8aa3b, v7
	v_fmamk_f32 v13, v103, 0x3c800000, v241
	v_exp_f32_e32 v15, v7
	v_mul_f32_e32 v7, 0xbfb8aa3b, v13
	v_fmamk_f32 v9, v99, 0x3c800000, v237
	v_exp_f32_e32 v17, v7
	v_mul_f32_e32 v7, 0xbfb8aa3b, v9
	v_pk_add_f32 v[8:9], v[10:11], 1.0 op_sel_hi:[1,0]
	v_mul_f32_e32 v6, 0xbfb8aa3b, v6
	v_exp_f32_e32 v6, v6
	v_exp_f32_e32 v7, v7
	v_rcp_f32_e32 v10, v9
	v_pk_add_f32 v[6:7], v[6:7], 1.0 op_sel_hi:[1,0]
	v_rcp_f32_e32 v11, v8
	v_pk_add_f32 v[8:9], v[16:17], 1.0 op_sel_hi:[1,0]
	s_nop 0
	v_rcp_f32_e32 v12, v8
	v_rcp_f32_e32 v13, v9
	v_pk_add_f32 v[8:9], v[14:15], 1.0 op_sel_hi:[1,0]
	s_nop 0
	v_rcp_f32_e32 v9, v9
	v_rcp_f32_e32 v8, v8
	v_rcp_f32_e32 v6, v6
	v_rcp_f32_e32 v7, v7
	s_nop 0
	v_cvt_pk_bf16_f32 v9, v9, v7
	v_cvt_pk_bf16_f32 v8, v8, v6
	v_cvt_pk_bf16_f32 v7, v10, v13
	v_cvt_pk_bf16_f32 v6, v11, v12
	global_store_dwordx4 v[4:5], v[6:9], off offset:256
	s_nop 0
	v_fmamk_f32 v4, v88, 0x3c800000, v226
	v_mul_f32_e32 v4, 0xbfb8aa3b, v4
	v_exp_f32_e32 v12, v4
	v_fmamk_f32 v4, v93, 0x3c800000, v231
	v_mul_f32_e32 v4, 0xbfb8aa3b, v4
	v_fmamk_f32 v8, v92, 0x3c800000, v230
	v_exp_f32_e32 v14, v4
	v_fmamk_f32 v4, v89, 0x3c800000, v227
	v_fmamk_f32 v5, v94, 0x3c800000, v232
	v_mul_f32_e32 v8, 0xbfb8aa3b, v8
	v_mul_f32_e32 v5, 0xbfb8aa3b, v5
	v_exp_f32_e32 v8, v8
	v_exp_f32_e32 v9, v5
	v_fmamk_f32 v5, v90, 0x3c800000, v228
	v_mul_f32_e32 v5, 0xbfb8aa3b, v5
	v_fmamk_f32 v11, v95, 0x3c800000, v233
	v_exp_f32_e32 v13, v5
	v_mul_f32_e32 v5, 0xbfb8aa3b, v11
	v_fmamk_f32 v7, v91, 0x3c800000, v229
	v_exp_f32_e32 v15, v5
	v_mul_f32_e32 v5, 0xbfb8aa3b, v7
	v_pk_add_f32 v[6:7], v[8:9], 1.0 op_sel_hi:[1,0]
	v_mul_f32_e32 v4, 0xbfb8aa3b, v4
	v_exp_f32_e32 v4, v4
	v_exp_f32_e32 v5, v5
	v_rcp_f32_e32 v8, v7
	v_pk_add_f32 v[4:5], v[4:5], 1.0 op_sel_hi:[1,0]
	v_rcp_f32_e32 v9, v6
	v_pk_add_f32 v[6:7], v[14:15], 1.0 op_sel_hi:[1,0]
	s_nop 0
	v_rcp_f32_e32 v10, v6
	v_rcp_f32_e32 v11, v7
	v_pk_add_f32 v[6:7], v[12:13], 1.0 op_sel_hi:[1,0]
	s_nop 0
	v_rcp_f32_e32 v7, v7
	v_rcp_f32_e32 v6, v6
	v_rcp_f32_e32 v4, v4
	s_mov_b64 s[8:9], 0x100000
	v_rcp_f32_e32 v5, v5
	v_bfe_u32 v14, v11, 16, 1
	v_bfe_u32 v15, v10, 16, 1
	v_add3_u32 v10, v10, v15, s33
	v_add3_u32 v11, v11, v14, s33
	v_bfe_u32 v12, v9, 16, 1
	v_bfe_u32 v13, v8, 16, 1
	v_add3_u32 v8, v8, v13, s33
	v_add3_u32 v9, v9, v12, s33
	v_lshrrev_b32_e32 v12, 16, v9
	v_lshrrev_b32_e32 v13, 16, v8
	v_cvt_pk_bf16_f32 v9, v7, v5
	v_cvt_pk_bf16_f32 v8, v6, v4
	v_lshl_add_u64 v[4:5], v[2:3], 0, s[8:9]
	s_mov_b32 s8, 0x100000
	v_and_or_b32 v6, v10, s67, v12
	v_add_co_u32_e32 v10, vcc, s8, v2
	v_and_or_b32 v7, v11, s67, v13
	s_nop 0
	v_addc_co_u32_e32 v11, vcc, 0, v3, vcc
	global_store_dwordx4 v[10:11], v[6:9], off
	s_nop 1
	s_nop 0
	v_fmamk_f32 v6, v80, 0x3c800000, v234
	v_mul_f32_e32 v6, 0xbfb8aa3b, v6
	v_exp_f32_e32 v14, v6
	v_fmamk_f32 v6, v85, 0x3c800000, v239
	v_mul_f32_e32 v6, 0xbfb8aa3b, v6
	v_fmamk_f32 v10, v84, 0x3c800000, v238
	v_exp_f32_e32 v16, v6
	v_fmamk_f32 v6, v81, 0x3c800000, v235
	v_fmamk_f32 v7, v86, 0x3c800000, v240
	v_mul_f32_e32 v10, 0xbfb8aa3b, v10
	v_mul_f32_e32 v7, 0xbfb8aa3b, v7
	v_exp_f32_e32 v10, v10
	v_exp_f32_e32 v11, v7
	v_fmamk_f32 v7, v82, 0x3c800000, v236
	v_mul_f32_e32 v7, 0xbfb8aa3b, v7
	v_fmamk_f32 v13, v87, 0x3c800000, v241
	v_exp_f32_e32 v15, v7
	v_mul_f32_e32 v7, 0xbfb8aa3b, v13
	v_fmamk_f32 v9, v83, 0x3c800000, v237
	v_exp_f32_e32 v17, v7
	v_mul_f32_e32 v7, 0xbfb8aa3b, v9
	v_pk_add_f32 v[8:9], v[10:11], 1.0 op_sel_hi:[1,0]
	v_mul_f32_e32 v6, 0xbfb8aa3b, v6
	v_exp_f32_e32 v6, v6
	v_exp_f32_e32 v7, v7
	v_rcp_f32_e32 v10, v9
	v_pk_add_f32 v[6:7], v[6:7], 1.0 op_sel_hi:[1,0]
	v_rcp_f32_e32 v11, v8
	v_pk_add_f32 v[8:9], v[16:17], 1.0 op_sel_hi:[1,0]
	s_nop 0
	v_rcp_f32_e32 v12, v8
	v_rcp_f32_e32 v13, v9
	v_pk_add_f32 v[8:9], v[14:15], 1.0 op_sel_hi:[1,0]
	s_nop 0
	v_rcp_f32_e32 v9, v9
	v_rcp_f32_e32 v8, v8
	v_rcp_f32_e32 v6, v6
	v_rcp_f32_e32 v7, v7
	s_nop 0
	v_cvt_pk_bf16_f32 v9, v9, v7
	v_cvt_pk_bf16_f32 v8, v8, v6
	v_cvt_pk_bf16_f32 v7, v10, v13
	v_cvt_pk_bf16_f32 v6, v11, v12
	global_store_dwordx4 v[4:5], v[6:9], off offset:256
	s_nop 0
	v_fmamk_f32 v4, v72, 0x3c800000, v226
	v_mul_f32_e32 v4, 0xbfb8aa3b, v4
	v_exp_f32_e32 v12, v4
	v_fmamk_f32 v4, v77, 0x3c800000, v231
	v_mul_f32_e32 v4, 0xbfb8aa3b, v4
	v_fmamk_f32 v8, v76, 0x3c800000, v230
	v_exp_f32_e32 v14, v4
	v_fmamk_f32 v4, v73, 0x3c800000, v227
	v_fmamk_f32 v5, v78, 0x3c800000, v232
	v_mul_f32_e32 v8, 0xbfb8aa3b, v8
	v_mul_f32_e32 v5, 0xbfb8aa3b, v5
	v_exp_f32_e32 v8, v8
	v_exp_f32_e32 v9, v5
	v_fmamk_f32 v5, v74, 0x3c800000, v228
	v_mul_f32_e32 v5, 0xbfb8aa3b, v5
	v_fmamk_f32 v11, v79, 0x3c800000, v233
	v_exp_f32_e32 v13, v5
	v_mul_f32_e32 v5, 0xbfb8aa3b, v11
	v_fmamk_f32 v7, v75, 0x3c800000, v229
	v_exp_f32_e32 v15, v5
	v_mul_f32_e32 v5, 0xbfb8aa3b, v7
	v_pk_add_f32 v[6:7], v[8:9], 1.0 op_sel_hi:[1,0]
	v_mul_f32_e32 v4, 0xbfb8aa3b, v4
	v_exp_f32_e32 v4, v4
	v_exp_f32_e32 v5, v5
	v_rcp_f32_e32 v8, v7
	v_pk_add_f32 v[4:5], v[4:5], 1.0 op_sel_hi:[1,0]
	v_rcp_f32_e32 v9, v6
; __device__ __forceinline__ unsigned pk2(float lo, float hi) { return f2bf(lo) | (f2bf(hi) << 16); }
;     __device__ __forceinline__ void operator()(const f32x4 (&acc)[2][2][4][2], const pg8::Unit& u, int wr, int wc, int fr, int fq) const {
;     ...
;                     } else if constexpr (MODE == 1) {
;                         const f32x4 b0 = *(const f32x4*)(vec + col), b1 = *(const f32x4*)(vec + col + 4);
;                         float r[8];
; #pragma unroll
;                         for (int i = 0; i < 4; ++i) { r[i] = 1.f / (1.f + __expf(-(v0[i] + b0[i]))); r[4 + i] = 1.f / (1.f + __expf(-(v1[i] + b1[i]))); }
;                         u32x4 w; w.x = pk2(r[0], r[1]); w.y = pk2(r[2], r[3]); w.z = pk2(r[4], r[5]); w.w = pk2(r[6], r[7]);
;                         *(u32x4*)(ob + row * 4096 + col) = w;
	v_pk_add_f32 v[6:7], v[14:15], 1.0 op_sel_hi:[1,0]
	s_nop 0
	v_rcp_f32_e32 v10, v6
	v_rcp_f32_e32 v11, v7
	v_pk_add_f32 v[6:7], v[12:13], 1.0 op_sel_hi:[1,0]
	s_nop 0
	v_rcp_f32_e32 v7, v7
	v_rcp_f32_e32 v6, v6
	v_rcp_f32_e32 v4, v4
	s_mov_b64 s[8:9], 0x120000
	v_rcp_f32_e32 v5, v5
	v_bfe_u32 v14, v11, 16, 1
	v_bfe_u32 v15, v10, 16, 1
	v_add3_u32 v10, v10, v15, s33
	v_add3_u32 v11, v11, v14, s33
	v_bfe_u32 v12, v9, 16, 1
	v_bfe_u32 v13, v8, 16, 1
	v_add3_u32 v8, v8, v13, s33
	v_add3_u32 v9, v9, v12, s33
	v_lshrrev_b32_e32 v12, 16, v9
	v_lshrrev_b32_e32 v13, 16, v8
	v_cvt_pk_bf16_f32 v9, v7, v5
	v_cvt_pk_bf16_f32 v8, v6, v4
	v_lshl_add_u64 v[4:5], v[2:3], 0, s[8:9]
	s_mov_b32 s8, 0x120000
	v_and_or_b32 v6, v10, s67, v12
	v_add_co_u32_e32 v10, vcc, s8, v2
	v_and_or_b32 v7, v11, s67, v13
	s_nop 0
	v_addc_co_u32_e32 v11, vcc, 0, v3, vcc
	global_store_dwordx4 v[10:11], v[6:9], off
	s_nop 1
	s_nop 0
	v_fmamk_f32 v6, v64, 0x3c800000, v234
	v_mul_f32_e32 v6, 0xbfb8aa3b, v6
	v_exp_f32_e32 v14, v6
	v_fmamk_f32 v6, v69, 0x3c800000, v239
	v_mul_f32_e32 v6, 0xbfb8aa3b, v6
	v_fmamk_f32 v10, v68, 0x3c800000, v238
	v_exp_f32_e32 v16, v6
	v_fmamk_f32 v6, v65, 0x3c800000, v235
	v_fmamk_f32 v7, v70, 0x3c800000, v240
	v_mul_f32_e32 v10, 0xbfb8aa3b, v10
	v_mul_f32_e32 v7, 0xbfb8aa3b, v7
	v_exp_f32_e32 v10, v10
	v_exp_f32_e32 v11, v7
	v_fmamk_f32 v7, v66, 0x3c800000, v236
	v_mul_f32_e32 v7, 0xbfb8aa3b, v7
	v_fmamk_f32 v13, v71, 0x3c800000, v241
	v_exp_f32_e32 v15, v7
	v_mul_f32_e32 v7, 0xbfb8aa3b, v13
	v_fmamk_f32 v9, v67, 0x3c800000, v237
	v_exp_f32_e32 v17, v7
	v_mul_f32_e32 v7, 0xbfb8aa3b, v9
	v_pk_add_f32 v[8:9], v[10:11], 1.0 op_sel_hi:[1,0]
	v_mul_f32_e32 v6, 0xbfb8aa3b, v6
	v_exp_f32_e32 v6, v6
	v_exp_f32_e32 v7, v7
	v_rcp_f32_e32 v10, v9
	v_pk_add_f32 v[6:7], v[6:7], 1.0 op_sel_hi:[1,0]
	v_rcp_f32_e32 v11, v8
	v_pk_add_f32 v[8:9], v[16:17], 1.0 op_sel_hi:[1,0]
	s_nop 0
	v_rcp_f32_e32 v12, v8
	v_rcp_f32_e32 v13, v9
	v_pk_add_f32 v[8:9], v[14:15], 1.0 op_sel_hi:[1,0]
	s_nop 0
	v_rcp_f32_e32 v9, v9
	v_rcp_f32_e32 v8, v8
	v_rcp_f32_e32 v6, v6
	v_rcp_f32_e32 v7, v7
	s_nop 0
	v_cvt_pk_bf16_f32 v9, v9, v7
	v_cvt_pk_bf16_f32 v8, v8, v6
	v_cvt_pk_bf16_f32 v7, v10, v13
	v_cvt_pk_bf16_f32 v6, v11, v12
	global_store_dwordx4 v[4:5], v[6:9], off offset:256
	s_nop 0
	v_fmamk_f32 v4, v56, 0x3c800000, v226
	v_mul_f32_e32 v4, 0xbfb8aa3b, v4
	v_exp_f32_e32 v12, v4
	v_fmamk_f32 v4, v61, 0x3c800000, v231
	v_mul_f32_e32 v4, 0xbfb8aa3b, v4
	v_fmamk_f32 v8, v60, 0x3c800000, v230
	v_exp_f32_e32 v14, v4
	v_fmamk_f32 v4, v57, 0x3c800000, v227
	v_fmamk_f32 v5, v62, 0x3c800000, v232
	v_mul_f32_e32 v8, 0xbfb8aa3b, v8
	v_mul_f32_e32 v5, 0xbfb8aa3b, v5
	v_exp_f32_e32 v8, v8
	v_exp_f32_e32 v9, v5
	v_fmamk_f32 v5, v58, 0x3c800000, v228
	v_mul_f32_e32 v5, 0xbfb8aa3b, v5
	v_fmamk_f32 v11, v63, 0x3c800000, v233
	v_exp_f32_e32 v13, v5
	v_mul_f32_e32 v5, 0xbfb8aa3b, v11
	v_fmamk_f32 v7, v59, 0x3c800000, v229
	v_exp_f32_e32 v15, v5
	v_mul_f32_e32 v5, 0xbfb8aa3b, v7
	v_pk_add_f32 v[6:7], v[8:9], 1.0 op_sel_hi:[1,0]
	v_mul_f32_e32 v4, 0xbfb8aa3b, v4
	v_exp_f32_e32 v4, v4
	v_exp_f32_e32 v5, v5
	v_rcp_f32_e32 v8, v7
	v_pk_add_f32 v[4:5], v[4:5], 1.0 op_sel_hi:[1,0]
	v_rcp_f32_e32 v9, v6
	v_pk_add_f32 v[6:7], v[14:15], 1.0 op_sel_hi:[1,0]
	s_nop 0
	v_rcp_f32_e32 v10, v6
	v_rcp_f32_e32 v11, v7
	v_pk_add_f32 v[6:7], v[12:13], 1.0 op_sel_hi:[1,0]
	s_nop 0
	v_rcp_f32_e32 v7, v7
	v_rcp_f32_e32 v6, v6
	v_rcp_f32_e32 v4, v4
	s_mov_b64 s[8:9], 0x140000
	v_rcp_f32_e32 v5, v5
	v_bfe_u32 v14, v11, 16, 1
	v_bfe_u32 v15, v10, 16, 1
	v_add3_u32 v10, v10, v15, s33
	v_add3_u32 v11, v11, v14, s33
	v_bfe_u32 v12, v9, 16, 1
	v_bfe_u32 v13, v8, 16, 1
	v_add3_u32 v8, v8, v13, s33
	v_add3_u32 v9, v9, v12, s33
	v_lshrrev_b32_e32 v12, 16, v9
	v_lshrrev_b32_e32 v13, 16, v8
	v_cvt_pk_bf16_f32 v9, v7, v5
	v_cvt_pk_bf16_f32 v8, v6, v4
	v_lshl_add_u64 v[4:5], v[2:3], 0, s[8:9]
	s_mov_b32 s8, 0x140000
	v_and_or_b32 v6, v10, s67, v12
	v_add_co_u32_e32 v10, vcc, s8, v2
	v_and_or_b32 v7, v11, s67, v13
	s_nop 0
	v_addc_co_u32_e32 v11, vcc, 0, v3, vcc
	global_store_dwordx4 v[10:11], v[6:9], off
	s_nop 1
	s_nop 0
	v_fmamk_f32 v6, v48, 0x3c800000, v234
	v_mul_f32_e32 v6, 0xbfb8aa3b, v6
	v_exp_f32_e32 v14, v6
	v_fmamk_f32 v6, v53, 0x3c800000, v239
	v_mul_f32_e32 v6, 0xbfb8aa3b, v6
	v_fmamk_f32 v10, v52, 0x3c800000, v238
	v_exp_f32_e32 v16, v6
	v_fmamk_f32 v6, v49, 0x3c800000, v235
	v_fmamk_f32 v7, v54, 0x3c800000, v240
	v_mul_f32_e32 v10, 0xbfb8aa3b, v10
	v_mul_f32_e32 v7, 0xbfb8aa3b, v7
	v_exp_f32_e32 v10, v10
	v_exp_f32_e32 v11, v7
	v_fmamk_f32 v7, v50, 0x3c800000, v236
	v_mul_f32_e32 v7, 0xbfb8aa3b, v7
	v_fmamk_f32 v13, v55, 0x3c800000, v241
	v_exp_f32_e32 v15, v7
	v_mul_f32_e32 v7, 0xbfb8aa3b, v13
	v_fmamk_f32 v9, v51, 0x3c800000, v237
	v_exp_f32_e32 v17, v7
	v_mul_f32_e32 v7, 0xbfb8aa3b, v9
; __device__ __forceinline__ unsigned pk2(float lo, float hi) { return f2bf(lo) | (f2bf(hi) << 16); }
; template <class Epi, class Sched, bool ALIGN_EPI = false, bool SP2 = false, bool F8 = false>
; __device__ __forceinline__ void gemm_phase(PG8_LAS unsigned char* lds, const Gemm g, const Sched& S, const Epi& E) {
;     ...
;         if constexpr (!Epi::AFTER_DRAIN) { E(acc, cur, wr, wc, fr, fq); S.done(cur); }
;         if (!has_next) break;
;     __device__ __forceinline__ void operator()(const f32x4 (&acc)[2][2][4][2], const pg8::Unit& u, int wr, int wc, int fr, int fq) const {
;     ...
;                     } else if constexpr (MODE == 1) {
;                         const f32x4 b0 = *(const f32x4*)(vec + col), b1 = *(const f32x4*)(vec + col + 4);
;                         float r[8];
; #pragma unroll
;                         for (int i = 0; i < 4; ++i) { r[i] = 1.f / (1.f + __expf(-(v0[i] + b0[i]))); r[4 + i] = 1.f / (1.f + __expf(-(v1[i] + b1[i]))); }
;                         u32x4 w; w.x = pk2(r[0], r[1]); w.y = pk2(r[2], r[3]); w.z = pk2(r[4], r[5]); w.w = pk2(r[6], r[7]);
;                         *(u32x4*)(ob + row * 4096 + col) = w;
	v_pk_add_f32 v[8:9], v[10:11], 1.0 op_sel_hi:[1,0]
	v_mul_f32_e32 v6, 0xbfb8aa3b, v6
	v_exp_f32_e32 v6, v6
	v_exp_f32_e32 v7, v7
	v_rcp_f32_e32 v10, v9
	v_pk_add_f32 v[6:7], v[6:7], 1.0 op_sel_hi:[1,0]
	v_rcp_f32_e32 v11, v8
	v_pk_add_f32 v[8:9], v[16:17], 1.0 op_sel_hi:[1,0]
	s_nop 0
	v_rcp_f32_e32 v12, v8
	v_rcp_f32_e32 v13, v9
	v_pk_add_f32 v[8:9], v[14:15], 1.0 op_sel_hi:[1,0]
	s_nop 0
	v_rcp_f32_e32 v9, v9
	v_rcp_f32_e32 v8, v8
	v_rcp_f32_e32 v6, v6
	v_div_scale_f32 v14, s[8:9], v7, v7, 1.0
	v_rcp_f32_e32 v15, v14
	s_nop 0
	v_fma_f32 v16, -v14, v15, 1.0
	v_fmac_f32_e32 v15, v16, v15
	v_div_scale_f32 v16, vcc, 1.0, v7, 1.0
	v_mul_f32_e32 v17, v16, v15
	v_fma_f32 v18, -v14, v17, v16
	v_fmac_f32_e32 v17, v18, v15
	v_rcp_f32_e32 v7, v7
	s_nop 0
	v_cvt_pk_bf16_f32 v9, v9, v7
	v_cvt_pk_bf16_f32 v8, v8, v6
	v_cvt_pk_bf16_f32 v7, v10, v13
	v_cvt_pk_bf16_f32 v6, v11, v12
	global_store_dwordx4 v[4:5], v[6:9], off offset:256
	s_nop 0
	v_fmamk_f32 v4, v40, 0x3c800000, v226
	v_mul_f32_e32 v4, 0xbfb8aa3b, v4
	v_exp_f32_e32 v12, v4
	v_fmamk_f32 v4, v45, 0x3c800000, v231
	v_mul_f32_e32 v4, 0xbfb8aa3b, v4
	v_fmamk_f32 v8, v44, 0x3c800000, v230
	v_exp_f32_e32 v14, v4
	v_fmamk_f32 v4, v41, 0x3c800000, v227
	v_fmamk_f32 v5, v46, 0x3c800000, v232
	v_mul_f32_e32 v8, 0xbfb8aa3b, v8
	v_mul_f32_e32 v5, 0xbfb8aa3b, v5
	v_exp_f32_e32 v8, v8
	v_exp_f32_e32 v9, v5
	v_fmamk_f32 v5, v42, 0x3c800000, v228
	v_mul_f32_e32 v5, 0xbfb8aa3b, v5
	v_fmamk_f32 v11, v47, 0x3c800000, v233
	v_exp_f32_e32 v13, v5
	v_mul_f32_e32 v5, 0xbfb8aa3b, v11
	v_fmamk_f32 v7, v43, 0x3c800000, v229
	v_exp_f32_e32 v15, v5
	v_mul_f32_e32 v5, 0xbfb8aa3b, v7
	v_pk_add_f32 v[6:7], v[8:9], 1.0 op_sel_hi:[1,0]
	v_mul_f32_e32 v4, 0xbfb8aa3b, v4
	v_exp_f32_e32 v4, v4
	v_exp_f32_e32 v5, v5
	v_rcp_f32_e32 v8, v7
	v_pk_add_f32 v[4:5], v[4:5], 1.0 op_sel_hi:[1,0]
	v_rcp_f32_e32 v9, v6
	v_pk_add_f32 v[6:7], v[14:15], 1.0 op_sel_hi:[1,0]
	s_nop 0
	v_rcp_f32_e32 v10, v6
	v_rcp_f32_e32 v11, v7
	v_pk_add_f32 v[6:7], v[12:13], 1.0 op_sel_hi:[1,0]
	s_nop 0
	v_rcp_f32_e32 v7, v7
	v_rcp_f32_e32 v6, v6
	v_rcp_f32_e32 v4, v4
	v_div_scale_f32 v12, s[8:9], v5, v5, 1.0
	v_rcp_f32_e32 v13, v12
	s_mov_b64 s[8:9], 0x160000
	v_fma_f32 v14, -v12, v13, 1.0
	v_fmac_f32_e32 v13, v14, v13
	v_div_scale_f32 v14, vcc, 1.0, v5, 1.0
	v_mul_f32_e32 v15, v14, v13
	v_fma_f32 v16, -v12, v15, v14
	v_rcp_f32_e32 v5, v5
	v_bfe_u32 v14, v11, 16, 1
	v_bfe_u32 v15, v10, 16, 1
	v_add3_u32 v10, v10, v15, s33
	v_add3_u32 v11, v11, v14, s33
	v_bfe_u32 v12, v9, 16, 1
	v_bfe_u32 v13, v8, 16, 1
	v_add3_u32 v8, v8, v13, s33
	v_add3_u32 v9, v9, v12, s33
	v_lshrrev_b32_e32 v12, 16, v9
	v_lshrrev_b32_e32 v13, 16, v8
	v_cvt_pk_bf16_f32 v9, v7, v5
	v_cvt_pk_bf16_f32 v8, v6, v4
	v_lshl_add_u64 v[4:5], v[2:3], 0, s[8:9]
	s_mov_b32 s8, 0x160000
	v_add_co_u32_e32 v2, vcc, s8, v2
	v_and_or_b32 v7, v11, s67, v13
	v_and_or_b32 v6, v10, s67, v12
	v_addc_co_u32_e32 v3, vcc, 0, v3, vcc
	global_store_dwordx4 v[2:3], v[6:9], off
	s_nop 1
	s_nop 0
	v_fmamk_f32 v9, v35, 0x3c800000, v237
	v_fmamk_f32 v0, v36, 0x3c800000, v238
	v_mul_f32_e32 v0, 0xbfb8aa3b, v0
	v_exp_f32_e32 v10, v0
	v_fmamk_f32 v0, v32, 0x3c800000, v234
	v_mul_f32_e32 v0, 0xbfb8aa3b, v0
	v_exp_f32_e32 v6, v0
	v_fmamk_f32 v0, v37, 0x3c800000, v239
	v_fmamk_f32 v1, v38, 0x3c800000, v240
	v_mul_f32_e32 v1, 0xbfb8aa3b, v1
	v_exp_f32_e32 v11, v1
	v_fmamk_f32 v1, v34, 0x3c800000, v236
	v_mul_f32_e32 v0, 0xbfb8aa3b, v0
	v_mul_f32_e32 v1, 0xbfb8aa3b, v1
	v_fmamk_f32 v3, v39, 0x3c800000, v241
	v_exp_f32_e32 v12, v0
	v_fmamk_f32 v0, v33, 0x3c800000, v235
	v_exp_f32_e32 v7, v1
	v_mul_f32_e32 v1, 0xbfb8aa3b, v3
	v_pk_add_f32 v[2:3], v[10:11], 1.0 op_sel_hi:[1,0]
	v_exp_f32_e32 v13, v1
	v_mul_f32_e32 v1, 0xbfb8aa3b, v9
	v_mul_f32_e32 v0, 0xbfb8aa3b, v0
	v_exp_f32_e32 v0, v0
	v_exp_f32_e32 v1, v1
	v_rcp_f32_e32 v8, v3
	v_pk_add_f32 v[0:1], v[0:1], 1.0 op_sel_hi:[1,0]
	v_rcp_f32_e32 v9, v2
	v_pk_add_f32 v[2:3], v[12:13], 1.0 op_sel_hi:[1,0]
	s_nop 0
	v_rcp_f32_e32 v10, v2
	v_rcp_f32_e32 v11, v3
	v_pk_add_f32 v[2:3], v[6:7], 1.0 op_sel_hi:[1,0]
	s_nop 0
	v_rcp_f32_e32 v3, v3
	v_rcp_f32_e32 v2, v2
	v_rcp_f32_e32 v0, v0
	v_div_scale_f32 v6, s[8:9], v1, v1, 1.0
	v_rcp_f32_e32 v7, v6
	s_nop 0
	v_fma_f32 v12, -v6, v7, 1.0
	v_fmac_f32_e32 v7, v12, v7
	v_div_scale_f32 v12, vcc, 1.0, v1, 1.0
	v_mul_f32_e32 v13, v12, v7
	v_fma_f32 v14, -v6, v13, v12
	v_fmac_f32_e32 v13, v14, v7
	v_fma_f32 v6, -v6, v13, v12
	v_div_fmas_f32 v6, v6, v7, v13
	v_rcp_f32_e32 v1, v1
	s_nop 0
	v_cvt_pk_bf16_f32 v3, v3, v1
	v_cvt_pk_bf16_f32 v2, v2, v0
	v_cvt_pk_bf16_f32 v1, v8, v11
	v_cvt_pk_bf16_f32 v0, v9, v10
	s_andn2_b64 vcc, exec, s[38:39]
	global_store_dwordx4 v[4:5], v[0:3], off offset:256
	s_mov_b32 s101, 1
	s_cbranch_vccnz .LBB0_1114
	s_andn2_b64 vcc, exec, s[0:1]
	s_cbranch_vccnz .LBB0_1113
	s_barrier
	s_branch .LBB0_1113

; #define PG8_STAGE(bufoff, gbase, voff) do { _Pragma("unroll") for (int _i = 0; _i < 2; ++_i) \
;         __builtin_amdgcn_global_load_lds((const unsigned*)((const char*)(gbase) + (voff)[_i]), (PG8_LAS unsigned*)(lds + (bufoff) + ldsw + _i * 8192), 16, 0, 0); } while (0)
; #define PG8_WAIT_V(n) asm volatile("s_waitcnt vmcnt(" #n ")" ::: "memory")
; #define PG8_BAR __builtin_amdgcn_s_barrier()
; template <class Epi, class Sched, bool ALIGN_EPI = false, bool SP2 = false, bool F8 = false>
; __device__ __forceinline__ void gemm_phase(PG8_LAS unsigned char* lds, const Gemm g, const Sched& S, const Epi& E) {
;     int tid_ = threadIdx.x; asm volatile("" : "+v"(tid_)); const int tid = tid_, wid = __builtin_amdgcn_readfirstlane(tid >> 6), lane = tid & 63, wr = wid >> 2, wc = wid & 3, fr = lane & 15, fq = lane >> 4;
;     const int K = g.K, nt = K / BK;
;     unsigned voffA[2], voffB[2];
; #pragma unroll
;     for (int i = 0; i < 2; ++i) { int R, C; stage_rc(tid * 16 + i * 8192, R, C); const int Rb = Epi::PERM ? ((R & ~31) + perm32(R & 31)) : R;
;         voffA[i] = (unsigned)(R * K + C) * 2u; voffB[i] = (unsigned)(Rb * K + C) * 2u; }
;     const size_t kstep = (size_t)(BK * 2);
;     const size_t hstep = (size_t)HALF * K * 2;
;     const size_t tstep = 2 * hstep;
;     const unsigned ldsw = (unsigned)wid * 1024u;
;     const int aoff = lds_byte(wr * 64 + fr, fq * 8), boff = lds_byte(wc * 32 + fr, fq * 8);
;     ...
;         PG8_STAGE(PG8_SB(0, 0), cB, voffB); PG8_STAGE(PG8_SB(0, 1), cB + hstep, voffB); PG8_STAGE(PG8_SA(0, 0), cA, voffA); PG8_STAGE(PG8_SA(0, 1), cA + hstep, voffA);
;         if (wr == 1) PG8_BAR;
;         PG8_WAIT_V(2); PG8_BAR;
;         PG8_STAGE(PG8_SB(1, 0), cB + kstep, voffB); PG8_STAGE(PG8_SA(1, 0), cA + kstep, voffA); PG8_STAGE(PG8_SB(1, 1), cB + hstep + kstep, voffB);
;         PG8_WAIT_V(6); PG8_BAR;
.LBB0_1138:
	s_waitcnt vmcnt(0)
	v_lshrrev_b32_e32 v16, 1, v14
	s_sext_i32_i8 s45, s4
	v_readlane_b32 s4, v250, 24
	v_and_b32_e32 v16, 24, v16
	v_readlane_b32 s5, v250, 25
	s_add_u32 s4, s4, 0xa000
	v_and_b32_e32 v15, 15, v14
	v_lshlrev_b32_e32 v17, 1, v16
	v_lshlrev_b32_e32 v14, 2, v14
	s_addc_u32 s5, s5, 0
	v_lshl_or_b32 v146, s8, 6, v15
	v_lshl_or_b32 v15, v15, 6, v17
	s_lshl_b32 s8, s8, 13
	v_and_b32_e32 v14, 32, v14
	v_bitop3_b32 v17, v15, s8, v14 bitop3:0xde
	s_lshl_b32 s8, s9, 5
	s_and_b32 s35, s8, 0x60
	s_lshl_b32 s8, s35, 7
	s_add_i32 m0, s23, 0x18000
	v_lshl_add_u64 v[6:7], v[6:7], 0, s[14:15]
	v_bitop3_b32 v147, v15, s8, v14 bitop3:0xde
	s_waitcnt vmcnt(2)
	s_barrier
	global_load_lds_dwordx4 v[6:7], off
	v_lshl_add_u64 v[4:5], v[4:5], 0, s[14:15]
	s_add_i32 m0, s23, 0x1a000
	s_add_i32 s8, s23, 0x8000
	s_add_i32 s9, s23, 0xa000
	global_load_lds_dwordx4 v[4:5], off
	v_lshl_add_u64 v[0:1], v[0:1], 0, s[14:15]
	s_mov_b32 m0, s8
	s_add_u32 s16, s48, 0x200080
	global_load_lds_dwordx4 v[0:1], off
	v_lshl_add_u64 v[0:1], v[2:3], 0, s[14:15]
	s_mov_b32 m0, s9
	s_addc_u32 s17, s49, 0
	global_load_lds_dwordx4 v[0:1], off
	s_add_i32 m0, s23, 0x1c000
	v_lshl_add_u64 v[0:1], s[16:17], 0, v[160:161]
	global_load_lds_dwordx4 v[0:1], off
	v_lshl_add_u64 v[0:1], s[16:17], 0, v[132:133]
	s_add_i32 m0, s23, 0x1e000
	s_cmpk_lt_u32 s10, 0x100
	global_load_lds_dwordx4 v[0:1], off
	v_lshlrev_b32_e32 v0, 17, v8
	v_and_b32_e32 v0, 0xfffc0000, v0
	v_lshl_add_u32 v0, v9, 14, v0
	v_and_b32_e32 v1, 1, v8
	v_lshl_or_b32 v0, v1, 6, v0
	v_lshl_add_u32 v134, v10, 1, v0
	v_lshlrev_b32_e32 v0, 17, v11
	v_and_b32_e32 v0, 0xfffc0000, v0
	s_waitcnt vmcnt(6)
	v_lshl_add_u32 v0, v12, 14, v0
	v_and_b32_e32 v1, 1, v11
	v_lshl_or_b32 v0, v1, 6, v0
	s_cselect_b64 s[10:11], -1, 0
	v_or_b32_e32 v148, s35, v16
	v_mov_b32_e32 v135, v161
	v_lshl_add_u32 v136, v13, 1, v0
	v_mov_b32_e32 v137, v161
	s_mov_b32 s35, 0
	v_add_u32_e32 v149, 0, v17
	s_barrier
	s_mov_b32 s101, 0
	s_branch .LBB0_1141

; #define PG8_STAGE(bufoff, gbase, voff) do { _Pragma("unroll") for (int _i = 0; _i < 2; ++_i) \
;         __builtin_amdgcn_global_load_lds((const unsigned*)((const char*)(gbase) + (voff)[_i]), (PG8_LAS unsigned*)(lds + (bufoff) + ldsw + _i * 8192), 16, 0, 0); } while (0)
; #define PG8_WAIT_V(n) asm volatile("s_waitcnt vmcnt(" #n ")" ::: "memory")
; #define PG8_WAIT_L(n) asm volatile("s_waitcnt lgkmcnt(" #n ")" ::: "memory")
; #define PG8_BAR __builtin_amdgcn_s_barrier()
; #define PG8_SCHED __builtin_amdgcn_sched_barrier(0)
; template <class Epi, class Sched, bool ALIGN_EPI = false, bool SP2 = false, bool F8 = false>
; __device__ __forceinline__ void gemm_phase(PG8_LAS unsigned char* lds, const Gemm g, const Sched& S, const Epi& E) {
;     ...
;             PG8_LDB(B0, 0, 0); PG8_LDB(B1, 0, 1); PG8_SCHED; PG8_LDA(At, 0, 0); PG8_STAGE(PG8_SA(1, 1), a1 + hstep, voffA);
;             PG8_WAIT_V(8); PG8_WAIT_L(0); PG8_BAR; PG8_MMA(0, 0, At, B0); PG8_MMA(0, 1, At, B1); PG8_BAR; PG8_SCHED;
;             PG8_LDA(At, 0, 1); PG8_STAGE(PG8_SB(0, 0), b2, voffB); PG8_STAGE(PG8_SB(0, 1), b2 + hstep, voffB); PG8_STAGE(PG8_SA(0, 0), a2, voffA);
.LBB0_1147:
	s_ashr_i32 s37, s36, 31
	s_lshl_b64 s[40:41], s[36:37], 22
	s_add_u32 s40, s20, s40
	s_addc_u32 s41, s21, s41
	s_and_b64 s[42:43], s[38:39], exec
	s_cselect_b32 s37, s41, s47
	s_cselect_b32 s52, s40, s46
	s_ashr_i32 s17, s16, 31
	s_lshl_b64 s[42:43], s[16:17], 22
	s_add_u32 s42, s13, s42
	s_addc_u32 s43, s19, s43
	s_and_b64 s[50:51], s[38:39], exec
	s_cselect_b32 s17, s43, s49
	s_cselect_b32 s53, s42, s48
	s_add_u32 s46, s46, 0x200080
	s_addc_u32 s47, s47, 0
	s_add_u32 s54, s48, 0x100
	s_addc_u32 s55, s49, 0
	s_mov_b32 s56, -2
	s_add_u32 s48, s46, 0xffe00080
	s_addc_u32 s49, s47, -1
	s_add_i32 s58, 0, 0x10000
	s_cmpk_eq_i32 s56, 0x7c
	s_cselect_b32 s51, s37, s49
	s_cselect_b32 s50, s52, s48
	s_cselect_b32 s49, s17, s55
	s_cselect_b32 s48, s53, s54
	s_add_i32 s60, 0, 0x14000
	v_add_u32_e32 v154, s58, v147
	v_add_u32_e32 v158, s60, v147
	ds_read_b128 v[138:141], v154
	ds_read_b128 v[142:145], v154 offset:1024
	ds_read_b128 v[150:153], v154 offset:2048
	ds_read_b128 v[154:157], v154 offset:3072
	ds_read_b128 v[184:187], v158
	ds_read_b128 v[188:191], v158 offset:1024
	ds_read_b128 v[192:195], v158 offset:2048
	ds_read_b128 v[196:199], v158 offset:3072
	v_lshl_add_u64 v[158:159], s[46:47], 0, v[134:135]
	s_add_i32 m0, s23, 0xc000
	ds_read_b128 v[200:203], v149
	ds_read_b128 v[214:217], v149 offset:1024
	ds_read_b128 v[218:221], v149 offset:2048
	ds_read_b128 v[222:225], v149 offset:3072
	ds_read_b128 v[226:229], v149 offset:4096
	ds_read_b128 v[230:233], v149 offset:5120
	ds_read_b128 v[234:237], v149 offset:6144
	ds_read_b128 v[238:241], v149 offset:7168
	global_load_lds_dwordx4 v[158:159], off
	v_lshl_add_u64 v[158:159], s[46:47], 0, v[136:137]
	s_add_i32 m0, s23, 0xe000
	s_nop 0
	global_load_lds_dwordx4 v[158:159], off
	s_cmp_lg_u32 s101, 0
	s_cbranch_scc1 .Lgk_nw1_1148
	s_waitcnt vmcnt(8)
.Lgk_nw1_1148:
	s_waitcnt lgkmcnt(0)
	s_barrier
	s_setprio 1
	s_waitcnt lgkmcnt(0)
	v_mfma_f32_16x16x32_bf16 v[124:127], v[138:141], v[200:203], 0
	v_mfma_f32_16x16x32_bf16 v[120:123], v[150:153], v[200:203], 0
	v_mfma_f32_16x16x32_bf16 v[108:111], v[138:141], v[218:221], 0
	v_mfma_f32_16x16x32_bf16 v[104:107], v[150:153], v[218:221], 0
	v_mfma_f32_16x16x32_bf16 v[92:95], v[138:141], v[226:229], 0
	v_mfma_f32_16x16x32_bf16 v[88:91], v[150:153], v[226:229], 0
	v_mfma_f32_16x16x32_bf16 v[76:79], v[138:141], v[234:237], 0
	v_mfma_f32_16x16x32_bf16 v[72:75], v[150:153], v[234:237], 0
	v_mfma_f32_16x16x32_bf16 v[124:127], v[142:145], v[214:217], v[124:127]
	v_mfma_f32_16x16x32_bf16 v[120:123], v[154:157], v[214:217], v[120:123]
	v_mfma_f32_16x16x32_bf16 v[108:111], v[142:145], v[222:225], v[108:111]
	v_mfma_f32_16x16x32_bf16 v[104:107], v[154:157], v[222:225], v[104:107]
	v_mfma_f32_16x16x32_bf16 v[92:95], v[142:145], v[230:233], v[92:95]
	v_mfma_f32_16x16x32_bf16 v[88:91], v[154:157], v[230:233], v[88:91]
	v_mfma_f32_16x16x32_bf16 v[76:79], v[142:145], v[238:241], v[76:79]
	v_mfma_f32_16x16x32_bf16 v[72:75], v[154:157], v[238:241], v[72:75]
	s_setprio 0
	s_setprio 1
	v_mfma_f32_16x16x32_bf16 v[116:119], v[184:187], v[200:203], 0
	v_mfma_f32_16x16x32_bf16 v[112:115], v[192:195], v[200:203], 0
	v_mfma_f32_16x16x32_bf16 v[100:103], v[184:187], v[218:221], 0
	v_mfma_f32_16x16x32_bf16 v[96:99], v[192:195], v[218:221], 0
	v_mfma_f32_16x16x32_bf16 v[84:87], v[184:187], v[226:229], 0
	v_mfma_f32_16x16x32_bf16 v[80:83], v[192:195], v[226:229], 0
	v_mfma_f32_16x16x32_bf16 v[68:71], v[184:187], v[234:237], 0
	v_mfma_f32_16x16x32_bf16 v[64:67], v[192:195], v[234:237], 0
	v_mfma_f32_16x16x32_bf16 v[116:119], v[188:191], v[214:217], v[116:119]
	v_mfma_f32_16x16x32_bf16 v[112:115], v[196:199], v[214:217], v[112:115]
	v_mfma_f32_16x16x32_bf16 v[100:103], v[188:191], v[222:225], v[100:103]
	v_mfma_f32_16x16x32_bf16 v[96:99], v[196:199], v[222:225], v[96:99]
	v_mfma_f32_16x16x32_bf16 v[84:87], v[188:191], v[230:233], v[84:87]
	v_mfma_f32_16x16x32_bf16 v[80:83], v[196:199], v[230:233], v[80:83]
	v_mfma_f32_16x16x32_bf16 v[68:71], v[188:191], v[238:241], v[68:71]
	v_mfma_f32_16x16x32_bf16 v[64:67], v[196:199], v[238:241], v[64:67]
	s_setprio 0
	s_barrier
	s_add_i32 s58, s58, s22
	v_lshl_add_u64 v[158:159], s[48:49], 0, v[160:161]
	s_mov_b32 m0, s58
	ds_read_b128 v[200:203], v149 offset:16384
	ds_read_b128 v[214:217], v149 offset:17408
	ds_read_b128 v[218:221], v149 offset:18432
	ds_read_b128 v[222:225], v149 offset:19456
	ds_read_b128 v[226:229], v149 offset:20480
	ds_read_b128 v[230:233], v149 offset:21504
	ds_read_b128 v[234:237], v149 offset:22528
	ds_read_b128 v[238:241], v149 offset:23552
	global_load_lds_dwordx4 v[158:159], off
	s_add_i32 m0, s58, 0x2000
	s_add_u32 s58, s48, 0x200000
	v_lshl_add_u64 v[162:163], s[48:49], 0, v[132:133]
	s_addc_u32 s59, s49, 0
	s_add_i32 s60, s60, s22
	global_load_lds_dwordx4 v[162:163], off
	v_lshl_add_u64 v[242:243], s[58:59], 0, v[160:161]
	s_mov_b32 m0, s60
	v_lshl_add_u64 v[244:245], s[50:51], 0, v[130:131]
	global_load_lds_dwordx4 v[242:243], off
	v_lshl_add_u64 v[242:243], s[58:59], 0, v[132:133]
	s_add_i32 m0, s60, 0x2000
	s_nop 0
	global_load_lds_dwordx4 v[242:243], off
	v_lshl_add_u64 v[242:243], s[50:51], 0, v[128:129]
	s_mov_b32 m0, s23
	s_nop 0
	global_load_lds_dwordx4 v[242:243], off
	s_mov_b32 m0, s28
	s_nop 0
	global_load_lds_dwordx4 v[244:245], off
	s_cmp_lg_u32 s101, 0
	s_cbranch_scc1 .Lgk_nw2_1148
	s_waitcnt vmcnt(8)
; #define PG8_STAGE(bufoff, gbase, voff) do { _Pragma("unroll") for (int _i = 0; _i < 2; ++_i) \
;         __builtin_amdgcn_global_load_lds((const unsigned*)((const char*)(gbase) + (voff)[_i]), (PG8_LAS unsigned*)(lds + (bufoff) + ldsw + _i * 8192), 16, 0, 0); } while (0)
; #define PG8_WAIT_V(n) asm volatile("s_waitcnt vmcnt(" #n ")" ::: "memory")
; #define PG8_WAIT_L(n) asm volatile("s_waitcnt lgkmcnt(" #n ")" ::: "memory")
; #define PG8_BAR __builtin_amdgcn_s_barrier()
; #define PG8_SCHED __builtin_amdgcn_sched_barrier(0)
; template <class Epi, class Sched, bool ALIGN_EPI = false, bool SP2 = false, bool F8 = false>
; __device__ __forceinline__ void gemm_phase(PG8_LAS unsigned char* lds, const Gemm g, const Sched& S, const Epi& E) {
;     ...
;             PG8_WAIT_V(8); PG8_WAIT_L(0); PG8_BAR; PG8_MMA(1, 0, At, B0); PG8_MMA(1, 1, At, B1); PG8_BAR; PG8_SCHED;
;             PG8_LDB(B0, 1, 0); PG8_LDB(B1, 1, 1); PG8_SCHED; PG8_LDA(At, 1, 0); PG8_STAGE(PG8_SA(0, 1), a2 + hstep, voffA);
;             PG8_WAIT_V(8); PG8_WAIT_L(0); PG8_BAR; PG8_MMA(0, 0, At, B0); PG8_MMA(0, 1, At, B1); PG8_BAR; PG8_SCHED;
.Lgk_nw2_1148:
	s_waitcnt lgkmcnt(0)
	s_barrier
	s_setprio 1
	s_waitcnt lgkmcnt(0)
	v_mfma_f32_16x16x32_bf16 v[60:63], v[138:141], v[200:203], 0
	v_mfma_f32_16x16x32_bf16 v[56:59], v[150:153], v[200:203], 0
	v_mfma_f32_16x16x32_bf16 v[44:47], v[138:141], v[218:221], 0
	v_mfma_f32_16x16x32_bf16 v[40:43], v[150:153], v[218:221], 0
	v_mfma_f32_16x16x32_bf16 v[28:31], v[138:141], v[226:229], 0
	v_mfma_f32_16x16x32_bf16 v[24:27], v[150:153], v[226:229], 0
	v_mfma_f32_16x16x32_bf16 v[12:15], v[138:141], v[234:237], 0
	v_mfma_f32_16x16x32_bf16 v[8:11], v[150:153], v[234:237], 0
	v_mfma_f32_16x16x32_bf16 v[60:63], v[142:145], v[214:217], v[60:63]
	v_mfma_f32_16x16x32_bf16 v[56:59], v[154:157], v[214:217], v[56:59]
	v_mfma_f32_16x16x32_bf16 v[44:47], v[142:145], v[222:225], v[44:47]
	v_mfma_f32_16x16x32_bf16 v[40:43], v[154:157], v[222:225], v[40:43]
	v_mfma_f32_16x16x32_bf16 v[28:31], v[142:145], v[230:233], v[28:31]
	v_mfma_f32_16x16x32_bf16 v[24:27], v[154:157], v[230:233], v[24:27]
	v_mfma_f32_16x16x32_bf16 v[12:15], v[142:145], v[238:241], v[12:15]
	v_mfma_f32_16x16x32_bf16 v[8:11], v[154:157], v[238:241], v[8:11]
	s_setprio 0
	s_setprio 1
	v_mfma_f32_16x16x32_bf16 v[52:55], v[184:187], v[200:203], 0
	v_mfma_f32_16x16x32_bf16 v[48:51], v[192:195], v[200:203], 0
	v_mfma_f32_16x16x32_bf16 v[36:39], v[184:187], v[218:221], 0
	v_mfma_f32_16x16x32_bf16 v[32:35], v[192:195], v[218:221], 0
	v_mfma_f32_16x16x32_bf16 v[20:23], v[184:187], v[226:229], 0
	v_mfma_f32_16x16x32_bf16 v[16:19], v[192:195], v[226:229], 0
	v_mfma_f32_16x16x32_bf16 v[4:7], v[184:187], v[234:237], 0
	v_mfma_f32_16x16x32_bf16 v[0:3], v[192:195], v[234:237], 0
	v_mfma_f32_16x16x32_bf16 v[52:55], v[188:191], v[214:217], v[52:55]
	v_mfma_f32_16x16x32_bf16 v[48:51], v[196:199], v[214:217], v[48:51]
	v_mfma_f32_16x16x32_bf16 v[36:39], v[188:191], v[222:225], v[36:39]
	v_mfma_f32_16x16x32_bf16 v[32:35], v[196:199], v[222:225], v[32:35]
	v_mfma_f32_16x16x32_bf16 v[20:23], v[188:191], v[230:233], v[20:23]
	v_mfma_f32_16x16x32_bf16 v[16:19], v[196:199], v[230:233], v[16:19]
	v_mfma_f32_16x16x32_bf16 v[4:7], v[188:191], v[238:241], v[4:7]
	v_mfma_f32_16x16x32_bf16 v[0:3], v[196:199], v[238:241], v[0:3]
	s_setprio 0
	s_barrier
	s_add_i32 s58, 0, 0x18000
	s_add_i32 s59, 0, 0x1c000
	v_add_u32_e32 v154, s58, v147
	v_add_u32_e32 v196, s59, v147
	ds_read_b128 v[138:141], v154
	ds_read_b128 v[142:145], v154 offset:1024
	ds_read_b128 v[150:153], v154 offset:2048
	ds_read_b128 v[154:157], v154 offset:3072
	ds_read_b128 v[184:187], v196
	ds_read_b128 v[188:191], v196 offset:1024
	ds_read_b128 v[192:195], v196 offset:2048
	ds_read_b128 v[196:199], v196 offset:3072
	s_add_u32 s50, s50, 0x200000
	s_addc_u32 s51, s51, 0
	s_mov_b32 m0, s29
	v_lshl_add_u64 v[246:247], s[50:51], 0, v[128:129]
	ds_read_b128 v[200:203], v149 offset:32768
	ds_read_b128 v[214:217], v149 offset:33792
	ds_read_b128 v[218:221], v149 offset:34816
	ds_read_b128 v[222:225], v149 offset:35840
	ds_read_b128 v[226:229], v149 offset:36864
	ds_read_b128 v[230:233], v149 offset:37888
	ds_read_b128 v[234:237], v149 offset:38912
	ds_read_b128 v[238:241], v149 offset:39936
	global_load_lds_dwordx4 v[246:247], off
	v_lshl_add_u64 v[246:247], s[50:51], 0, v[130:131]
	s_mov_b32 m0, s34
	s_nop 0
	global_load_lds_dwordx4 v[246:247], off
	s_waitcnt vmcnt(8)
	s_waitcnt lgkmcnt(0)
	s_barrier
	s_setprio 1
	s_waitcnt lgkmcnt(0)
	v_mfma_f32_16x16x32_bf16 v[124:127], v[138:141], v[200:203], v[124:127]
	v_mfma_f32_16x16x32_bf16 v[120:123], v[150:153], v[200:203], v[120:123]
	v_mfma_f32_16x16x32_bf16 v[108:111], v[138:141], v[218:221], v[108:111]
	v_mfma_f32_16x16x32_bf16 v[104:107], v[150:153], v[218:221], v[104:107]
	v_mfma_f32_16x16x32_bf16 v[92:95], v[138:141], v[226:229], v[92:95]
	v_mfma_f32_16x16x32_bf16 v[88:91], v[150:153], v[226:229], v[88:91]
	v_mfma_f32_16x16x32_bf16 v[76:79], v[138:141], v[234:237], v[76:79]
	v_mfma_f32_16x16x32_bf16 v[72:75], v[150:153], v[234:237], v[72:75]
	v_mfma_f32_16x16x32_bf16 v[124:127], v[142:145], v[214:217], v[124:127]
	v_mfma_f32_16x16x32_bf16 v[120:123], v[154:157], v[214:217], v[120:123]
	v_mfma_f32_16x16x32_bf16 v[108:111], v[142:145], v[222:225], v[108:111]
	v_mfma_f32_16x16x32_bf16 v[104:107], v[154:157], v[222:225], v[104:107]
	v_mfma_f32_16x16x32_bf16 v[92:95], v[142:145], v[230:233], v[92:95]
	v_mfma_f32_16x16x32_bf16 v[88:91], v[154:157], v[230:233], v[88:91]
	v_mfma_f32_16x16x32_bf16 v[76:79], v[142:145], v[238:241], v[76:79]
	v_mfma_f32_16x16x32_bf16 v[72:75], v[154:157], v[238:241], v[72:75]
	s_setprio 0
	s_setprio 1
	v_mfma_f32_16x16x32_bf16 v[116:119], v[184:187], v[200:203], v[116:119]
	v_mfma_f32_16x16x32_bf16 v[112:115], v[192:195], v[200:203], v[112:115]
	v_mfma_f32_16x16x32_bf16 v[100:103], v[184:187], v[218:221], v[100:103]
	v_mfma_f32_16x16x32_bf16 v[96:99], v[192:195], v[218:221], v[96:99]
	v_mfma_f32_16x16x32_bf16 v[84:87], v[184:187], v[226:229], v[84:87]
	v_mfma_f32_16x16x32_bf16 v[80:83], v[192:195], v[226:229], v[80:83]
	v_mfma_f32_16x16x32_bf16 v[68:71], v[184:187], v[234:237], v[68:71]
	v_mfma_f32_16x16x32_bf16 v[64:67], v[192:195], v[234:237], v[64:67]
	v_mfma_f32_16x16x32_bf16 v[116:119], v[188:191], v[214:217], v[116:119]
	v_mfma_f32_16x16x32_bf16 v[112:115], v[196:199], v[214:217], v[112:115]
	v_mfma_f32_16x16x32_bf16 v[100:103], v[188:191], v[222:225], v[100:103]
	v_mfma_f32_16x16x32_bf16 v[96:99], v[196:199], v[222:225], v[96:99]
	v_mfma_f32_16x16x32_bf16 v[84:87], v[188:191], v[230:233], v[84:87]
	v_mfma_f32_16x16x32_bf16 v[80:83], v[196:199], v[230:233], v[80:83]
	v_mfma_f32_16x16x32_bf16 v[68:71], v[188:191], v[238:241], v[68:71]
	v_mfma_f32_16x16x32_bf16 v[64:67], v[196:199], v[238:241], v[64:67]
	s_setprio 0
	s_barrier
; #define PG8_STAGE(bufoff, gbase, voff) do { _Pragma("unroll") for (int _i = 0; _i < 2; ++_i) \
;         __builtin_amdgcn_global_load_lds((const unsigned*)((const char*)(gbase) + (voff)[_i]), (PG8_LAS unsigned*)(lds + (bufoff) + ldsw + _i * 8192), 16, 0, 0); } while (0)
; #define PG8_WAIT_V(n) asm volatile("s_waitcnt vmcnt(" #n ")" ::: "memory")
; #define PG8_WAIT_L(n) asm volatile("s_waitcnt lgkmcnt(" #n ")" ::: "memory")
; #define PG8_BAR __builtin_amdgcn_s_barrier()
; #define PG8_SCHED __builtin_amdgcn_sched_barrier(0)
; template <class Epi, class Sched, bool ALIGN_EPI = false, bool SP2 = false, bool F8 = false>
; __device__ __forceinline__ void gemm_phase(PG8_LAS unsigned char* lds, const Gemm g, const Sched& S, const Epi& E) {
;     ...
;             PG8_LDA(At, 1, 1); PG8_STAGE(PG8_SB(1, 0), b3, voffB); PG8_STAGE(PG8_SB(1, 1), b3 + hstep, voffB); PG8_STAGE(PG8_SA(1, 0), a3, voffA);
;             PG8_WAIT_V(8); PG8_WAIT_L(0); PG8_BAR; PG8_MMA(1, 0, At, B0); PG8_MMA(1, 1, At, B1); PG8_BAR; PG8_SCHED;
	s_add_i32 s50, s58, s22
	v_lshl_add_u64 v[158:159], v[158:159], 0, s[14:15]
	s_mov_b32 m0, s50
	ds_read_b128 v[200:203], v149 offset:49152
	ds_read_b128 v[214:217], v149 offset:50176
	ds_read_b128 v[218:221], v149 offset:51200
	ds_read_b128 v[222:225], v149 offset:52224
	ds_read_b128 v[226:229], v149 offset:53248
	ds_read_b128 v[230:233], v149 offset:54272
	ds_read_b128 v[234:237], v149 offset:55296
	ds_read_b128 v[238:241], v149 offset:56320
	global_load_lds_dwordx4 v[158:159], off
	s_add_i32 m0, s50, 0x2000
	s_add_u32 s48, s48, 0x200080
	v_lshl_add_u64 v[158:159], v[162:163], 0, s[14:15]
	s_addc_u32 s49, s49, 0
	s_add_i32 s50, s59, s22
	global_load_lds_dwordx4 v[158:159], off
	v_lshl_add_u64 v[158:159], s[48:49], 0, v[160:161]
	s_mov_b32 m0, s50
	s_nop 0
	global_load_lds_dwordx4 v[158:159], off
	v_lshl_add_u64 v[158:159], s[48:49], 0, v[132:133]
	s_add_i32 m0, s50, 0x2000
	s_nop 0
	global_load_lds_dwordx4 v[158:159], off
	v_lshl_add_u64 v[158:159], v[242:243], 0, s[14:15]
	s_mov_b32 m0, s8
	s_nop 0
	global_load_lds_dwordx4 v[158:159], off
	v_lshl_add_u64 v[158:159], v[244:245], 0, s[14:15]
	s_mov_b32 m0, s9
	s_nop 0
	global_load_lds_dwordx4 v[158:159], off
	s_waitcnt vmcnt(8)
	s_waitcnt lgkmcnt(0)
	s_barrier
	s_setprio 1
	s_waitcnt lgkmcnt(0)
	v_mfma_f32_16x16x32_bf16 v[60:63], v[138:141], v[200:203], v[60:63]
	v_mfma_f32_16x16x32_bf16 v[56:59], v[150:153], v[200:203], v[56:59]
	v_mfma_f32_16x16x32_bf16 v[44:47], v[138:141], v[218:221], v[44:47]
	v_mfma_f32_16x16x32_bf16 v[40:43], v[150:153], v[218:221], v[40:43]
	v_mfma_f32_16x16x32_bf16 v[28:31], v[138:141], v[226:229], v[28:31]
	v_mfma_f32_16x16x32_bf16 v[24:27], v[150:153], v[226:229], v[24:27]
	v_mfma_f32_16x16x32_bf16 v[12:15], v[138:141], v[234:237], v[12:15]
	v_mfma_f32_16x16x32_bf16 v[8:11], v[150:153], v[234:237], v[8:11]
	v_mfma_f32_16x16x32_bf16 v[60:63], v[142:145], v[214:217], v[60:63]
	v_mfma_f32_16x16x32_bf16 v[56:59], v[154:157], v[214:217], v[56:59]
	v_mfma_f32_16x16x32_bf16 v[44:47], v[142:145], v[222:225], v[44:47]
	v_mfma_f32_16x16x32_bf16 v[40:43], v[154:157], v[222:225], v[40:43]
	v_mfma_f32_16x16x32_bf16 v[28:31], v[142:145], v[230:233], v[28:31]
	v_mfma_f32_16x16x32_bf16 v[24:27], v[154:157], v[230:233], v[24:27]
	v_mfma_f32_16x16x32_bf16 v[12:15], v[142:145], v[238:241], v[12:15]
	v_mfma_f32_16x16x32_bf16 v[8:11], v[154:157], v[238:241], v[8:11]
	s_setprio 0
	s_setprio 1
	v_mfma_f32_16x16x32_bf16 v[52:55], v[184:187], v[200:203], v[52:55]
	v_mfma_f32_16x16x32_bf16 v[48:51], v[192:195], v[200:203], v[48:51]
	v_mfma_f32_16x16x32_bf16 v[36:39], v[184:187], v[218:221], v[36:39]
	v_mfma_f32_16x16x32_bf16 v[32:35], v[192:195], v[218:221], v[32:35]
	v_mfma_f32_16x16x32_bf16 v[20:23], v[184:187], v[226:229], v[20:23]
	v_mfma_f32_16x16x32_bf16 v[16:19], v[192:195], v[226:229], v[16:19]
	v_mfma_f32_16x16x32_bf16 v[4:7], v[184:187], v[234:237], v[4:7]
	v_mfma_f32_16x16x32_bf16 v[0:3], v[192:195], v[234:237], v[0:3]
	v_mfma_f32_16x16x32_bf16 v[52:55], v[188:191], v[214:217], v[52:55]
	v_mfma_f32_16x16x32_bf16 v[48:51], v[196:199], v[214:217], v[48:51]
	v_mfma_f32_16x16x32_bf16 v[36:39], v[188:191], v[222:225], v[36:39]
	v_mfma_f32_16x16x32_bf16 v[32:35], v[196:199], v[222:225], v[32:35]
	v_mfma_f32_16x16x32_bf16 v[20:23], v[188:191], v[230:233], v[20:23]
	v_mfma_f32_16x16x32_bf16 v[16:19], v[196:199], v[230:233], v[16:19]
	v_mfma_f32_16x16x32_bf16 v[4:7], v[188:191], v[238:241], v[4:7]
	v_mfma_f32_16x16x32_bf16 v[0:3], v[196:199], v[238:241], v[0:3]
	s_setprio 0
	s_barrier
	s_add_i32 s56, s56, 2
	s_add_u32 s46, s46, 0x100
	s_addc_u32 s47, s47, 0
	s_add_u32 s54, s54, 0x100
	s_addc_u32 s55, s55, 0
	s_cmpk_gt_u32 s56, 0x7d
	s_cbranch_scc0 .LBB0_1148
	s_branch .Lgk_after_1148

;     __device__ __forceinline__ void operator()(const f32x4 (&acc)[2][2][4][2], const pg8::Unit& u, int wr, int wc, int fr, int fq) const {
;     ...
;                     } else if constexpr (MODE == 4) {
;                         const f32x4 g0 = *(const f32x4*)(vec + col), g1 = *(const f32x4*)(vec + col + 4);
;                         const f32x4 x0 = *(const f32x4*)(xsrc + row * DM + col), x1 = *(const f32x4*)(xsrc + row * DM + col + 4);
;                         *(f32x4*)(of + row * DM + col) = x0 + g0 * v0; *(f32x4*)(of + row * DM + col + 4) = x1 + g1 * v1;
.LBB0_1151:
	v_lshl_add_u32 v144, s44, 8, v146
	v_lshl_or_b32 v158, s45, 8, v148
	v_ashrrev_i32_e32 v145, 31, v144
	v_ashrrev_i32_e32 v159, 31, v158
	v_lshlrev_b64 v[138:139], 13, v[144:145]
	v_lshlrev_b64 v[142:143], 2, v[158:159]
	v_lshl_add_u64 v[138:139], s[6:7], 0, v[138:139]
	v_lshl_add_u64 v[140:141], s[4:5], 0, v[142:143]
	v_lshl_add_u64 v[138:139], v[138:139], 0, v[142:143]
	global_load_dwordx4 v[192:195], v[140:141], off offset:16
	global_load_dwordx4 v[196:199], v[140:141], off
	global_load_dwordx4 v[200:203], v[138:139], off offset:16
	global_load_dwordx4 v[214:217], v[138:139], off
	v_or_b32_e32 v234, 0x80, v158
	v_ashrrev_i32_e32 v235, 31, v234
	v_lshl_add_u64 v[234:235], v[234:235], 2, s[4:5]
	global_load_dwordx4 v[218:221], v[234:235], off offset:16
	global_load_dwordx4 v[222:225], v[234:235], off
	global_load_dwordx4 v[226:229], v[138:139], off offset:528
	global_load_dwordx4 v[230:233], v[138:139], off offset:512
	s_mov_b32 s17, 0x100000
	s_mov_b64 s[44:45], 0x100000
	v_readlane_b32 s37, v254, 63
	s_waitcnt vmcnt(4)
	v_pk_fma_f32 v[122:123], v[122:123], v[194:195], v[202:203]
	v_pk_fma_f32 v[120:121], v[120:121], v[192:193], v[200:201]
	global_store_dwordx4 v[138:139], v[120:123], off offset:16
	v_pk_fma_f32 v[126:127], v[126:127], v[198:199], v[216:217]
	v_pk_fma_f32 v[124:125], v[124:125], v[196:197], v[214:215]
	v_or_b32_e32 v120, 0x80, v158
	v_ashrrev_i32_e32 v121, 31, v120
	global_store_dwordx4 v[138:139], v[124:127], off
	v_lshl_add_u64 v[120:121], v[120:121], 2, s[4:5]
	global_load_dwordx4 v[192:195], v[140:141], off offset:16
	global_load_dwordx4 v[196:199], v[140:141], off
	v_or_b32_e32 v234, 16, v144
	v_ashrrev_i32_e32 v235, 31, v234
	v_lshlrev_b64 v[234:235], 13, v[234:235]
	v_lshl_add_u64 v[234:235], s[6:7], 0, v[234:235]
	v_lshl_add_u64 v[236:237], v[234:235], 0, v[142:143]
	global_load_dwordx4 v[200:203], v[236:237], off offset:16
	global_load_dwordx4 v[214:217], v[236:237], off
	s_waitcnt vmcnt(6)
	v_pk_fma_f32 v[112:113], v[112:113], v[218:219], v[226:227]
	v_or_b32_e32 v122, 16, v144
	v_ashrrev_i32_e32 v123, 31, v122
	v_lshlrev_b64 v[122:123], 13, v[122:123]
	v_pk_fma_f32 v[118:119], v[118:119], v[224:225], v[232:233]
	v_pk_fma_f32 v[116:117], v[116:117], v[222:223], v[230:231]
	v_pk_fma_f32 v[114:115], v[114:115], v[220:221], v[228:229]
	v_lshl_add_u64 v[122:123], s[6:7], 0, v[122:123]
	global_store_dwordx4 v[138:139], v[116:119], off offset:512
	global_store_dwordx4 v[138:139], v[112:115], off offset:528
	v_lshl_add_u64 v[126:127], v[122:123], 0, v[142:143]
	v_or_b32_e32 v234, 0x80, v158
	v_ashrrev_i32_e32 v235, 31, v234
	v_lshl_add_u64 v[234:235], v[234:235], 2, s[4:5]
	global_load_dwordx4 v[218:221], v[234:235], off offset:16
	global_load_dwordx4 v[222:225], v[234:235], off
	v_or_b32_e32 v234, 16, v144
	v_ashrrev_i32_e32 v235, 31, v234
	v_lshlrev_b64 v[234:235], 13, v[234:235]
	v_lshl_add_u64 v[234:235], s[6:7], 0, v[234:235]
	v_lshl_add_u64 v[236:237], v[234:235], 0, v[142:143]
	global_load_dwordx4 v[226:229], v[236:237], off offset:528
	global_load_dwordx4 v[230:233], v[236:237], off offset:512
	s_waitcnt vmcnt(6)
	v_pk_fma_f32 v[106:107], v[106:107], v[194:195], v[202:203]
	v_pk_fma_f32 v[110:111], v[110:111], v[198:199], v[216:217]
	v_pk_fma_f32 v[108:109], v[108:109], v[196:197], v[214:215]
	v_pk_fma_f32 v[104:105], v[104:105], v[192:193], v[200:201]
	global_store_dwordx4 v[126:127], v[108:111], off
	global_store_dwordx4 v[126:127], v[104:107], off offset:16
	global_load_dwordx4 v[192:195], v[140:141], off offset:16
	global_load_dwordx4 v[196:199], v[140:141], off
	v_or_b32_e32 v234, 32, v144
	v_ashrrev_i32_e32 v235, 31, v234
	v_lshlrev_b64 v[234:235], 13, v[234:235]
	v_lshl_add_u64 v[234:235], s[6:7], 0, v[234:235]
	v_lshl_add_u64 v[236:237], v[234:235], 0, v[142:143]
	global_load_dwordx4 v[200:203], v[236:237], off offset:16
	global_load_dwordx4 v[214:217], v[236:237], off
	s_nop 0
	s_waitcnt vmcnt(6)
	v_pk_fma_f32 v[96:97], v[96:97], v[218:219], v[226:227]
	v_or_b32_e32 v104, 32, v144
	v_ashrrev_i32_e32 v105, 31, v104
	v_lshlrev_b64 v[104:105], 13, v[104:105]
	v_pk_fma_f32 v[102:103], v[102:103], v[224:225], v[232:233]
	v_pk_fma_f32 v[100:101], v[100:101], v[222:223], v[230:231]
	v_pk_fma_f32 v[98:99], v[98:99], v[220:221], v[228:229]
	v_lshl_add_u64 v[104:105], s[6:7], 0, v[104:105]
	global_store_dwordx4 v[126:127], v[100:103], off offset:512
	global_store_dwordx4 v[126:127], v[96:99], off offset:528
	v_lshl_add_u64 v[112:113], v[104:105], 0, v[142:143]
	v_or_b32_e32 v234, 0x80, v158
	v_ashrrev_i32_e32 v235, 31, v234
	v_lshl_add_u64 v[234:235], v[234:235], 2, s[4:5]
	global_load_dwordx4 v[218:221], v[234:235], off offset:16
	global_load_dwordx4 v[222:225], v[234:235], off
	v_or_b32_e32 v234, 32, v144
	v_ashrrev_i32_e32 v235, 31, v234
	v_lshlrev_b64 v[234:235], 13, v[234:235]
	v_lshl_add_u64 v[234:235], s[6:7], 0, v[234:235]
	v_lshl_add_u64 v[236:237], v[234:235], 0, v[142:143]
	global_load_dwordx4 v[226:229], v[236:237], off offset:528
	global_load_dwordx4 v[230:233], v[236:237], off offset:512
	s_waitcnt vmcnt(6)
	v_pk_fma_f32 v[90:91], v[90:91], v[194:195], v[202:203]
	v_pk_fma_f32 v[94:95], v[94:95], v[198:199], v[216:217]
	v_pk_fma_f32 v[92:93], v[92:93], v[196:197], v[214:215]
	v_pk_fma_f32 v[88:89], v[88:89], v[192:193], v[200:201]
	global_store_dwordx4 v[112:113], v[92:95], off
	global_store_dwordx4 v[112:113], v[88:91], off offset:16
	global_load_dwordx4 v[192:195], v[140:141], off offset:16
	global_load_dwordx4 v[196:199], v[140:141], off
	v_or_b32_e32 v234, 48, v144
	v_ashrrev_i32_e32 v235, 31, v234
	v_lshlrev_b64 v[234:235], 13, v[234:235]
	v_lshl_add_u64 v[234:235], s[6:7], 0, v[234:235]
	v_lshl_add_u64 v[236:237], v[234:235], 0, v[142:143]
	global_load_dwordx4 v[200:203], v[236:237], off offset:16
	global_load_dwordx4 v[214:217], v[236:237], off
	s_nop 0
	s_waitcnt vmcnt(6)
;     __device__ __forceinline__ void operator()(const f32x4 (&acc)[2][2][4][2], const pg8::Unit& u, int wr, int wc, int fr, int fq) const {
;     ...
;                     } else if constexpr (MODE == 4) {
;                         const f32x4 g0 = *(const f32x4*)(vec + col), g1 = *(const f32x4*)(vec + col + 4);
;                         const f32x4 x0 = *(const f32x4*)(xsrc + row * DM + col), x1 = *(const f32x4*)(xsrc + row * DM + col + 4);
;                         *(f32x4*)(of + row * DM + col) = x0 + g0 * v0; *(f32x4*)(of + row * DM + col + 4) = x1 + g1 * v1;
	v_pk_fma_f32 v[80:81], v[80:81], v[218:219], v[226:227]
	v_or_b32_e32 v88, 48, v144
	v_ashrrev_i32_e32 v89, 31, v88
	v_lshlrev_b64 v[88:89], 13, v[88:89]
	v_pk_fma_f32 v[86:87], v[86:87], v[224:225], v[232:233]
	v_pk_fma_f32 v[84:85], v[84:85], v[222:223], v[230:231]
	v_pk_fma_f32 v[82:83], v[82:83], v[220:221], v[228:229]
	v_lshl_add_u64 v[88:89], s[6:7], 0, v[88:89]
	global_store_dwordx4 v[112:113], v[84:87], off offset:512
	global_store_dwordx4 v[112:113], v[80:83], off offset:528
	v_lshl_add_u64 v[96:97], v[88:89], 0, v[142:143]
	v_or_b32_e32 v234, 0x80, v158
	v_ashrrev_i32_e32 v235, 31, v234
	v_lshl_add_u64 v[234:235], v[234:235], 2, s[4:5]
	global_load_dwordx4 v[218:221], v[234:235], off offset:16
	global_load_dwordx4 v[222:225], v[234:235], off
	v_or_b32_e32 v234, 48, v144
	v_ashrrev_i32_e32 v235, 31, v234
	v_lshlrev_b64 v[234:235], 13, v[234:235]
	v_lshl_add_u64 v[234:235], s[6:7], 0, v[234:235]
	v_lshl_add_u64 v[236:237], v[234:235], 0, v[142:143]
	global_load_dwordx4 v[226:229], v[236:237], off offset:528
	global_load_dwordx4 v[230:233], v[236:237], off offset:512
	s_waitcnt vmcnt(6)
	v_pk_fma_f32 v[74:75], v[74:75], v[194:195], v[202:203]
	v_pk_fma_f32 v[78:79], v[78:79], v[198:199], v[216:217]
	v_pk_fma_f32 v[76:77], v[76:77], v[196:197], v[214:215]
	v_pk_fma_f32 v[72:73], v[72:73], v[192:193], v[200:201]
	global_store_dwordx4 v[96:97], v[76:79], off
	global_store_dwordx4 v[96:97], v[72:75], off offset:16
	global_load_dwordx4 v[192:195], v[140:141], off offset:16
	global_load_dwordx4 v[196:199], v[140:141], off
	s_mov_b32 s98, 0x100000
	v_add_co_u32_e32 v234, vcc, s98, v138
	s_nop 1
	v_addc_co_u32_e32 v235, vcc, 0, v139, vcc
	global_load_dwordx4 v[200:203], v[234:235], off
	s_mov_b64 s[98:99], 0x100000
	v_lshl_add_u64 v[234:235], v[138:139], 0, s[98:99]
	global_load_dwordx4 v[214:217], v[234:235], off offset:16
	s_nop 0
	s_waitcnt vmcnt(6)
	v_pk_fma_f32 v[66:67], v[66:67], v[220:221], v[228:229]
	v_pk_fma_f32 v[70:71], v[70:71], v[224:225], v[232:233]
	v_pk_fma_f32 v[68:69], v[68:69], v[222:223], v[230:231]
	v_pk_fma_f32 v[64:65], v[64:65], v[218:219], v[226:227]
	v_add_co_u32_e32 v82, vcc, s17, v138
	global_store_dwordx4 v[96:97], v[68:71], off offset:512
	global_store_dwordx4 v[96:97], v[64:67], off offset:528
	v_addc_co_u32_e32 v83, vcc, 0, v139, vcc
	v_or_b32_e32 v234, 0x80, v158
	v_ashrrev_i32_e32 v235, 31, v234
	v_lshl_add_u64 v[234:235], v[234:235], 2, s[4:5]
	global_load_dwordx4 v[218:221], v[234:235], off offset:16
	global_load_dwordx4 v[222:225], v[234:235], off
	s_mov_b64 s[98:99], 0x100000
	v_lshl_add_u64 v[234:235], v[138:139], 0, s[98:99]
	global_load_dwordx4 v[226:229], v[234:235], off offset:528
	s_mov_b64 s[98:99], 0x100000
	global_load_dwordx4 v[230:233], v[234:235], off offset:512
	v_lshl_add_u64 v[80:81], v[138:139], 0, s[44:45]
	s_mov_b32 s17, 0x120000
	s_mov_b64 s[44:45], 0x120000
	s_waitcnt vmcnt(6)
	v_pk_fma_f32 v[62:63], v[62:63], v[198:199], v[202:203]
	v_pk_fma_f32 v[60:61], v[60:61], v[196:197], v[200:201]
	v_pk_fma_f32 v[58:59], v[58:59], v[194:195], v[216:217]
	v_pk_fma_f32 v[56:57], v[56:57], v[192:193], v[214:215]
	global_store_dwordx4 v[82:83], v[60:63], off
	global_store_dwordx4 v[80:81], v[56:59], off offset:16
	global_load_dwordx4 v[192:195], v[140:141], off offset:16
	global_load_dwordx4 v[196:199], v[140:141], off
	s_mov_b32 s98, 0x120000
	v_add_co_u32_e32 v234, vcc, s98, v138
	s_nop 1
	v_addc_co_u32_e32 v235, vcc, 0, v139, vcc
	global_load_dwordx4 v[200:203], v[234:235], off
	s_mov_b64 s[98:99], 0x120000
	v_lshl_add_u64 v[234:235], v[138:139], 0, s[98:99]
	global_load_dwordx4 v[214:217], v[234:235], off offset:16
	s_nop 0
	s_waitcnt vmcnt(6)
	v_pk_fma_f32 v[50:51], v[50:51], v[220:221], v[228:229]
	v_pk_fma_f32 v[54:55], v[54:55], v[224:225], v[232:233]
	v_pk_fma_f32 v[52:53], v[52:53], v[222:223], v[230:231]
	v_pk_fma_f32 v[48:49], v[48:49], v[218:219], v[226:227]
	v_add_co_u32_e32 v66, vcc, s17, v138
	global_store_dwordx4 v[80:81], v[52:55], off offset:512
	global_store_dwordx4 v[80:81], v[48:51], off offset:528
	v_addc_co_u32_e32 v67, vcc, 0, v139, vcc
	v_or_b32_e32 v234, 0x80, v158
	v_ashrrev_i32_e32 v235, 31, v234
	v_lshl_add_u64 v[234:235], v[234:235], 2, s[4:5]
	global_load_dwordx4 v[218:221], v[234:235], off offset:16
	global_load_dwordx4 v[222:225], v[234:235], off
	s_mov_b64 s[98:99], 0x120000
	v_lshl_add_u64 v[234:235], v[138:139], 0, s[98:99]
	global_load_dwordx4 v[226:229], v[234:235], off offset:528
	s_mov_b64 s[98:99], 0x120000
	global_load_dwordx4 v[230:233], v[234:235], off offset:512
	v_lshl_add_u64 v[64:65], v[138:139], 0, s[44:45]
	s_mov_b32 s17, 0x140000
	s_mov_b64 s[44:45], 0x140000
	s_waitcnt vmcnt(6)
; template <class Epi, class Sched, bool ALIGN_EPI = false, bool SP2 = false, bool F8 = false>
; __device__ __forceinline__ void gemm_phase(PG8_LAS unsigned char* lds, const Gemm g, const Sched& S, const Epi& E) {
;     ...
;         if constexpr (!Epi::AFTER_DRAIN) { E(acc, cur, wr, wc, fr, fq); S.done(cur); }
;         if (!has_next) break;
;     __device__ __forceinline__ void operator()(const f32x4 (&acc)[2][2][4][2], const pg8::Unit& u, int wr, int wc, int fr, int fq) const {
;     ...
;                     } else if constexpr (MODE == 4) {
;                         const f32x4 g0 = *(const f32x4*)(vec + col), g1 = *(const f32x4*)(vec + col + 4);
;                         const f32x4 x0 = *(const f32x4*)(xsrc + row * DM + col), x1 = *(const f32x4*)(xsrc + row * DM + col + 4);
;                         *(f32x4*)(of + row * DM + col) = x0 + g0 * v0; *(f32x4*)(of + row * DM + col + 4) = x1 + g1 * v1;
	v_pk_fma_f32 v[46:47], v[46:47], v[198:199], v[202:203]
	v_pk_fma_f32 v[44:45], v[44:45], v[196:197], v[200:201]
	v_pk_fma_f32 v[42:43], v[42:43], v[194:195], v[216:217]
	v_pk_fma_f32 v[40:41], v[40:41], v[192:193], v[214:215]
	global_store_dwordx4 v[66:67], v[44:47], off
	global_store_dwordx4 v[64:65], v[40:43], off offset:16
	global_load_dwordx4 v[192:195], v[140:141], off offset:16
	global_load_dwordx4 v[196:199], v[140:141], off
	s_mov_b32 s98, 0x140000
	v_add_co_u32_e32 v234, vcc, s98, v138
	s_nop 1
	v_addc_co_u32_e32 v235, vcc, 0, v139, vcc
	global_load_dwordx4 v[200:203], v[234:235], off
	s_mov_b64 s[98:99], 0x140000
	v_lshl_add_u64 v[234:235], v[138:139], 0, s[98:99]
	global_load_dwordx4 v[214:217], v[234:235], off offset:16
	s_nop 0
	s_waitcnt vmcnt(6)
	v_pk_fma_f32 v[34:35], v[34:35], v[220:221], v[228:229]
	v_pk_fma_f32 v[38:39], v[38:39], v[224:225], v[232:233]
	v_pk_fma_f32 v[36:37], v[36:37], v[222:223], v[230:231]
	v_pk_fma_f32 v[32:33], v[32:33], v[218:219], v[226:227]
	v_add_co_u32_e32 v50, vcc, s17, v138
	global_store_dwordx4 v[64:65], v[36:39], off offset:512
	global_store_dwordx4 v[64:65], v[32:35], off offset:528
	v_addc_co_u32_e32 v51, vcc, 0, v139, vcc
	v_or_b32_e32 v234, 0x80, v158
	v_ashrrev_i32_e32 v235, 31, v234
	v_lshl_add_u64 v[234:235], v[234:235], 2, s[4:5]
	global_load_dwordx4 v[218:221], v[234:235], off offset:16
	global_load_dwordx4 v[222:225], v[234:235], off
	s_mov_b64 s[98:99], 0x140000
	v_lshl_add_u64 v[234:235], v[138:139], 0, s[98:99]
	global_load_dwordx4 v[226:229], v[234:235], off offset:528
	s_mov_b64 s[98:99], 0x140000
	global_load_dwordx4 v[230:233], v[234:235], off offset:512
	v_lshl_add_u64 v[48:49], v[138:139], 0, s[44:45]
	s_mov_b32 s17, 0x160000
	s_mov_b64 s[44:45], 0x160000
	s_waitcnt vmcnt(6)
	v_pk_fma_f32 v[30:31], v[30:31], v[198:199], v[202:203]
	v_pk_fma_f32 v[28:29], v[28:29], v[196:197], v[200:201]
	v_pk_fma_f32 v[26:27], v[26:27], v[194:195], v[216:217]
	v_pk_fma_f32 v[24:25], v[24:25], v[192:193], v[214:215]
	global_store_dwordx4 v[50:51], v[28:31], off
	global_store_dwordx4 v[48:49], v[24:27], off offset:16
	global_load_dwordx4 v[192:195], v[140:141], off offset:16
	global_load_dwordx4 v[196:199], v[140:141], off
	s_mov_b32 s98, 0x160000
	v_add_co_u32_e32 v234, vcc, s98, v138
	s_nop 1
	v_addc_co_u32_e32 v235, vcc, 0, v139, vcc
	global_load_dwordx4 v[200:203], v[234:235], off
	s_mov_b64 s[98:99], 0x160000
	v_lshl_add_u64 v[234:235], v[138:139], 0, s[98:99]
	global_load_dwordx4 v[214:217], v[234:235], off offset:16
	s_nop 0
	s_waitcnt vmcnt(6)
	v_pk_fma_f32 v[18:19], v[18:19], v[220:221], v[228:229]
	v_pk_fma_f32 v[22:23], v[22:23], v[224:225], v[232:233]
	v_pk_fma_f32 v[20:21], v[20:21], v[222:223], v[230:231]
	v_pk_fma_f32 v[16:17], v[16:17], v[218:219], v[226:227]
	v_add_co_u32_e32 v34, vcc, s17, v138
	global_store_dwordx4 v[48:49], v[20:23], off offset:512
	global_store_dwordx4 v[48:49], v[16:19], off offset:528
	v_addc_co_u32_e32 v35, vcc, 0, v139, vcc
	v_or_b32_e32 v234, 0x80, v158
	v_ashrrev_i32_e32 v235, 31, v234
	v_lshl_add_u64 v[234:235], v[234:235], 2, s[4:5]
	global_load_dwordx4 v[218:221], v[234:235], off offset:16
	global_load_dwordx4 v[222:225], v[234:235], off
	s_mov_b64 s[98:99], 0x160000
	v_lshl_add_u64 v[234:235], v[138:139], 0, s[98:99]
	global_load_dwordx4 v[226:229], v[234:235], off offset:528
	s_mov_b64 s[98:99], 0x160000
	global_load_dwordx4 v[230:233], v[234:235], off offset:512
	v_lshl_add_u64 v[32:33], v[138:139], 0, s[44:45]
	s_mov_b64 s[44:45], -1
	s_andn2_b64 vcc, exec, s[38:39]
	s_waitcnt vmcnt(6)
	v_pk_fma_f32 v[14:15], v[14:15], v[198:199], v[202:203]
	v_pk_fma_f32 v[12:13], v[12:13], v[196:197], v[200:201]
	v_pk_fma_f32 v[10:11], v[10:11], v[194:195], v[216:217]
	v_pk_fma_f32 v[8:9], v[8:9], v[192:193], v[214:215]
	global_store_dwordx4 v[34:35], v[12:15], off
	global_store_dwordx4 v[32:33], v[8:11], off offset:16
	s_nop 0
	s_waitcnt vmcnt(2)
	v_pk_fma_f32 v[2:3], v[2:3], v[220:221], v[228:229]
	v_pk_fma_f32 v[6:7], v[6:7], v[224:225], v[232:233]
	v_pk_fma_f32 v[4:5], v[4:5], v[222:223], v[230:231]
	v_pk_fma_f32 v[0:1], v[0:1], v[218:219], v[226:227]
	global_store_dwordx4 v[32:33], v[4:7], off offset:512
	global_store_dwordx4 v[32:33], v[0:3], off offset:528
	s_mov_b32 s101, 1
	s_cbranch_vccnz .LBB0_1140
	s_andn2_b64 vcc, exec, s[0:1]
	s_cbranch_vccnz .LBB0_1139
	s_barrier
	s_branch .LBB0_1139
